# speedup vs baseline: 1.0371x; 1.0064x over previous
; __device__ __forceinline__ float bfs2f(short h) { return __uint_as_float(((unsigned)(u16)h) << 16); }
;   __device__ __forceinline__ void tile(const float* reg, int row0, int col0, int lane) const {
;     rows4(reg, lane, [&](int it, int rr, int c4, float4 v) {
;       int idx = (row0 + rr) * 1024 + col0 + c4;
;       bf16x4 gt = *(const bf16x4*)(gate + idx);
;       *(bf16x4*)(merged + idx) = pack4(bfs2f(gt[0]) * v.x, bfs2f(gt[1]) * v.y, bfs2f(gt[2]) * v.z, bfs2f(gt[3]) * v.w);
;     });
; template <int MF, class Epi>
; __device__ __forceinline__ void staged_epilogue(f32x4 (&acc)[MF][4], int row0, int col0, const Epi& epi) {
;     ...
; #pragma unroll
;   for (int mp = 0; mp < MF / 2; ++mp) {
;     __builtin_amdgcn_sched_barrier(0);
; #pragma unroll
;     for (int mm = 0; mm < 2; ++mm)
; #pragma unroll
;       for (int n = 0; n < 4; ++n)
; #pragma unroll
;         for (int j = 0; j < 4; ++j) reg[(mm * 16 + fq * 4 + j) * 68 + n * 16 + fr] = acc[mp * 2 + mm][n][j];
;     __builtin_amdgcn_fence(__ATOMIC_ACQ_REL, "wavefront");
;     epi.tile(reg, row0 + mp * 32, col0, lane);
.LBB0_1372:
	v_mov_b32_e32 v128, v204
	v_mov_b32_e32 v130, v204
	s_nop 0
	v_lshrrev_b32_e32 v130, 6, v130
	v_mul_lo_u32 v130, v130, s46
	v_and_b32_e32 v131, 15, v128
	v_add_u32_e32 v130, 0x10000, v130
	v_lshrrev_b32_e32 v134, 2, v128
	v_bfe_u32 v140, v128, 4, 2
	v_lshlrev_b32_e32 v128, 2, v128
	v_lshl_or_b32 v142, v131, 2, v130
	v_and_b32_e32 v131, 60, v128
	v_lshl_or_b32 v128, v131, 2, v130
	v_and_b32_e32 v141, 12, v134
	v_mad_u32_u24 v128, v140, s47, v128
	v_add_u32_e32 v129, v131, v129
	v_or_b32_e32 v139, 4, v140
	v_or_b32_e32 v138, 8, v140
	v_or_b32_e32 v137, 12, v140
	v_or_b32_e32 v136, 16, v140
	v_or_b32_e32 v134, 20, v140
	v_or_b32_e32 v131, 24, v140
	v_or_b32_e32 v130, 28, v140
	v_mad_u32_u24 v141, v141, s47, v142
	ds_write2_b32 v141, v120, v124 offset1:16
	ds_write2_b32 v141, v121, v125 offset0:68 offset1:84
	ds_write2_b32 v141, v122, v126 offset0:136 offset1:152
	ds_write2_b32 v141, v123, v127 offset0:204 offset1:220
	ds_write2_b32 v141, v112, v116 offset0:32 offset1:48
	ds_write2_b32 v141, v113, v117 offset0:100 offset1:116
	ds_write2_b32 v141, v114, v118 offset0:168 offset1:184
	ds_write2_b32 v141, v115, v119 offset0:236 offset1:252
	v_add_u32_e32 v112, 0x1000, v141
	ds_write2_b32 v112, v104, v108 offset0:64 offset1:80
	ds_write2_b32 v112, v105, v109 offset0:132 offset1:148
	ds_write2_b32 v112, v106, v110 offset0:200 offset1:216
	v_add_u32_e32 v104, 0x1400, v141
	ds_write2_b32 v104, v107, v111 offset0:12 offset1:28
	ds_write2_b32 v112, v96, v100 offset0:96 offset1:112
	ds_write2_b32 v112, v97, v101 offset0:164 offset1:180
	ds_write2_b32 v112, v98, v102 offset0:232 offset1:248
	ds_write2_b32 v104, v99, v103 offset0:44 offset1:60
	v_add_u32_e32 v176, v140, v135
	v_lshl_add_u32 v176, v176, 10, v129
	v_ashrrev_i32_e32 v177, 31, v176
	v_lshlrev_b64 v[178:179], 1, v[176:177]
	v_lshl_add_u64 v[176:177], s[4:5], 0, v[178:179]
	global_load_dwordx2 v[144:145], v[176:177], off
	v_add_u32_e32 v184, v139, v135
	v_lshl_add_u32 v176, v184, 10, v129
	v_ashrrev_i32_e32 v177, 31, v176
	v_lshlrev_b64 v[176:177], 1, v[176:177]
	v_lshl_add_u64 v[178:179], s[4:5], 0, v[176:177]
	global_load_dwordx2 v[146:147], v[178:179], off
	v_add_u32_e32 v176, v138, v135
	v_lshl_add_u32 v176, v176, 10, v129
	v_ashrrev_i32_e32 v177, 31, v176
	v_lshlrev_b64 v[178:179], 1, v[176:177]
	v_lshl_add_u64 v[180:181], s[4:5], 0, v[178:179]
	global_load_dwordx2 v[148:149], v[180:181], off
	v_add_u32_e32 v184, v137, v135
	v_lshl_add_u32 v176, v184, 10, v129
	v_ashrrev_i32_e32 v177, 31, v176
	v_lshlrev_b64 v[176:177], 1, v[176:177]
	v_lshl_add_u64 v[178:179], s[4:5], 0, v[176:177]
	global_load_dwordx2 v[150:151], v[178:179], off
	v_add_u32_e32 v176, v136, v135
	v_lshl_add_u32 v176, v176, 10, v129
	v_ashrrev_i32_e32 v177, 31, v176
	v_lshlrev_b64 v[178:179], 1, v[176:177]
	v_lshl_add_u64 v[176:177], s[4:5], 0, v[178:179]
	global_load_dwordx2 v[152:153], v[176:177], off
	v_add_u32_e32 v184, v134, v135
	v_lshl_add_u32 v176, v184, 10, v129
	v_ashrrev_i32_e32 v177, 31, v176
	v_lshlrev_b64 v[176:177], 1, v[176:177]
	v_lshl_add_u64 v[178:179], s[4:5], 0, v[176:177]
	global_load_dwordx2 v[154:155], v[178:179], off
	v_add_u32_e32 v176, v131, v135
	v_lshl_add_u32 v176, v176, 10, v129
	v_ashrrev_i32_e32 v177, 31, v176
	v_lshlrev_b64 v[178:179], 1, v[176:177]
	v_lshl_add_u64 v[180:181], s[4:5], 0, v[178:179]
	global_load_dwordx2 v[156:157], v[180:181], off
	v_add_u32_e32 v184, v130, v135
	v_lshl_add_u32 v176, v184, 10, v129
	v_ashrrev_i32_e32 v177, 31, v176
	v_lshlrev_b64 v[176:177], 1, v[176:177]
	v_lshl_add_u64 v[178:179], s[4:5], 0, v[176:177]
	global_load_dwordx2 v[158:159], v[178:179], off
	v_add_u32_e32 v96, v140, v135
	v_lshl_add_u32 v96, v96, 10, v129
	v_ashrrev_i32_e32 v97, 31, v96
	v_lshlrev_b64 v[106:107], 1, v[96:97]
	v_lshl_add_u64 v[96:97], s[4:5], 0, v[106:107]
	s_waitcnt vmcnt(7)
	v_mov_b32_e32 v108, v144
	v_mov_b32_e32 v109, v145
	ds_read_b128 v[96:99], v128
	ds_read_b128 v[100:103], v128 offset:1088
	v_add_u32_e32 v105, v139, v135
	v_lshl_add_u32 v110, v105, 10, v129
	v_ashrrev_i32_e32 v111, 31, v110
	v_lshlrev_b64 v[110:111], 1, v[110:111]
	v_lshl_add_u64 v[106:107], s[10:11], 0, v[106:107]
	v_lshl_add_u64 v[114:115], s[4:5], 0, v[110:111]
	v_add_u32_e32 v105, v137, v135
	v_and_b32_e32 v117, 0xffff0000, v108
	v_lshlrev_b32_e32 v116, 16, v108
	v_and_b32_e32 v119, 0xffff0000, v109
	v_lshlrev_b32_e32 v118, 16, v109
	s_waitcnt lgkmcnt(0)
	v_pk_mul_f32 v[96:97], v[96:97], v[116:117]
	v_pk_mul_f32 v[98:99], v[98:99], v[118:119]
	v_cvt_pk_bf16_f32 v96, v96, v97
	v_cvt_pk_bf16_f32 v97, v98, v99
	global_store_dwordx2 v[106:107], v[96:97], off
	v_add_u32_e32 v98, v138, v135
	v_lshl_add_u32 v98, v98, 10, v129
	v_ashrrev_i32_e32 v99, 31, v98
	v_lshlrev_b64 v[106:107], 1, v[98:99]
	v_lshl_add_u64 v[98:99], s[10:11], 0, v[110:111]
	v_lshl_add_u64 v[108:109], s[4:5], 0, v[106:107]
	v_lshl_add_u64 v[106:107], s[10:11], 0, v[106:107]
	s_waitcnt vmcnt(7)
	v_mov_b32_e32 v96, v146
	v_mov_b32_e32 v97, v147
	v_and_b32_e32 v111, 0xffff0000, v96
	v_lshlrev_b32_e32 v110, 16, v96
	v_and_b32_e32 v115, 0xffff0000, v97
	v_lshlrev_b32_e32 v114, 16, v97
	v_pk_mul_f32 v[96:97], v[100:101], v[110:111]
	v_pk_mul_f32 v[100:101], v[102:103], v[114:115]
	v_cvt_pk_bf16_f32 v96, v96, v97
	v_cvt_pk_bf16_f32 v97, v100, v101
	global_store_dwordx2 v[98:99], v[96:97], off
	ds_read_b128 v[96:99], v128 offset:2176
	ds_read_b128 v[100:103], v128 offset:3264
	v_lshl_add_u32 v110, v105, 10, v129
	v_ashrrev_i32_e32 v111, 31, v110
	v_lshlrev_b64 v[110:111], 1, v[110:111]
	v_lshl_add_u64 v[114:115], s[4:5], 0, v[110:111]
	s_waitcnt vmcnt(7)
; __device__ __forceinline__ float bfs2f(short h) { return __uint_as_float(((unsigned)(u16)h) << 16); }
;   __device__ __forceinline__ void tile(const float* reg, int row0, int col0, int lane) const {
;     rows4(reg, lane, [&](int it, int rr, int c4, float4 v) {
;       int idx = (row0 + rr) * 1024 + col0 + c4;
;       bf16x4 gt = *(const bf16x4*)(gate + idx);
;       *(bf16x4*)(merged + idx) = pack4(bfs2f(gt[0]) * v.x, bfs2f(gt[1]) * v.y, bfs2f(gt[2]) * v.z, bfs2f(gt[3]) * v.w);
;     });
; template <int MF, class Epi>
; __device__ __forceinline__ void staged_epilogue(f32x4 (&acc)[MF][4], int row0, int col0, const Epi& epi) {
;     ...
; #pragma unroll
;   for (int mp = 0; mp < MF / 2; ++mp) {
;     __builtin_amdgcn_sched_barrier(0);
; #pragma unroll
;     for (int mm = 0; mm < 2; ++mm)
; #pragma unroll
;       for (int n = 0; n < 4; ++n)
; #pragma unroll
;         for (int j = 0; j < 4; ++j) reg[(mm * 16 + fq * 4 + j) * 68 + n * 16 + fr] = acc[mp * 2 + mm][n][j];
;     __builtin_amdgcn_fence(__ATOMIC_ACQ_REL, "wavefront");
;     epi.tile(reg, row0 + mp * 32, col0, lane);
	v_mov_b32_e32 v108, v148
	v_mov_b32_e32 v109, v149
	v_and_b32_e32 v117, 0xffff0000, v108
	v_lshlrev_b32_e32 v116, 16, v108
	v_and_b32_e32 v119, 0xffff0000, v109
	v_lshlrev_b32_e32 v118, 16, v109
	s_waitcnt lgkmcnt(1)
	v_pk_mul_f32 v[96:97], v[96:97], v[116:117]
	v_pk_mul_f32 v[98:99], v[98:99], v[118:119]
	v_cvt_pk_bf16_f32 v96, v96, v97
	v_cvt_pk_bf16_f32 v97, v98, v99
	global_store_dwordx2 v[106:107], v[96:97], off
	s_waitcnt vmcnt(7)
	v_mov_b32_e32 v96, v150
	v_mov_b32_e32 v97, v151
	v_and_b32_e32 v99, 0xffff0000, v96
	v_lshlrev_b32_e32 v98, 16, v96
	v_and_b32_e32 v107, 0xffff0000, v97
	v_lshlrev_b32_e32 v106, 16, v97
	s_waitcnt lgkmcnt(0)
	v_pk_mul_f32 v[96:97], v[100:101], v[98:99]
	v_pk_mul_f32 v[98:99], v[102:103], v[106:107]
	v_cvt_pk_bf16_f32 v96, v96, v97
	v_cvt_pk_bf16_f32 v97, v98, v99
	v_lshl_add_u64 v[98:99], s[10:11], 0, v[110:111]
	global_store_dwordx2 v[98:99], v[96:97], off
	v_add_u32_e32 v96, v136, v135
	v_lshl_add_u32 v96, v96, 10, v129
	v_ashrrev_i32_e32 v97, 31, v96
	v_lshlrev_b64 v[106:107], 1, v[96:97]
	v_lshl_add_u64 v[96:97], s[4:5], 0, v[106:107]
	ds_read_b128 v[96:99], v128 offset:4352
	ds_read_b128 v[100:103], v128 offset:5440
	v_add_u32_e32 v105, v134, v135
	v_lshl_add_u32 v110, v105, 10, v129
	v_ashrrev_i32_e32 v111, 31, v110
	v_lshlrev_b64 v[110:111], 1, v[110:111]
	v_lshl_add_u64 v[106:107], s[10:11], 0, v[106:107]
	v_lshl_add_u64 v[114:115], s[4:5], 0, v[110:111]
	v_add_u32_e32 v105, v130, v135
	s_waitcnt vmcnt(7)
	v_mov_b32_e32 v108, v152
	v_mov_b32_e32 v109, v153
	v_and_b32_e32 v117, 0xffff0000, v108
	v_lshlrev_b32_e32 v116, 16, v108
	v_and_b32_e32 v119, 0xffff0000, v109
	v_lshlrev_b32_e32 v118, 16, v109
	s_waitcnt lgkmcnt(1)
	v_pk_mul_f32 v[96:97], v[96:97], v[116:117]
	v_pk_mul_f32 v[98:99], v[98:99], v[118:119]
	v_cvt_pk_bf16_f32 v96, v96, v97
	v_cvt_pk_bf16_f32 v97, v98, v99
	global_store_dwordx2 v[106:107], v[96:97], off
	v_add_u32_e32 v98, v131, v135
	v_lshl_add_u32 v98, v98, 10, v129
	v_ashrrev_i32_e32 v99, 31, v98
	v_lshlrev_b64 v[106:107], 1, v[98:99]
	v_lshl_add_u64 v[98:99], s[10:11], 0, v[110:111]
	v_lshl_add_u64 v[108:109], s[4:5], 0, v[106:107]
	v_lshl_add_u64 v[106:107], s[10:11], 0, v[106:107]
	s_waitcnt vmcnt(7)
	v_mov_b32_e32 v96, v154
	v_mov_b32_e32 v97, v155
	v_and_b32_e32 v111, 0xffff0000, v96
	v_lshlrev_b32_e32 v110, 16, v96
	v_and_b32_e32 v115, 0xffff0000, v97
	v_lshlrev_b32_e32 v114, 16, v97
	s_waitcnt lgkmcnt(0)
	v_pk_mul_f32 v[96:97], v[100:101], v[110:111]
	v_pk_mul_f32 v[100:101], v[102:103], v[114:115]
	v_cvt_pk_bf16_f32 v96, v96, v97
	v_cvt_pk_bf16_f32 v97, v100, v101
	global_store_dwordx2 v[98:99], v[96:97], off
	ds_read_b128 v[96:99], v128 offset:6528
	ds_read_b128 v[100:103], v128 offset:7616
	v_lshl_add_u32 v110, v105, 10, v129
	v_ashrrev_i32_e32 v111, 31, v110
	v_lshlrev_b64 v[110:111], 1, v[110:111]
	v_lshl_add_u64 v[114:115], s[4:5], 0, v[110:111]
	s_waitcnt vmcnt(7)
	v_mov_b32_e32 v108, v156
	v_mov_b32_e32 v109, v157
	v_and_b32_e32 v117, 0xffff0000, v108
	v_lshlrev_b32_e32 v116, 16, v108
	v_and_b32_e32 v119, 0xffff0000, v109
	v_lshlrev_b32_e32 v118, 16, v109
	s_waitcnt lgkmcnt(1)
	v_pk_mul_f32 v[96:97], v[96:97], v[116:117]
	v_pk_mul_f32 v[98:99], v[98:99], v[118:119]
	v_cvt_pk_bf16_f32 v96, v96, v97
	v_cvt_pk_bf16_f32 v97, v98, v99
	global_store_dwordx2 v[106:107], v[96:97], off
	v_lshl_add_u64 v[98:99], s[10:11], 0, v[110:111]
	s_waitcnt vmcnt(7)
	v_mov_b32_e32 v96, v158
	v_mov_b32_e32 v97, v159
	v_and_b32_e32 v107, 0xffff0000, v96
	v_lshlrev_b32_e32 v106, 16, v96
	v_and_b32_e32 v109, 0xffff0000, v97
	v_lshlrev_b32_e32 v108, 16, v97
	s_waitcnt lgkmcnt(0)
	v_pk_mul_f32 v[96:97], v[100:101], v[106:107]
	v_pk_mul_f32 v[100:101], v[102:103], v[108:109]
	v_cvt_pk_bf16_f32 v96, v96, v97
	v_cvt_pk_bf16_f32 v97, v100, v101
	global_store_dwordx2 v[98:99], v[96:97], off
	ds_write2_b32 v141, v88, v92 offset1:16
	ds_write2_b32 v141, v89, v93 offset0:68 offset1:84
	ds_write2_b32 v141, v90, v94 offset0:136 offset1:152
	ds_write2_b32 v141, v91, v95 offset0:204 offset1:220
	ds_write2_b32 v141, v80, v84 offset0:32 offset1:48
	ds_write2_b32 v141, v81, v85 offset0:100 offset1:116
	ds_write2_b32 v141, v82, v86 offset0:168 offset1:184
	ds_write2_b32 v141, v83, v87 offset0:236 offset1:252
	ds_write2_b32 v112, v72, v76 offset0:64 offset1:80
	ds_write2_b32 v112, v73, v77 offset0:132 offset1:148
	ds_write2_b32 v112, v74, v78 offset0:200 offset1:216
	ds_write2_b32 v104, v75, v79 offset0:12 offset1:28
	ds_write2_b32 v112, v64, v68 offset0:96 offset1:112
	ds_write2_b32 v112, v65, v69 offset0:164 offset1:180
	ds_write2_b32 v112, v66, v70 offset0:232 offset1:248
	ds_write2_b32 v104, v67, v71 offset0:44 offset1:60
	v_add_u32_e32 v184, 32, v135
	v_add_u32_e32 v176, v140, v184
	v_lshl_add_u32 v176, v176, 10, v129
	v_ashrrev_i32_e32 v177, 31, v176
	v_lshlrev_b64 v[178:179], 1, v[176:177]
	v_lshl_add_u64 v[176:177], s[4:5], 0, v[178:179]
	global_load_dwordx2 v[144:145], v[176:177], off
	v_add_u32_e32 v184, 32, v135
	v_add_u32_e32 v176, v139, v184
	v_lshl_add_u32 v176, v176, 10, v129
	v_ashrrev_i32_e32 v177, 31, v176
	v_lshlrev_b64 v[176:177], 1, v[176:177]
	v_lshl_add_u64 v[178:179], s[4:5], 0, v[176:177]
	global_load_dwordx2 v[146:147], v[178:179], off
	v_add_u32_e32 v184, 32, v135
	v_add_u32_e32 v176, v138, v184
	v_lshl_add_u32 v176, v176, 10, v129
	v_ashrrev_i32_e32 v177, 31, v176
	v_lshlrev_b64 v[178:179], 1, v[176:177]
	v_lshl_add_u64 v[180:181], s[4:5], 0, v[178:179]
	global_load_dwordx2 v[148:149], v[180:181], off
	v_add_u32_e32 v184, 32, v135
	v_add_u32_e32 v176, v137, v184
	v_lshl_add_u32 v176, v176, 10, v129
	v_ashrrev_i32_e32 v177, 31, v176
	v_lshlrev_b64 v[176:177], 1, v[176:177]
; __device__ __forceinline__ float bfs2f(short h) { return __uint_as_float(((unsigned)(u16)h) << 16); }
;   __device__ __forceinline__ void tile(const float* reg, int row0, int col0, int lane) const {
;     rows4(reg, lane, [&](int it, int rr, int c4, float4 v) {
;       int idx = (row0 + rr) * 1024 + col0 + c4;
;       bf16x4 gt = *(const bf16x4*)(gate + idx);
;       *(bf16x4*)(merged + idx) = pack4(bfs2f(gt[0]) * v.x, bfs2f(gt[1]) * v.y, bfs2f(gt[2]) * v.z, bfs2f(gt[3]) * v.w);
;     });
; template <int MF, class Epi>
; __device__ __forceinline__ void staged_epilogue(f32x4 (&acc)[MF][4], int row0, int col0, const Epi& epi) {
;     ...
; #pragma unroll
;   for (int mp = 0; mp < MF / 2; ++mp) {
;     __builtin_amdgcn_sched_barrier(0);
; #pragma unroll
;     for (int mm = 0; mm < 2; ++mm)
; #pragma unroll
;       for (int n = 0; n < 4; ++n)
; #pragma unroll
;         for (int j = 0; j < 4; ++j) reg[(mm * 16 + fq * 4 + j) * 68 + n * 16 + fr] = acc[mp * 2 + mm][n][j];
;     __builtin_amdgcn_fence(__ATOMIC_ACQ_REL, "wavefront");
;     epi.tile(reg, row0 + mp * 32, col0, lane);
	v_lshl_add_u64 v[178:179], s[4:5], 0, v[176:177]
	global_load_dwordx2 v[150:151], v[178:179], off
	v_add_u32_e32 v184, 32, v135
	v_add_u32_e32 v176, v136, v184
	v_lshl_add_u32 v176, v176, 10, v129
	v_ashrrev_i32_e32 v177, 31, v176
	v_lshlrev_b64 v[178:179], 1, v[176:177]
	v_lshl_add_u64 v[176:177], s[4:5], 0, v[178:179]
	global_load_dwordx2 v[152:153], v[176:177], off
	v_add_u32_e32 v184, 32, v135
	v_add_u32_e32 v176, v134, v184
	v_lshl_add_u32 v176, v176, 10, v129
	v_ashrrev_i32_e32 v177, 31, v176
	v_lshlrev_b64 v[176:177], 1, v[176:177]
	v_lshl_add_u64 v[178:179], s[4:5], 0, v[176:177]
	global_load_dwordx2 v[154:155], v[178:179], off
	v_add_u32_e32 v184, 32, v135
	v_add_u32_e32 v176, v131, v184
	v_lshl_add_u32 v176, v176, 10, v129
	v_ashrrev_i32_e32 v177, 31, v176
	v_lshlrev_b64 v[178:179], 1, v[176:177]
	v_lshl_add_u64 v[180:181], s[4:5], 0, v[178:179]
	global_load_dwordx2 v[156:157], v[180:181], off
	v_add_u32_e32 v184, 32, v135
	v_add_u32_e32 v176, v130, v184
	v_lshl_add_u32 v176, v176, 10, v129
	v_ashrrev_i32_e32 v177, 31, v176
	v_lshlrev_b64 v[176:177], 1, v[176:177]
	v_lshl_add_u64 v[178:179], s[4:5], 0, v[176:177]
	global_load_dwordx2 v[158:159], v[178:179], off
	v_add_u32_e32 v84, 32, v135
	v_add_u32_e32 v64, v140, v84
	v_lshl_add_u32 v64, v64, 10, v129
	v_ashrrev_i32_e32 v65, 31, v64
	v_lshlrev_b64 v[72:73], 1, v[64:65]
	v_lshl_add_u64 v[64:65], s[4:5], 0, v[72:73]
	ds_read_b128 v[64:67], v128
	ds_read_b128 v[68:71], v128 offset:1088
	v_add_u32_e32 v76, v139, v84
	v_lshl_add_u32 v76, v76, 10, v129
	v_ashrrev_i32_e32 v77, 31, v76
	v_lshlrev_b64 v[76:77], 1, v[76:77]
	v_lshl_add_u64 v[72:73], s[10:11], 0, v[72:73]
	v_lshl_add_u64 v[78:79], s[4:5], 0, v[76:77]
	s_waitcnt vmcnt(7)
	v_mov_b32_e32 v74, v144
	v_mov_b32_e32 v75, v145
	v_and_b32_e32 v81, 0xffff0000, v74
	v_lshlrev_b32_e32 v80, 16, v74
	v_and_b32_e32 v83, 0xffff0000, v75
	v_lshlrev_b32_e32 v82, 16, v75
	s_waitcnt lgkmcnt(1)
	v_pk_mul_f32 v[64:65], v[64:65], v[80:81]
	v_pk_mul_f32 v[66:67], v[66:67], v[82:83]
	v_cvt_pk_bf16_f32 v64, v64, v65
	v_cvt_pk_bf16_f32 v65, v66, v67
	global_store_dwordx2 v[72:73], v[64:65], off
	v_add_u32_e32 v66, v138, v84
	v_lshl_add_u32 v66, v66, 10, v129
	v_ashrrev_i32_e32 v67, 31, v66
	v_lshlrev_b64 v[72:73], 1, v[66:67]
	v_lshl_add_u64 v[66:67], s[10:11], 0, v[76:77]
	v_lshl_add_u64 v[74:75], s[4:5], 0, v[72:73]
	v_lshl_add_u64 v[72:73], s[10:11], 0, v[72:73]
	s_waitcnt vmcnt(7)
	v_mov_b32_e32 v64, v146
	v_mov_b32_e32 v65, v147
	v_and_b32_e32 v77, 0xffff0000, v64
	v_lshlrev_b32_e32 v76, 16, v64
	v_and_b32_e32 v79, 0xffff0000, v65
	v_lshlrev_b32_e32 v78, 16, v65
	s_waitcnt lgkmcnt(0)
	v_pk_mul_f32 v[64:65], v[68:69], v[76:77]
	v_pk_mul_f32 v[68:69], v[70:71], v[78:79]
	v_cvt_pk_bf16_f32 v64, v64, v65
	v_cvt_pk_bf16_f32 v65, v68, v69
	global_store_dwordx2 v[66:67], v[64:65], off
	ds_read_b128 v[64:67], v128 offset:2176
	ds_read_b128 v[68:71], v128 offset:3264
	v_add_u32_e32 v76, v137, v84
	v_lshl_add_u32 v76, v76, 10, v129
	v_ashrrev_i32_e32 v77, 31, v76
	v_lshlrev_b64 v[76:77], 1, v[76:77]
	v_lshl_add_u64 v[78:79], s[4:5], 0, v[76:77]
	s_waitcnt vmcnt(7)
	v_mov_b32_e32 v74, v148
	v_mov_b32_e32 v75, v149
	v_and_b32_e32 v81, 0xffff0000, v74
	v_lshlrev_b32_e32 v80, 16, v74
	v_and_b32_e32 v83, 0xffff0000, v75
	v_lshlrev_b32_e32 v82, 16, v75
	s_waitcnt lgkmcnt(1)
	v_pk_mul_f32 v[64:65], v[64:65], v[80:81]
	v_pk_mul_f32 v[66:67], v[66:67], v[82:83]
	v_cvt_pk_bf16_f32 v64, v64, v65
	v_cvt_pk_bf16_f32 v65, v66, v67
	global_store_dwordx2 v[72:73], v[64:65], off
	s_waitcnt vmcnt(7)
	v_mov_b32_e32 v64, v150
	v_mov_b32_e32 v65, v151
	v_and_b32_e32 v67, 0xffff0000, v64
	v_lshlrev_b32_e32 v66, 16, v64
	v_and_b32_e32 v73, 0xffff0000, v65
	v_lshlrev_b32_e32 v72, 16, v65
	s_waitcnt lgkmcnt(0)
	v_pk_mul_f32 v[64:65], v[68:69], v[66:67]
	v_pk_mul_f32 v[66:67], v[70:71], v[72:73]
	v_cvt_pk_bf16_f32 v64, v64, v65
	v_cvt_pk_bf16_f32 v65, v66, v67
	v_lshl_add_u64 v[66:67], s[10:11], 0, v[76:77]
	global_store_dwordx2 v[66:67], v[64:65], off
	v_add_u32_e32 v64, v136, v84
	v_lshl_add_u32 v64, v64, 10, v129
	v_ashrrev_i32_e32 v65, 31, v64
	v_lshlrev_b64 v[72:73], 1, v[64:65]
	v_lshl_add_u64 v[64:65], s[4:5], 0, v[72:73]
	ds_read_b128 v[64:67], v128 offset:4352
	ds_read_b128 v[68:71], v128 offset:5440
	v_add_u32_e32 v76, v134, v84
	v_lshl_add_u32 v76, v76, 10, v129
	v_ashrrev_i32_e32 v77, 31, v76
	v_lshlrev_b64 v[76:77], 1, v[76:77]
	v_lshl_add_u64 v[72:73], s[10:11], 0, v[72:73]
	v_lshl_add_u64 v[78:79], s[4:5], 0, v[76:77]
	s_waitcnt vmcnt(7)
	v_mov_b32_e32 v74, v152
	v_mov_b32_e32 v75, v153
	v_and_b32_e32 v81, 0xffff0000, v74
	v_lshlrev_b32_e32 v80, 16, v74
	v_and_b32_e32 v83, 0xffff0000, v75
	v_lshlrev_b32_e32 v82, 16, v75
	s_waitcnt lgkmcnt(1)
	v_pk_mul_f32 v[64:65], v[64:65], v[80:81]
	v_pk_mul_f32 v[66:67], v[66:67], v[82:83]
	v_cvt_pk_bf16_f32 v64, v64, v65
	v_cvt_pk_bf16_f32 v65, v66, v67
	global_store_dwordx2 v[72:73], v[64:65], off
	v_add_u32_e32 v66, v131, v84
	v_lshl_add_u32 v66, v66, 10, v129
	v_ashrrev_i32_e32 v67, 31, v66
	v_lshlrev_b64 v[72:73], 1, v[66:67]
	v_lshl_add_u64 v[66:67], s[10:11], 0, v[76:77]
	v_lshl_add_u64 v[74:75], s[4:5], 0, v[72:73]
	v_lshl_add_u64 v[72:73], s[10:11], 0, v[72:73]
	s_waitcnt vmcnt(7)
	v_mov_b32_e32 v64, v154
	v_mov_b32_e32 v65, v155
	v_and_b32_e32 v77, 0xffff0000, v64
	v_lshlrev_b32_e32 v76, 16, v64
	v_and_b32_e32 v79, 0xffff0000, v65
	v_lshlrev_b32_e32 v78, 16, v65
	s_waitcnt lgkmcnt(0)
; __device__ __forceinline__ float bfs2f(short h) { return __uint_as_float(((unsigned)(u16)h) << 16); }
;   __device__ __forceinline__ void tile(const float* reg, int row0, int col0, int lane) const {
;     rows4(reg, lane, [&](int it, int rr, int c4, float4 v) {
;       int idx = (row0 + rr) * 1024 + col0 + c4;
;       bf16x4 gt = *(const bf16x4*)(gate + idx);
;       *(bf16x4*)(merged + idx) = pack4(bfs2f(gt[0]) * v.x, bfs2f(gt[1]) * v.y, bfs2f(gt[2]) * v.z, bfs2f(gt[3]) * v.w);
;     });
; template <int MF, class Epi>
; __device__ __forceinline__ void staged_epilogue(f32x4 (&acc)[MF][4], int row0, int col0, const Epi& epi) {
;     ...
; #pragma unroll
;   for (int mp = 0; mp < MF / 2; ++mp) {
;     __builtin_amdgcn_sched_barrier(0);
; #pragma unroll
;     for (int mm = 0; mm < 2; ++mm)
; #pragma unroll
;       for (int n = 0; n < 4; ++n)
; #pragma unroll
;         for (int j = 0; j < 4; ++j) reg[(mm * 16 + fq * 4 + j) * 68 + n * 16 + fr] = acc[mp * 2 + mm][n][j];
;     __builtin_amdgcn_fence(__ATOMIC_ACQ_REL, "wavefront");
;     epi.tile(reg, row0 + mp * 32, col0, lane);
	v_pk_mul_f32 v[64:65], v[68:69], v[76:77]
	v_pk_mul_f32 v[68:69], v[70:71], v[78:79]
	v_cvt_pk_bf16_f32 v64, v64, v65
	v_cvt_pk_bf16_f32 v65, v68, v69
	global_store_dwordx2 v[66:67], v[64:65], off
	ds_read_b128 v[64:67], v128 offset:6528
	ds_read_b128 v[68:71], v128 offset:7616
	v_add_u32_e32 v76, v130, v84
	v_lshl_add_u32 v76, v76, 10, v129
	v_ashrrev_i32_e32 v77, 31, v76
	v_lshlrev_b64 v[76:77], 1, v[76:77]
	v_lshl_add_u64 v[78:79], s[4:5], 0, v[76:77]
	s_waitcnt vmcnt(7)
	v_mov_b32_e32 v74, v156
	v_mov_b32_e32 v75, v157
	v_and_b32_e32 v81, 0xffff0000, v74
	v_lshlrev_b32_e32 v80, 16, v74
	v_and_b32_e32 v83, 0xffff0000, v75
	v_lshlrev_b32_e32 v82, 16, v75
	s_waitcnt lgkmcnt(1)
	v_pk_mul_f32 v[64:65], v[64:65], v[80:81]
	v_pk_mul_f32 v[66:67], v[66:67], v[82:83]
	v_cvt_pk_bf16_f32 v64, v64, v65
	v_cvt_pk_bf16_f32 v65, v66, v67
	global_store_dwordx2 v[72:73], v[64:65], off
	v_lshl_add_u64 v[66:67], s[10:11], 0, v[76:77]
	s_waitcnt vmcnt(7)
	v_mov_b32_e32 v64, v158
	v_mov_b32_e32 v65, v159
	v_and_b32_e32 v73, 0xffff0000, v64
	v_lshlrev_b32_e32 v72, 16, v64
	v_and_b32_e32 v75, 0xffff0000, v65
	v_lshlrev_b32_e32 v74, 16, v65
	s_waitcnt lgkmcnt(0)
	v_pk_mul_f32 v[64:65], v[68:69], v[72:73]
	v_pk_mul_f32 v[68:69], v[70:71], v[74:75]
	v_cvt_pk_bf16_f32 v64, v64, v65
	v_cvt_pk_bf16_f32 v65, v68, v69
	global_store_dwordx2 v[66:67], v[64:65], off
	ds_write2_b32 v141, v56, v60 offset1:16
	ds_write2_b32 v141, v57, v61 offset0:68 offset1:84
	ds_write2_b32 v141, v58, v62 offset0:136 offset1:152
	ds_write2_b32 v141, v59, v63 offset0:204 offset1:220
	ds_write2_b32 v141, v48, v52 offset0:32 offset1:48
	ds_write2_b32 v141, v49, v53 offset0:100 offset1:116
	ds_write2_b32 v141, v50, v54 offset0:168 offset1:184
	ds_write2_b32 v141, v51, v55 offset0:236 offset1:252
	ds_write2_b32 v112, v40, v44 offset0:64 offset1:80
	ds_write2_b32 v112, v41, v45 offset0:132 offset1:148
	ds_write2_b32 v112, v42, v46 offset0:200 offset1:216
	ds_write2_b32 v104, v43, v47 offset0:12 offset1:28
	ds_write2_b32 v112, v32, v36 offset0:96 offset1:112
	ds_write2_b32 v112, v33, v37 offset0:164 offset1:180
	ds_write2_b32 v112, v34, v38 offset0:232 offset1:248
	ds_write2_b32 v104, v35, v39 offset0:44 offset1:60
	v_add_u32_e32 v184, 64, v135
	v_add_u32_e32 v176, v140, v184
	v_lshl_add_u32 v176, v176, 10, v129
	v_ashrrev_i32_e32 v177, 31, v176
	v_lshlrev_b64 v[178:179], 1, v[176:177]
	v_lshl_add_u64 v[176:177], s[4:5], 0, v[178:179]
	global_load_dwordx2 v[144:145], v[176:177], off
	v_add_u32_e32 v184, 64, v135
	v_add_u32_e32 v176, v139, v184
	v_lshl_add_u32 v176, v176, 10, v129
	v_ashrrev_i32_e32 v177, 31, v176
	v_lshlrev_b64 v[176:177], 1, v[176:177]
	v_lshl_add_u64 v[178:179], s[4:5], 0, v[176:177]
	global_load_dwordx2 v[146:147], v[178:179], off
	v_add_u32_e32 v184, 64, v135
	v_add_u32_e32 v176, v138, v184
	v_lshl_add_u32 v176, v176, 10, v129
	v_ashrrev_i32_e32 v177, 31, v176
	v_lshlrev_b64 v[178:179], 1, v[176:177]
	v_lshl_add_u64 v[180:181], s[4:5], 0, v[178:179]
	global_load_dwordx2 v[148:149], v[180:181], off
	v_add_u32_e32 v184, 64, v135
	v_add_u32_e32 v176, v137, v184
	v_lshl_add_u32 v176, v176, 10, v129
	v_ashrrev_i32_e32 v177, 31, v176
	v_lshlrev_b64 v[176:177], 1, v[176:177]
	v_lshl_add_u64 v[178:179], s[4:5], 0, v[176:177]
	global_load_dwordx2 v[150:151], v[178:179], off
	v_add_u32_e32 v184, 64, v135
	v_add_u32_e32 v176, v136, v184
	v_lshl_add_u32 v176, v176, 10, v129
	v_ashrrev_i32_e32 v177, 31, v176
	v_lshlrev_b64 v[178:179], 1, v[176:177]
	v_lshl_add_u64 v[176:177], s[4:5], 0, v[178:179]
	global_load_dwordx2 v[152:153], v[176:177], off
	v_add_u32_e32 v184, 64, v135
	v_add_u32_e32 v176, v134, v184
	v_lshl_add_u32 v176, v176, 10, v129
	v_ashrrev_i32_e32 v177, 31, v176
	v_lshlrev_b64 v[176:177], 1, v[176:177]
	v_lshl_add_u64 v[178:179], s[4:5], 0, v[176:177]
	global_load_dwordx2 v[154:155], v[178:179], off
	v_add_u32_e32 v184, 64, v135
	v_add_u32_e32 v176, v131, v184
	v_lshl_add_u32 v176, v176, 10, v129
	v_ashrrev_i32_e32 v177, 31, v176
	v_lshlrev_b64 v[178:179], 1, v[176:177]
	v_lshl_add_u64 v[180:181], s[4:5], 0, v[178:179]
	global_load_dwordx2 v[156:157], v[180:181], off
	v_add_u32_e32 v184, 64, v135
	v_add_u32_e32 v176, v130, v184
	v_lshl_add_u32 v176, v176, 10, v129
	v_ashrrev_i32_e32 v177, 31, v176
	v_lshlrev_b64 v[176:177], 1, v[176:177]
	v_lshl_add_u64 v[178:179], s[4:5], 0, v[176:177]
	global_load_dwordx2 v[158:159], v[178:179], off
	v_add_u32_e32 v52, 64, v135
	v_add_u32_e32 v32, v140, v52
	v_lshl_add_u32 v32, v32, 10, v129
	v_ashrrev_i32_e32 v33, 31, v32
	v_lshlrev_b64 v[40:41], 1, v[32:33]
	v_lshl_add_u64 v[32:33], s[4:5], 0, v[40:41]
	ds_read_b128 v[32:35], v128
	ds_read_b128 v[36:39], v128 offset:1088
	v_add_u32_e32 v44, v139, v52
	v_lshl_add_u32 v44, v44, 10, v129
	v_ashrrev_i32_e32 v45, 31, v44
	v_lshlrev_b64 v[44:45], 1, v[44:45]
	v_lshl_add_u64 v[40:41], s[10:11], 0, v[40:41]
	v_lshl_add_u64 v[46:47], s[4:5], 0, v[44:45]
	s_waitcnt vmcnt(7)
	v_mov_b32_e32 v42, v144
	v_mov_b32_e32 v43, v145
	v_and_b32_e32 v49, 0xffff0000, v42
	v_lshlrev_b32_e32 v48, 16, v42
	v_and_b32_e32 v51, 0xffff0000, v43
	v_lshlrev_b32_e32 v50, 16, v43
	s_waitcnt lgkmcnt(1)
	v_pk_mul_f32 v[32:33], v[32:33], v[48:49]
	v_pk_mul_f32 v[34:35], v[34:35], v[50:51]
	v_cvt_pk_bf16_f32 v32, v32, v33
	v_cvt_pk_bf16_f32 v33, v34, v35
	global_store_dwordx2 v[40:41], v[32:33], off
	v_add_u32_e32 v34, v138, v52
	v_lshl_add_u32 v34, v34, 10, v129
	v_ashrrev_i32_e32 v35, 31, v34
	v_lshlrev_b64 v[40:41], 1, v[34:35]
	v_lshl_add_u64 v[34:35], s[10:11], 0, v[44:45]
	v_lshl_add_u64 v[42:43], s[4:5], 0, v[40:41]
	v_lshl_add_u64 v[40:41], s[10:11], 0, v[40:41]
	s_waitcnt vmcnt(7)
; __device__ __forceinline__ float bfs2f(short h) { return __uint_as_float(((unsigned)(u16)h) << 16); }
;   __device__ __forceinline__ void tile(const float* reg, int row0, int col0, int lane) const {
;     rows4(reg, lane, [&](int it, int rr, int c4, float4 v) {
;       int idx = (row0 + rr) * 1024 + col0 + c4;
;       bf16x4 gt = *(const bf16x4*)(gate + idx);
;       *(bf16x4*)(merged + idx) = pack4(bfs2f(gt[0]) * v.x, bfs2f(gt[1]) * v.y, bfs2f(gt[2]) * v.z, bfs2f(gt[3]) * v.w);
;     });
; template <int MF, class Epi>
; __device__ __forceinline__ void staged_epilogue(f32x4 (&acc)[MF][4], int row0, int col0, const Epi& epi) {
;     ...
; #pragma unroll
;   for (int mp = 0; mp < MF / 2; ++mp) {
;     __builtin_amdgcn_sched_barrier(0);
; #pragma unroll
;     for (int mm = 0; mm < 2; ++mm)
; #pragma unroll
;       for (int n = 0; n < 4; ++n)
; #pragma unroll
;         for (int j = 0; j < 4; ++j) reg[(mm * 16 + fq * 4 + j) * 68 + n * 16 + fr] = acc[mp * 2 + mm][n][j];
;     __builtin_amdgcn_fence(__ATOMIC_ACQ_REL, "wavefront");
;     epi.tile(reg, row0 + mp * 32, col0, lane);
	v_mov_b32_e32 v32, v146
	v_mov_b32_e32 v33, v147
	v_and_b32_e32 v45, 0xffff0000, v32
	v_lshlrev_b32_e32 v44, 16, v32
	v_and_b32_e32 v47, 0xffff0000, v33
	v_lshlrev_b32_e32 v46, 16, v33
	s_waitcnt lgkmcnt(0)
	v_pk_mul_f32 v[32:33], v[36:37], v[44:45]
	v_pk_mul_f32 v[36:37], v[38:39], v[46:47]
	v_cvt_pk_bf16_f32 v32, v32, v33
	v_cvt_pk_bf16_f32 v33, v36, v37
	global_store_dwordx2 v[34:35], v[32:33], off
	ds_read_b128 v[32:35], v128 offset:2176
	ds_read_b128 v[36:39], v128 offset:3264
	v_add_u32_e32 v44, v137, v52
	v_lshl_add_u32 v44, v44, 10, v129
	v_ashrrev_i32_e32 v45, 31, v44
	v_lshlrev_b64 v[44:45], 1, v[44:45]
	v_lshl_add_u64 v[46:47], s[4:5], 0, v[44:45]
	s_waitcnt vmcnt(7)
	v_mov_b32_e32 v42, v148
	v_mov_b32_e32 v43, v149
	v_and_b32_e32 v49, 0xffff0000, v42
	v_lshlrev_b32_e32 v48, 16, v42
	v_and_b32_e32 v51, 0xffff0000, v43
	v_lshlrev_b32_e32 v50, 16, v43
	s_waitcnt lgkmcnt(1)
	v_pk_mul_f32 v[32:33], v[32:33], v[48:49]
	v_pk_mul_f32 v[34:35], v[34:35], v[50:51]
	v_cvt_pk_bf16_f32 v32, v32, v33
	v_cvt_pk_bf16_f32 v33, v34, v35
	global_store_dwordx2 v[40:41], v[32:33], off
	s_waitcnt vmcnt(7)
	v_mov_b32_e32 v32, v150
	v_mov_b32_e32 v33, v151
	v_and_b32_e32 v35, 0xffff0000, v32
	v_lshlrev_b32_e32 v34, 16, v32
	v_and_b32_e32 v41, 0xffff0000, v33
	v_lshlrev_b32_e32 v40, 16, v33
	s_waitcnt lgkmcnt(0)
	v_pk_mul_f32 v[32:33], v[36:37], v[34:35]
	v_pk_mul_f32 v[34:35], v[38:39], v[40:41]
	v_cvt_pk_bf16_f32 v32, v32, v33
	v_cvt_pk_bf16_f32 v33, v34, v35
	v_lshl_add_u64 v[34:35], s[10:11], 0, v[44:45]
	global_store_dwordx2 v[34:35], v[32:33], off
	v_add_u32_e32 v32, v136, v52
	v_lshl_add_u32 v32, v32, 10, v129
	v_ashrrev_i32_e32 v33, 31, v32
	v_lshlrev_b64 v[40:41], 1, v[32:33]
	v_lshl_add_u64 v[32:33], s[4:5], 0, v[40:41]
	ds_read_b128 v[32:35], v128 offset:4352
	ds_read_b128 v[36:39], v128 offset:5440
	v_add_u32_e32 v44, v134, v52
	v_lshl_add_u32 v44, v44, 10, v129
	v_ashrrev_i32_e32 v45, 31, v44
	v_lshlrev_b64 v[44:45], 1, v[44:45]
	v_lshl_add_u64 v[40:41], s[10:11], 0, v[40:41]
	v_lshl_add_u64 v[46:47], s[4:5], 0, v[44:45]
	s_waitcnt vmcnt(7)
	v_mov_b32_e32 v42, v152
	v_mov_b32_e32 v43, v153
	v_and_b32_e32 v49, 0xffff0000, v42
	v_lshlrev_b32_e32 v48, 16, v42
	v_and_b32_e32 v51, 0xffff0000, v43
	v_lshlrev_b32_e32 v50, 16, v43
	s_waitcnt lgkmcnt(1)
	v_pk_mul_f32 v[32:33], v[32:33], v[48:49]
	v_pk_mul_f32 v[34:35], v[34:35], v[50:51]
	v_cvt_pk_bf16_f32 v32, v32, v33
	v_cvt_pk_bf16_f32 v33, v34, v35
	global_store_dwordx2 v[40:41], v[32:33], off
	v_add_u32_e32 v34, v131, v52
	v_lshl_add_u32 v34, v34, 10, v129
	v_ashrrev_i32_e32 v35, 31, v34
	v_lshlrev_b64 v[40:41], 1, v[34:35]
	v_lshl_add_u64 v[34:35], s[10:11], 0, v[44:45]
	v_lshl_add_u64 v[42:43], s[4:5], 0, v[40:41]
	v_lshl_add_u64 v[40:41], s[10:11], 0, v[40:41]
	s_waitcnt vmcnt(7)
	v_mov_b32_e32 v32, v154
	v_mov_b32_e32 v33, v155
	v_and_b32_e32 v45, 0xffff0000, v32
	v_lshlrev_b32_e32 v44, 16, v32
	v_and_b32_e32 v47, 0xffff0000, v33
	v_lshlrev_b32_e32 v46, 16, v33
	s_waitcnt lgkmcnt(0)
	v_pk_mul_f32 v[32:33], v[36:37], v[44:45]
	v_pk_mul_f32 v[36:37], v[38:39], v[46:47]
	v_cvt_pk_bf16_f32 v32, v32, v33
	v_cvt_pk_bf16_f32 v33, v36, v37
	global_store_dwordx2 v[34:35], v[32:33], off
	ds_read_b128 v[32:35], v128 offset:6528
	ds_read_b128 v[36:39], v128 offset:7616
	v_add_u32_e32 v44, v130, v52
	v_lshl_add_u32 v44, v44, 10, v129
	v_ashrrev_i32_e32 v45, 31, v44
	v_lshlrev_b64 v[44:45], 1, v[44:45]
	v_lshl_add_u64 v[46:47], s[4:5], 0, v[44:45]
	s_waitcnt vmcnt(7)
	v_mov_b32_e32 v42, v156
	v_mov_b32_e32 v43, v157
	v_and_b32_e32 v49, 0xffff0000, v42
	v_lshlrev_b32_e32 v48, 16, v42
	v_and_b32_e32 v51, 0xffff0000, v43
	v_lshlrev_b32_e32 v50, 16, v43
	s_waitcnt lgkmcnt(1)
	v_pk_mul_f32 v[32:33], v[32:33], v[48:49]
	v_pk_mul_f32 v[34:35], v[34:35], v[50:51]
	v_cvt_pk_bf16_f32 v32, v32, v33
	v_cvt_pk_bf16_f32 v33, v34, v35
	global_store_dwordx2 v[40:41], v[32:33], off
	v_lshl_add_u64 v[34:35], s[10:11], 0, v[44:45]
	s_waitcnt vmcnt(7)
	v_mov_b32_e32 v32, v158
	v_mov_b32_e32 v33, v159
	v_and_b32_e32 v41, 0xffff0000, v32
	v_lshlrev_b32_e32 v40, 16, v32
	v_and_b32_e32 v43, 0xffff0000, v33
	v_lshlrev_b32_e32 v42, 16, v33
	s_waitcnt lgkmcnt(0)
	v_pk_mul_f32 v[32:33], v[36:37], v[40:41]
	v_pk_mul_f32 v[36:37], v[38:39], v[42:43]
	v_cvt_pk_bf16_f32 v32, v32, v33
	v_cvt_pk_bf16_f32 v33, v36, v37
	global_store_dwordx2 v[34:35], v[32:33], off
	ds_write2_b32 v141, v24, v28 offset1:16
	ds_write2_b32 v141, v25, v29 offset0:68 offset1:84
	ds_write2_b32 v141, v26, v30 offset0:136 offset1:152
	ds_write2_b32 v141, v27, v31 offset0:204 offset1:220
	ds_write2_b32 v141, v16, v20 offset0:32 offset1:48
	ds_write2_b32 v141, v17, v21 offset0:100 offset1:116
	ds_write2_b32 v141, v18, v22 offset0:168 offset1:184
	ds_write2_b32 v141, v19, v23 offset0:236 offset1:252
	ds_write2_b32 v112, v4, v8 offset0:64 offset1:80
	ds_write2_b32 v112, v5, v9 offset0:132 offset1:148
	ds_write2_b32 v112, v6, v10 offset0:200 offset1:216
	ds_write2_b32 v104, v7, v11 offset0:12 offset1:28
	ds_write2_b32 v112, v0, v12 offset0:96 offset1:112
	ds_write2_b32 v112, v1, v13 offset0:164 offset1:180
	ds_write2_b32 v112, v2, v14 offset0:232 offset1:248
	ds_write2_b32 v104, v3, v15 offset0:44 offset1:60
	v_add_u32_e32 v184, 0x60, v135
	v_add_u32_e32 v176, v140, v184
	v_lshl_add_u32 v176, v176, 10, v129
	v_ashrrev_i32_e32 v177, 31, v176
	v_lshlrev_b64 v[178:179], 1, v[176:177]
	v_lshl_add_u64 v[176:177], s[4:5], 0, v[178:179]
	global_load_dwordx2 v[144:145], v[176:177], off
	v_add_u32_e32 v184, 0x60, v135
	v_add_u32_e32 v176, v139, v184
	v_lshl_add_u32 v176, v176, 10, v129
	v_ashrrev_i32_e32 v177, 31, v176
	v_lshlrev_b64 v[176:177], 1, v[176:177]
; __device__ __forceinline__ float bfs2f(short h) { return __uint_as_float(((unsigned)(u16)h) << 16); }
;   __device__ __forceinline__ void tile(const float* reg, int row0, int col0, int lane) const {
;     rows4(reg, lane, [&](int it, int rr, int c4, float4 v) {
;       int idx = (row0 + rr) * 1024 + col0 + c4;
;       bf16x4 gt = *(const bf16x4*)(gate + idx);
;       *(bf16x4*)(merged + idx) = pack4(bfs2f(gt[0]) * v.x, bfs2f(gt[1]) * v.y, bfs2f(gt[2]) * v.z, bfs2f(gt[3]) * v.w);
;     });
	v_lshl_add_u64 v[178:179], s[4:5], 0, v[176:177]
	global_load_dwordx2 v[146:147], v[178:179], off
	v_add_u32_e32 v184, 0x60, v135
	v_add_u32_e32 v176, v138, v184
	v_lshl_add_u32 v176, v176, 10, v129
	v_ashrrev_i32_e32 v177, 31, v176
	v_lshlrev_b64 v[178:179], 1, v[176:177]
	v_lshl_add_u64 v[180:181], s[4:5], 0, v[178:179]
	global_load_dwordx2 v[148:149], v[180:181], off
	v_add_u32_e32 v184, 0x60, v135
	v_add_u32_e32 v176, v137, v184
	v_lshl_add_u32 v176, v176, 10, v129
	v_ashrrev_i32_e32 v177, 31, v176
	v_lshlrev_b64 v[176:177], 1, v[176:177]
	v_lshl_add_u64 v[178:179], s[4:5], 0, v[176:177]
	global_load_dwordx2 v[150:151], v[178:179], off
	v_add_u32_e32 v184, 0x60, v135
	v_add_u32_e32 v176, v136, v184
	v_lshl_add_u32 v176, v176, 10, v129
	v_ashrrev_i32_e32 v177, 31, v176
	v_lshlrev_b64 v[178:179], 1, v[176:177]
	v_lshl_add_u64 v[176:177], s[4:5], 0, v[178:179]
	global_load_dwordx2 v[152:153], v[176:177], off
	v_add_u32_e32 v184, 0x60, v135
	v_add_u32_e32 v176, v134, v184
	v_lshl_add_u32 v176, v176, 10, v129
	v_ashrrev_i32_e32 v177, 31, v176
	v_lshlrev_b64 v[176:177], 1, v[176:177]
	v_lshl_add_u64 v[178:179], s[4:5], 0, v[176:177]
	global_load_dwordx2 v[154:155], v[178:179], off
	v_add_u32_e32 v184, 0x60, v135
	v_add_u32_e32 v176, v131, v184
	v_lshl_add_u32 v176, v176, 10, v129
	v_ashrrev_i32_e32 v177, 31, v176
	v_lshlrev_b64 v[178:179], 1, v[176:177]
	v_lshl_add_u64 v[180:181], s[4:5], 0, v[178:179]
	global_load_dwordx2 v[156:157], v[180:181], off
	v_add_u32_e32 v184, 0x60, v135
	v_add_u32_e32 v176, v130, v184
	v_lshl_add_u32 v176, v176, 10, v129
	v_ashrrev_i32_e32 v177, 31, v176
	v_lshlrev_b64 v[176:177], 1, v[176:177]
	v_lshl_add_u64 v[178:179], s[4:5], 0, v[176:177]
	global_load_dwordx2 v[158:159], v[178:179], off
	v_add_u32_e32 v20, 0x60, v135
	v_add_u32_e32 v0, v140, v20
	v_lshl_add_u32 v0, v0, 10, v129
	v_ashrrev_i32_e32 v1, 31, v0
	v_lshlrev_b64 v[8:9], 1, v[0:1]
	v_lshl_add_u64 v[0:1], s[4:5], 0, v[8:9]
	ds_read_b128 v[0:3], v128
	ds_read_b128 v[4:7], v128 offset:1088
	v_add_u32_e32 v12, v139, v20
	v_lshl_add_u32 v12, v12, 10, v129
	v_ashrrev_i32_e32 v13, 31, v12
	v_lshlrev_b64 v[12:13], 1, v[12:13]
	v_lshl_add_u64 v[8:9], s[10:11], 0, v[8:9]
	v_lshl_add_u64 v[14:15], s[4:5], 0, v[12:13]
	s_waitcnt vmcnt(7)
	v_mov_b32_e32 v10, v144
	v_mov_b32_e32 v11, v145
	v_and_b32_e32 v17, 0xffff0000, v10
	v_lshlrev_b32_e32 v16, 16, v10
	v_and_b32_e32 v19, 0xffff0000, v11
	v_lshlrev_b32_e32 v18, 16, v11
	s_waitcnt lgkmcnt(1)
	v_pk_mul_f32 v[0:1], v[0:1], v[16:17]
	v_pk_mul_f32 v[2:3], v[2:3], v[18:19]
	v_cvt_pk_bf16_f32 v0, v0, v1
	v_cvt_pk_bf16_f32 v1, v2, v3
	global_store_dwordx2 v[8:9], v[0:1], off
	v_add_u32_e32 v2, v138, v20
	v_lshl_add_u32 v2, v2, 10, v129
	v_ashrrev_i32_e32 v3, 31, v2
	v_lshlrev_b64 v[8:9], 1, v[2:3]
	v_lshl_add_u64 v[2:3], s[10:11], 0, v[12:13]
	v_lshl_add_u64 v[10:11], s[4:5], 0, v[8:9]
	v_lshl_add_u64 v[8:9], s[10:11], 0, v[8:9]
	s_waitcnt vmcnt(7)
	v_mov_b32_e32 v0, v146
	v_mov_b32_e32 v1, v147
	v_and_b32_e32 v13, 0xffff0000, v0
	v_lshlrev_b32_e32 v12, 16, v0
	v_and_b32_e32 v15, 0xffff0000, v1
	v_lshlrev_b32_e32 v14, 16, v1
	s_waitcnt lgkmcnt(0)
	v_pk_mul_f32 v[0:1], v[4:5], v[12:13]
	v_pk_mul_f32 v[4:5], v[6:7], v[14:15]
	v_cvt_pk_bf16_f32 v0, v0, v1
	v_cvt_pk_bf16_f32 v1, v4, v5
	global_store_dwordx2 v[2:3], v[0:1], off
	ds_read_b128 v[0:3], v128 offset:2176
	ds_read_b128 v[4:7], v128 offset:3264
	v_add_u32_e32 v12, v137, v20
	v_lshl_add_u32 v12, v12, 10, v129
	v_ashrrev_i32_e32 v13, 31, v12
	v_lshlrev_b64 v[12:13], 1, v[12:13]
	v_lshl_add_u64 v[14:15], s[4:5], 0, v[12:13]
	s_waitcnt vmcnt(7)
; __device__ __forceinline__ float bfs2f(short h) { return __uint_as_float(((unsigned)(u16)h) << 16); }
;   __device__ __forceinline__ void tile(const float* reg, int row0, int col0, int lane) const {
;     rows4(reg, lane, [&](int it, int rr, int c4, float4 v) {
;       int idx = (row0 + rr) * 1024 + col0 + c4;
;       bf16x4 gt = *(const bf16x4*)(gate + idx);
;       *(bf16x4*)(merged + idx) = pack4(bfs2f(gt[0]) * v.x, bfs2f(gt[1]) * v.y, bfs2f(gt[2]) * v.z, bfs2f(gt[3]) * v.w);
;     });
	v_mov_b32_e32 v10, v148
	v_mov_b32_e32 v11, v149
	v_and_b32_e32 v17, 0xffff0000, v10
	v_lshlrev_b32_e32 v16, 16, v10
	v_and_b32_e32 v19, 0xffff0000, v11
	v_lshlrev_b32_e32 v18, 16, v11
	s_waitcnt lgkmcnt(1)
	v_pk_mul_f32 v[0:1], v[0:1], v[16:17]
	v_pk_mul_f32 v[2:3], v[2:3], v[18:19]
	v_cvt_pk_bf16_f32 v0, v0, v1
	v_cvt_pk_bf16_f32 v1, v2, v3
	global_store_dwordx2 v[8:9], v[0:1], off
	s_waitcnt vmcnt(7)
	v_mov_b32_e32 v0, v150
	v_mov_b32_e32 v1, v151
	v_and_b32_e32 v3, 0xffff0000, v0
	v_lshlrev_b32_e32 v2, 16, v0
	v_and_b32_e32 v9, 0xffff0000, v1
	v_lshlrev_b32_e32 v8, 16, v1
	s_waitcnt lgkmcnt(0)
	v_pk_mul_f32 v[0:1], v[4:5], v[2:3]
	v_pk_mul_f32 v[2:3], v[6:7], v[8:9]
	v_cvt_pk_bf16_f32 v0, v0, v1
	v_cvt_pk_bf16_f32 v1, v2, v3
	v_lshl_add_u64 v[2:3], s[10:11], 0, v[12:13]
	global_store_dwordx2 v[2:3], v[0:1], off
	v_add_u32_e32 v0, v136, v20
	v_lshl_add_u32 v0, v0, 10, v129
	v_ashrrev_i32_e32 v1, 31, v0
	v_lshlrev_b64 v[8:9], 1, v[0:1]
	v_lshl_add_u64 v[0:1], s[4:5], 0, v[8:9]
	ds_read_b128 v[0:3], v128 offset:4352
	ds_read_b128 v[4:7], v128 offset:5440
	v_add_u32_e32 v12, v134, v20
	v_lshl_add_u32 v12, v12, 10, v129
	v_ashrrev_i32_e32 v13, 31, v12
	v_lshlrev_b64 v[12:13], 1, v[12:13]
	v_lshl_add_u64 v[8:9], s[10:11], 0, v[8:9]
	v_lshl_add_u64 v[14:15], s[4:5], 0, v[12:13]
	s_andn2_b64 vcc, exec, s[42:43]
	s_waitcnt vmcnt(7)
	v_mov_b32_e32 v10, v152
	v_mov_b32_e32 v11, v153
	v_and_b32_e32 v17, 0xffff0000, v10
	v_lshlrev_b32_e32 v16, 16, v10
	v_and_b32_e32 v19, 0xffff0000, v11
	v_lshlrev_b32_e32 v18, 16, v11
	s_waitcnt lgkmcnt(1)
	v_pk_mul_f32 v[0:1], v[0:1], v[16:17]
	v_pk_mul_f32 v[2:3], v[2:3], v[18:19]
	v_cvt_pk_bf16_f32 v0, v0, v1
	v_cvt_pk_bf16_f32 v1, v2, v3
	global_store_dwordx2 v[8:9], v[0:1], off
	v_add_u32_e32 v2, v131, v20
	v_lshl_add_u32 v2, v2, 10, v129
	v_ashrrev_i32_e32 v3, 31, v2
	v_lshlrev_b64 v[8:9], 1, v[2:3]
	v_lshl_add_u64 v[2:3], s[10:11], 0, v[12:13]
	v_lshl_add_u64 v[10:11], s[4:5], 0, v[8:9]
	v_lshl_add_u64 v[8:9], s[10:11], 0, v[8:9]
	s_waitcnt vmcnt(7)
	v_mov_b32_e32 v0, v154
	v_mov_b32_e32 v1, v155
	v_and_b32_e32 v13, 0xffff0000, v0
	v_lshlrev_b32_e32 v12, 16, v0
	v_and_b32_e32 v15, 0xffff0000, v1
	v_lshlrev_b32_e32 v14, 16, v1
	s_waitcnt lgkmcnt(0)
	v_pk_mul_f32 v[0:1], v[4:5], v[12:13]
	v_pk_mul_f32 v[4:5], v[6:7], v[14:15]
	v_cvt_pk_bf16_f32 v0, v0, v1
	v_cvt_pk_bf16_f32 v1, v4, v5
	global_store_dwordx2 v[2:3], v[0:1], off
	ds_read_b128 v[0:3], v128 offset:6528
	ds_read_b128 v[4:7], v128 offset:7616
	v_add_u32_e32 v12, v130, v20
	v_lshl_add_u32 v12, v12, 10, v129
	v_ashrrev_i32_e32 v13, 31, v12
	v_lshlrev_b64 v[12:13], 1, v[12:13]
	v_lshl_add_u64 v[14:15], s[4:5], 0, v[12:13]
	s_waitcnt vmcnt(7)
	v_mov_b32_e32 v10, v156
	v_mov_b32_e32 v11, v157
	v_and_b32_e32 v17, 0xffff0000, v10
	v_lshlrev_b32_e32 v16, 16, v10
	v_and_b32_e32 v19, 0xffff0000, v11
	v_lshlrev_b32_e32 v18, 16, v11
	s_waitcnt lgkmcnt(1)
	v_pk_mul_f32 v[0:1], v[0:1], v[16:17]
	v_pk_mul_f32 v[2:3], v[2:3], v[18:19]
	v_cvt_pk_bf16_f32 v0, v0, v1
	v_cvt_pk_bf16_f32 v1, v2, v3
	global_store_dwordx2 v[8:9], v[0:1], off
	v_lshl_add_u64 v[2:3], s[10:11], 0, v[12:13]
	s_waitcnt vmcnt(7)
	v_mov_b32_e32 v0, v158
	v_mov_b32_e32 v1, v159
	v_and_b32_e32 v9, 0xffff0000, v0
	v_lshlrev_b32_e32 v8, 16, v0
	v_and_b32_e32 v11, 0xffff0000, v1
	v_lshlrev_b32_e32 v10, 16, v1
	s_waitcnt lgkmcnt(0)
	v_pk_mul_f32 v[0:1], v[4:5], v[8:9]
	v_pk_mul_f32 v[4:5], v[6:7], v[10:11]
	v_cvt_pk_bf16_f32 v0, v0, v1
	v_cvt_pk_bf16_f32 v1, v4, v5
	global_store_dwordx2 v[2:3], v[0:1], off
	s_cbranch_vccz .LBB0_1377

; __device__ __forceinline__ float bfs2f(short h) { return __uint_as_float(((unsigned)(u16)h) << 16); }
;   __device__ __forceinline__ void tile(const float* reg, int row0, int col0, int lane) const {
;     rows4(reg, lane, [&](int it, int rr, int c4, float4 v) {
;       int idx = (row0 + rr) * 1024 + col0 + c4;
;       bf16x4 gt = *(const bf16x4*)(gate + idx), mo = *(const bf16x4*)(merged + idx);
;       *(bf16x4*)(merged + idx) = pack4(fmaf(bfs2f(gt[0]), v.x, bfs2f(mo[0])), fmaf(bfs2f(gt[1]), v.y, bfs2f(mo[1])),
;                                        fmaf(bfs2f(gt[2]), v.z, bfs2f(mo[2])), fmaf(bfs2f(gt[3]), v.w, bfs2f(mo[3])));
;     });
; template <int MF, class Epi>
; __device__ __forceinline__ void staged_epilogue(f32x4 (&acc)[MF][4], int row0, int col0, const Epi& epi) {
;     ...
; #pragma unroll
;   for (int mp = 0; mp < MF / 2; ++mp) {
;     __builtin_amdgcn_sched_barrier(0);
; #pragma unroll
;     for (int mm = 0; mm < 2; ++mm)
; #pragma unroll
;       for (int n = 0; n < 4; ++n)
; #pragma unroll
;         for (int j = 0; j < 4; ++j) reg[(mm * 16 + fq * 4 + j) * 68 + n * 16 + fr] = acc[mp * 2 + mm][n][j];
;     __builtin_amdgcn_fence(__ATOMIC_ACQ_REL, "wavefront");
;     epi.tile(reg, row0 + mp * 32, col0, lane);
.LBB0_1384:
	v_mov_b32_e32 v128, v204
	v_mov_b32_e32 v130, v204
	s_nop 0
	v_lshrrev_b32_e32 v130, 6, v130
	v_mul_lo_u32 v130, v130, s52
	v_and_b32_e32 v131, 15, v128
	v_add_u32_e32 v130, 0x10000, v130
	v_lshrrev_b32_e32 v134, 2, v128
	v_bfe_u32 v140, v128, 4, 2
	v_lshlrev_b32_e32 v128, 2, v128
	v_lshl_or_b32 v142, v131, 2, v130
	v_and_b32_e32 v131, 60, v128
	v_lshl_or_b32 v128, v131, 2, v130
	v_and_b32_e32 v141, 12, v134
	v_mad_u32_u24 v128, v140, s53, v128
	v_add_u32_e32 v129, v131, v129
	v_or_b32_e32 v139, 4, v140
	v_or_b32_e32 v138, 8, v140
	v_or_b32_e32 v137, 12, v140
	v_or_b32_e32 v135, 16, v140
	v_or_b32_e32 v134, 20, v140
	v_or_b32_e32 v131, 24, v140
	v_or_b32_e32 v130, 28, v140
	v_mad_u32_u24 v141, v141, s53, v142
	ds_write2_b32 v141, v120, v124 offset1:16
	ds_write2_b32 v141, v121, v125 offset0:68 offset1:84
	ds_write2_b32 v141, v122, v126 offset0:136 offset1:152
	ds_write2_b32 v141, v123, v127 offset0:204 offset1:220
	ds_write2_b32 v141, v112, v116 offset0:32 offset1:48
	ds_write2_b32 v141, v113, v117 offset0:100 offset1:116
	ds_write2_b32 v141, v114, v118 offset0:168 offset1:184
	ds_write2_b32 v141, v115, v119 offset0:236 offset1:252
	v_add_u32_e32 v112, 0x1000, v141
	ds_write2_b32 v112, v104, v108 offset0:64 offset1:80
	ds_write2_b32 v112, v105, v109 offset0:132 offset1:148
	ds_write2_b32 v112, v106, v110 offset0:200 offset1:216
	v_add_u32_e32 v104, 0x1400, v141
	ds_write2_b32 v104, v107, v111 offset0:12 offset1:28
	ds_write2_b32 v112, v96, v100 offset0:96 offset1:112
	ds_write2_b32 v112, v97, v101 offset0:164 offset1:180
	ds_write2_b32 v112, v98, v102 offset0:232 offset1:248
	ds_write2_b32 v104, v99, v103 offset0:44 offset1:60
	v_add_u32_e32 v176, v140, v136
	v_lshl_add_u32 v176, v176, 10, v129
	v_ashrrev_i32_e32 v177, 31, v176
	v_lshlrev_b64 v[176:177], 1, v[176:177]
	v_lshl_add_u64 v[178:179], s[16:17], 0, v[176:177]
	global_load_dwordx2 v[144:145], v[178:179], off
	v_add_u32_e32 v176, v140, v136
	v_lshl_add_u32 v176, v176, 10, v129
	v_ashrrev_i32_e32 v177, 31, v176
	v_lshlrev_b64 v[176:177], 1, v[176:177]
	v_lshl_add_u64 v[178:179], s[10:11], 0, v[176:177]
	global_load_dwordx2 v[146:147], v[178:179], off
	v_add_u32_e32 v184, v139, v136
	v_lshl_add_u32 v176, v184, 10, v129
	v_ashrrev_i32_e32 v177, 31, v176
	v_lshlrev_b64 v[176:177], 1, v[176:177]
	v_lshl_add_u64 v[178:179], s[16:17], 0, v[176:177]
	global_load_dwordx2 v[148:149], v[178:179], off
	v_add_u32_e32 v184, v139, v136
	v_lshl_add_u32 v178, v184, 10, v129
	v_ashrrev_i32_e32 v179, 31, v178
	v_lshlrev_b64 v[178:179], 1, v[178:179]
	v_lshl_add_u64 v[176:177], s[10:11], 0, v[178:179]
	global_load_dwordx2 v[150:151], v[176:177], off
	v_add_u32_e32 v184, v138, v136
	v_lshl_add_u32 v176, v184, 10, v129
	v_ashrrev_i32_e32 v177, 31, v176
	v_lshlrev_b64 v[176:177], 1, v[176:177]
	v_lshl_add_u64 v[178:179], s[16:17], 0, v[176:177]
	global_load_dwordx2 v[152:153], v[178:179], off
	v_add_u32_e32 v184, v138, v136
	v_lshl_add_u32 v176, v184, 10, v129
	v_ashrrev_i32_e32 v177, 31, v176
	v_lshlrev_b64 v[176:177], 1, v[176:177]
	v_lshl_add_u64 v[176:177], s[10:11], 0, v[176:177]
	global_load_dwordx2 v[154:155], v[176:177], off
	v_add_u32_e32 v184, v137, v136
	v_lshl_add_u32 v176, v184, 10, v129
	v_ashrrev_i32_e32 v177, 31, v176
	v_lshlrev_b64 v[176:177], 1, v[176:177]
	v_lshl_add_u64 v[178:179], s[16:17], 0, v[176:177]
	global_load_dwordx2 v[156:157], v[178:179], off
	v_add_u32_e32 v184, v137, v136
	v_lshl_add_u32 v178, v184, 10, v129
	v_ashrrev_i32_e32 v179, 31, v178
	v_lshlrev_b64 v[178:179], 1, v[178:179]
	v_lshl_add_u64 v[176:177], s[10:11], 0, v[178:179]
	global_load_dwordx2 v[158:159], v[176:177], off
	v_add_u32_e32 v176, v135, v136
	v_lshl_add_u32 v176, v176, 10, v129
	v_ashrrev_i32_e32 v177, 31, v176
	v_lshlrev_b64 v[176:177], 1, v[176:177]
	v_lshl_add_u64 v[178:179], s[16:17], 0, v[176:177]
	global_load_dwordx2 v[160:161], v[178:179], off
	v_add_u32_e32 v176, v135, v136
	v_lshl_add_u32 v176, v176, 10, v129
	v_ashrrev_i32_e32 v177, 31, v176
	v_lshlrev_b64 v[176:177], 1, v[176:177]
	v_lshl_add_u64 v[178:179], s[10:11], 0, v[176:177]
	global_load_dwordx2 v[162:163], v[178:179], off
	v_add_u32_e32 v184, v134, v136
	v_lshl_add_u32 v176, v184, 10, v129
	v_ashrrev_i32_e32 v177, 31, v176
	v_lshlrev_b64 v[176:177], 1, v[176:177]
	v_lshl_add_u64 v[178:179], s[16:17], 0, v[176:177]
	global_load_dwordx2 v[164:165], v[178:179], off
	v_add_u32_e32 v184, v134, v136
	v_lshl_add_u32 v178, v184, 10, v129
	v_ashrrev_i32_e32 v179, 31, v178
	v_lshlrev_b64 v[178:179], 1, v[178:179]
	v_lshl_add_u64 v[176:177], s[10:11], 0, v[178:179]
	global_load_dwordx2 v[166:167], v[176:177], off
	v_add_u32_e32 v184, v131, v136
	v_lshl_add_u32 v176, v184, 10, v129
	v_ashrrev_i32_e32 v177, 31, v176
	v_lshlrev_b64 v[176:177], 1, v[176:177]
	v_lshl_add_u64 v[178:179], s[16:17], 0, v[176:177]
	global_load_dwordx2 v[168:169], v[178:179], off
	v_add_u32_e32 v184, v131, v136
	v_lshl_add_u32 v176, v184, 10, v129
	v_ashrrev_i32_e32 v177, 31, v176
	v_lshlrev_b64 v[176:177], 1, v[176:177]
	v_lshl_add_u64 v[176:177], s[10:11], 0, v[176:177]
	global_load_dwordx2 v[170:171], v[176:177], off
	v_add_u32_e32 v184, v130, v136
	v_lshl_add_u32 v176, v184, 10, v129
	v_ashrrev_i32_e32 v177, 31, v176
	v_lshlrev_b64 v[176:177], 1, v[176:177]
	v_lshl_add_u64 v[178:179], s[16:17], 0, v[176:177]
	global_load_dwordx2 v[172:173], v[178:179], off
	v_add_u32_e32 v184, v130, v136
	v_lshl_add_u32 v178, v184, 10, v129
	v_ashrrev_i32_e32 v179, 31, v178
	v_lshlrev_b64 v[178:179], 1, v[178:179]
	v_lshl_add_u64 v[176:177], s[10:11], 0, v[178:179]
	global_load_dwordx2 v[174:175], v[176:177], off
	v_add_u32_e32 v96, v140, v136
	v_lshl_add_u32 v96, v96, 10, v129
	v_ashrrev_i32_e32 v97, 31, v96
	v_lshlrev_b64 v[96:97], 1, v[96:97]
	v_lshl_add_u64 v[98:99], s[16:17], 0, v[96:97]
	v_lshl_add_u64 v[108:109], s[10:11], 0, v[96:97]
	s_waitcnt vmcnt(14)
; __device__ __forceinline__ float bfs2f(short h) { return __uint_as_float(((unsigned)(u16)h) << 16); }
;   __device__ __forceinline__ void tile(const float* reg, int row0, int col0, int lane) const {
;     rows4(reg, lane, [&](int it, int rr, int c4, float4 v) {
;       int idx = (row0 + rr) * 1024 + col0 + c4;
;       bf16x4 gt = *(const bf16x4*)(gate + idx), mo = *(const bf16x4*)(merged + idx);
;       *(bf16x4*)(merged + idx) = pack4(fmaf(bfs2f(gt[0]), v.x, bfs2f(mo[0])), fmaf(bfs2f(gt[1]), v.y, bfs2f(mo[1])),
;                                        fmaf(bfs2f(gt[2]), v.z, bfs2f(mo[2])), fmaf(bfs2f(gt[3]), v.w, bfs2f(mo[3])));
;     });
	v_mov_b32_e32 v106, v144
	v_mov_b32_e32 v107, v145
	v_mov_b32_e32 v110, v146
	v_mov_b32_e32 v111, v147
	ds_read_b128 v[96:99], v128
	ds_read_b128 v[100:103], v128 offset:1088
	v_add_u32_e32 v105, v139, v136
	v_lshl_add_u32 v114, v105, 10, v129
	v_ashrrev_i32_e32 v115, 31, v114
	v_lshlrev_b64 v[114:115], 1, v[114:115]
	v_lshl_add_u64 v[116:117], s[16:17], 0, v[114:115]
	v_add_u32_e32 v105, v138, v136
	v_and_b32_e32 v119, 0xffff0000, v106
	v_lshlrev_b32_e32 v118, 16, v106
	v_and_b32_e32 v121, 0xffff0000, v110
	v_lshlrev_b32_e32 v120, 16, v110
	v_and_b32_e32 v123, 0xffff0000, v107
	v_lshlrev_b32_e32 v122, 16, v107
	v_and_b32_e32 v107, 0xffff0000, v111
	v_lshlrev_b32_e32 v106, 16, v111
	s_waitcnt lgkmcnt(0)
	v_pk_fma_f32 v[96:97], v[118:119], v[96:97], v[120:121]
	v_pk_fma_f32 v[98:99], v[122:123], v[98:99], v[106:107]
	v_cvt_pk_bf16_f32 v96, v96, v97
	v_cvt_pk_bf16_f32 v97, v98, v99
	global_store_dwordx2 v[108:109], v[96:97], off
	v_lshl_add_u64 v[98:99], s[10:11], 0, v[114:115]
	v_lshl_add_u32 v108, v105, 10, v129
	v_ashrrev_i32_e32 v109, 31, v108
	v_lshlrev_b64 v[108:109], 1, v[108:109]
	v_lshl_add_u64 v[110:111], s[16:17], 0, v[108:109]
	v_lshl_add_u64 v[108:109], s[10:11], 0, v[108:109]
	v_add_u32_e32 v105, v137, v136
	s_waitcnt vmcnt(14)
	v_mov_b32_e32 v96, v148
	v_mov_b32_e32 v97, v149
	v_and_b32_e32 v115, 0xffff0000, v96
	v_lshlrev_b32_e32 v114, 16, v96
	s_waitcnt vmcnt(13)
	v_mov_b32_e32 v106, v150
	v_mov_b32_e32 v107, v151
	v_and_b32_e32 v117, 0xffff0000, v106
	v_lshlrev_b32_e32 v116, 16, v106
	v_and_b32_e32 v119, 0xffff0000, v97
	v_lshlrev_b32_e32 v118, 16, v97
	v_and_b32_e32 v97, 0xffff0000, v107
	v_lshlrev_b32_e32 v96, 16, v107
	v_pk_fma_f32 v[100:101], v[114:115], v[100:101], v[116:117]
	v_pk_fma_f32 v[96:97], v[118:119], v[102:103], v[96:97]
	v_cvt_pk_bf16_f32 v100, v100, v101
	v_cvt_pk_bf16_f32 v101, v96, v97
	global_store_dwordx2 v[98:99], v[100:101], off
	v_lshl_add_u32 v114, v105, 10, v129
	ds_read_b128 v[96:99], v128 offset:2176
	ds_read_b128 v[100:103], v128 offset:3264
	v_ashrrev_i32_e32 v115, 31, v114
	v_lshlrev_b64 v[114:115], 1, v[114:115]
	v_lshl_add_u64 v[116:117], s[16:17], 0, v[114:115]
	s_waitcnt vmcnt(13)
	v_mov_b32_e32 v106, v152
	v_mov_b32_e32 v107, v153
	v_and_b32_e32 v119, 0xffff0000, v106
	v_lshlrev_b32_e32 v118, 16, v106
	s_waitcnt vmcnt(12)
	v_mov_b32_e32 v110, v154
	v_mov_b32_e32 v111, v155
	v_and_b32_e32 v121, 0xffff0000, v110
	v_lshlrev_b32_e32 v120, 16, v110
	v_and_b32_e32 v123, 0xffff0000, v107
	v_lshlrev_b32_e32 v122, 16, v107
	v_and_b32_e32 v107, 0xffff0000, v111
	v_lshlrev_b32_e32 v106, 16, v111
	s_waitcnt lgkmcnt(1)
	v_pk_fma_f32 v[96:97], v[118:119], v[96:97], v[120:121]
	v_pk_fma_f32 v[98:99], v[122:123], v[98:99], v[106:107]
	v_cvt_pk_bf16_f32 v96, v96, v97
	v_cvt_pk_bf16_f32 v97, v98, v99
	global_store_dwordx2 v[108:109], v[96:97], off
	v_lshl_add_u64 v[98:99], s[10:11], 0, v[114:115]
	s_waitcnt vmcnt(12)
	v_mov_b32_e32 v96, v156
	v_mov_b32_e32 v97, v157
	v_and_b32_e32 v109, 0xffff0000, v96
	v_lshlrev_b32_e32 v108, 16, v96
	s_waitcnt vmcnt(11)
	v_mov_b32_e32 v106, v158
	v_mov_b32_e32 v107, v159
	v_and_b32_e32 v111, 0xffff0000, v106
	v_lshlrev_b32_e32 v110, 16, v106
	v_and_b32_e32 v115, 0xffff0000, v97
	v_lshlrev_b32_e32 v114, 16, v97
	v_and_b32_e32 v97, 0xffff0000, v107
	v_lshlrev_b32_e32 v96, 16, v107
	s_waitcnt lgkmcnt(0)
	v_pk_fma_f32 v[100:101], v[108:109], v[100:101], v[110:111]
	v_pk_fma_f32 v[96:97], v[114:115], v[102:103], v[96:97]
	v_cvt_pk_bf16_f32 v100, v100, v101
	v_cvt_pk_bf16_f32 v101, v96, v97
	global_store_dwordx2 v[98:99], v[100:101], off
	v_add_u32_e32 v96, v135, v136
	v_lshl_add_u32 v96, v96, 10, v129
	v_ashrrev_i32_e32 v97, 31, v96
	v_lshlrev_b64 v[96:97], 1, v[96:97]
	v_lshl_add_u64 v[98:99], s[16:17], 0, v[96:97]
	v_lshl_add_u64 v[108:109], s[10:11], 0, v[96:97]
	ds_read_b128 v[96:99], v128 offset:4352
	ds_read_b128 v[100:103], v128 offset:5440
	v_add_u32_e32 v105, v134, v136
	v_lshl_add_u32 v114, v105, 10, v129
	v_ashrrev_i32_e32 v115, 31, v114
	v_lshlrev_b64 v[114:115], 1, v[114:115]
	v_lshl_add_u64 v[116:117], s[16:17], 0, v[114:115]
	v_add_u32_e32 v105, v131, v136
	s_waitcnt vmcnt(11)
	v_mov_b32_e32 v106, v160
	v_mov_b32_e32 v107, v161
	v_and_b32_e32 v119, 0xffff0000, v106
	v_lshlrev_b32_e32 v118, 16, v106
	s_waitcnt vmcnt(10)
	v_mov_b32_e32 v110, v162
	v_mov_b32_e32 v111, v163
	v_and_b32_e32 v121, 0xffff0000, v110
	v_lshlrev_b32_e32 v120, 16, v110
	v_and_b32_e32 v123, 0xffff0000, v107
	v_lshlrev_b32_e32 v122, 16, v107
	v_and_b32_e32 v107, 0xffff0000, v111
	v_lshlrev_b32_e32 v106, 16, v111
	s_waitcnt lgkmcnt(1)
	v_pk_fma_f32 v[96:97], v[118:119], v[96:97], v[120:121]
	v_pk_fma_f32 v[98:99], v[122:123], v[98:99], v[106:107]
	v_cvt_pk_bf16_f32 v96, v96, v97
	v_cvt_pk_bf16_f32 v97, v98, v99
	global_store_dwordx2 v[108:109], v[96:97], off
	v_lshl_add_u64 v[98:99], s[10:11], 0, v[114:115]
	v_lshl_add_u32 v108, v105, 10, v129
	v_ashrrev_i32_e32 v109, 31, v108
	v_lshlrev_b64 v[108:109], 1, v[108:109]
	v_lshl_add_u64 v[110:111], s[16:17], 0, v[108:109]
	v_lshl_add_u64 v[108:109], s[10:11], 0, v[108:109]
	v_add_u32_e32 v105, v130, v136
	s_waitcnt vmcnt(10)
	v_mov_b32_e32 v96, v164
	v_mov_b32_e32 v97, v165
	v_and_b32_e32 v115, 0xffff0000, v96
	v_lshlrev_b32_e32 v114, 16, v96
	s_waitcnt vmcnt(9)
	v_mov_b32_e32 v106, v166
	v_mov_b32_e32 v107, v167
	v_and_b32_e32 v117, 0xffff0000, v106
	v_lshlrev_b32_e32 v116, 16, v106
	v_and_b32_e32 v119, 0xffff0000, v97
	v_lshlrev_b32_e32 v118, 16, v97
	v_and_b32_e32 v97, 0xffff0000, v107
	v_lshlrev_b32_e32 v96, 16, v107
	s_waitcnt lgkmcnt(0)
; __device__ __forceinline__ float bfs2f(short h) { return __uint_as_float(((unsigned)(u16)h) << 16); }
;   __device__ __forceinline__ void tile(const float* reg, int row0, int col0, int lane) const {
;     rows4(reg, lane, [&](int it, int rr, int c4, float4 v) {
;       int idx = (row0 + rr) * 1024 + col0 + c4;
;       bf16x4 gt = *(const bf16x4*)(gate + idx), mo = *(const bf16x4*)(merged + idx);
;       *(bf16x4*)(merged + idx) = pack4(fmaf(bfs2f(gt[0]), v.x, bfs2f(mo[0])), fmaf(bfs2f(gt[1]), v.y, bfs2f(mo[1])),
;                                        fmaf(bfs2f(gt[2]), v.z, bfs2f(mo[2])), fmaf(bfs2f(gt[3]), v.w, bfs2f(mo[3])));
;     });
;   }
; template <int MF, class Epi>
; __device__ __forceinline__ void staged_epilogue(f32x4 (&acc)[MF][4], int row0, int col0, const Epi& epi) {
;     ...
; #pragma unroll
;   for (int mp = 0; mp < MF / 2; ++mp) {
;     __builtin_amdgcn_sched_barrier(0);
; #pragma unroll
;     for (int mm = 0; mm < 2; ++mm)
; #pragma unroll
;       for (int n = 0; n < 4; ++n)
; #pragma unroll
;         for (int j = 0; j < 4; ++j) reg[(mm * 16 + fq * 4 + j) * 68 + n * 16 + fr] = acc[mp * 2 + mm][n][j];
;     __builtin_amdgcn_fence(__ATOMIC_ACQ_REL, "wavefront");
;     epi.tile(reg, row0 + mp * 32, col0, lane);
;     __builtin_amdgcn_fence(__ATOMIC_ACQ_REL, "wavefront");
	v_pk_fma_f32 v[100:101], v[114:115], v[100:101], v[116:117]
	v_pk_fma_f32 v[96:97], v[118:119], v[102:103], v[96:97]
	v_cvt_pk_bf16_f32 v100, v100, v101
	v_cvt_pk_bf16_f32 v101, v96, v97
	global_store_dwordx2 v[98:99], v[100:101], off
	v_lshl_add_u32 v114, v105, 10, v129
	ds_read_b128 v[96:99], v128 offset:6528
	ds_read_b128 v[100:103], v128 offset:7616
	v_ashrrev_i32_e32 v115, 31, v114
	v_lshlrev_b64 v[114:115], 1, v[114:115]
	v_lshl_add_u64 v[116:117], s[16:17], 0, v[114:115]
	s_waitcnt vmcnt(9)
	v_mov_b32_e32 v106, v168
	v_mov_b32_e32 v107, v169
	v_and_b32_e32 v119, 0xffff0000, v106
	v_lshlrev_b32_e32 v118, 16, v106
	s_waitcnt vmcnt(8)
	v_mov_b32_e32 v110, v170
	v_mov_b32_e32 v111, v171
	v_and_b32_e32 v121, 0xffff0000, v110
	v_lshlrev_b32_e32 v120, 16, v110
	v_and_b32_e32 v123, 0xffff0000, v107
	v_lshlrev_b32_e32 v122, 16, v107
	v_and_b32_e32 v107, 0xffff0000, v111
	v_lshlrev_b32_e32 v106, 16, v111
	s_waitcnt lgkmcnt(1)
	v_pk_fma_f32 v[96:97], v[118:119], v[96:97], v[120:121]
	v_pk_fma_f32 v[98:99], v[122:123], v[98:99], v[106:107]
	v_cvt_pk_bf16_f32 v96, v96, v97
	v_cvt_pk_bf16_f32 v97, v98, v99
	global_store_dwordx2 v[108:109], v[96:97], off
	v_lshl_add_u64 v[98:99], s[10:11], 0, v[114:115]
	s_waitcnt vmcnt(8)
	v_mov_b32_e32 v96, v172
	v_mov_b32_e32 v97, v173
	v_and_b32_e32 v109, 0xffff0000, v96
	v_lshlrev_b32_e32 v108, 16, v96
	s_waitcnt vmcnt(7)
	v_mov_b32_e32 v106, v174
	v_mov_b32_e32 v107, v175
	v_and_b32_e32 v111, 0xffff0000, v106
	v_lshlrev_b32_e32 v110, 16, v106
	v_and_b32_e32 v115, 0xffff0000, v97
	v_lshlrev_b32_e32 v114, 16, v97
	v_and_b32_e32 v97, 0xffff0000, v107
	v_lshlrev_b32_e32 v96, 16, v107
	s_waitcnt lgkmcnt(0)
	v_pk_fma_f32 v[100:101], v[108:109], v[100:101], v[110:111]
	v_pk_fma_f32 v[96:97], v[114:115], v[102:103], v[96:97]
	v_cvt_pk_bf16_f32 v100, v100, v101
	v_cvt_pk_bf16_f32 v101, v96, v97
	global_store_dwordx2 v[98:99], v[100:101], off
	ds_write2_b32 v141, v88, v92 offset1:16
	ds_write2_b32 v141, v89, v93 offset0:68 offset1:84
	ds_write2_b32 v141, v90, v94 offset0:136 offset1:152
	ds_write2_b32 v141, v91, v95 offset0:204 offset1:220
	ds_write2_b32 v141, v80, v84 offset0:32 offset1:48
	ds_write2_b32 v141, v81, v85 offset0:100 offset1:116
	ds_write2_b32 v141, v82, v86 offset0:168 offset1:184
	ds_write2_b32 v141, v83, v87 offset0:236 offset1:252
	ds_write2_b32 v112, v72, v76 offset0:64 offset1:80
	ds_write2_b32 v112, v73, v77 offset0:132 offset1:148
	ds_write2_b32 v112, v74, v78 offset0:200 offset1:216
	ds_write2_b32 v104, v75, v79 offset0:12 offset1:28
	ds_write2_b32 v112, v64, v68 offset0:96 offset1:112
	ds_write2_b32 v112, v65, v69 offset0:164 offset1:180
	ds_write2_b32 v112, v66, v70 offset0:232 offset1:248
	ds_write2_b32 v104, v67, v71 offset0:44 offset1:60
	v_add_u32_e32 v184, 32, v136
	v_add_u32_e32 v176, v140, v184
	v_lshl_add_u32 v176, v176, 10, v129
	v_ashrrev_i32_e32 v177, 31, v176
	v_lshlrev_b64 v[176:177], 1, v[176:177]
	v_lshl_add_u64 v[178:179], s[16:17], 0, v[176:177]
	global_load_dwordx2 v[144:145], v[178:179], off
	v_add_u32_e32 v184, 32, v136
	v_add_u32_e32 v176, v140, v184
	v_lshl_add_u32 v176, v176, 10, v129
	v_ashrrev_i32_e32 v177, 31, v176
	v_lshlrev_b64 v[176:177], 1, v[176:177]
	v_lshl_add_u64 v[178:179], s[10:11], 0, v[176:177]
	global_load_dwordx2 v[146:147], v[178:179], off
	v_add_u32_e32 v184, 32, v136
	v_add_u32_e32 v176, v139, v184
	v_lshl_add_u32 v176, v176, 10, v129
	v_ashrrev_i32_e32 v177, 31, v176
	v_lshlrev_b64 v[176:177], 1, v[176:177]
	v_lshl_add_u64 v[178:179], s[16:17], 0, v[176:177]
	global_load_dwordx2 v[148:149], v[178:179], off
	v_add_u32_e32 v184, 32, v136
	v_add_u32_e32 v178, v139, v184
	v_lshl_add_u32 v178, v178, 10, v129
	v_ashrrev_i32_e32 v179, 31, v178
	v_lshlrev_b64 v[178:179], 1, v[178:179]
	v_lshl_add_u64 v[176:177], s[10:11], 0, v[178:179]
	global_load_dwordx2 v[150:151], v[176:177], off
	v_add_u32_e32 v184, 32, v136
	v_add_u32_e32 v176, v138, v184
	v_lshl_add_u32 v176, v176, 10, v129
	v_ashrrev_i32_e32 v177, 31, v176
	v_lshlrev_b64 v[176:177], 1, v[176:177]
	v_lshl_add_u64 v[178:179], s[16:17], 0, v[176:177]
	global_load_dwordx2 v[152:153], v[178:179], off
	v_add_u32_e32 v184, 32, v136
	v_add_u32_e32 v176, v138, v184
	v_lshl_add_u32 v176, v176, 10, v129
	v_ashrrev_i32_e32 v177, 31, v176
	v_lshlrev_b64 v[176:177], 1, v[176:177]
	v_lshl_add_u64 v[176:177], s[10:11], 0, v[176:177]
	global_load_dwordx2 v[154:155], v[176:177], off
	v_add_u32_e32 v184, 32, v136
	v_add_u32_e32 v176, v137, v184
	v_lshl_add_u32 v176, v176, 10, v129
	v_ashrrev_i32_e32 v177, 31, v176
	v_lshlrev_b64 v[176:177], 1, v[176:177]
	v_lshl_add_u64 v[178:179], s[16:17], 0, v[176:177]
	global_load_dwordx2 v[156:157], v[178:179], off
	v_add_u32_e32 v184, 32, v136
	v_add_u32_e32 v178, v137, v184
	v_lshl_add_u32 v178, v178, 10, v129
	v_ashrrev_i32_e32 v179, 31, v178
	v_lshlrev_b64 v[178:179], 1, v[178:179]
	v_lshl_add_u64 v[176:177], s[10:11], 0, v[178:179]
	global_load_dwordx2 v[158:159], v[176:177], off
	v_add_u32_e32 v184, 32, v136
	v_add_u32_e32 v176, v135, v184
	v_lshl_add_u32 v176, v176, 10, v129
	v_ashrrev_i32_e32 v177, 31, v176
	v_lshlrev_b64 v[176:177], 1, v[176:177]
	v_lshl_add_u64 v[178:179], s[16:17], 0, v[176:177]
	global_load_dwordx2 v[160:161], v[178:179], off
	v_add_u32_e32 v184, 32, v136
	v_add_u32_e32 v176, v135, v184
	v_lshl_add_u32 v176, v176, 10, v129
	v_ashrrev_i32_e32 v177, 31, v176
	v_lshlrev_b64 v[176:177], 1, v[176:177]
	v_lshl_add_u64 v[178:179], s[10:11], 0, v[176:177]
	global_load_dwordx2 v[162:163], v[178:179], off
	v_add_u32_e32 v184, 32, v136
	v_add_u32_e32 v176, v134, v184
	v_lshl_add_u32 v176, v176, 10, v129
	v_ashrrev_i32_e32 v177, 31, v176
; __device__ __forceinline__ float bfs2f(short h) { return __uint_as_float(((unsigned)(u16)h) << 16); }
;   __device__ __forceinline__ void tile(const float* reg, int row0, int col0, int lane) const {
;     rows4(reg, lane, [&](int it, int rr, int c4, float4 v) {
;       int idx = (row0 + rr) * 1024 + col0 + c4;
;       bf16x4 gt = *(const bf16x4*)(gate + idx), mo = *(const bf16x4*)(merged + idx);
;       *(bf16x4*)(merged + idx) = pack4(fmaf(bfs2f(gt[0]), v.x, bfs2f(mo[0])), fmaf(bfs2f(gt[1]), v.y, bfs2f(mo[1])),
;                                        fmaf(bfs2f(gt[2]), v.z, bfs2f(mo[2])), fmaf(bfs2f(gt[3]), v.w, bfs2f(mo[3])));
;     });
;   }
	v_lshlrev_b64 v[176:177], 1, v[176:177]
	v_lshl_add_u64 v[178:179], s[16:17], 0, v[176:177]
	global_load_dwordx2 v[164:165], v[178:179], off
	v_add_u32_e32 v184, 32, v136
	v_add_u32_e32 v178, v134, v184
	v_lshl_add_u32 v178, v178, 10, v129
	v_ashrrev_i32_e32 v179, 31, v178
	v_lshlrev_b64 v[178:179], 1, v[178:179]
	v_lshl_add_u64 v[176:177], s[10:11], 0, v[178:179]
	global_load_dwordx2 v[166:167], v[176:177], off
	v_add_u32_e32 v184, 32, v136
	v_add_u32_e32 v176, v131, v184
	v_lshl_add_u32 v176, v176, 10, v129
	v_ashrrev_i32_e32 v177, 31, v176
	v_lshlrev_b64 v[176:177], 1, v[176:177]
	v_lshl_add_u64 v[178:179], s[16:17], 0, v[176:177]
	global_load_dwordx2 v[168:169], v[178:179], off
	v_add_u32_e32 v184, 32, v136
	v_add_u32_e32 v176, v131, v184
	v_lshl_add_u32 v176, v176, 10, v129
	v_ashrrev_i32_e32 v177, 31, v176
	v_lshlrev_b64 v[176:177], 1, v[176:177]
	v_lshl_add_u64 v[176:177], s[10:11], 0, v[176:177]
	global_load_dwordx2 v[170:171], v[176:177], off
	v_add_u32_e32 v184, 32, v136
	v_add_u32_e32 v176, v130, v184
	v_lshl_add_u32 v176, v176, 10, v129
	v_ashrrev_i32_e32 v177, 31, v176
	v_lshlrev_b64 v[176:177], 1, v[176:177]
	v_lshl_add_u64 v[178:179], s[16:17], 0, v[176:177]
	global_load_dwordx2 v[172:173], v[178:179], off
	v_add_u32_e32 v184, 32, v136
	v_add_u32_e32 v178, v130, v184
	v_lshl_add_u32 v178, v178, 10, v129
	v_ashrrev_i32_e32 v179, 31, v178
	v_lshlrev_b64 v[178:179], 1, v[178:179]
	v_lshl_add_u64 v[176:177], s[10:11], 0, v[178:179]
	global_load_dwordx2 v[174:175], v[176:177], off
	v_add_u32_e32 v88, 32, v136
	v_add_u32_e32 v64, v140, v88
	v_lshl_add_u32 v64, v64, 10, v129
	v_ashrrev_i32_e32 v65, 31, v64
	v_lshlrev_b64 v[64:65], 1, v[64:65]
	v_lshl_add_u64 v[66:67], s[16:17], 0, v[64:65]
	v_lshl_add_u64 v[74:75], s[10:11], 0, v[64:65]
	ds_read_b128 v[64:67], v128
	ds_read_b128 v[68:71], v128 offset:1088
	v_add_u32_e32 v78, v139, v88
	v_lshl_add_u32 v78, v78, 10, v129
	v_ashrrev_i32_e32 v79, 31, v78
	v_lshlrev_b64 v[78:79], 1, v[78:79]
	v_lshl_add_u64 v[80:81], s[16:17], 0, v[78:79]
	s_waitcnt vmcnt(15)
	v_mov_b32_e32 v72, v144
	v_mov_b32_e32 v73, v145
	v_and_b32_e32 v83, 0xffff0000, v72
	v_lshlrev_b32_e32 v82, 16, v72
	s_waitcnt vmcnt(14)
	v_mov_b32_e32 v76, v146
	v_mov_b32_e32 v77, v147
	v_and_b32_e32 v85, 0xffff0000, v76
	v_lshlrev_b32_e32 v84, 16, v76
	v_and_b32_e32 v87, 0xffff0000, v73
	v_lshlrev_b32_e32 v86, 16, v73
	v_and_b32_e32 v73, 0xffff0000, v77
	v_lshlrev_b32_e32 v72, 16, v77
	s_waitcnt lgkmcnt(1)
	v_pk_fma_f32 v[64:65], v[82:83], v[64:65], v[84:85]
	v_pk_fma_f32 v[66:67], v[86:87], v[66:67], v[72:73]
	v_cvt_pk_bf16_f32 v64, v64, v65
	v_cvt_pk_bf16_f32 v65, v66, v67
	global_store_dwordx2 v[74:75], v[64:65], off
	v_lshl_add_u64 v[66:67], s[10:11], 0, v[78:79]
	v_add_u32_e32 v74, v138, v88
	v_lshl_add_u32 v74, v74, 10, v129
	v_ashrrev_i32_e32 v75, 31, v74
	v_lshlrev_b64 v[74:75], 1, v[74:75]
	v_lshl_add_u64 v[76:77], s[16:17], 0, v[74:75]
	v_lshl_add_u64 v[74:75], s[10:11], 0, v[74:75]
	s_waitcnt vmcnt(14)
	v_mov_b32_e32 v64, v148
	v_mov_b32_e32 v65, v149
	v_and_b32_e32 v79, 0xffff0000, v64
	v_lshlrev_b32_e32 v78, 16, v64
	s_waitcnt vmcnt(13)
	v_mov_b32_e32 v72, v150
	v_mov_b32_e32 v73, v151
	v_and_b32_e32 v81, 0xffff0000, v72
	v_lshlrev_b32_e32 v80, 16, v72
	v_and_b32_e32 v83, 0xffff0000, v65
	v_lshlrev_b32_e32 v82, 16, v65
	v_and_b32_e32 v65, 0xffff0000, v73
	v_lshlrev_b32_e32 v64, 16, v73
	s_waitcnt lgkmcnt(0)
	v_pk_fma_f32 v[68:69], v[78:79], v[68:69], v[80:81]
	v_pk_fma_f32 v[64:65], v[82:83], v[70:71], v[64:65]
	v_cvt_pk_bf16_f32 v68, v68, v69
	v_cvt_pk_bf16_f32 v69, v64, v65
	global_store_dwordx2 v[66:67], v[68:69], off
	v_add_u32_e32 v78, v137, v88
	ds_read_b128 v[64:67], v128 offset:2176
	ds_read_b128 v[68:71], v128 offset:3264
	v_lshl_add_u32 v78, v78, 10, v129
	v_ashrrev_i32_e32 v79, 31, v78
	v_lshlrev_b64 v[78:79], 1, v[78:79]
	v_lshl_add_u64 v[80:81], s[16:17], 0, v[78:79]
	s_waitcnt vmcnt(13)
	v_mov_b32_e32 v72, v152
	v_mov_b32_e32 v73, v153
	v_and_b32_e32 v83, 0xffff0000, v72
	v_lshlrev_b32_e32 v82, 16, v72
	s_waitcnt vmcnt(12)
	v_mov_b32_e32 v76, v154
	v_mov_b32_e32 v77, v155
	v_and_b32_e32 v85, 0xffff0000, v76
	v_lshlrev_b32_e32 v84, 16, v76
	v_and_b32_e32 v87, 0xffff0000, v73
	v_lshlrev_b32_e32 v86, 16, v73
	v_and_b32_e32 v73, 0xffff0000, v77
	v_lshlrev_b32_e32 v72, 16, v77
	s_waitcnt lgkmcnt(1)
	v_pk_fma_f32 v[64:65], v[82:83], v[64:65], v[84:85]
	v_pk_fma_f32 v[66:67], v[86:87], v[66:67], v[72:73]
	v_cvt_pk_bf16_f32 v64, v64, v65
	v_cvt_pk_bf16_f32 v65, v66, v67
	global_store_dwordx2 v[74:75], v[64:65], off
	v_lshl_add_u64 v[66:67], s[10:11], 0, v[78:79]
	s_waitcnt vmcnt(12)
	v_mov_b32_e32 v64, v156
	v_mov_b32_e32 v65, v157
	v_and_b32_e32 v75, 0xffff0000, v64
	v_lshlrev_b32_e32 v74, 16, v64
	s_waitcnt vmcnt(11)
	v_mov_b32_e32 v72, v158
	v_mov_b32_e32 v73, v159
	v_and_b32_e32 v77, 0xffff0000, v72
	v_lshlrev_b32_e32 v76, 16, v72
	v_and_b32_e32 v79, 0xffff0000, v65
	v_lshlrev_b32_e32 v78, 16, v65
	v_and_b32_e32 v65, 0xffff0000, v73
	v_lshlrev_b32_e32 v64, 16, v73
	s_waitcnt lgkmcnt(0)
	v_pk_fma_f32 v[68:69], v[74:75], v[68:69], v[76:77]
	v_pk_fma_f32 v[64:65], v[78:79], v[70:71], v[64:65]
	v_cvt_pk_bf16_f32 v68, v68, v69
	v_cvt_pk_bf16_f32 v69, v64, v65
	global_store_dwordx2 v[66:67], v[68:69], off
	v_add_u32_e32 v64, v135, v88
	v_lshl_add_u32 v64, v64, 10, v129
	v_ashrrev_i32_e32 v65, 31, v64
	v_lshlrev_b64 v[64:65], 1, v[64:65]
	v_lshl_add_u64 v[66:67], s[16:17], 0, v[64:65]
	v_lshl_add_u64 v[74:75], s[10:11], 0, v[64:65]
	ds_read_b128 v[64:67], v128 offset:4352
	ds_read_b128 v[68:71], v128 offset:5440
	v_add_u32_e32 v78, v134, v88
	v_lshl_add_u32 v78, v78, 10, v129
	v_ashrrev_i32_e32 v79, 31, v78
	v_lshlrev_b64 v[78:79], 1, v[78:79]
	v_lshl_add_u64 v[80:81], s[16:17], 0, v[78:79]
	s_waitcnt vmcnt(11)
; __device__ __forceinline__ float bfs2f(short h) { return __uint_as_float(((unsigned)(u16)h) << 16); }
;   __device__ __forceinline__ void tile(const float* reg, int row0, int col0, int lane) const {
;     rows4(reg, lane, [&](int it, int rr, int c4, float4 v) {
;       int idx = (row0 + rr) * 1024 + col0 + c4;
;       bf16x4 gt = *(const bf16x4*)(gate + idx), mo = *(const bf16x4*)(merged + idx);
;       *(bf16x4*)(merged + idx) = pack4(fmaf(bfs2f(gt[0]), v.x, bfs2f(mo[0])), fmaf(bfs2f(gt[1]), v.y, bfs2f(mo[1])),
;                                        fmaf(bfs2f(gt[2]), v.z, bfs2f(mo[2])), fmaf(bfs2f(gt[3]), v.w, bfs2f(mo[3])));
;     });
;   }
; template <int MF, class Epi>
; __device__ __forceinline__ void staged_epilogue(f32x4 (&acc)[MF][4], int row0, int col0, const Epi& epi) {
;     ...
; #pragma unroll
;   for (int mp = 0; mp < MF / 2; ++mp) {
;     __builtin_amdgcn_sched_barrier(0);
; #pragma unroll
;     for (int mm = 0; mm < 2; ++mm)
; #pragma unroll
;       for (int n = 0; n < 4; ++n)
; #pragma unroll
;         for (int j = 0; j < 4; ++j) reg[(mm * 16 + fq * 4 + j) * 68 + n * 16 + fr] = acc[mp * 2 + mm][n][j];
;     __builtin_amdgcn_fence(__ATOMIC_ACQ_REL, "wavefront");
;     epi.tile(reg, row0 + mp * 32, col0, lane);
;     __builtin_amdgcn_fence(__ATOMIC_ACQ_REL, "wavefront");
	v_mov_b32_e32 v72, v160
	v_mov_b32_e32 v73, v161
	v_and_b32_e32 v83, 0xffff0000, v72
	v_lshlrev_b32_e32 v82, 16, v72
	s_waitcnt vmcnt(10)
	v_mov_b32_e32 v76, v162
	v_mov_b32_e32 v77, v163
	v_and_b32_e32 v85, 0xffff0000, v76
	v_lshlrev_b32_e32 v84, 16, v76
	v_and_b32_e32 v87, 0xffff0000, v73
	v_lshlrev_b32_e32 v86, 16, v73
	v_and_b32_e32 v73, 0xffff0000, v77
	v_lshlrev_b32_e32 v72, 16, v77
	s_waitcnt lgkmcnt(1)
	v_pk_fma_f32 v[64:65], v[82:83], v[64:65], v[84:85]
	v_pk_fma_f32 v[66:67], v[86:87], v[66:67], v[72:73]
	v_cvt_pk_bf16_f32 v64, v64, v65
	v_cvt_pk_bf16_f32 v65, v66, v67
	global_store_dwordx2 v[74:75], v[64:65], off
	v_lshl_add_u64 v[66:67], s[10:11], 0, v[78:79]
	v_add_u32_e32 v74, v131, v88
	v_lshl_add_u32 v74, v74, 10, v129
	v_ashrrev_i32_e32 v75, 31, v74
	v_lshlrev_b64 v[74:75], 1, v[74:75]
	v_lshl_add_u64 v[76:77], s[16:17], 0, v[74:75]
	v_lshl_add_u64 v[74:75], s[10:11], 0, v[74:75]
	s_waitcnt vmcnt(10)
	v_mov_b32_e32 v64, v164
	v_mov_b32_e32 v65, v165
	v_and_b32_e32 v79, 0xffff0000, v64
	v_lshlrev_b32_e32 v78, 16, v64
	s_waitcnt vmcnt(9)
	v_mov_b32_e32 v72, v166
	v_mov_b32_e32 v73, v167
	v_and_b32_e32 v81, 0xffff0000, v72
	v_lshlrev_b32_e32 v80, 16, v72
	v_and_b32_e32 v83, 0xffff0000, v65
	v_lshlrev_b32_e32 v82, 16, v65
	v_and_b32_e32 v65, 0xffff0000, v73
	v_lshlrev_b32_e32 v64, 16, v73
	s_waitcnt lgkmcnt(0)
	v_pk_fma_f32 v[68:69], v[78:79], v[68:69], v[80:81]
	v_pk_fma_f32 v[64:65], v[82:83], v[70:71], v[64:65]
	v_cvt_pk_bf16_f32 v68, v68, v69
	v_cvt_pk_bf16_f32 v69, v64, v65
	global_store_dwordx2 v[66:67], v[68:69], off
	v_add_u32_e32 v78, v130, v88
	ds_read_b128 v[64:67], v128 offset:6528
	ds_read_b128 v[68:71], v128 offset:7616
	v_lshl_add_u32 v78, v78, 10, v129
	v_ashrrev_i32_e32 v79, 31, v78
	v_lshlrev_b64 v[78:79], 1, v[78:79]
	v_lshl_add_u64 v[80:81], s[16:17], 0, v[78:79]
	s_waitcnt vmcnt(9)
	v_mov_b32_e32 v72, v168
	v_mov_b32_e32 v73, v169
	v_and_b32_e32 v83, 0xffff0000, v72
	v_lshlrev_b32_e32 v82, 16, v72
	s_waitcnt vmcnt(8)
	v_mov_b32_e32 v76, v170
	v_mov_b32_e32 v77, v171
	v_and_b32_e32 v85, 0xffff0000, v76
	v_lshlrev_b32_e32 v84, 16, v76
	v_and_b32_e32 v87, 0xffff0000, v73
	v_lshlrev_b32_e32 v86, 16, v73
	v_and_b32_e32 v73, 0xffff0000, v77
	v_lshlrev_b32_e32 v72, 16, v77
	s_waitcnt lgkmcnt(1)
	v_pk_fma_f32 v[64:65], v[82:83], v[64:65], v[84:85]
	v_pk_fma_f32 v[66:67], v[86:87], v[66:67], v[72:73]
	v_cvt_pk_bf16_f32 v64, v64, v65
	v_cvt_pk_bf16_f32 v65, v66, v67
	global_store_dwordx2 v[74:75], v[64:65], off
	v_lshl_add_u64 v[66:67], s[10:11], 0, v[78:79]
	s_waitcnt vmcnt(8)
	v_mov_b32_e32 v64, v172
	v_mov_b32_e32 v65, v173
	v_and_b32_e32 v75, 0xffff0000, v64
	v_lshlrev_b32_e32 v74, 16, v64
	s_waitcnt vmcnt(7)
	v_mov_b32_e32 v72, v174
	v_mov_b32_e32 v73, v175
	v_and_b32_e32 v77, 0xffff0000, v72
	v_lshlrev_b32_e32 v76, 16, v72
	v_and_b32_e32 v79, 0xffff0000, v65
	v_lshlrev_b32_e32 v78, 16, v65
	v_and_b32_e32 v65, 0xffff0000, v73
	v_lshlrev_b32_e32 v64, 16, v73
	s_waitcnt lgkmcnt(0)
	v_pk_fma_f32 v[68:69], v[74:75], v[68:69], v[76:77]
	v_pk_fma_f32 v[64:65], v[78:79], v[70:71], v[64:65]
	v_cvt_pk_bf16_f32 v68, v68, v69
	v_cvt_pk_bf16_f32 v69, v64, v65
	global_store_dwordx2 v[66:67], v[68:69], off
	ds_write2_b32 v141, v56, v60 offset1:16
	ds_write2_b32 v141, v57, v61 offset0:68 offset1:84
	ds_write2_b32 v141, v58, v62 offset0:136 offset1:152
	ds_write2_b32 v141, v59, v63 offset0:204 offset1:220
	ds_write2_b32 v141, v48, v52 offset0:32 offset1:48
	ds_write2_b32 v141, v49, v53 offset0:100 offset1:116
	ds_write2_b32 v141, v50, v54 offset0:168 offset1:184
	ds_write2_b32 v141, v51, v55 offset0:236 offset1:252
	ds_write2_b32 v112, v40, v44 offset0:64 offset1:80
	ds_write2_b32 v112, v41, v45 offset0:132 offset1:148
	ds_write2_b32 v112, v42, v46 offset0:200 offset1:216
	ds_write2_b32 v104, v43, v47 offset0:12 offset1:28
	ds_write2_b32 v112, v32, v36 offset0:96 offset1:112
	ds_write2_b32 v112, v33, v37 offset0:164 offset1:180
	ds_write2_b32 v112, v34, v38 offset0:232 offset1:248
	ds_write2_b32 v104, v35, v39 offset0:44 offset1:60
	v_add_u32_e32 v184, 64, v136
	v_add_u32_e32 v176, v140, v184
	v_lshl_add_u32 v176, v176, 10, v129
	v_ashrrev_i32_e32 v177, 31, v176
	v_lshlrev_b64 v[176:177], 1, v[176:177]
	v_lshl_add_u64 v[178:179], s[16:17], 0, v[176:177]
	global_load_dwordx2 v[144:145], v[178:179], off
	v_add_u32_e32 v184, 64, v136
	v_add_u32_e32 v176, v140, v184
	v_lshl_add_u32 v176, v176, 10, v129
	v_ashrrev_i32_e32 v177, 31, v176
	v_lshlrev_b64 v[176:177], 1, v[176:177]
	v_lshl_add_u64 v[178:179], s[10:11], 0, v[176:177]
	global_load_dwordx2 v[146:147], v[178:179], off
	v_add_u32_e32 v184, 64, v136
	v_add_u32_e32 v176, v139, v184
	v_lshl_add_u32 v176, v176, 10, v129
	v_ashrrev_i32_e32 v177, 31, v176
	v_lshlrev_b64 v[176:177], 1, v[176:177]
	v_lshl_add_u64 v[178:179], s[16:17], 0, v[176:177]
	global_load_dwordx2 v[148:149], v[178:179], off
	v_add_u32_e32 v184, 64, v136
	v_add_u32_e32 v178, v139, v184
	v_lshl_add_u32 v178, v178, 10, v129
	v_ashrrev_i32_e32 v179, 31, v178
	v_lshlrev_b64 v[178:179], 1, v[178:179]
	v_lshl_add_u64 v[176:177], s[10:11], 0, v[178:179]
	global_load_dwordx2 v[150:151], v[176:177], off
	v_add_u32_e32 v184, 64, v136
	v_add_u32_e32 v176, v138, v184
	v_lshl_add_u32 v176, v176, 10, v129
	v_ashrrev_i32_e32 v177, 31, v176
	v_lshlrev_b64 v[176:177], 1, v[176:177]
	v_lshl_add_u64 v[178:179], s[16:17], 0, v[176:177]
	global_load_dwordx2 v[152:153], v[178:179], off
	v_add_u32_e32 v184, 64, v136
	v_add_u32_e32 v176, v138, v184
	v_lshl_add_u32 v176, v176, 10, v129
	v_ashrrev_i32_e32 v177, 31, v176
	v_lshlrev_b64 v[176:177], 1, v[176:177]
	v_lshl_add_u64 v[176:177], s[10:11], 0, v[176:177]
; __device__ __forceinline__ float bfs2f(short h) { return __uint_as_float(((unsigned)(u16)h) << 16); }
;   __device__ __forceinline__ void tile(const float* reg, int row0, int col0, int lane) const {
;     rows4(reg, lane, [&](int it, int rr, int c4, float4 v) {
;       int idx = (row0 + rr) * 1024 + col0 + c4;
;       bf16x4 gt = *(const bf16x4*)(gate + idx), mo = *(const bf16x4*)(merged + idx);
;       *(bf16x4*)(merged + idx) = pack4(fmaf(bfs2f(gt[0]), v.x, bfs2f(mo[0])), fmaf(bfs2f(gt[1]), v.y, bfs2f(mo[1])),
;                                        fmaf(bfs2f(gt[2]), v.z, bfs2f(mo[2])), fmaf(bfs2f(gt[3]), v.w, bfs2f(mo[3])));
;     });
;   }
	global_load_dwordx2 v[154:155], v[176:177], off
	v_add_u32_e32 v184, 64, v136
	v_add_u32_e32 v176, v137, v184
	v_lshl_add_u32 v176, v176, 10, v129
	v_ashrrev_i32_e32 v177, 31, v176
	v_lshlrev_b64 v[176:177], 1, v[176:177]
	v_lshl_add_u64 v[178:179], s[16:17], 0, v[176:177]
	global_load_dwordx2 v[156:157], v[178:179], off
	v_add_u32_e32 v184, 64, v136
	v_add_u32_e32 v178, v137, v184
	v_lshl_add_u32 v178, v178, 10, v129
	v_ashrrev_i32_e32 v179, 31, v178
	v_lshlrev_b64 v[178:179], 1, v[178:179]
	v_lshl_add_u64 v[176:177], s[10:11], 0, v[178:179]
	global_load_dwordx2 v[158:159], v[176:177], off
	v_add_u32_e32 v184, 64, v136
	v_add_u32_e32 v176, v135, v184
	v_lshl_add_u32 v176, v176, 10, v129
	v_ashrrev_i32_e32 v177, 31, v176
	v_lshlrev_b64 v[176:177], 1, v[176:177]
	v_lshl_add_u64 v[178:179], s[16:17], 0, v[176:177]
	global_load_dwordx2 v[160:161], v[178:179], off
	v_add_u32_e32 v184, 64, v136
	v_add_u32_e32 v176, v135, v184
	v_lshl_add_u32 v176, v176, 10, v129
	v_ashrrev_i32_e32 v177, 31, v176
	v_lshlrev_b64 v[176:177], 1, v[176:177]
	v_lshl_add_u64 v[178:179], s[10:11], 0, v[176:177]
	global_load_dwordx2 v[162:163], v[178:179], off
	v_add_u32_e32 v184, 64, v136
	v_add_u32_e32 v176, v134, v184
	v_lshl_add_u32 v176, v176, 10, v129
	v_ashrrev_i32_e32 v177, 31, v176
	v_lshlrev_b64 v[176:177], 1, v[176:177]
	v_lshl_add_u64 v[178:179], s[16:17], 0, v[176:177]
	global_load_dwordx2 v[164:165], v[178:179], off
	v_add_u32_e32 v184, 64, v136
	v_add_u32_e32 v178, v134, v184
	v_lshl_add_u32 v178, v178, 10, v129
	v_ashrrev_i32_e32 v179, 31, v178
	v_lshlrev_b64 v[178:179], 1, v[178:179]
	v_lshl_add_u64 v[176:177], s[10:11], 0, v[178:179]
	global_load_dwordx2 v[166:167], v[176:177], off
	v_add_u32_e32 v184, 64, v136
	v_add_u32_e32 v176, v131, v184
	v_lshl_add_u32 v176, v176, 10, v129
	v_ashrrev_i32_e32 v177, 31, v176
	v_lshlrev_b64 v[176:177], 1, v[176:177]
	v_lshl_add_u64 v[178:179], s[16:17], 0, v[176:177]
	global_load_dwordx2 v[168:169], v[178:179], off
	v_add_u32_e32 v184, 64, v136
	v_add_u32_e32 v176, v131, v184
	v_lshl_add_u32 v176, v176, 10, v129
	v_ashrrev_i32_e32 v177, 31, v176
	v_lshlrev_b64 v[176:177], 1, v[176:177]
	v_lshl_add_u64 v[176:177], s[10:11], 0, v[176:177]
	global_load_dwordx2 v[170:171], v[176:177], off
	v_add_u32_e32 v184, 64, v136
	v_add_u32_e32 v176, v130, v184
	v_lshl_add_u32 v176, v176, 10, v129
	v_ashrrev_i32_e32 v177, 31, v176
	v_lshlrev_b64 v[176:177], 1, v[176:177]
	v_lshl_add_u64 v[178:179], s[16:17], 0, v[176:177]
	global_load_dwordx2 v[172:173], v[178:179], off
	v_add_u32_e32 v184, 64, v136
	v_add_u32_e32 v178, v130, v184
	v_lshl_add_u32 v178, v178, 10, v129
	v_ashrrev_i32_e32 v179, 31, v178
	v_lshlrev_b64 v[178:179], 1, v[178:179]
	v_lshl_add_u64 v[176:177], s[10:11], 0, v[178:179]
	global_load_dwordx2 v[174:175], v[176:177], off
	v_add_u32_e32 v56, 64, v136
	v_add_u32_e32 v32, v140, v56
	v_lshl_add_u32 v32, v32, 10, v129
	v_ashrrev_i32_e32 v33, 31, v32
	v_lshlrev_b64 v[32:33], 1, v[32:33]
	v_lshl_add_u64 v[34:35], s[16:17], 0, v[32:33]
	v_lshl_add_u64 v[42:43], s[10:11], 0, v[32:33]
	ds_read_b128 v[32:35], v128
	ds_read_b128 v[36:39], v128 offset:1088
	v_add_u32_e32 v46, v139, v56
	v_lshl_add_u32 v46, v46, 10, v129
	v_ashrrev_i32_e32 v47, 31, v46
	v_lshlrev_b64 v[46:47], 1, v[46:47]
	v_lshl_add_u64 v[48:49], s[16:17], 0, v[46:47]
	s_waitcnt vmcnt(15)
	v_mov_b32_e32 v40, v144
	v_mov_b32_e32 v41, v145
	v_and_b32_e32 v51, 0xffff0000, v40
	v_lshlrev_b32_e32 v50, 16, v40
	s_waitcnt vmcnt(14)
	v_mov_b32_e32 v44, v146
	v_mov_b32_e32 v45, v147
	v_and_b32_e32 v53, 0xffff0000, v44
	v_lshlrev_b32_e32 v52, 16, v44
	v_and_b32_e32 v55, 0xffff0000, v41
	v_lshlrev_b32_e32 v54, 16, v41
	v_and_b32_e32 v41, 0xffff0000, v45
	v_lshlrev_b32_e32 v40, 16, v45
	s_waitcnt lgkmcnt(1)
	v_pk_fma_f32 v[32:33], v[50:51], v[32:33], v[52:53]
	v_pk_fma_f32 v[34:35], v[54:55], v[34:35], v[40:41]
	v_cvt_pk_bf16_f32 v32, v32, v33
	v_cvt_pk_bf16_f32 v33, v34, v35
	global_store_dwordx2 v[42:43], v[32:33], off
	v_lshl_add_u64 v[34:35], s[10:11], 0, v[46:47]
	v_add_u32_e32 v42, v138, v56
	v_lshl_add_u32 v42, v42, 10, v129
	v_ashrrev_i32_e32 v43, 31, v42
	v_lshlrev_b64 v[42:43], 1, v[42:43]
	v_lshl_add_u64 v[44:45], s[16:17], 0, v[42:43]
	v_lshl_add_u64 v[42:43], s[10:11], 0, v[42:43]
	s_waitcnt vmcnt(14)
	v_mov_b32_e32 v32, v148
	v_mov_b32_e32 v33, v149
	v_and_b32_e32 v47, 0xffff0000, v32
	v_lshlrev_b32_e32 v46, 16, v32
	s_waitcnt vmcnt(13)
	v_mov_b32_e32 v40, v150
	v_mov_b32_e32 v41, v151
	v_and_b32_e32 v49, 0xffff0000, v40
	v_lshlrev_b32_e32 v48, 16, v40
	v_and_b32_e32 v51, 0xffff0000, v33
	v_lshlrev_b32_e32 v50, 16, v33
	v_and_b32_e32 v33, 0xffff0000, v41
	v_lshlrev_b32_e32 v32, 16, v41
	s_waitcnt lgkmcnt(0)
	v_pk_fma_f32 v[36:37], v[46:47], v[36:37], v[48:49]
	v_pk_fma_f32 v[32:33], v[50:51], v[38:39], v[32:33]
	v_cvt_pk_bf16_f32 v36, v36, v37
	v_cvt_pk_bf16_f32 v37, v32, v33
	global_store_dwordx2 v[34:35], v[36:37], off
	v_add_u32_e32 v46, v137, v56
	ds_read_b128 v[32:35], v128 offset:2176
	ds_read_b128 v[36:39], v128 offset:3264
	v_lshl_add_u32 v46, v46, 10, v129
	v_ashrrev_i32_e32 v47, 31, v46
	v_lshlrev_b64 v[46:47], 1, v[46:47]
	v_lshl_add_u64 v[48:49], s[16:17], 0, v[46:47]
	s_waitcnt vmcnt(13)
	v_mov_b32_e32 v40, v152
	v_mov_b32_e32 v41, v153
	v_and_b32_e32 v51, 0xffff0000, v40
	v_lshlrev_b32_e32 v50, 16, v40
	s_waitcnt vmcnt(12)
	v_mov_b32_e32 v44, v154
	v_mov_b32_e32 v45, v155
	v_and_b32_e32 v53, 0xffff0000, v44
	v_lshlrev_b32_e32 v52, 16, v44
	v_and_b32_e32 v55, 0xffff0000, v41
	v_lshlrev_b32_e32 v54, 16, v41
	v_and_b32_e32 v41, 0xffff0000, v45
	v_lshlrev_b32_e32 v40, 16, v45
	s_waitcnt lgkmcnt(1)
; __device__ __forceinline__ float bfs2f(short h) { return __uint_as_float(((unsigned)(u16)h) << 16); }
;   __device__ __forceinline__ void tile(const float* reg, int row0, int col0, int lane) const {
;     rows4(reg, lane, [&](int it, int rr, int c4, float4 v) {
;       int idx = (row0 + rr) * 1024 + col0 + c4;
;       bf16x4 gt = *(const bf16x4*)(gate + idx), mo = *(const bf16x4*)(merged + idx);
;       *(bf16x4*)(merged + idx) = pack4(fmaf(bfs2f(gt[0]), v.x, bfs2f(mo[0])), fmaf(bfs2f(gt[1]), v.y, bfs2f(mo[1])),
;                                        fmaf(bfs2f(gt[2]), v.z, bfs2f(mo[2])), fmaf(bfs2f(gt[3]), v.w, bfs2f(mo[3])));
;     });
;   }
	v_pk_fma_f32 v[32:33], v[50:51], v[32:33], v[52:53]
	v_pk_fma_f32 v[34:35], v[54:55], v[34:35], v[40:41]
	v_cvt_pk_bf16_f32 v32, v32, v33
	v_cvt_pk_bf16_f32 v33, v34, v35
	global_store_dwordx2 v[42:43], v[32:33], off
	v_lshl_add_u64 v[34:35], s[10:11], 0, v[46:47]
	s_waitcnt vmcnt(12)
	v_mov_b32_e32 v32, v156
	v_mov_b32_e32 v33, v157
	v_and_b32_e32 v43, 0xffff0000, v32
	v_lshlrev_b32_e32 v42, 16, v32
	s_waitcnt vmcnt(11)
	v_mov_b32_e32 v40, v158
	v_mov_b32_e32 v41, v159
	v_and_b32_e32 v45, 0xffff0000, v40
	v_lshlrev_b32_e32 v44, 16, v40
	v_and_b32_e32 v47, 0xffff0000, v33
	v_lshlrev_b32_e32 v46, 16, v33
	v_and_b32_e32 v33, 0xffff0000, v41
	v_lshlrev_b32_e32 v32, 16, v41
	s_waitcnt lgkmcnt(0)
	v_pk_fma_f32 v[36:37], v[42:43], v[36:37], v[44:45]
	v_pk_fma_f32 v[32:33], v[46:47], v[38:39], v[32:33]
	v_cvt_pk_bf16_f32 v36, v36, v37
	v_cvt_pk_bf16_f32 v37, v32, v33
	global_store_dwordx2 v[34:35], v[36:37], off
	v_add_u32_e32 v32, v135, v56
	v_lshl_add_u32 v32, v32, 10, v129
	v_ashrrev_i32_e32 v33, 31, v32
	v_lshlrev_b64 v[32:33], 1, v[32:33]
	v_lshl_add_u64 v[34:35], s[16:17], 0, v[32:33]
	v_lshl_add_u64 v[42:43], s[10:11], 0, v[32:33]
	ds_read_b128 v[32:35], v128 offset:4352
	ds_read_b128 v[36:39], v128 offset:5440
	v_add_u32_e32 v46, v134, v56
	v_lshl_add_u32 v46, v46, 10, v129
	v_ashrrev_i32_e32 v47, 31, v46
	v_lshlrev_b64 v[46:47], 1, v[46:47]
	v_lshl_add_u64 v[48:49], s[16:17], 0, v[46:47]
	s_waitcnt vmcnt(11)
	v_mov_b32_e32 v40, v160
	v_mov_b32_e32 v41, v161
	v_and_b32_e32 v51, 0xffff0000, v40
	v_lshlrev_b32_e32 v50, 16, v40
	s_waitcnt vmcnt(10)
	v_mov_b32_e32 v44, v162
	v_mov_b32_e32 v45, v163
	v_and_b32_e32 v53, 0xffff0000, v44
	v_lshlrev_b32_e32 v52, 16, v44
	v_and_b32_e32 v55, 0xffff0000, v41
	v_lshlrev_b32_e32 v54, 16, v41
	v_and_b32_e32 v41, 0xffff0000, v45
	v_lshlrev_b32_e32 v40, 16, v45
	s_waitcnt lgkmcnt(1)
	v_pk_fma_f32 v[32:33], v[50:51], v[32:33], v[52:53]
	v_pk_fma_f32 v[34:35], v[54:55], v[34:35], v[40:41]
	v_cvt_pk_bf16_f32 v32, v32, v33
	v_cvt_pk_bf16_f32 v33, v34, v35
	global_store_dwordx2 v[42:43], v[32:33], off
	v_lshl_add_u64 v[34:35], s[10:11], 0, v[46:47]
	v_add_u32_e32 v42, v131, v56
	v_lshl_add_u32 v42, v42, 10, v129
	v_ashrrev_i32_e32 v43, 31, v42
	v_lshlrev_b64 v[42:43], 1, v[42:43]
	v_lshl_add_u64 v[44:45], s[16:17], 0, v[42:43]
	v_lshl_add_u64 v[42:43], s[10:11], 0, v[42:43]
	s_waitcnt vmcnt(10)
	v_mov_b32_e32 v32, v164
	v_mov_b32_e32 v33, v165
	v_and_b32_e32 v47, 0xffff0000, v32
	v_lshlrev_b32_e32 v46, 16, v32
	s_waitcnt vmcnt(9)
	v_mov_b32_e32 v40, v166
	v_mov_b32_e32 v41, v167
	v_and_b32_e32 v49, 0xffff0000, v40
	v_lshlrev_b32_e32 v48, 16, v40
	v_and_b32_e32 v51, 0xffff0000, v33
	v_lshlrev_b32_e32 v50, 16, v33
	v_and_b32_e32 v33, 0xffff0000, v41
	v_lshlrev_b32_e32 v32, 16, v41
	s_waitcnt lgkmcnt(0)
	v_pk_fma_f32 v[36:37], v[46:47], v[36:37], v[48:49]
	v_pk_fma_f32 v[32:33], v[50:51], v[38:39], v[32:33]
	v_cvt_pk_bf16_f32 v36, v36, v37
	v_cvt_pk_bf16_f32 v37, v32, v33
	global_store_dwordx2 v[34:35], v[36:37], off
	v_add_u32_e32 v46, v130, v56
	ds_read_b128 v[32:35], v128 offset:6528
	ds_read_b128 v[36:39], v128 offset:7616
	v_lshl_add_u32 v46, v46, 10, v129
	v_ashrrev_i32_e32 v47, 31, v46
	v_lshlrev_b64 v[46:47], 1, v[46:47]
	v_lshl_add_u64 v[48:49], s[16:17], 0, v[46:47]
	s_waitcnt vmcnt(9)
	v_mov_b32_e32 v40, v168
	v_mov_b32_e32 v41, v169
	v_and_b32_e32 v51, 0xffff0000, v40
	v_lshlrev_b32_e32 v50, 16, v40
	s_waitcnt vmcnt(8)
	v_mov_b32_e32 v44, v170
	v_mov_b32_e32 v45, v171
	v_and_b32_e32 v53, 0xffff0000, v44
	v_lshlrev_b32_e32 v52, 16, v44
	v_and_b32_e32 v55, 0xffff0000, v41
	v_lshlrev_b32_e32 v54, 16, v41
	v_and_b32_e32 v41, 0xffff0000, v45
	v_lshlrev_b32_e32 v40, 16, v45
	s_waitcnt lgkmcnt(1)
	v_pk_fma_f32 v[32:33], v[50:51], v[32:33], v[52:53]
	v_pk_fma_f32 v[34:35], v[54:55], v[34:35], v[40:41]
	v_cvt_pk_bf16_f32 v32, v32, v33
	v_cvt_pk_bf16_f32 v33, v34, v35
	global_store_dwordx2 v[42:43], v[32:33], off
	v_lshl_add_u64 v[34:35], s[10:11], 0, v[46:47]
	s_waitcnt vmcnt(8)
	v_mov_b32_e32 v32, v172
	v_mov_b32_e32 v33, v173
	v_and_b32_e32 v43, 0xffff0000, v32
	v_lshlrev_b32_e32 v42, 16, v32
	s_waitcnt vmcnt(7)
	v_mov_b32_e32 v40, v174
	v_mov_b32_e32 v41, v175
	v_and_b32_e32 v45, 0xffff0000, v40
	v_lshlrev_b32_e32 v44, 16, v40
	v_and_b32_e32 v47, 0xffff0000, v33
	v_lshlrev_b32_e32 v46, 16, v33
	v_and_b32_e32 v33, 0xffff0000, v41
	v_lshlrev_b32_e32 v32, 16, v41
	s_waitcnt lgkmcnt(0)
; __device__ __forceinline__ float bfs2f(short h) { return __uint_as_float(((unsigned)(u16)h) << 16); }
;   __device__ __forceinline__ void tile(const float* reg, int row0, int col0, int lane) const {
;     rows4(reg, lane, [&](int it, int rr, int c4, float4 v) {
;       int idx = (row0 + rr) * 1024 + col0 + c4;
;       bf16x4 gt = *(const bf16x4*)(gate + idx), mo = *(const bf16x4*)(merged + idx);
;       *(bf16x4*)(merged + idx) = pack4(fmaf(bfs2f(gt[0]), v.x, bfs2f(mo[0])), fmaf(bfs2f(gt[1]), v.y, bfs2f(mo[1])),
;                                        fmaf(bfs2f(gt[2]), v.z, bfs2f(mo[2])), fmaf(bfs2f(gt[3]), v.w, bfs2f(mo[3])));
;     });
;   }
; template <int MF, class Epi>
; __device__ __forceinline__ void staged_epilogue(f32x4 (&acc)[MF][4], int row0, int col0, const Epi& epi) {
;     ...
; #pragma unroll
;   for (int mp = 0; mp < MF / 2; ++mp) {
;     __builtin_amdgcn_sched_barrier(0);
; #pragma unroll
;     for (int mm = 0; mm < 2; ++mm)
; #pragma unroll
;       for (int n = 0; n < 4; ++n)
; #pragma unroll
;         for (int j = 0; j < 4; ++j) reg[(mm * 16 + fq * 4 + j) * 68 + n * 16 + fr] = acc[mp * 2 + mm][n][j];
;     __builtin_amdgcn_fence(__ATOMIC_ACQ_REL, "wavefront");
;     epi.tile(reg, row0 + mp * 32, col0, lane);
;     __builtin_amdgcn_fence(__ATOMIC_ACQ_REL, "wavefront");
	v_pk_fma_f32 v[36:37], v[42:43], v[36:37], v[44:45]
	v_pk_fma_f32 v[32:33], v[46:47], v[38:39], v[32:33]
	v_cvt_pk_bf16_f32 v36, v36, v37
	v_cvt_pk_bf16_f32 v37, v32, v33
	global_store_dwordx2 v[34:35], v[36:37], off
	ds_write2_b32 v141, v24, v28 offset1:16
	ds_write2_b32 v141, v25, v29 offset0:68 offset1:84
	ds_write2_b32 v141, v26, v30 offset0:136 offset1:152
	ds_write2_b32 v141, v27, v31 offset0:204 offset1:220
	ds_write2_b32 v141, v16, v20 offset0:32 offset1:48
	ds_write2_b32 v141, v17, v21 offset0:100 offset1:116
	ds_write2_b32 v141, v18, v22 offset0:168 offset1:184
	ds_write2_b32 v141, v19, v23 offset0:236 offset1:252
	ds_write2_b32 v112, v4, v8 offset0:64 offset1:80
	ds_write2_b32 v112, v5, v9 offset0:132 offset1:148
	ds_write2_b32 v112, v6, v10 offset0:200 offset1:216
	ds_write2_b32 v104, v7, v11 offset0:12 offset1:28
	ds_write2_b32 v112, v0, v12 offset0:96 offset1:112
	ds_write2_b32 v112, v1, v13 offset0:164 offset1:180
	ds_write2_b32 v112, v2, v14 offset0:232 offset1:248
	ds_write2_b32 v104, v3, v15 offset0:44 offset1:60
	v_add_u32_e32 v184, 0x60, v136
	v_add_u32_e32 v176, v140, v184
	v_lshl_add_u32 v176, v176, 10, v129
	v_ashrrev_i32_e32 v177, 31, v176
	v_lshlrev_b64 v[176:177], 1, v[176:177]
	v_lshl_add_u64 v[178:179], s[16:17], 0, v[176:177]
	global_load_dwordx2 v[144:145], v[178:179], off
	v_add_u32_e32 v184, 0x60, v136
	v_add_u32_e32 v176, v140, v184
	v_lshl_add_u32 v176, v176, 10, v129
	v_ashrrev_i32_e32 v177, 31, v176
	v_lshlrev_b64 v[176:177], 1, v[176:177]
	v_lshl_add_u64 v[178:179], s[10:11], 0, v[176:177]
	global_load_dwordx2 v[146:147], v[178:179], off
	v_add_u32_e32 v184, 0x60, v136
	v_add_u32_e32 v176, v139, v184
	v_lshl_add_u32 v176, v176, 10, v129
	v_ashrrev_i32_e32 v177, 31, v176
	v_lshlrev_b64 v[176:177], 1, v[176:177]
	v_lshl_add_u64 v[178:179], s[16:17], 0, v[176:177]
	global_load_dwordx2 v[148:149], v[178:179], off
	v_add_u32_e32 v184, 0x60, v136
	v_add_u32_e32 v178, v139, v184
	v_lshl_add_u32 v178, v178, 10, v129
	v_ashrrev_i32_e32 v179, 31, v178
	v_lshlrev_b64 v[178:179], 1, v[178:179]
	v_lshl_add_u64 v[176:177], s[10:11], 0, v[178:179]
	global_load_dwordx2 v[150:151], v[176:177], off
	v_add_u32_e32 v184, 0x60, v136
	v_add_u32_e32 v176, v138, v184
	v_lshl_add_u32 v176, v176, 10, v129
	v_ashrrev_i32_e32 v177, 31, v176
	v_lshlrev_b64 v[176:177], 1, v[176:177]
	v_lshl_add_u64 v[178:179], s[16:17], 0, v[176:177]
	global_load_dwordx2 v[152:153], v[178:179], off
	v_add_u32_e32 v184, 0x60, v136
	v_add_u32_e32 v176, v138, v184
	v_lshl_add_u32 v176, v176, 10, v129
	v_ashrrev_i32_e32 v177, 31, v176
	v_lshlrev_b64 v[176:177], 1, v[176:177]
	v_lshl_add_u64 v[176:177], s[10:11], 0, v[176:177]
	global_load_dwordx2 v[154:155], v[176:177], off
	v_add_u32_e32 v184, 0x60, v136
	v_add_u32_e32 v176, v137, v184
	v_lshl_add_u32 v176, v176, 10, v129
	v_ashrrev_i32_e32 v177, 31, v176
	v_lshlrev_b64 v[176:177], 1, v[176:177]
	v_lshl_add_u64 v[178:179], s[16:17], 0, v[176:177]
	global_load_dwordx2 v[156:157], v[178:179], off
	v_add_u32_e32 v184, 0x60, v136
	v_add_u32_e32 v178, v137, v184
	v_lshl_add_u32 v178, v178, 10, v129
	v_ashrrev_i32_e32 v179, 31, v178
	v_lshlrev_b64 v[178:179], 1, v[178:179]
	v_lshl_add_u64 v[176:177], s[10:11], 0, v[178:179]
	global_load_dwordx2 v[158:159], v[176:177], off
	v_add_u32_e32 v184, 0x60, v136
	v_add_u32_e32 v176, v135, v184
	v_lshl_add_u32 v176, v176, 10, v129
	v_ashrrev_i32_e32 v177, 31, v176
	v_lshlrev_b64 v[176:177], 1, v[176:177]
	v_lshl_add_u64 v[178:179], s[16:17], 0, v[176:177]
	global_load_dwordx2 v[160:161], v[178:179], off
	v_add_u32_e32 v184, 0x60, v136
	v_add_u32_e32 v176, v135, v184
	v_lshl_add_u32 v176, v176, 10, v129
	v_ashrrev_i32_e32 v177, 31, v176
	v_lshlrev_b64 v[176:177], 1, v[176:177]
	v_lshl_add_u64 v[178:179], s[10:11], 0, v[176:177]
	global_load_dwordx2 v[162:163], v[178:179], off
	v_add_u32_e32 v184, 0x60, v136
	v_add_u32_e32 v176, v134, v184
	v_lshl_add_u32 v176, v176, 10, v129
	v_ashrrev_i32_e32 v177, 31, v176
	v_lshlrev_b64 v[176:177], 1, v[176:177]
	v_lshl_add_u64 v[178:179], s[16:17], 0, v[176:177]
	global_load_dwordx2 v[164:165], v[178:179], off
	v_add_u32_e32 v184, 0x60, v136
	v_add_u32_e32 v178, v134, v184
	v_lshl_add_u32 v178, v178, 10, v129
	v_ashrrev_i32_e32 v179, 31, v178
	v_lshlrev_b64 v[178:179], 1, v[178:179]
	v_lshl_add_u64 v[176:177], s[10:11], 0, v[178:179]
	global_load_dwordx2 v[166:167], v[176:177], off
	v_add_u32_e32 v184, 0x60, v136
	v_add_u32_e32 v176, v131, v184
	v_lshl_add_u32 v176, v176, 10, v129
	v_ashrrev_i32_e32 v177, 31, v176
	v_lshlrev_b64 v[176:177], 1, v[176:177]
	v_lshl_add_u64 v[178:179], s[16:17], 0, v[176:177]
	global_load_dwordx2 v[168:169], v[178:179], off
	v_add_u32_e32 v184, 0x60, v136
	v_add_u32_e32 v176, v131, v184
	v_lshl_add_u32 v176, v176, 10, v129
	v_ashrrev_i32_e32 v177, 31, v176
	v_lshlrev_b64 v[176:177], 1, v[176:177]
	v_lshl_add_u64 v[176:177], s[10:11], 0, v[176:177]
	global_load_dwordx2 v[170:171], v[176:177], off
	v_add_u32_e32 v184, 0x60, v136
	v_add_u32_e32 v176, v130, v184
	v_lshl_add_u32 v176, v176, 10, v129
	v_ashrrev_i32_e32 v177, 31, v176
	v_lshlrev_b64 v[176:177], 1, v[176:177]
	v_lshl_add_u64 v[178:179], s[16:17], 0, v[176:177]
	global_load_dwordx2 v[172:173], v[178:179], off
	v_add_u32_e32 v184, 0x60, v136
	v_add_u32_e32 v178, v130, v184
	v_lshl_add_u32 v178, v178, 10, v129
	v_ashrrev_i32_e32 v179, 31, v178
	v_lshlrev_b64 v[178:179], 1, v[178:179]
	v_lshl_add_u64 v[176:177], s[10:11], 0, v[178:179]
	global_load_dwordx2 v[174:175], v[176:177], off
	v_add_u32_e32 v24, 0x60, v136
	v_add_u32_e32 v0, v140, v24
	v_lshl_add_u32 v0, v0, 10, v129
	v_ashrrev_i32_e32 v1, 31, v0
	v_lshlrev_b64 v[0:1], 1, v[0:1]
	v_lshl_add_u64 v[2:3], s[16:17], 0, v[0:1]
	v_lshl_add_u64 v[10:11], s[10:11], 0, v[0:1]
	ds_read_b128 v[0:3], v128
	ds_read_b128 v[4:7], v128 offset:1088
	v_add_u32_e32 v14, v139, v24
	v_lshl_add_u32 v14, v14, 10, v129
	v_ashrrev_i32_e32 v15, 31, v14
	v_lshlrev_b64 v[14:15], 1, v[14:15]
	v_lshl_add_u64 v[16:17], s[16:17], 0, v[14:15]
	s_waitcnt vmcnt(15)
; __device__ __forceinline__ float bfs2f(short h) { return __uint_as_float(((unsigned)(u16)h) << 16); }
;   __device__ __forceinline__ void tile(const float* reg, int row0, int col0, int lane) const {
;     rows4(reg, lane, [&](int it, int rr, int c4, float4 v) {
;       int idx = (row0 + rr) * 1024 + col0 + c4;
;       bf16x4 gt = *(const bf16x4*)(gate + idx), mo = *(const bf16x4*)(merged + idx);
;       *(bf16x4*)(merged + idx) = pack4(fmaf(bfs2f(gt[0]), v.x, bfs2f(mo[0])), fmaf(bfs2f(gt[1]), v.y, bfs2f(mo[1])),
;                                        fmaf(bfs2f(gt[2]), v.z, bfs2f(mo[2])), fmaf(bfs2f(gt[3]), v.w, bfs2f(mo[3])));
;     });
;   }
; template <int MF, class Epi>
; __device__ __forceinline__ void staged_epilogue(f32x4 (&acc)[MF][4], int row0, int col0, const Epi& epi) {
;     ...
; #pragma unroll
;   for (int mp = 0; mp < MF / 2; ++mp) {
;     __builtin_amdgcn_sched_barrier(0);
; #pragma unroll
;     for (int mm = 0; mm < 2; ++mm)
; #pragma unroll
;       for (int n = 0; n < 4; ++n)
; #pragma unroll
;         for (int j = 0; j < 4; ++j) reg[(mm * 16 + fq * 4 + j) * 68 + n * 16 + fr] = acc[mp * 2 + mm][n][j];
;     __builtin_amdgcn_fence(__ATOMIC_ACQ_REL, "wavefront");
;     epi.tile(reg, row0 + mp * 32, col0, lane);
;     __builtin_amdgcn_fence(__ATOMIC_ACQ_REL, "wavefront");
	v_mov_b32_e32 v8, v144
	v_mov_b32_e32 v9, v145
	v_and_b32_e32 v19, 0xffff0000, v8
	v_lshlrev_b32_e32 v18, 16, v8
	s_waitcnt vmcnt(14)
	v_mov_b32_e32 v12, v146
	v_mov_b32_e32 v13, v147
	v_and_b32_e32 v21, 0xffff0000, v12
	v_lshlrev_b32_e32 v20, 16, v12
	v_and_b32_e32 v23, 0xffff0000, v9
	v_lshlrev_b32_e32 v22, 16, v9
	v_and_b32_e32 v9, 0xffff0000, v13
	v_lshlrev_b32_e32 v8, 16, v13
	s_waitcnt lgkmcnt(1)
	v_pk_fma_f32 v[0:1], v[18:19], v[0:1], v[20:21]
	v_pk_fma_f32 v[2:3], v[22:23], v[2:3], v[8:9]
	v_cvt_pk_bf16_f32 v0, v0, v1
	v_cvt_pk_bf16_f32 v1, v2, v3
	global_store_dwordx2 v[10:11], v[0:1], off
	v_lshl_add_u64 v[2:3], s[10:11], 0, v[14:15]
	v_add_u32_e32 v10, v138, v24
	v_lshl_add_u32 v10, v10, 10, v129
	v_ashrrev_i32_e32 v11, 31, v10
	v_lshlrev_b64 v[10:11], 1, v[10:11]
	v_lshl_add_u64 v[12:13], s[16:17], 0, v[10:11]
	v_lshl_add_u64 v[10:11], s[10:11], 0, v[10:11]
	s_waitcnt vmcnt(14)
	v_mov_b32_e32 v0, v148
	v_mov_b32_e32 v1, v149
	v_and_b32_e32 v15, 0xffff0000, v0
	v_lshlrev_b32_e32 v14, 16, v0
	s_waitcnt vmcnt(13)
	v_mov_b32_e32 v8, v150
	v_mov_b32_e32 v9, v151
	v_and_b32_e32 v17, 0xffff0000, v8
	v_lshlrev_b32_e32 v16, 16, v8
	v_and_b32_e32 v19, 0xffff0000, v1
	v_lshlrev_b32_e32 v18, 16, v1
	v_and_b32_e32 v1, 0xffff0000, v9
	v_lshlrev_b32_e32 v0, 16, v9
	s_waitcnt lgkmcnt(0)
	v_pk_fma_f32 v[4:5], v[14:15], v[4:5], v[16:17]
	v_pk_fma_f32 v[0:1], v[18:19], v[6:7], v[0:1]
	v_cvt_pk_bf16_f32 v4, v4, v5
	v_cvt_pk_bf16_f32 v5, v0, v1
	global_store_dwordx2 v[2:3], v[4:5], off
	v_add_u32_e32 v14, v137, v24
	ds_read_b128 v[0:3], v128 offset:2176
	ds_read_b128 v[4:7], v128 offset:3264
	v_lshl_add_u32 v14, v14, 10, v129
	v_ashrrev_i32_e32 v15, 31, v14
	v_lshlrev_b64 v[14:15], 1, v[14:15]
	v_lshl_add_u64 v[16:17], s[16:17], 0, v[14:15]
	s_waitcnt vmcnt(13)
	v_mov_b32_e32 v8, v152
	v_mov_b32_e32 v9, v153
	v_and_b32_e32 v19, 0xffff0000, v8
	v_lshlrev_b32_e32 v18, 16, v8
	s_waitcnt vmcnt(12)
	v_mov_b32_e32 v12, v154
	v_mov_b32_e32 v13, v155
	v_and_b32_e32 v21, 0xffff0000, v12
	v_lshlrev_b32_e32 v20, 16, v12
	v_and_b32_e32 v23, 0xffff0000, v9
	v_lshlrev_b32_e32 v22, 16, v9
	v_and_b32_e32 v9, 0xffff0000, v13
	v_lshlrev_b32_e32 v8, 16, v13
	s_waitcnt lgkmcnt(1)
	v_pk_fma_f32 v[0:1], v[18:19], v[0:1], v[20:21]
	v_pk_fma_f32 v[2:3], v[22:23], v[2:3], v[8:9]
	v_cvt_pk_bf16_f32 v0, v0, v1
	v_cvt_pk_bf16_f32 v1, v2, v3
	global_store_dwordx2 v[10:11], v[0:1], off
	v_lshl_add_u64 v[2:3], s[10:11], 0, v[14:15]
	s_waitcnt vmcnt(12)
	v_mov_b32_e32 v0, v156
	v_mov_b32_e32 v1, v157
	v_and_b32_e32 v11, 0xffff0000, v0
	v_lshlrev_b32_e32 v10, 16, v0
	s_waitcnt vmcnt(11)
	v_mov_b32_e32 v8, v158
	v_mov_b32_e32 v9, v159
	v_and_b32_e32 v13, 0xffff0000, v8
	v_lshlrev_b32_e32 v12, 16, v8
	v_and_b32_e32 v15, 0xffff0000, v1
	v_lshlrev_b32_e32 v14, 16, v1
	v_and_b32_e32 v1, 0xffff0000, v9
	v_lshlrev_b32_e32 v0, 16, v9
	s_waitcnt lgkmcnt(0)
	v_pk_fma_f32 v[4:5], v[10:11], v[4:5], v[12:13]
	v_pk_fma_f32 v[0:1], v[14:15], v[6:7], v[0:1]
	v_cvt_pk_bf16_f32 v4, v4, v5
	v_cvt_pk_bf16_f32 v5, v0, v1
	global_store_dwordx2 v[2:3], v[4:5], off
	v_add_u32_e32 v0, v135, v24
	v_lshl_add_u32 v0, v0, 10, v129
	v_ashrrev_i32_e32 v1, 31, v0
	v_lshlrev_b64 v[0:1], 1, v[0:1]
	v_lshl_add_u64 v[2:3], s[16:17], 0, v[0:1]
	v_lshl_add_u64 v[10:11], s[10:11], 0, v[0:1]
	ds_read_b128 v[0:3], v128 offset:4352
	ds_read_b128 v[4:7], v128 offset:5440
	v_add_u32_e32 v14, v134, v24
	v_lshl_add_u32 v14, v14, 10, v129
	v_ashrrev_i32_e32 v15, 31, v14
	v_lshlrev_b64 v[14:15], 1, v[14:15]
	v_lshl_add_u64 v[16:17], s[16:17], 0, v[14:15]
	s_andn2_b64 vcc, exec, s[64:65]
	s_waitcnt vmcnt(11)
	v_mov_b32_e32 v8, v160
	v_mov_b32_e32 v9, v161
	v_and_b32_e32 v19, 0xffff0000, v8
	v_lshlrev_b32_e32 v18, 16, v8
	s_waitcnt vmcnt(10)
	v_mov_b32_e32 v12, v162
	v_mov_b32_e32 v13, v163
	v_and_b32_e32 v21, 0xffff0000, v12
	v_lshlrev_b32_e32 v20, 16, v12
	v_and_b32_e32 v23, 0xffff0000, v9
	v_lshlrev_b32_e32 v22, 16, v9
	v_and_b32_e32 v9, 0xffff0000, v13
	v_lshlrev_b32_e32 v8, 16, v13
	s_waitcnt lgkmcnt(1)
	v_pk_fma_f32 v[0:1], v[18:19], v[0:1], v[20:21]
	v_pk_fma_f32 v[2:3], v[22:23], v[2:3], v[8:9]
	v_cvt_pk_bf16_f32 v0, v0, v1
	v_cvt_pk_bf16_f32 v1, v2, v3
	global_store_dwordx2 v[10:11], v[0:1], off
	v_lshl_add_u64 v[2:3], s[10:11], 0, v[14:15]
	v_add_u32_e32 v10, v131, v24
	v_lshl_add_u32 v10, v10, 10, v129
	v_ashrrev_i32_e32 v11, 31, v10
	v_lshlrev_b64 v[10:11], 1, v[10:11]
	v_lshl_add_u64 v[12:13], s[16:17], 0, v[10:11]
	v_lshl_add_u64 v[10:11], s[10:11], 0, v[10:11]
	s_waitcnt vmcnt(10)
	v_mov_b32_e32 v0, v164
	v_mov_b32_e32 v1, v165
	v_and_b32_e32 v15, 0xffff0000, v0
	v_lshlrev_b32_e32 v14, 16, v0
	s_waitcnt vmcnt(9)
	v_mov_b32_e32 v8, v166
	v_mov_b32_e32 v9, v167
	v_and_b32_e32 v17, 0xffff0000, v8
	v_lshlrev_b32_e32 v16, 16, v8
	v_and_b32_e32 v19, 0xffff0000, v1
	v_lshlrev_b32_e32 v18, 16, v1
	v_and_b32_e32 v1, 0xffff0000, v9
	v_lshlrev_b32_e32 v0, 16, v9
	s_waitcnt lgkmcnt(0)
	v_pk_fma_f32 v[4:5], v[14:15], v[4:5], v[16:17]
	v_pk_fma_f32 v[0:1], v[18:19], v[6:7], v[0:1]
	v_cvt_pk_bf16_f32 v4, v4, v5
	v_cvt_pk_bf16_f32 v5, v0, v1
	global_store_dwordx2 v[2:3], v[4:5], off
	v_add_u32_e32 v14, v130, v24
	ds_read_b128 v[0:3], v128 offset:6528
	ds_read_b128 v[4:7], v128 offset:7616
	v_lshl_add_u32 v14, v14, 10, v129
	v_ashrrev_i32_e32 v15, 31, v14
	v_lshlrev_b64 v[14:15], 1, v[14:15]
	v_lshl_add_u64 v[16:17], s[16:17], 0, v[14:15]
	s_waitcnt vmcnt(9)
	v_mov_b32_e32 v8, v168
	v_mov_b32_e32 v9, v169
	v_and_b32_e32 v19, 0xffff0000, v8
	v_lshlrev_b32_e32 v18, 16, v8
	s_waitcnt vmcnt(8)
	v_mov_b32_e32 v12, v170
	v_mov_b32_e32 v13, v171
	v_and_b32_e32 v21, 0xffff0000, v12
	v_lshlrev_b32_e32 v20, 16, v12
	v_and_b32_e32 v23, 0xffff0000, v9
	v_lshlrev_b32_e32 v22, 16, v9
	v_and_b32_e32 v9, 0xffff0000, v13
	v_lshlrev_b32_e32 v8, 16, v13
	s_waitcnt lgkmcnt(1)
	v_pk_fma_f32 v[0:1], v[18:19], v[0:1], v[20:21]
	v_pk_fma_f32 v[2:3], v[22:23], v[2:3], v[8:9]
	v_cvt_pk_bf16_f32 v0, v0, v1
	v_cvt_pk_bf16_f32 v1, v2, v3
	global_store_dwordx2 v[10:11], v[0:1], off
	v_lshl_add_u64 v[2:3], s[10:11], 0, v[14:15]
	s_waitcnt vmcnt(8)
	v_mov_b32_e32 v0, v172
	v_mov_b32_e32 v1, v173
	v_and_b32_e32 v11, 0xffff0000, v0
	v_lshlrev_b32_e32 v10, 16, v0
	s_waitcnt vmcnt(7)
	v_mov_b32_e32 v8, v174
	v_mov_b32_e32 v9, v175
	v_and_b32_e32 v13, 0xffff0000, v8
	v_lshlrev_b32_e32 v12, 16, v8
	v_and_b32_e32 v15, 0xffff0000, v1
	v_lshlrev_b32_e32 v14, 16, v1
	v_and_b32_e32 v1, 0xffff0000, v9
	v_lshlrev_b32_e32 v0, 16, v9
	s_waitcnt lgkmcnt(0)
	v_pk_fma_f32 v[4:5], v[10:11], v[4:5], v[12:13]
	v_pk_fma_f32 v[0:1], v[14:15], v[6:7], v[0:1]
	v_cvt_pk_bf16_f32 v4, v4, v5
	v_cvt_pk_bf16_f32 v5, v0, v1
	global_store_dwordx2 v[2:3], v[4:5], off
	s_cbranch_vccz .LBB0_1389

; template <class Epi>
; __device__ __forceinline__ void small_gemm(const u16* __restrict__ A, const u16* __restrict__ Bt, int K, int N, const Epi& epi) {
;     ...
;   for (int piece = blockIdx.x; piece < npieces; piece += gridDim.x) {
;     int row0 = (piece & 3) * 32, col0 = (piece >> 2) * 64;
;     f32x4 acc[2][4] = {};
;     int kper = K >> 3, k0 = wid * kper;
;     for (int kk = k0; kk < k0 + kper; kk += 32) {
;       bf16x8 a[2], b[4];
; #pragma unroll
;       for (int m = 0; m < 2; ++m) a[m] = *(const bf16x8*)(A + (size_t)(row0 + m * 16 + fr) * K + kk + fq * 8);
; #pragma unroll
;       for (int n = 0; n < 4; ++n) b[n] = *(const bf16x8*)(Bt + (size_t)(col0 + n * 16 + fr) * K + kk + fq * 8);
; #pragma unroll
;       for (int m = 0; m < 2; ++m)
; #pragma unroll
;         for (int n = 0; n < 4; ++n) acc[m][n] = __builtin_amdgcn_mfma_f32_16x16x32_bf16(a[m], b[n], acc[m][n], 0, 0, 0);
;     }
;     __syncthreads();
; #pragma unroll
;     for (int m = 0; m < 2; ++m)
; #pragma unroll
;       for (int n = 0; n < 4; ++n) red[(wid * 8 + m * 4 + n) * 64 + lane] = acc[m][n];
;     __syncthreads();
.LBB0_1392:
	s_and_b32 s18, s2, 0xffffffc0
	v_or_b32_e32 v30, s18, v22
	s_and_b32 s17, s6, 0x60
	v_ashrrev_i32_e32 v31, 31, v30
	v_or_b32_e32 v0, s17, v22
	s_waitcnt vmcnt(4)
	v_lshlrev_b64 v[16:17], 11, v[30:31]
	v_or_b32_e32 v26, 16, v30
	v_or_b32_e32 v32, s2, v24
	v_or_b32_e32 v30, 32, v30
	v_lshlrev_b32_e32 v0, 11, v0
	v_ashrrev_i32_e32 v27, 31, v26
	v_ashrrev_i32_e32 v33, 31, v32
	v_ashrrev_i32_e32 v31, 31, v30
	v_lshl_add_u64 v[20:21], v[2:3], 0, v[0:1]
	v_lshlrev_b64 v[26:27], 11, v[26:27]
	v_lshlrev_b64 v[42:43], 11, v[32:33]
	v_lshlrev_b64 v[34:35], 11, v[30:31]
	v_or_b32_e32 v0, 0x8000, v0
	v_lshl_add_u64 v[74:75], v[4:5], 0, v[16:17]
	v_lshl_add_u64 v[82:83], v[4:5], 0, v[26:27]
	v_lshl_add_u64 v[90:91], v[4:5], 0, v[34:35]
	v_lshl_add_u64 v[102:103], v[4:5], 0, v[42:43]
	v_lshl_add_u64 v[66:67], v[2:3], 0, v[0:1]
	global_load_dwordx4 v[12:15], v[20:21], off
	global_load_dwordx4 v[16:19], v[74:75], off
	global_load_dwordx4 v[26:29], v[82:83], off
	global_load_dwordx4 v[30:33], v[20:21], off offset:64
	global_load_dwordx4 v[38:41], v[90:91], off
	global_load_dwordx4 v[42:45], v[74:75], off offset:192
	global_load_dwordx4 v[50:53], v[102:103], off
	global_load_dwordx4 v[54:57], v[82:83], off offset:192
	global_load_dwordx4 v[62:65], v[90:91], off offset:192
	v_lshl_add_u64 v[104:105], v[6:7], 0, v[0:1]
	global_load_dwordx4 v[66:69], v[66:67], off
	s_waitcnt vmcnt(8)
	v_mfma_f32_16x16x32_bf16 v[34:37], v[12:15], v[16:19], 0
	s_waitcnt vmcnt(7)
	v_mfma_f32_16x16x32_bf16 v[46:49], v[12:15], v[26:29], 0
	s_waitcnt vmcnt(5)
	v_mfma_f32_16x16x32_bf16 v[58:61], v[12:15], v[38:41], 0
	s_waitcnt vmcnt(3)
	v_mfma_f32_16x16x32_bf16 v[12:15], v[12:15], v[50:53], 0
	s_waitcnt vmcnt(0)
	v_mfma_f32_16x16x32_bf16 v[16:19], v[66:69], v[16:19], 0
	v_mfma_f32_16x16x32_bf16 v[26:29], v[66:69], v[26:29], 0
	v_mfma_f32_16x16x32_bf16 v[38:41], v[66:69], v[38:41], 0
	v_mfma_f32_16x16x32_bf16 v[50:53], v[66:69], v[50:53], 0
	global_load_dwordx4 v[66:69], v[74:75], off offset:64
	global_load_dwordx4 v[70:73], v[74:75], off offset:128
	s_nop 0
	global_load_dwordx4 v[74:77], v[82:83], off offset:64
	global_load_dwordx4 v[78:81], v[82:83], off offset:128
	s_nop 0
	global_load_dwordx4 v[82:85], v[90:91], off offset:64
	global_load_dwordx4 v[86:89], v[90:91], off offset:128
	global_load_dwordx4 v[94:97], v[102:103], off offset:128
	s_waitcnt vmcnt(6)
	v_mfma_f32_16x16x32_bf16 v[34:37], v[30:33], v[66:69], v[34:37]
	global_load_dwordx4 v[90:93], v[102:103], off offset:64
	s_waitcnt vmcnt(5)
	v_mfma_f32_16x16x32_bf16 v[46:49], v[30:33], v[74:77], v[46:49]
	s_waitcnt vmcnt(3)
	v_mfma_f32_16x16x32_bf16 v[58:61], v[30:33], v[82:85], v[58:61]
	s_waitcnt vmcnt(0)
	v_mfma_f32_16x16x32_bf16 v[12:15], v[30:33], v[90:93], v[12:15]
	global_load_dwordx4 v[30:33], v[104:105], off
	global_load_dwordx4 v[98:101], v[102:103], off offset:192
	s_waitcnt vmcnt(1)
	v_mfma_f32_16x16x32_bf16 v[16:19], v[30:33], v[66:69], v[16:19]
	v_mfma_f32_16x16x32_bf16 v[26:29], v[30:33], v[74:77], v[26:29]
	v_mfma_f32_16x16x32_bf16 v[38:41], v[30:33], v[82:85], v[38:41]
	v_mfma_f32_16x16x32_bf16 v[30:33], v[30:33], v[90:93], v[50:53]
	s_nop 2
	global_load_dwordx4 v[50:53], v[20:21], off offset:128
	global_load_dwordx4 v[66:69], v[20:21], off offset:192
	v_lshl_add_u64 v[20:21], v[8:9], 0, v[0:1]
	global_load_dwordx4 v[74:77], v[20:21], off
	v_lshl_add_u64 v[20:21], v[10:11], 0, v[0:1]
	s_waitcnt vmcnt(2)
	v_mfma_f32_16x16x32_bf16 v[34:37], v[50:53], v[70:73], v[34:37]
	v_mfma_f32_16x16x32_bf16 v[46:49], v[50:53], v[78:81], v[46:49]
	v_mfma_f32_16x16x32_bf16 v[58:61], v[50:53], v[86:89], v[58:61]
	v_mfma_f32_16x16x32_bf16 v[12:15], v[50:53], v[94:97], v[12:15]
	global_load_dwordx4 v[50:53], v[20:21], off
	s_barrier
	s_waitcnt vmcnt(1)
	v_mfma_f32_16x16x32_bf16 v[16:19], v[74:77], v[70:73], v[16:19]
	v_mfma_f32_16x16x32_bf16 v[26:29], v[74:77], v[78:81], v[26:29]
	v_mfma_f32_16x16x32_bf16 v[38:41], v[74:77], v[86:89], v[38:41]
	v_mfma_f32_16x16x32_bf16 v[34:37], v[66:69], v[42:45], v[34:37]
	v_mfma_f32_16x16x32_bf16 v[46:49], v[66:69], v[54:57], v[46:49]
	v_mfma_f32_16x16x32_bf16 v[58:61], v[66:69], v[62:65], v[58:61]
	s_nop 5
	ds_write_b128 v25, v[34:37]
	v_mfma_f32_16x16x32_bf16 v[30:33], v[74:77], v[94:97], v[30:33]
	v_mfma_f32_16x16x32_bf16 v[12:15], v[66:69], v[98:101], v[12:15]
	ds_write_b128 v25, v[46:49] offset:1024
	ds_write_b128 v25, v[58:61] offset:2048
	s_nop 5
	ds_write_b128 v25, v[12:15] offset:3072
	s_waitcnt vmcnt(0)
	v_mfma_f32_16x16x32_bf16 v[16:19], v[50:53], v[42:45], v[16:19]
	v_mfma_f32_16x16x32_bf16 v[26:29], v[50:53], v[54:57], v[26:29]
	v_mfma_f32_16x16x32_bf16 v[12:15], v[50:53], v[62:65], v[38:41]
	s_nop 5
	ds_write_b128 v25, v[16:19] offset:4096
	ds_write_b128 v25, v[26:29] offset:5120
	ds_write_b128 v25, v[12:15] offset:6144
	v_mfma_f32_16x16x32_bf16 v[12:15], v[50:53], v[98:101], v[30:33]
	s_nop 7
	ds_write_b128 v25, v[12:15] offset:7168
	s_waitcnt lgkmcnt(0)
	s_barrier
	s_and_saveexec_b64 s[0:1], vcc
	s_cbranch_execz .LBB0_1391
; template <class Epi>
; __device__ __forceinline__ void small_gemm(const u16* __restrict__ A, const u16* __restrict__ Bt, int K, int N, const Epi& epi) {
;     ...
;     if (wid == 0) {
; #pragma unroll
;       for (int m = 0; m < 2; ++m)
; #pragma unroll
;         for (int n = 0; n < 4; ++n) {
;           f32x4 s = red[(m * 4 + n) * 64 + lane];
; #pragma unroll
;           for (int w = 1; w < 8; ++w) s += red[(w * 8 + m * 4 + n) * 64 + lane];
;           acc[m][n] = s;
;         }
	ds_read_b128 v[12:15], v23
	ds_read_b128 v[16:19], v23 offset:8192
	ds_read_b128 v[26:29], v23 offset:16384
	ds_read_b128 v[30:33], v23 offset:1024
	ds_read_b128 v[34:37], v23 offset:9216
	v_mov_b32_e32 v0, v204
	s_waitcnt lgkmcnt(3)
	v_pk_add_f32 v[20:21], v[14:15], v[18:19]
	v_pk_add_f32 v[38:39], v[12:13], v[16:17]
	ds_read_b128 v[12:15], v23 offset:24576
	ds_read_b128 v[16:19], v23 offset:17408
	s_waitcnt lgkmcnt(4)
	v_pk_add_f32 v[20:21], v[20:21], v[28:29]
	v_pk_add_f32 v[42:43], v[38:39], v[26:27]
	ds_read_b128 v[26:29], v23 offset:32768
	ds_read_b128 v[38:41], v23 offset:25600
	s_waitcnt lgkmcnt(3)
	v_pk_add_f32 v[20:21], v[20:21], v[14:15]
	v_pk_add_f32 v[46:47], v[42:43], v[12:13]
	ds_read_b128 v[12:15], v23 offset:40960
	ds_read_b128 v[42:45], v23 offset:33792
	s_waitcnt lgkmcnt(3)
	v_pk_add_f32 v[20:21], v[20:21], v[28:29]
	v_pk_add_f32 v[50:51], v[46:47], v[26:27]
	ds_read_b128 v[26:29], v23 offset:49152
	ds_read_b128 v[46:49], v23 offset:41984
	s_waitcnt lgkmcnt(3)
	v_pk_add_f32 v[12:13], v[50:51], v[12:13]
	ds_read_b128 v[50:53], v23 offset:57344
	ds_read_b128 v[54:57], v23 offset:50176
	v_pk_add_f32 v[14:15], v[20:21], v[14:15]
	s_waitcnt lgkmcnt(3)
	v_pk_add_f32 v[20:21], v[12:13], v[26:27]
	v_pk_add_f32 v[14:15], v[14:15], v[28:29]
	ds_read_b128 v[26:29], v23 offset:58368
	s_waitcnt lgkmcnt(2)
	v_pk_add_f32 v[12:13], v[14:15], v[52:53]
	v_pk_add_f32 v[14:15], v[20:21], v[50:51]
	v_pk_add_f32 v[20:21], v[32:33], v[36:37]
	v_pk_add_f32 v[30:31], v[30:31], v[34:35]
	v_pk_add_f32 v[18:19], v[20:21], v[18:19]
	v_pk_add_f32 v[16:17], v[30:31], v[16:17]
	v_pk_add_f32 v[18:19], v[18:19], v[40:41]
	v_pk_add_f32 v[16:17], v[16:17], v[38:39]
	v_pk_add_f32 v[18:19], v[18:19], v[44:45]
	v_pk_add_f32 v[16:17], v[16:17], v[42:43]
	v_pk_add_f32 v[18:19], v[18:19], v[48:49]
	v_pk_add_f32 v[16:17], v[16:17], v[46:47]
	s_waitcnt lgkmcnt(1)
	v_pk_add_f32 v[18:19], v[18:19], v[56:57]
	v_pk_add_f32 v[20:21], v[16:17], v[54:55]
	s_waitcnt lgkmcnt(0)
	v_pk_add_f32 v[16:17], v[18:19], v[28:29]
	ds_read_b128 v[28:31], v23 offset:2048
	ds_read_b128 v[32:35], v23 offset:10240
	v_pk_add_f32 v[18:19], v[20:21], v[26:27]
	ds_read_b128 v[36:39], v23 offset:18432
	ds_read_b128 v[40:43], v23 offset:3072
	ds_read_b128 v[44:47], v23 offset:11264
	s_waitcnt lgkmcnt(3)
	v_pk_add_f32 v[20:21], v[30:31], v[34:35]
	v_pk_add_f32 v[34:35], v[28:29], v[32:33]
	ds_read_b128 v[26:29], v23 offset:26624
	ds_read_b128 v[30:33], v23 offset:19456
	s_waitcnt lgkmcnt(4)
	v_pk_add_f32 v[20:21], v[20:21], v[38:39]
	v_pk_add_f32 v[38:39], v[34:35], v[36:37]
	ds_read_b128 v[34:37], v23 offset:34816
	ds_read_b128 v[48:51], v23 offset:27648
	s_waitcnt lgkmcnt(3)
	v_pk_add_f32 v[20:21], v[20:21], v[28:29]
	v_pk_add_f32 v[38:39], v[38:39], v[26:27]
	ds_read_b128 v[26:29], v23 offset:43008
	ds_read_b128 v[52:55], v23 offset:35840
	s_waitcnt lgkmcnt(3)
	v_pk_add_f32 v[20:21], v[20:21], v[36:37]
	v_pk_add_f32 v[38:39], v[38:39], v[34:35]
	ds_read_b128 v[34:37], v23 offset:51200
	ds_read_b128 v[56:59], v23 offset:44032
	s_waitcnt lgkmcnt(3)
	v_pk_add_f32 v[20:21], v[20:21], v[28:29]
	v_pk_add_f32 v[38:39], v[38:39], v[26:27]
	ds_read_b128 v[26:29], v23 offset:59392
	ds_read_b128 v[60:63], v23 offset:52224
	s_waitcnt lgkmcnt(3)
	v_pk_add_f32 v[38:39], v[38:39], v[34:35]
	v_pk_add_f32 v[20:21], v[20:21], v[36:37]
	ds_read_b128 v[34:37], v23 offset:60416
	s_waitcnt lgkmcnt(2)
	v_pk_add_f32 v[64:65], v[38:39], v[26:27]
	v_pk_add_f32 v[26:27], v[42:43], v[46:47]
	v_pk_add_f32 v[20:21], v[20:21], v[28:29]
	v_pk_add_f32 v[28:29], v[40:41], v[44:45]
	v_pk_add_f32 v[26:27], v[26:27], v[32:33]
	v_pk_add_f32 v[28:29], v[28:29], v[30:31]
	v_pk_add_f32 v[26:27], v[26:27], v[50:51]
	v_pk_add_f32 v[28:29], v[28:29], v[48:49]
	v_pk_add_f32 v[26:27], v[26:27], v[54:55]
	v_pk_add_f32 v[28:29], v[28:29], v[52:53]
	v_pk_add_f32 v[26:27], v[26:27], v[58:59]
	v_pk_add_f32 v[28:29], v[28:29], v[56:57]
	s_waitcnt lgkmcnt(1)
	v_pk_add_f32 v[26:27], v[26:27], v[62:63]
	v_pk_add_f32 v[38:39], v[28:29], v[60:61]
	s_waitcnt lgkmcnt(0)
	v_pk_add_f32 v[62:63], v[26:27], v[36:37]
	ds_read_b128 v[26:29], v23 offset:4096
	ds_read_b128 v[30:33], v23 offset:12288
	v_pk_add_f32 v[66:67], v[38:39], v[34:35]
	ds_read_b128 v[34:37], v23 offset:20480
	ds_read_b128 v[38:41], v23 offset:5120
	ds_read_b128 v[42:45], v23 offset:13312
	s_waitcnt lgkmcnt(3)
	v_pk_add_f32 v[46:47], v[28:29], v[32:33]
	v_pk_add_f32 v[48:49], v[26:27], v[30:31]
	ds_read_b128 v[26:29], v23 offset:28672
	ds_read_b128 v[30:33], v23 offset:21504
	s_waitcnt lgkmcnt(4)
	v_pk_add_f32 v[50:51], v[46:47], v[36:37]
	v_pk_add_f32 v[52:53], v[48:49], v[34:35]
	ds_read_b128 v[34:37], v23 offset:36864
	ds_read_b128 v[46:49], v23 offset:29696
	s_waitcnt lgkmcnt(3)
	v_pk_add_f32 v[54:55], v[50:51], v[28:29]
	v_pk_add_f32 v[56:57], v[52:53], v[26:27]
	ds_read_b128 v[26:29], v23 offset:45056
	ds_read_b128 v[50:53], v23 offset:37888
	s_waitcnt lgkmcnt(3)
	v_pk_add_f32 v[58:59], v[54:55], v[36:37]
	v_pk_add_f32 v[60:61], v[56:57], v[34:35]
	ds_read_b128 v[34:37], v23 offset:53248
	ds_read_b128 v[54:57], v23 offset:46080
	s_waitcnt lgkmcnt(3)
	v_pk_add_f32 v[68:69], v[58:59], v[28:29]
	v_pk_add_f32 v[70:71], v[60:61], v[26:27]
	ds_read_b128 v[26:29], v23 offset:61440
	ds_read_b128 v[58:61], v23 offset:54272
	s_waitcnt lgkmcnt(3)
	v_pk_add_f32 v[70:71], v[70:71], v[34:35]
	v_pk_add_f32 v[68:69], v[68:69], v[36:37]
	ds_read_b128 v[34:37], v23 offset:62464
	s_waitcnt lgkmcnt(2)
; __device__ __forceinline__ float bfs2f(short h) { return __uint_as_float(((unsigned)(u16)h) << 16); }
;   __device__ __forceinline__ void tile(const float* reg, int row0, int col0, int lane) const {
;     rows4(reg, lane, [&](int it, int rr, int c4, float4 v) {
;       int idx = (row0 + rr) * 1024 + col0 + c4;
;       bf16x4 gt = *(const bf16x4*)(gate + idx), mo = *(const bf16x4*)(merged + idx);
;       *(bf16x4*)(merged + idx) = pack4(fmaf(bfs2f(gt[0]), v.x, bfs2f(mo[0])), fmaf(bfs2f(gt[1]), v.y, bfs2f(mo[1])),
; template <int MF, class Epi>
; __device__ __forceinline__ void staged_epilogue(f32x4 (&acc)[MF][4], int row0, int col0, const Epi& epi) {
;     ...
;     for (int mm = 0; mm < 2; ++mm)
; #pragma unroll
;       for (int n = 0; n < 4; ++n)
; #pragma unroll
;         for (int j = 0; j < 4; ++j) reg[(mm * 16 + fq * 4 + j) * 68 + n * 16 + fr] = acc[mp * 2 + mm][n][j];
; template <class Epi>
; __device__ __forceinline__ void small_gemm(const u16* __restrict__ A, const u16* __restrict__ Bt, int K, int N, const Epi& epi) {
;     ...
;           f32x4 s = red[(m * 4 + n) * 64 + lane];
; #pragma unroll
;           for (int w = 1; w < 8; ++w) s += red[(w * 8 + m * 4 + n) * 64 + lane];
;           acc[m][n] = s;
;         }
;       staged_epilogue<2>(acc, row0, col0, epi);
	v_pk_add_f32 v[70:71], v[70:71], v[26:27]
	v_pk_add_f32 v[26:27], v[40:41], v[44:45]
	v_pk_add_f32 v[68:69], v[68:69], v[28:29]
	v_pk_add_f32 v[28:29], v[38:39], v[42:43]
	v_pk_add_f32 v[26:27], v[26:27], v[32:33]
	v_pk_add_f32 v[28:29], v[28:29], v[30:31]
	v_pk_add_f32 v[26:27], v[26:27], v[48:49]
	v_pk_add_f32 v[28:29], v[28:29], v[46:47]
	v_pk_add_f32 v[26:27], v[26:27], v[52:53]
	v_pk_add_f32 v[28:29], v[28:29], v[50:51]
	v_pk_add_f32 v[26:27], v[26:27], v[56:57]
	v_pk_add_f32 v[28:29], v[28:29], v[54:55]
	s_waitcnt lgkmcnt(1)
	v_pk_add_f32 v[26:27], v[26:27], v[60:61]
	v_pk_add_f32 v[38:39], v[28:29], v[58:59]
	s_waitcnt lgkmcnt(0)
	v_pk_add_f32 v[72:73], v[26:27], v[36:37]
	ds_read_b128 v[26:29], v23 offset:6144
	ds_read_b128 v[30:33], v23 offset:14336
	v_pk_add_f32 v[74:75], v[38:39], v[34:35]
	ds_read_b128 v[34:37], v23 offset:22528
	ds_read_b128 v[38:41], v23 offset:7168
	ds_read_b128 v[42:45], v23 offset:15360
	s_waitcnt lgkmcnt(3)
	v_pk_add_f32 v[46:47], v[28:29], v[32:33]
	v_pk_add_f32 v[48:49], v[26:27], v[30:31]
	ds_read_b128 v[26:29], v23 offset:30720
	ds_read_b128 v[30:33], v23 offset:23552
	s_waitcnt lgkmcnt(4)
	v_pk_add_f32 v[50:51], v[46:47], v[36:37]
	v_pk_add_f32 v[52:53], v[48:49], v[34:35]
	ds_read_b128 v[34:37], v23 offset:38912
	ds_read_b128 v[46:49], v23 offset:31744
	s_waitcnt lgkmcnt(3)
	v_pk_add_f32 v[54:55], v[50:51], v[28:29]
	v_pk_add_f32 v[56:57], v[52:53], v[26:27]
	ds_read_b128 v[26:29], v23 offset:47104
	ds_read_b128 v[50:53], v23 offset:39936
	s_waitcnt lgkmcnt(3)
	v_pk_add_f32 v[58:59], v[54:55], v[36:37]
	v_pk_add_f32 v[60:61], v[56:57], v[34:35]
	ds_read_b128 v[34:37], v23 offset:55296
	ds_read_b128 v[54:57], v23 offset:48128
	s_waitcnt lgkmcnt(3)
	v_pk_add_f32 v[76:77], v[58:59], v[28:29]
	v_pk_add_f32 v[78:79], v[60:61], v[26:27]
	ds_read_b128 v[26:29], v23 offset:63488
	ds_read_b128 v[58:61], v23 offset:56320
	v_pk_add_f32 v[38:39], v[38:39], v[42:43]
	s_waitcnt lgkmcnt(3)
	v_pk_add_f32 v[76:77], v[76:77], v[36:37]
	v_pk_add_f32 v[78:79], v[78:79], v[34:35]
	ds_read_b128 v[34:37], v23 offset:64512
	v_pk_add_f32 v[30:31], v[38:39], v[30:31]
	v_pk_add_f32 v[40:41], v[40:41], v[44:45]
	v_pk_add_f32 v[30:31], v[30:31], v[46:47]
	v_pk_add_f32 v[32:33], v[40:41], v[32:33]
	v_pk_add_f32 v[30:31], v[30:31], v[50:51]
	v_pk_add_f32 v[32:33], v[32:33], v[48:49]
	s_waitcnt lgkmcnt(3)
	v_pk_add_f32 v[30:31], v[30:31], v[54:55]
	v_pk_add_f32 v[32:33], v[32:33], v[52:53]
	s_waitcnt lgkmcnt(1)
	v_pk_add_f32 v[30:31], v[30:31], v[58:59]
	v_pk_add_f32 v[32:33], v[32:33], v[56:57]
	s_waitcnt lgkmcnt(0)
	v_pk_add_f32 v[30:31], v[30:31], v[34:35]
	v_mov_b32_e32 v34, v204
	v_pk_add_f32 v[32:33], v[32:33], v[60:61]
	v_lshrrev_b32_e32 v34, 6, v34
	v_mul_lo_u32 v34, v34, s14
	v_pk_add_f32 v[32:33], v[32:33], v[36:37]
	v_and_b32_e32 v35, 15, v0
	v_add_u32_e32 v34, 0x10000, v34
	v_lshrrev_b32_e32 v36, 2, v0
	v_pk_add_f32 v[28:29], v[76:77], v[28:29]
	v_pk_add_f32 v[26:27], v[78:79], v[26:27]
	v_and_b32_e32 v36, 12, v36
	v_lshl_or_b32 v35, v35, 2, v34
	v_mad_u32_u24 v35, v36, s15, v35
	ds_write2_b32 v35, v14, v18 offset1:16
	ds_write2_b32 v35, v15, v19 offset0:68 offset1:84
	ds_write2_b32 v35, v12, v16 offset0:136 offset1:152
	ds_write2_b32 v35, v13, v17 offset0:204 offset1:220
	ds_write2_b32 v35, v64, v66 offset0:32 offset1:48
	ds_write2_b32 v35, v65, v67 offset0:100 offset1:116
	ds_write2_b32 v35, v20, v62 offset0:168 offset1:184
	ds_write2_b32 v35, v21, v63 offset0:236 offset1:252
	v_add_u32_e32 v12, 0x1000, v35
	v_add_u32_e32 v13, 0x1400, v35
	ds_write2_b32 v12, v70, v74 offset0:64 offset1:80
	ds_write2_b32 v12, v71, v75 offset0:132 offset1:148
	ds_write2_b32 v12, v68, v72 offset0:200 offset1:216
	ds_write2_b32 v13, v69, v73 offset0:12 offset1:28
	ds_write2_b32 v12, v26, v30 offset0:96 offset1:112
	ds_write2_b32 v12, v27, v31 offset0:164 offset1:180
	ds_write2_b32 v12, v28, v32 offset0:232 offset1:248
	ds_write2_b32 v13, v29, v33 offset0:44 offset1:60
	v_bfe_u32 v178, v0, 4, 2
	v_lshlrev_b32_e32 v184, 2, v0
	v_and_b32_e32 v184, 60, v184
	v_or_b32_e32 v176, s18, v184
	v_or_b32_e32 v185, s17, v178
	v_lshlrev_b32_e32 v177, 10, v185
	v_add_u32_e32 v176, v176, v177
	v_ashrrev_i32_e32 v177, 31, v176
	v_lshlrev_b64 v[176:177], 1, v[176:177]
	v_lshl_add_u64 v[178:179], s[10:11], 0, v[176:177]
	global_load_dwordx2 v[144:145], v[178:179], off
	v_bfe_u32 v186, v0, 4, 2
	v_lshlrev_b32_e32 v184, 2, v0
	v_and_b32_e32 v184, 60, v184
	v_or_b32_e32 v176, s18, v184
	v_or_b32_e32 v185, s17, v186
	v_lshlrev_b32_e32 v177, 10, v185
	v_add_u32_e32 v176, v176, v177
	v_ashrrev_i32_e32 v177, 31, v176
	v_lshlrev_b64 v[176:177], 1, v[176:177]
	v_lshl_add_u64 v[178:179], s[12:13], 0, v[176:177]
	global_load_dwordx2 v[146:147], v[178:179], off
	v_bfe_u32 v182, v0, 4, 2
	v_lshlrev_b32_e32 v184, 2, v0
	v_and_b32_e32 v184, 60, v184
	v_or_b32_e32 v186, s18, v184
	v_or_b32_e32 v185, s17, v182
	v_lshlrev_b32_e32 v187, 10, v185
	v_or_b32_e32 v176, 0x1000, v187
	v_add_u32_e32 v176, v176, v186
	v_ashrrev_i32_e32 v177, 31, v176
	v_lshlrev_b64 v[178:179], 1, v[176:177]
	v_lshl_add_u64 v[180:181], s[10:11], 0, v[178:179]
	global_load_dwordx2 v[148:149], v[180:181], off
	v_bfe_u32 v186, v0, 4, 2
	v_lshlrev_b32_e32 v184, 2, v0
	v_and_b32_e32 v184, 60, v184
	v_or_b32_e32 v178, s18, v184
	v_or_b32_e32 v185, s17, v186
	v_lshlrev_b32_e32 v179, 10, v185
	v_or_b32_e32 v176, 0x1000, v179
	v_add_u32_e32 v176, v176, v178
	v_ashrrev_i32_e32 v177, 31, v176
	v_lshlrev_b64 v[180:181], 1, v[176:177]
	v_lshl_add_u64 v[178:179], s[12:13], 0, v[180:181]
	global_load_dwordx2 v[150:151], v[178:179], off
	v_bfe_u32 v181, v0, 4, 2
	v_lshlrev_b32_e32 v184, 2, v0
	v_and_b32_e32 v184, 60, v184
; __device__ __forceinline__ float bfs2f(short h) { return __uint_as_float(((unsigned)(u16)h) << 16); }
;   __device__ __forceinline__ void tile(const float* reg, int row0, int col0, int lane) const {
;     rows4(reg, lane, [&](int it, int rr, int c4, float4 v) {
;       int idx = (row0 + rr) * 1024 + col0 + c4;
;       bf16x4 gt = *(const bf16x4*)(gate + idx), mo = *(const bf16x4*)(merged + idx);
;       *(bf16x4*)(merged + idx) = pack4(fmaf(bfs2f(gt[0]), v.x, bfs2f(mo[0])), fmaf(bfs2f(gt[1]), v.y, bfs2f(mo[1])),
;                                        fmaf(bfs2f(gt[2]), v.z, bfs2f(mo[2])), fmaf(bfs2f(gt[3]), v.w, bfs2f(mo[3])));
;     });
;   }
	v_or_b32_e32 v187, s18, v184
	v_or_b32_e32 v185, s17, v181
	v_lshlrev_b32_e32 v180, 10, v185
	v_or_b32_e32 v186, 0x2000, v180
	v_add_u32_e32 v176, v186, v187
	v_ashrrev_i32_e32 v177, 31, v176
	v_lshlrev_b64 v[176:177], 1, v[176:177]
	v_lshl_add_u64 v[178:179], s[10:11], 0, v[176:177]
	global_load_dwordx2 v[152:153], v[178:179], off
	v_bfe_u32 v179, v0, 4, 2
	v_lshlrev_b32_e32 v184, 2, v0
	v_and_b32_e32 v184, 60, v184
	v_or_b32_e32 v187, s18, v184
	v_or_b32_e32 v185, s17, v179
	v_lshlrev_b32_e32 v178, 10, v185
	v_or_b32_e32 v186, 0x2000, v178
	v_add_u32_e32 v176, v186, v187
	v_ashrrev_i32_e32 v177, 31, v176
	v_lshlrev_b64 v[176:177], 1, v[176:177]
	v_lshl_add_u64 v[176:177], s[12:13], 0, v[176:177]
	global_load_dwordx2 v[154:155], v[176:177], off
	v_bfe_u32 v181, v0, 4, 2
	v_lshlrev_b32_e32 v184, 2, v0
	v_and_b32_e32 v184, 60, v184
	v_or_b32_e32 v187, s18, v184
	v_or_b32_e32 v185, s17, v181
	v_lshlrev_b32_e32 v180, 10, v185
	v_or_b32_e32 v186, 0x3000, v180
	v_add_u32_e32 v176, v186, v187
	v_ashrrev_i32_e32 v177, 31, v176
	v_lshlrev_b64 v[176:177], 1, v[176:177]
	v_lshl_add_u64 v[178:179], s[10:11], 0, v[176:177]
	global_load_dwordx2 v[156:157], v[178:179], off
	v_bfe_u32 v187, v0, 4, 2
	v_lshlrev_b32_e32 v184, 2, v0
	v_and_b32_e32 v184, 60, v184
	v_or_b32_e32 v176, s18, v184
	v_or_b32_e32 v185, s17, v187
	v_lshlrev_b32_e32 v177, 10, v185
	v_or_b32_e32 v186, 0x3000, v177
	v_add_u32_e32 v178, v186, v176
	v_ashrrev_i32_e32 v179, 31, v178
	v_lshlrev_b64 v[178:179], 1, v[178:179]
	v_lshl_add_u64 v[176:177], s[12:13], 0, v[178:179]
	global_load_dwordx2 v[158:159], v[176:177], off
	v_bfe_u32 v186, v0, 4, 2
	v_lshlrev_b32_e32 v184, 2, v0
	v_and_b32_e32 v184, 60, v184
	v_or_b32_e32 v178, s18, v184
	v_or_b32_e32 v185, s17, v186
	v_lshlrev_b32_e32 v179, 10, v185
	v_or_b32_e32 v176, 0x4000, v179
	v_add_u32_e32 v180, v176, v178
	v_ashrrev_i32_e32 v181, 31, v180
	v_lshlrev_b64 v[176:177], 1, v[180:181]
	v_lshl_add_u64 v[178:179], s[10:11], 0, v[176:177]
	global_load_dwordx2 v[160:161], v[178:179], off
	v_bfe_u32 v182, v0, 4, 2
	v_lshlrev_b32_e32 v184, 2, v0
	v_and_b32_e32 v184, 60, v184
	v_or_b32_e32 v186, s18, v184
	v_or_b32_e32 v185, s17, v182
	v_lshlrev_b32_e32 v187, 10, v185
	v_or_b32_e32 v176, 0x4000, v187
	v_add_u32_e32 v178, v176, v186
	v_ashrrev_i32_e32 v179, 31, v178
	v_lshlrev_b64 v[176:177], 1, v[178:179]
	v_lshl_add_u64 v[180:181], s[12:13], 0, v[176:177]
	global_load_dwordx2 v[162:163], v[180:181], off
	v_bfe_u32 v181, v0, 4, 2
	v_lshlrev_b32_e32 v184, 2, v0
	v_and_b32_e32 v184, 60, v184
	v_or_b32_e32 v187, s18, v184
	v_or_b32_e32 v185, s17, v181
	v_lshlrev_b32_e32 v180, 10, v185
	v_or_b32_e32 v186, 0x5000, v180
	v_add_u32_e32 v176, v186, v187
	v_ashrrev_i32_e32 v177, 31, v176
	v_lshlrev_b64 v[176:177], 1, v[176:177]
	v_lshl_add_u64 v[178:179], s[10:11], 0, v[176:177]
	global_load_dwordx2 v[164:165], v[178:179], off
	v_bfe_u32 v187, v0, 4, 2
	v_lshlrev_b32_e32 v184, 2, v0
	v_and_b32_e32 v184, 60, v184
	v_or_b32_e32 v176, s18, v184
	v_or_b32_e32 v185, s17, v187
	v_lshlrev_b32_e32 v177, 10, v185
	v_or_b32_e32 v186, 0x5000, v177
	v_add_u32_e32 v178, v186, v176
	v_ashrrev_i32_e32 v179, 31, v178
	v_lshlrev_b64 v[178:179], 1, v[178:179]
	v_lshl_add_u64 v[176:177], s[12:13], 0, v[178:179]
	global_load_dwordx2 v[166:167], v[176:177], off
	v_bfe_u32 v187, v0, 4, 2
	v_lshlrev_b32_e32 v184, 2, v0
	v_and_b32_e32 v184, 60, v184
	v_or_b32_e32 v185, s18, v184
	v_or_b32_e32 v176, s17, v187
	v_lshlrev_b32_e32 v186, 10, v176
	v_or_b32_e32 v176, 0x6000, v186
	v_add_u32_e32 v176, v176, v185
	v_ashrrev_i32_e32 v177, 31, v176
	v_lshlrev_b64 v[176:177], 1, v[176:177]
	v_lshl_add_u64 v[178:179], s[10:11], 0, v[176:177]
	global_load_dwordx2 v[168:169], v[178:179], off
	v_bfe_u32 v178, v0, 4, 2
	v_lshlrev_b32_e32 v184, 2, v0
	v_and_b32_e32 v184, 60, v184
	v_or_b32_e32 v185, s18, v184
	v_or_b32_e32 v176, s17, v178
	v_lshlrev_b32_e32 v186, 10, v176
	v_or_b32_e32 v176, 0x6000, v186
	v_add_u32_e32 v176, v176, v185
	v_ashrrev_i32_e32 v177, 31, v176
	v_lshlrev_b64 v[176:177], 1, v[176:177]
	v_lshl_add_u64 v[178:179], s[12:13], 0, v[176:177]
	global_load_dwordx2 v[170:171], v[178:179], off
	v_bfe_u32 v187, v0, 4, 2
	v_lshlrev_b32_e32 v184, 2, v0
	v_and_b32_e32 v184, 60, v184
	v_or_b32_e32 v185, 28, v187
	v_or_b32_e32 v186, s18, v184
	v_or_b32_e32 v176, s17, v185
	v_lshl_add_u32 v176, v176, 10, v186
	v_ashrrev_i32_e32 v177, 31, v176
	v_lshlrev_b64 v[178:179], 1, v[176:177]
	v_lshl_add_u64 v[180:181], s[10:11], 0, v[178:179]
	global_load_dwordx2 v[172:173], v[180:181], off
	v_bfe_u32 v186, v0, 4, 2
	v_lshlrev_b32_e32 v184, 2, v0
	v_and_b32_e32 v184, 60, v184
	v_or_b32_e32 v178, 28, v186
	v_or_b32_e32 v185, s18, v184
	v_or_b32_e32 v176, s17, v178
	v_lshl_add_u32 v176, v176, 10, v185
	v_ashrrev_i32_e32 v177, 31, v176
	v_lshlrev_b64 v[180:181], 1, v[176:177]
	v_lshl_add_u64 v[178:179], s[12:13], 0, v[180:181]
	global_load_dwordx2 v[174:175], v[178:179], off
	v_bfe_u32 v26, v0, 4, 2
	v_lshlrev_b32_e32 v0, 2, v0
	v_and_b32_e32 v0, 60, v0
	v_or_b32_e32 v14, 28, v26
	v_or_b32_e32 v18, s18, v0
	v_lshl_or_b32 v0, v0, 2, v34
	v_or_b32_e32 v12, s17, v14
	v_mad_u32_u24 v52, v14, s15, v0
	v_or_b32_e32 v14, s17, v26
	v_lshlrev_b32_e32 v19, 10, v14
	v_or_b32_e32 v16, 0x5000, v19
	v_add_u32_e32 v20, v16, v18
	v_or_b32_e32 v16, 0x4000, v19
	v_add_u32_e32 v30, v16, v18
	v_or_b32_e32 v16, 0x3000, v19
	v_add_u32_e32 v32, v16, v18
	v_or_b32_e32 v16, 0x2000, v19
	v_or_b32_e32 v14, 0x6000, v19
	v_add_u32_e32 v34, v16, v18
	v_or_b32_e32 v16, 0x1000, v19
	v_lshl_add_u32 v12, v12, 10, v18
	v_add_u32_e32 v14, v14, v18
	v_add_u32_e32 v16, v16, v18
	v_add_u32_e32 v18, v18, v19
	v_ashrrev_i32_e32 v13, 31, v12
	v_ashrrev_i32_e32 v15, 31, v14
	v_add_u32_e32 v53, 0xfffffbc0, v52
	v_ashrrev_i32_e32 v21, 31, v20
	v_add_u32_e32 v54, 0xfffff780, v52
	v_ashrrev_i32_e32 v31, 31, v30
	v_add_u32_e32 v55, 0xfffff340, v52
	v_ashrrev_i32_e32 v33, 31, v32
	v_add_u32_e32 v56, 0xffffef00, v52
	v_ashrrev_i32_e32 v35, 31, v34
	v_add_u32_e32 v57, 0xffffeac0, v52
	v_ashrrev_i32_e32 v17, 31, v16
	v_add_u32_e32 v28, 0xffffe680, v52
	v_ashrrev_i32_e32 v19, 31, v18
	v_mad_u32_u24 v0, v26, s15, v0
	v_lshlrev_b64 v[18:19], 1, v[18:19]
	v_lshl_add_u64 v[26:27], s[10:11], 0, v[18:19]
	v_lshl_add_u64 v[38:39], s[12:13], 0, v[18:19]
	v_lshlrev_b64 v[42:43], 1, v[16:17]
	ds_read_b128 v[16:19], v0
	ds_read_b128 v[26:29], v28
	v_lshl_add_u64 v[44:45], s[10:11], 0, v[42:43]
	v_lshlrev_b64 v[34:35], 1, v[34:35]
	v_lshlrev_b64 v[32:33], 1, v[32:33]
	s_waitcnt vmcnt(15)
; __device__ __forceinline__ float bfs2f(short h) { return __uint_as_float(((unsigned)(u16)h) << 16); }
;   __device__ __forceinline__ void tile(const float* reg, int row0, int col0, int lane) const {
;     rows4(reg, lane, [&](int it, int rr, int c4, float4 v) {
;       int idx = (row0 + rr) * 1024 + col0 + c4;
;       bf16x4 gt = *(const bf16x4*)(gate + idx), mo = *(const bf16x4*)(merged + idx);
;       *(bf16x4*)(merged + idx) = pack4(fmaf(bfs2f(gt[0]), v.x, bfs2f(mo[0])), fmaf(bfs2f(gt[1]), v.y, bfs2f(mo[1])),
;                                        fmaf(bfs2f(gt[2]), v.z, bfs2f(mo[2])), fmaf(bfs2f(gt[3]), v.w, bfs2f(mo[3])));
;     });
;   }
	v_mov_b32_e32 v36, v144
	v_mov_b32_e32 v37, v145
	v_and_b32_e32 v47, 0xffff0000, v36
	v_lshlrev_b32_e32 v46, 16, v36
	s_waitcnt vmcnt(14)
	v_mov_b32_e32 v40, v146
	v_mov_b32_e32 v41, v147
	v_and_b32_e32 v49, 0xffff0000, v40
	v_lshlrev_b32_e32 v48, 16, v40
	v_and_b32_e32 v51, 0xffff0000, v37
	v_lshlrev_b32_e32 v50, 16, v37
	v_and_b32_e32 v37, 0xffff0000, v41
	v_lshlrev_b32_e32 v36, 16, v41
	s_waitcnt lgkmcnt(1)
	v_pk_fma_f32 v[16:17], v[46:47], v[16:17], v[48:49]
	v_pk_fma_f32 v[18:19], v[50:51], v[18:19], v[36:37]
	v_cvt_pk_bf16_f32 v16, v16, v17
	v_cvt_pk_bf16_f32 v17, v18, v19
	global_store_dwordx2 v[38:39], v[16:17], off
	v_lshl_add_u64 v[18:19], s[12:13], 0, v[42:43]
	v_lshl_add_u64 v[38:39], s[10:11], 0, v[34:35]
	v_lshl_add_u64 v[34:35], s[12:13], 0, v[34:35]
	s_waitcnt vmcnt(14)
	v_mov_b32_e32 v16, v148
	v_mov_b32_e32 v17, v149
	v_and_b32_e32 v41, 0xffff0000, v16
	v_lshlrev_b32_e32 v40, 16, v16
	s_waitcnt vmcnt(13)
	v_mov_b32_e32 v36, v150
	v_mov_b32_e32 v37, v151
	v_and_b32_e32 v43, 0xffff0000, v36
	v_lshlrev_b32_e32 v42, 16, v36
	v_and_b32_e32 v45, 0xffff0000, v17
	v_lshlrev_b32_e32 v44, 16, v17
	v_and_b32_e32 v17, 0xffff0000, v37
	v_lshlrev_b32_e32 v16, 16, v37
	s_waitcnt lgkmcnt(0)
	v_pk_fma_f32 v[26:27], v[40:41], v[26:27], v[42:43]
	v_pk_fma_f32 v[16:17], v[44:45], v[28:29], v[16:17]
	v_cvt_pk_bf16_f32 v26, v26, v27
	v_cvt_pk_bf16_f32 v27, v16, v17
	global_store_dwordx2 v[18:19], v[26:27], off
	v_lshl_add_u64 v[40:41], s[10:11], 0, v[32:33]
	ds_read_b128 v[16:19], v57
	ds_read_b128 v[26:29], v56
	s_waitcnt vmcnt(13)
	v_mov_b32_e32 v36, v152
	v_mov_b32_e32 v37, v153
	v_and_b32_e32 v43, 0xffff0000, v36
	v_lshlrev_b32_e32 v42, 16, v36
	s_waitcnt vmcnt(12)
	v_mov_b32_e32 v38, v154
	v_mov_b32_e32 v39, v155
	v_and_b32_e32 v45, 0xffff0000, v38
	v_lshlrev_b32_e32 v44, 16, v38
	v_and_b32_e32 v47, 0xffff0000, v37
	v_lshlrev_b32_e32 v46, 16, v37
	v_and_b32_e32 v37, 0xffff0000, v39
	v_lshlrev_b32_e32 v36, 16, v39
	s_waitcnt lgkmcnt(1)
	v_pk_fma_f32 v[16:17], v[42:43], v[16:17], v[44:45]
	v_pk_fma_f32 v[18:19], v[46:47], v[18:19], v[36:37]
	v_cvt_pk_bf16_f32 v16, v16, v17
	v_cvt_pk_bf16_f32 v17, v18, v19
	global_store_dwordx2 v[34:35], v[16:17], off
	v_lshl_add_u64 v[18:19], s[12:13], 0, v[32:33]
	s_waitcnt vmcnt(12)
	v_mov_b32_e32 v16, v156
	v_mov_b32_e32 v17, v157
	v_and_b32_e32 v35, 0xffff0000, v16
	v_lshlrev_b32_e32 v34, 16, v16
	s_waitcnt vmcnt(11)
	v_mov_b32_e32 v32, v158
	v_mov_b32_e32 v33, v159
	v_and_b32_e32 v37, 0xffff0000, v32
	v_lshlrev_b32_e32 v36, 16, v32
	v_and_b32_e32 v39, 0xffff0000, v17
	v_lshlrev_b32_e32 v38, 16, v17
	v_and_b32_e32 v17, 0xffff0000, v33
	v_lshlrev_b32_e32 v16, 16, v33
	s_waitcnt lgkmcnt(0)
	v_pk_fma_f32 v[26:27], v[34:35], v[26:27], v[36:37]
	v_pk_fma_f32 v[16:17], v[38:39], v[28:29], v[16:17]
	v_cvt_pk_bf16_f32 v26, v26, v27
	v_cvt_pk_bf16_f32 v27, v16, v17
	global_store_dwordx2 v[18:19], v[26:27], off
	v_lshlrev_b64 v[16:17], 1, v[30:31]
	v_lshl_add_u64 v[18:19], s[10:11], 0, v[16:17]
	v_lshl_add_u64 v[32:33], s[12:13], 0, v[16:17]
	ds_read_b128 v[16:19], v55
	ds_read_b128 v[26:29], v54
	v_lshlrev_b64 v[20:21], 1, v[20:21]
	v_lshl_add_u64 v[36:37], s[10:11], 0, v[20:21]
	v_lshlrev_b64 v[14:15], 1, v[14:15]
	s_waitcnt vmcnt(11)
	v_mov_b32_e32 v30, v160
	v_mov_b32_e32 v31, v161
	v_and_b32_e32 v39, 0xffff0000, v30
	v_lshlrev_b32_e32 v38, 16, v30
	s_waitcnt vmcnt(10)
	v_mov_b32_e32 v34, v162
	v_mov_b32_e32 v35, v163
	v_and_b32_e32 v41, 0xffff0000, v34
	v_lshlrev_b32_e32 v40, 16, v34
	v_and_b32_e32 v43, 0xffff0000, v31
	v_lshlrev_b32_e32 v42, 16, v31
	v_and_b32_e32 v31, 0xffff0000, v35
	v_lshlrev_b32_e32 v30, 16, v35
	s_waitcnt lgkmcnt(1)
	v_pk_fma_f32 v[16:17], v[38:39], v[16:17], v[40:41]
	v_pk_fma_f32 v[18:19], v[42:43], v[18:19], v[30:31]
	v_cvt_pk_bf16_f32 v16, v16, v17
	v_cvt_pk_bf16_f32 v17, v18, v19
	global_store_dwordx2 v[32:33], v[16:17], off
	v_lshl_add_u64 v[18:19], s[12:13], 0, v[20:21]
	v_lshl_add_u64 v[30:31], s[10:11], 0, v[14:15]
	s_waitcnt vmcnt(10)
	v_mov_b32_e32 v16, v164
	v_mov_b32_e32 v17, v165
	v_and_b32_e32 v33, 0xffff0000, v16
	v_lshlrev_b32_e32 v32, 16, v16
	s_waitcnt vmcnt(9)
	v_mov_b32_e32 v20, v166
	v_mov_b32_e32 v21, v167
	v_and_b32_e32 v35, 0xffff0000, v20
	v_lshlrev_b32_e32 v34, 16, v20
	v_and_b32_e32 v37, 0xffff0000, v17
	v_lshlrev_b32_e32 v36, 16, v17
	v_and_b32_e32 v17, 0xffff0000, v21
	v_lshlrev_b32_e32 v16, 16, v21
	s_waitcnt lgkmcnt(0)
	v_pk_fma_f32 v[20:21], v[32:33], v[26:27], v[34:35]
	v_pk_fma_f32 v[16:17], v[36:37], v[28:29], v[16:17]
	v_cvt_pk_bf16_f32 v20, v20, v21
	v_cvt_pk_bf16_f32 v21, v16, v17
	global_store_dwordx2 v[18:19], v[20:21], off
	v_lshl_add_u64 v[26:27], s[12:13], 0, v[14:15]
	v_lshlrev_b64 v[30:31], 1, v[12:13]
	ds_read_b128 v[12:15], v53
	ds_read_b128 v[16:19], v52
	v_lshl_add_u64 v[32:33], s[10:11], 0, v[30:31]
	s_waitcnt vmcnt(9)
	v_mov_b32_e32 v20, v168
	v_mov_b32_e32 v21, v169
	v_and_b32_e32 v35, 0xffff0000, v20
	v_lshlrev_b32_e32 v34, 16, v20
	s_waitcnt vmcnt(8)
	v_mov_b32_e32 v28, v170
	v_mov_b32_e32 v29, v171
	v_and_b32_e32 v37, 0xffff0000, v28
	v_lshlrev_b32_e32 v36, 16, v28
	v_and_b32_e32 v39, 0xffff0000, v21
	v_lshlrev_b32_e32 v38, 16, v21
	v_and_b32_e32 v21, 0xffff0000, v29
	v_lshlrev_b32_e32 v20, 16, v29
	s_waitcnt lgkmcnt(1)
	v_pk_fma_f32 v[12:13], v[34:35], v[12:13], v[36:37]
	v_pk_fma_f32 v[14:15], v[38:39], v[14:15], v[20:21]
	v_cvt_pk_bf16_f32 v12, v12, v13
	v_cvt_pk_bf16_f32 v13, v14, v15
	global_store_dwordx2 v[26:27], v[12:13], off
	v_lshl_add_u64 v[14:15], s[12:13], 0, v[30:31]
	s_waitcnt vmcnt(8)
	v_mov_b32_e32 v12, v172
	v_mov_b32_e32 v13, v173
	v_and_b32_e32 v27, 0xffff0000, v12
	v_lshlrev_b32_e32 v26, 16, v12
	s_waitcnt vmcnt(7)
	v_mov_b32_e32 v20, v174
	v_mov_b32_e32 v21, v175
	v_and_b32_e32 v29, 0xffff0000, v20
	v_lshlrev_b32_e32 v28, 16, v20
	v_and_b32_e32 v31, 0xffff0000, v13
	v_lshlrev_b32_e32 v30, 16, v13
	v_and_b32_e32 v13, 0xffff0000, v21
	v_lshlrev_b32_e32 v12, 16, v21
	s_waitcnt lgkmcnt(0)
	v_pk_fma_f32 v[16:17], v[26:27], v[16:17], v[28:29]
	v_pk_fma_f32 v[12:13], v[30:31], v[18:19], v[12:13]
	v_cvt_pk_bf16_f32 v16, v16, v17
	v_cvt_pk_bf16_f32 v17, v12, v13
	global_store_dwordx2 v[14:15], v[16:17], off
	s_branch .LBB0_1391

; __device__ __forceinline__ float bfs2f(short h) { return __uint_as_float(((unsigned)(u16)h) << 16); }
; __device__ __forceinline__ float sigm(float x) { return __builtin_amdgcn_rcpf(1.f + __expf(-x)); }
; __device__ __forceinline__ float rs_of(float ss) { return rsqrtf(ss * (1.f / 1024) + EPS); }
;   __device__ __forceinline__ void tile(const float* reg, int row0, int col0, int lane) const {
;     float rsv[8];
; #pragma unroll
;     for (int i = 0; i < 8; ++i) rsv[i] = rs_of(ssq[row0 + i * 4 + (lane >> 4)]);
;     rows4(reg, lane, [&](int it, int rr, int c4, float4 v) {
;       int row = row0 + rr, idx = row * 1024 + col0 + c4;
;       float rs = rsv[it];
;       float4 xo = *(const float4*)(xold + idx);
;       bf16x4 t = *(const bf16x4*)(tmp + idx);
;       v.x = fmaf(sigm(v.x * rs), bfs2f(t[0]), xo.x); v.y = fmaf(sigm(v.y * rs), bfs2f(t[1]), xo.y);
;       v.z = fmaf(sigm(v.z * rs), bfs2f(t[2]), xo.z); v.w = fmaf(sigm(v.w * rs), bfs2f(t[3]), xo.w);
;       *(float4*)(xnew + idx) = v;
;       *(bf16x4*)(xb + idx) = pack4(v.x, v.y, v.z, v.w);
; template <int MF, class Epi>
; __device__ __forceinline__ void staged_epilogue(f32x4 (&acc)[MF][4], int row0, int col0, const Epi& epi) {
;     ...
;     for (int mm = 0; mm < 2; ++mm)
; #pragma unroll
;       for (int n = 0; n < 4; ++n)
; #pragma unroll
;         for (int j = 0; j < 4; ++j) reg[(mm * 16 + fq * 4 + j) * 68 + n * 16 + fr] = acc[mp * 2 + mm][n][j];
.LBB0_1641:
	v_mov_b32_e32 v131, v204
	v_mov_b32_e32 v130, v204
	s_nop 0
	v_lshrrev_b32_e32 v130, 6, v130
	v_mul_lo_u32 v130, v130, s46
	v_add_u32_e32 v136, 0x10000, v130
	v_lshrrev_b32_e32 v130, 2, v131
	v_and_b32_e32 v137, 15, v131
	v_and_b32_e32 v138, 12, v130
	v_bfe_u32 v130, v131, 4, 2
	v_lshlrev_b32_e32 v131, 2, v131
	v_and_b32_e32 v131, 60, v131
	v_lshl_or_b32 v139, v137, 2, v136
	v_lshl_or_b32 v136, v131, 2, v136
	v_add_u32_e32 v128, v131, v128
	v_cmp_eq_u32_e32 vcc, 0, v137
	v_mad_u32_u24 v140, v130, s47, v136
	v_mad_u32_u24 v131, v138, s47, v139
	ds_write2_b32 v131, v120, v124 offset1:16
	ds_write2_b32 v131, v121, v125 offset0:68 offset1:84
	ds_write2_b32 v131, v122, v126 offset0:136 offset1:152
	ds_write2_b32 v131, v123, v127 offset0:204 offset1:220
	ds_write2_b32 v131, v112, v116 offset0:32 offset1:48
	ds_write2_b32 v131, v113, v117 offset0:100 offset1:116
	ds_write2_b32 v131, v114, v118 offset0:168 offset1:184
	ds_write2_b32 v131, v115, v119 offset0:236 offset1:252
	v_add_u32_e32 v112, 0x1000, v131
	ds_write2_b32 v112, v104, v108 offset0:64 offset1:80
	ds_write2_b32 v112, v105, v109 offset0:132 offset1:148
	ds_write2_b32 v112, v106, v110 offset0:200 offset1:216
	v_add_u32_e32 v104, 0x1400, v131
	ds_write2_b32 v104, v107, v111 offset0:12 offset1:28
	ds_write2_b32 v112, v96, v100 offset0:96 offset1:112
	ds_write2_b32 v112, v97, v101 offset0:164 offset1:180
	ds_write2_b32 v112, v98, v102 offset0:232 offset1:248
	ds_write2_b32 v104, v99, v103 offset0:44 offset1:60
	v_add_u32_e32 v200, v130, v129
	v_ashrrev_i32_e32 v201, 31, v200
	v_lshl_add_u64 v[202:203], v[200:201], 2, s[28:29]
	global_load_dword v144, v[202:203], off
	v_add_u32_e32 v210, v130, v129
	v_add_u32_e32 v200, 4, v210
	v_ashrrev_i32_e32 v201, 31, v200
	v_lshl_add_u64 v[200:201], v[200:201], 2, s[28:29]
	global_load_dword v145, v[200:201], off
	v_add_u32_e32 v210, v130, v129
	v_add_u32_e32 v200, 8, v210
	v_ashrrev_i32_e32 v201, 31, v200
	v_lshl_add_u64 v[202:203], v[200:201], 2, s[28:29]
	global_load_dword v146, v[202:203], off
	v_add_u32_e32 v210, v130, v129
	v_add_u32_e32 v200, 12, v210
	v_ashrrev_i32_e32 v201, 31, v200
	v_lshl_add_u64 v[202:203], v[200:201], 2, s[28:29]
	global_load_dword v147, v[202:203], off
	v_add_u32_e32 v210, v130, v129
	v_add_u32_e32 v200, 16, v210
	v_ashrrev_i32_e32 v201, 31, v200
	v_lshl_add_u64 v[202:203], v[200:201], 2, s[28:29]
	global_load_dword v148, v[202:203], off
	v_add_u32_e32 v210, v130, v129
	v_add_u32_e32 v200, 20, v210
	v_ashrrev_i32_e32 v201, 31, v200
	v_lshl_add_u64 v[202:203], v[200:201], 2, s[28:29]
	global_load_dword v149, v[202:203], off
	v_add_u32_e32 v210, v130, v129
	v_add_u32_e32 v200, 24, v210
	v_ashrrev_i32_e32 v201, 31, v200
	v_lshl_add_u64 v[202:203], v[200:201], 2, s[28:29]
	global_load_dword v150, v[202:203], off
	v_add_u32_e32 v210, v130, v129
	v_add_u32_e32 v200, 28, v210
	v_ashrrev_i32_e32 v201, 31, v200
	v_lshl_add_u64 v[202:203], v[200:201], 2, s[28:29]
	global_load_dword v151, v[202:203], off
	v_add_u32_e32 v210, v130, v129
	v_lshl_add_u32 v200, v210, 10, v128
	v_ashrrev_i32_e32 v201, 31, v200
	v_lshlrev_b64 v[202:203], 1, v[200:201]
	v_lshl_add_u64 v[206:207], s[18:19], 0, v[202:203]
	global_load_dwordx2 v[152:153], v[206:207], off
	v_add_u32_e32 v210, v130, v129
	v_lshl_add_u32 v200, v210, 10, v128
	v_ashrrev_i32_e32 v201, 31, v200
	v_lshl_add_u64 v[200:201], v[200:201], 2, s[12:13]
	global_load_dwordx4 v[154:157], v[200:201], off
	v_or_b32_e32 v211, 4, v130
	v_add_u32_e32 v210, v211, v129
	v_lshl_add_u32 v200, v210, 10, v128
	v_ashrrev_i32_e32 v201, 31, v200
	v_lshlrev_b64 v[206:207], 1, v[200:201]
	v_lshl_add_u64 v[202:203], s[18:19], 0, v[206:207]
	global_load_dwordx2 v[158:159], v[202:203], off
	v_or_b32_e32 v211, 4, v130
	v_add_u32_e32 v210, v211, v129
	v_lshl_add_u32 v200, v210, 10, v128
	v_ashrrev_i32_e32 v201, 31, v200
	v_lshl_add_u64 v[202:203], v[200:201], 2, s[12:13]
	global_load_dwordx4 v[160:163], v[202:203], off
	v_or_b32_e32 v211, 8, v130
	v_add_u32_e32 v210, v211, v129
	v_lshl_add_u32 v200, v210, 10, v128
	v_ashrrev_i32_e32 v201, 31, v200
	v_lshlrev_b64 v[206:207], 1, v[200:201]
	v_lshl_add_u64 v[202:203], s[18:19], 0, v[206:207]
	global_load_dwordx2 v[164:165], v[202:203], off
	v_or_b32_e32 v211, 8, v130
	v_add_u32_e32 v210, v211, v129
	v_lshl_add_u32 v200, v210, 10, v128
	v_ashrrev_i32_e32 v201, 31, v200
	v_lshl_add_u64 v[202:203], v[200:201], 2, s[12:13]
	global_load_dwordx4 v[166:169], v[202:203], off
	v_or_b32_e32 v211, 12, v130
	v_add_u32_e32 v210, v211, v129
	v_lshl_add_u32 v200, v210, 10, v128
	v_ashrrev_i32_e32 v201, 31, v200
	v_lshlrev_b64 v[206:207], 1, v[200:201]
	v_lshl_add_u64 v[202:203], s[18:19], 0, v[206:207]
	global_load_dwordx2 v[170:171], v[202:203], off
	v_or_b32_e32 v211, 12, v130
	v_add_u32_e32 v210, v211, v129
	v_lshl_add_u32 v200, v210, 10, v128
	v_ashrrev_i32_e32 v201, 31, v200
	v_lshl_add_u64 v[202:203], v[200:201], 2, s[12:13]
	global_load_dwordx4 v[172:175], v[202:203], off
	v_or_b32_e32 v211, 16, v130
	v_add_u32_e32 v210, v211, v129
	v_lshl_add_u32 v200, v210, 10, v128
	v_ashrrev_i32_e32 v201, 31, v200
	v_lshlrev_b64 v[206:207], 1, v[200:201]
	v_lshl_add_u64 v[202:203], s[18:19], 0, v[206:207]
	global_load_dwordx2 v[176:177], v[202:203], off
	v_or_b32_e32 v211, 16, v130
	v_add_u32_e32 v210, v211, v129
	v_lshl_add_u32 v200, v210, 10, v128
	v_ashrrev_i32_e32 v201, 31, v200
	v_lshl_add_u64 v[202:203], v[200:201], 2, s[12:13]
	global_load_dwordx4 v[178:181], v[202:203], off
	v_or_b32_e32 v211, 20, v130
	v_add_u32_e32 v210, v211, v129
	v_lshl_add_u32 v200, v210, 10, v128
	v_ashrrev_i32_e32 v201, 31, v200
	v_lshlrev_b64 v[206:207], 1, v[200:201]
; __device__ __forceinline__ float bfs2f(short h) { return __uint_as_float(((unsigned)(u16)h) << 16); }
; __device__ __forceinline__ float sigm(float x) { return __builtin_amdgcn_rcpf(1.f + __expf(-x)); }
; __device__ __forceinline__ float rs_of(float ss) { return rsqrtf(ss * (1.f / 1024) + EPS); }
;   __device__ __forceinline__ void tile(const float* reg, int row0, int col0, int lane) const {
;     float rsv[8];
; #pragma unroll
;     for (int i = 0; i < 8; ++i) rsv[i] = rs_of(ssq[row0 + i * 4 + (lane >> 4)]);
;     rows4(reg, lane, [&](int it, int rr, int c4, float4 v) {
;       int row = row0 + rr, idx = row * 1024 + col0 + c4;
;       float rs = rsv[it];
;       float4 xo = *(const float4*)(xold + idx);
;       bf16x4 t = *(const bf16x4*)(tmp + idx);
;       v.x = fmaf(sigm(v.x * rs), bfs2f(t[0]), xo.x); v.y = fmaf(sigm(v.y * rs), bfs2f(t[1]), xo.y);
;       v.z = fmaf(sigm(v.z * rs), bfs2f(t[2]), xo.z); v.w = fmaf(sigm(v.w * rs), bfs2f(t[3]), xo.w);
;       *(float4*)(xnew + idx) = v;
;       *(bf16x4*)(xb + idx) = pack4(v.x, v.y, v.z, v.w);
;       float s = row16_sum(v.x * v.x + v.y * v.y + v.z * v.z + v.w * v.w);
;       if ((lane & 15) == 0) atomicAdd(ssqn + row, s);
;     });
	v_lshl_add_u64 v[202:203], s[18:19], 0, v[206:207]
	global_load_dwordx2 v[182:183], v[202:203], off
	v_or_b32_e32 v211, 20, v130
	v_add_u32_e32 v210, v211, v129
	v_lshl_add_u32 v200, v210, 10, v128
	v_ashrrev_i32_e32 v201, 31, v200
	v_lshl_add_u64 v[202:203], v[200:201], 2, s[12:13]
	global_load_dwordx4 v[184:187], v[202:203], off
	v_or_b32_e32 v211, 24, v130
	v_add_u32_e32 v210, v211, v129
	v_lshl_add_u32 v200, v210, 10, v128
	v_ashrrev_i32_e32 v201, 31, v200
	v_lshlrev_b64 v[206:207], 1, v[200:201]
	v_lshl_add_u64 v[202:203], s[18:19], 0, v[206:207]
	global_load_dwordx2 v[188:189], v[202:203], off
	v_or_b32_e32 v211, 24, v130
	v_add_u32_e32 v210, v211, v129
	v_lshl_add_u32 v200, v210, 10, v128
	v_ashrrev_i32_e32 v201, 31, v200
	v_lshl_add_u64 v[202:203], v[200:201], 2, s[12:13]
	global_load_dwordx4 v[190:193], v[202:203], off
	v_or_b32_e32 v211, 28, v130
	v_add_u32_e32 v210, v211, v129
	v_lshl_add_u32 v200, v210, 10, v128
	v_ashrrev_i32_e32 v201, 31, v200
	v_lshlrev_b64 v[206:207], 1, v[200:201]
	v_lshl_add_u64 v[202:203], s[18:19], 0, v[206:207]
	global_load_dwordx2 v[194:195], v[202:203], off
	v_or_b32_e32 v211, 28, v130
	v_add_u32_e32 v210, v211, v129
	v_lshl_add_u32 v200, v210, 10, v128
	v_ashrrev_i32_e32 v201, 31, v200
	v_lshl_add_u64 v[202:203], v[200:201], 2, s[12:13]
	global_load_dwordx4 v[196:199], v[202:203], off
	v_add_u32_e32 v96, v130, v129
	v_add_u32_e32 v100, 8, v96
	v_ashrrev_i32_e32 v101, 31, v100
	v_lshl_add_u64 v[102:103], v[100:101], 2, s[28:29]
	v_add_u32_e32 v100, 12, v96
	v_ashrrev_i32_e32 v101, 31, v100
	v_lshl_add_u64 v[106:107], v[100:101], 2, s[28:29]
	v_add_u32_e32 v100, 16, v96
	v_ashrrev_i32_e32 v101, 31, v100
	v_ashrrev_i32_e32 v97, 31, v96
	v_lshl_add_u64 v[108:109], v[100:101], 2, s[28:29]
	v_add_u32_e32 v100, 20, v96
	v_lshl_add_u64 v[98:99], v[96:97], 2, s[28:29]
	v_ashrrev_i32_e32 v101, 31, v100
	v_lshl_add_u64 v[110:111], v[100:101], 2, s[28:29]
	v_add_u32_e32 v100, 24, v96
	v_add_u32_e32 v98, 4, v96
	v_ashrrev_i32_e32 v101, 31, v100
	v_ashrrev_i32_e32 v99, 31, v98
	v_lshl_add_u64 v[114:115], v[100:101], 2, s[28:29]
	v_add_u32_e32 v100, 28, v96
	v_lshl_add_u64 v[98:99], v[98:99], 2, s[28:29]
	v_ashrrev_i32_e32 v101, 31, v100
	v_lshl_add_u64 v[116:117], v[100:101], 2, s[28:29]
	s_nop 0
	s_nop 0
	s_nop 0
	s_waitcnt vmcnt(16)
	v_mov_b32_e32 v113, v144
	v_mov_b32_e32 v100, v145
	v_mov_b32_e32 v101, v146
	v_mov_b32_e32 v98, v147
	v_mov_b32_e32 v105, v148
	v_mov_b32_e32 v106, v149
	v_mov_b32_e32 v107, v150
	v_mov_b32_e32 v110, v151
	v_fmamk_f32 v99, v113, 0x3a800000, v135
	v_mul_f32_e32 v102, 0x4b800000, v99
	v_cmp_gt_f32_e64 s[10:11], s52, v99
	s_nop 1
	v_cndmask_b32_e64 v99, v99, v102, s[10:11]
	v_rsq_f32_e32 v99, v99
	s_nop 0
	v_mul_f32_e32 v102, 0x45800000, v99
	v_cndmask_b32_e64 v99, v99, v102, s[10:11]
	v_lshl_add_u32 v102, v96, 10, v128
	v_ashrrev_i32_e32 v103, 31, v102
	v_lshlrev_b64 v[108:109], 1, v[102:103]
	v_lshl_add_u64 v[114:115], s[18:19], 0, v[108:109]
	v_lshl_add_u64 v[102:103], v[102:103], 2, s[12:13]
	ds_read_b128 v[118:121], v140
	v_lshl_add_u64 v[108:109], s[26:27], 0, v[108:109]
	s_waitcnt lgkmcnt(0)
	v_mul_f32_e32 v111, v99, v118
	v_mul_f32_e32 v113, v99, v119
	v_mul_f32_e32 v118, v99, v120
	v_mul_f32_e32 v99, v99, v121
	v_mul_f32_e32 v111, 0xbfb8aa3b, v111
	v_mul_f32_e32 v113, 0xbfb8aa3b, v113
	v_mul_f32_e32 v118, 0xbfb8aa3b, v118
	v_mul_f32_e32 v99, 0xbfb8aa3b, v99
	v_exp_f32_e32 v111, v111
	v_exp_f32_e32 v113, v113
	v_exp_f32_e32 v118, v118
	v_exp_f32_e32 v99, v99
	v_add_f32_e32 v111, 1.0, v111
	v_add_f32_e32 v113, 1.0, v113
	v_add_f32_e32 v120, 1.0, v118
	v_add_f32_e32 v99, 1.0, v99
	v_rcp_f32_e32 v118, v111
	v_rcp_f32_e32 v119, v113
	v_rcp_f32_e32 v120, v120
	v_rcp_f32_e32 v121, v99
	s_waitcnt vmcnt(15)
	v_mov_b32_e32 v122, v152
	v_mov_b32_e32 v123, v153
	v_and_b32_e32 v125, 0xffff0000, v122
	v_lshlrev_b32_e32 v124, 16, v122
	v_and_b32_e32 v127, 0xffff0000, v123
	v_lshlrev_b32_e32 v126, 16, v123
	s_waitcnt vmcnt(14)
	v_mov_b32_e32 v114, v154
	v_mov_b32_e32 v115, v155
	v_mov_b32_e32 v116, v156
	v_mov_b32_e32 v117, v157
	v_pk_fma_f32 v[114:115], v[118:119], v[124:125], v[114:115]
	v_pk_fma_f32 v[116:117], v[120:121], v[126:127], v[116:117]
	global_store_dwordx4 v[102:103], v[114:117], off
	v_cvt_pk_bf16_f32 v102, v114, v115
	v_cvt_pk_bf16_f32 v103, v116, v117
	v_pk_mul_f32 v[114:115], v[114:115], v[114:115]
	v_pk_mul_f32 v[116:117], v[116:117], v[116:117]
	v_add_f32_e32 v99, v114, v115
	v_add_f32_e32 v99, v116, v99
	v_add_f32_e32 v99, v117, v99
	global_store_dwordx2 v[108:109], v[102:103], off
	v_mov_b32_e32 v102, 0
	v_add_f32_dpp v99, v99, v99 quad_perm:[1,0,3,2] row_mask:0xf bank_mask:0xf bound_ctrl:1
	s_nop 1
	v_add_f32_dpp v99, v99, v99 quad_perm:[2,3,0,1] row_mask:0xf bank_mask:0xf bound_ctrl:1
	s_nop 1
	v_add_f32_dpp v99, v99, v99 row_half_mirror row_mask:0xf bank_mask:0xf bound_ctrl:1
	s_nop 1
	v_mov_b32_dpp v102, v99 row_mirror row_mask:0xf bank_mask:0xf
	s_and_saveexec_b64 s[0:1], vcc
	s_cbranch_execz .LBB0_1643
	v_add_f32_e32 v99, v99, v102
	v_lshl_add_u64 v[96:97], v[96:97], 2, s[30:31]
	global_atomic_add_f32 v[96:97], v99, off
; __device__ __forceinline__ float bfs2f(short h) { return __uint_as_float(((unsigned)(u16)h) << 16); }
; __device__ __forceinline__ float sigm(float x) { return __builtin_amdgcn_rcpf(1.f + __expf(-x)); }
;   __device__ __forceinline__ void tile(const float* reg, int row0, int col0, int lane) const {
;     ...
;     rows4(reg, lane, [&](int it, int rr, int c4, float4 v) {
;       int row = row0 + rr, idx = row * 1024 + col0 + c4;
;       float rs = rsv[it];
;       float4 xo = *(const float4*)(xold + idx);
;       bf16x4 t = *(const bf16x4*)(tmp + idx);
;       v.x = fmaf(sigm(v.x * rs), bfs2f(t[0]), xo.x); v.y = fmaf(sigm(v.y * rs), bfs2f(t[1]), xo.y);
;       v.z = fmaf(sigm(v.z * rs), bfs2f(t[2]), xo.z); v.w = fmaf(sigm(v.w * rs), bfs2f(t[3]), xo.w);
;       *(float4*)(xnew + idx) = v;
;       *(bf16x4*)(xb + idx) = pack4(v.x, v.y, v.z, v.w);
;       float s = row16_sum(v.x * v.x + v.y * v.y + v.z * v.z + v.w * v.w);
;       if ((lane & 15) == 0) atomicAdd(ssqn + row, s);
;     });
.LBB0_1643:
	s_or_b64 exec, exec, s[0:1]
	v_or_b32_e32 v99, 4, v130
	v_add_u32_e32 v96, v99, v129
	v_lshl_add_u32 v102, v96, 10, v128
	v_ashrrev_i32_e32 v103, 31, v102
	v_lshlrev_b64 v[122:123], 1, v[102:103]
	v_lshl_add_u64 v[108:109], s[18:19], 0, v[122:123]
	v_lshl_add_u64 v[126:127], v[102:103], 2, s[12:13]
	v_fmamk_f32 v97, v100, 0x3a800000, v135
	v_mul_u32_u24_e32 v109, 0x110, v130
	v_mul_f32_e32 v100, 0x4b800000, v97
	v_cmp_gt_f32_e64 s[10:11], s52, v97
	v_add_u32_e32 v103, 0x440, v109
	v_add_u32_e32 v102, v136, v103
	v_cndmask_b32_e64 v97, v97, v100, s[10:11]
	v_rsq_f32_e32 v97, v97
	ds_read_b128 v[118:121], v102
	v_lshl_add_u64 v[122:123], s[26:27], 0, v[122:123]
	v_mul_f32_e32 v100, 0x45800000, v97
	v_cndmask_b32_e64 v97, v97, v100, s[10:11]
	s_waitcnt lgkmcnt(0)
	v_mul_f32_e32 v100, v97, v118
	v_mul_f32_e32 v108, v97, v119
	v_mul_f32_e32 v111, v97, v120
	v_mul_f32_e32 v97, v97, v121
	v_mul_f32_e32 v100, 0xbfb8aa3b, v100
	v_mul_f32_e32 v108, 0xbfb8aa3b, v108
	v_mul_f32_e32 v111, 0xbfb8aa3b, v111
	v_mul_f32_e32 v97, 0xbfb8aa3b, v97
	v_exp_f32_e32 v100, v100
	v_exp_f32_e32 v108, v108
	v_exp_f32_e32 v111, v111
	v_exp_f32_e32 v97, v97
	v_add_f32_e32 v100, 1.0, v100
	v_add_f32_e32 v108, 1.0, v108
	v_add_f32_e32 v111, 1.0, v111
	v_add_f32_e32 v97, 1.0, v97
	v_rcp_f32_e32 v118, v100
	v_rcp_f32_e32 v119, v108
	v_rcp_f32_e32 v120, v111
	v_rcp_f32_e32 v121, v97
	v_mov_b32_e32 v100, 0
	s_waitcnt vmcnt(16)
	v_mov_b32_e32 v124, v158
	v_mov_b32_e32 v125, v159
	v_and_b32_e32 v139, 0xffff0000, v124
	v_lshlrev_b32_e32 v138, 16, v124
	v_and_b32_e32 v141, 0xffff0000, v125
	v_lshlrev_b32_e32 v140, 16, v125
	s_waitcnt vmcnt(15)
	v_mov_b32_e32 v114, v160
	v_mov_b32_e32 v115, v161
	v_mov_b32_e32 v116, v162
	v_mov_b32_e32 v117, v163
	v_pk_fma_f32 v[114:115], v[118:119], v[138:139], v[114:115]
	v_pk_fma_f32 v[116:117], v[120:121], v[140:141], v[116:117]
	global_store_dwordx4 v[126:127], v[114:117], off
	v_cvt_pk_bf16_f32 v118, v114, v115
	v_cvt_pk_bf16_f32 v119, v116, v117
	v_pk_mul_f32 v[114:115], v[114:115], v[114:115]
	v_pk_mul_f32 v[116:117], v[116:117], v[116:117]
	v_add_f32_e32 v97, v114, v115
	v_add_f32_e32 v97, v116, v97
	v_add_f32_e32 v97, v117, v97
	global_store_dwordx2 v[122:123], v[118:119], off
	s_nop 0
	v_add_f32_dpp v97, v97, v97 quad_perm:[1,0,3,2] row_mask:0xf bank_mask:0xf bound_ctrl:1
	s_nop 1
	v_add_f32_dpp v97, v97, v97 quad_perm:[2,3,0,1] row_mask:0xf bank_mask:0xf bound_ctrl:1
	s_nop 1
	v_add_f32_dpp v97, v97, v97 row_half_mirror row_mask:0xf bank_mask:0xf bound_ctrl:1
	s_nop 1
	v_mov_b32_dpp v100, v97 row_mirror row_mask:0xf bank_mask:0xf
	s_and_saveexec_b64 s[0:1], vcc
	s_cbranch_execz .LBB0_1645
	v_add_f32_e32 v100, v97, v100
	v_ashrrev_i32_e32 v97, 31, v96
	v_lshl_add_u64 v[96:97], v[96:97], 2, s[30:31]
	global_atomic_add_f32 v[96:97], v100, off
.LBB0_1645:
	s_or_b64 exec, exec, s[0:1]
	v_or_b32_e32 v100, 8, v130
	v_add_u32_e32 v96, v100, v129
	v_lshl_add_u32 v114, v96, 10, v128
	v_ashrrev_i32_e32 v115, 31, v114
	v_lshlrev_b64 v[122:123], 1, v[114:115]
	v_lshl_add_u64 v[116:117], s[18:19], 0, v[122:123]
	v_lshl_add_u64 v[126:127], v[114:115], 2, s[12:13]
	v_fmamk_f32 v97, v101, 0x3a800000, v135
	v_mul_f32_e32 v101, 0x4b800000, v97
	v_cmp_gt_f32_e64 s[10:11], s52, v97
	v_add_u32_e32 v108, 0x440, v103
	v_add_u32_e32 v103, v136, v108
	v_cndmask_b32_e64 v97, v97, v101, s[10:11]
	v_rsq_f32_e32 v97, v97
	ds_read_b128 v[118:121], v103
	v_lshl_add_u64 v[122:123], s[26:27], 0, v[122:123]
	v_mul_f32_e32 v101, 0x45800000, v97
	v_cndmask_b32_e64 v97, v97, v101, s[10:11]
	s_waitcnt lgkmcnt(0)
	v_mul_f32_e32 v101, v97, v118
	v_mul_f32_e32 v111, v97, v119
	v_mul_f32_e32 v113, v97, v120
	v_mul_f32_e32 v97, v97, v121
	v_mul_f32_e32 v101, 0xbfb8aa3b, v101
	v_mul_f32_e32 v111, 0xbfb8aa3b, v111
	v_mul_f32_e32 v113, 0xbfb8aa3b, v113
	v_mul_f32_e32 v97, 0xbfb8aa3b, v97
	v_exp_f32_e32 v101, v101
	v_exp_f32_e32 v111, v111
	v_exp_f32_e32 v113, v113
	v_exp_f32_e32 v97, v97
	v_add_f32_e32 v101, 1.0, v101
	v_add_f32_e32 v111, 1.0, v111
	v_add_f32_e32 v113, 1.0, v113
	v_add_f32_e32 v97, 1.0, v97
	v_rcp_f32_e32 v118, v101
	v_rcp_f32_e32 v119, v111
	v_rcp_f32_e32 v120, v113
	v_rcp_f32_e32 v121, v97
	v_mov_b32_e32 v101, 0
	s_waitcnt vmcnt(17)
	v_mov_b32_e32 v124, v164
	v_mov_b32_e32 v125, v165
	v_and_b32_e32 v139, 0xffff0000, v124
	v_lshlrev_b32_e32 v138, 16, v124
	v_and_b32_e32 v141, 0xffff0000, v125
	v_lshlrev_b32_e32 v140, 16, v125
	s_waitcnt vmcnt(16)
	v_mov_b32_e32 v114, v166
	v_mov_b32_e32 v115, v167
	v_mov_b32_e32 v116, v168
	v_mov_b32_e32 v117, v169
	v_pk_fma_f32 v[114:115], v[118:119], v[138:139], v[114:115]
	v_pk_fma_f32 v[116:117], v[120:121], v[140:141], v[116:117]
	global_store_dwordx4 v[126:127], v[114:117], off
	v_cvt_pk_bf16_f32 v118, v114, v115
	v_cvt_pk_bf16_f32 v119, v116, v117
	v_pk_mul_f32 v[114:115], v[114:115], v[114:115]
	v_pk_mul_f32 v[116:117], v[116:117], v[116:117]
	v_add_f32_e32 v97, v114, v115
	v_add_f32_e32 v97, v116, v97
	v_add_f32_e32 v97, v117, v97
	global_store_dwordx2 v[122:123], v[118:119], off
	s_nop 0
	v_add_f32_dpp v97, v97, v97 quad_perm:[1,0,3,2] row_mask:0xf bank_mask:0xf bound_ctrl:1
	s_nop 1
	v_add_f32_dpp v97, v97, v97 quad_perm:[2,3,0,1] row_mask:0xf bank_mask:0xf bound_ctrl:1
	s_nop 1
	v_add_f32_dpp v97, v97, v97 row_half_mirror row_mask:0xf bank_mask:0xf bound_ctrl:1
	s_nop 1
	v_mov_b32_dpp v101, v97 row_mirror row_mask:0xf bank_mask:0xf
	s_and_saveexec_b64 s[0:1], vcc
	s_cbranch_execz .LBB0_1647
	v_add_f32_e32 v101, v97, v101
	v_ashrrev_i32_e32 v97, 31, v96
	v_lshl_add_u64 v[96:97], v[96:97], 2, s[30:31]
	global_atomic_add_f32 v[96:97], v101, off
; __device__ __forceinline__ float bfs2f(short h) { return __uint_as_float(((unsigned)(u16)h) << 16); }
; __device__ __forceinline__ float sigm(float x) { return __builtin_amdgcn_rcpf(1.f + __expf(-x)); }
;   __device__ __forceinline__ void tile(const float* reg, int row0, int col0, int lane) const {
;     ...
;     rows4(reg, lane, [&](int it, int rr, int c4, float4 v) {
;       int row = row0 + rr, idx = row * 1024 + col0 + c4;
;       float rs = rsv[it];
;       float4 xo = *(const float4*)(xold + idx);
;       bf16x4 t = *(const bf16x4*)(tmp + idx);
;       v.x = fmaf(sigm(v.x * rs), bfs2f(t[0]), xo.x); v.y = fmaf(sigm(v.y * rs), bfs2f(t[1]), xo.y);
;       v.z = fmaf(sigm(v.z * rs), bfs2f(t[2]), xo.z); v.w = fmaf(sigm(v.w * rs), bfs2f(t[3]), xo.w);
;       *(float4*)(xnew + idx) = v;
;       *(bf16x4*)(xb + idx) = pack4(v.x, v.y, v.z, v.w);
;       float s = row16_sum(v.x * v.x + v.y * v.y + v.z * v.z + v.w * v.w);
;       if ((lane & 15) == 0) atomicAdd(ssqn + row, s);
;     });
.LBB0_1647:
	s_or_b64 exec, exec, s[0:1]
	v_or_b32_e32 v101, 12, v130
	v_add_u32_e32 v96, v101, v129
	v_lshl_add_u32 v114, v96, 10, v128
	v_ashrrev_i32_e32 v115, 31, v114
	v_lshlrev_b64 v[122:123], 1, v[114:115]
	v_lshl_add_u64 v[116:117], s[18:19], 0, v[122:123]
	v_lshl_add_u64 v[126:127], v[114:115], 2, s[12:13]
	v_add_u32_e32 v97, 0x440, v108
	v_fmamk_f32 v108, v98, 0x3a800000, v135
	v_mul_f32_e32 v111, 0x4b800000, v108
	v_cmp_gt_f32_e64 s[10:11], s52, v108
	v_add_u32_e32 v98, v136, v97
	ds_read_b128 v[118:121], v98
	v_cndmask_b32_e64 v97, v108, v111, s[10:11]
	v_rsq_f32_e32 v97, v97
	v_lshl_add_u64 v[122:123], s[26:27], 0, v[122:123]
	v_mul_f32_e32 v108, 0x45800000, v97
	v_cndmask_b32_e64 v97, v97, v108, s[10:11]
	s_waitcnt lgkmcnt(0)
	v_mul_f32_e32 v108, v97, v118
	v_mul_f32_e32 v111, v97, v119
	v_mul_f32_e32 v113, v97, v120
	v_mul_f32_e32 v97, v97, v121
	v_mul_f32_e32 v108, 0xbfb8aa3b, v108
	v_mul_f32_e32 v111, 0xbfb8aa3b, v111
	v_mul_f32_e32 v113, 0xbfb8aa3b, v113
	v_mul_f32_e32 v97, 0xbfb8aa3b, v97
	v_exp_f32_e32 v108, v108
	v_exp_f32_e32 v111, v111
	v_exp_f32_e32 v113, v113
	v_exp_f32_e32 v97, v97
	v_add_f32_e32 v108, 1.0, v108
	v_add_f32_e32 v111, 1.0, v111
	v_add_f32_e32 v113, 1.0, v113
	v_add_f32_e32 v97, 1.0, v97
	v_rcp_f32_e32 v118, v108
	v_rcp_f32_e32 v119, v111
	v_rcp_f32_e32 v120, v113
	v_rcp_f32_e32 v121, v97
	v_mov_b32_e32 v108, 0
	s_waitcnt vmcnt(18)
	v_mov_b32_e32 v124, v170
	v_mov_b32_e32 v125, v171
	v_and_b32_e32 v139, 0xffff0000, v124
	v_lshlrev_b32_e32 v138, 16, v124
	v_and_b32_e32 v141, 0xffff0000, v125
	v_lshlrev_b32_e32 v140, 16, v125
	s_waitcnt vmcnt(17)
	v_mov_b32_e32 v114, v172
	v_mov_b32_e32 v115, v173
	v_mov_b32_e32 v116, v174
	v_mov_b32_e32 v117, v175
	v_pk_fma_f32 v[114:115], v[118:119], v[138:139], v[114:115]
	v_pk_fma_f32 v[116:117], v[120:121], v[140:141], v[116:117]
	global_store_dwordx4 v[126:127], v[114:117], off
	v_cvt_pk_bf16_f32 v118, v114, v115
	v_cvt_pk_bf16_f32 v119, v116, v117
	v_pk_mul_f32 v[114:115], v[114:115], v[114:115]
	v_pk_mul_f32 v[116:117], v[116:117], v[116:117]
	v_add_f32_e32 v97, v114, v115
	v_add_f32_e32 v97, v116, v97
	v_add_f32_e32 v97, v117, v97
	global_store_dwordx2 v[122:123], v[118:119], off
	s_nop 0
	v_add_f32_dpp v97, v97, v97 quad_perm:[1,0,3,2] row_mask:0xf bank_mask:0xf bound_ctrl:1
	s_nop 1
	v_add_f32_dpp v97, v97, v97 quad_perm:[2,3,0,1] row_mask:0xf bank_mask:0xf bound_ctrl:1
	s_nop 1
	v_add_f32_dpp v97, v97, v97 row_half_mirror row_mask:0xf bank_mask:0xf bound_ctrl:1
	s_nop 1
	v_mov_b32_dpp v108, v97 row_mirror row_mask:0xf bank_mask:0xf
	s_and_saveexec_b64 s[0:1], vcc
	s_cbranch_execz .LBB0_1649
	v_add_f32_e32 v108, v97, v108
	v_ashrrev_i32_e32 v97, 31, v96
	v_lshl_add_u64 v[96:97], v[96:97], 2, s[30:31]
	global_atomic_add_f32 v[96:97], v108, off
.LBB0_1649:
	s_or_b64 exec, exec, s[0:1]
	v_fmamk_f32 v96, v105, 0x3a800000, v135
	v_mul_f32_e32 v97, 0x4b800000, v96
	v_cmp_gt_f32_e64 s[10:11], s52, v96
	v_or_b32_e32 v108, 16, v130
	s_nop 0
	v_cndmask_b32_e64 v96, v96, v97, s[10:11]
	v_rsq_f32_e32 v96, v96
	s_nop 0
	v_mul_f32_e32 v97, 0x45800000, v96
	v_cndmask_b32_e64 v97, v96, v97, s[10:11]
	v_add_u32_e32 v96, v108, v129
	v_lshl_add_u32 v114, v96, 10, v128
	v_ashrrev_i32_e32 v115, 31, v114
	v_lshlrev_b64 v[122:123], 1, v[114:115]
	v_lshl_add_u64 v[116:117], s[18:19], 0, v[122:123]
	v_lshl_add_u64 v[126:127], v[114:115], 2, s[12:13]
	ds_read_b128 v[118:121], v98 offset:1088
	v_lshl_add_u64 v[122:123], s[26:27], 0, v[122:123]
	s_waitcnt lgkmcnt(0)
	v_mul_f32_e32 v105, v97, v118
	v_mul_f32_e32 v111, v97, v119
	v_mul_f32_e32 v113, v97, v120
	v_mul_f32_e32 v97, v97, v121
	v_mul_f32_e32 v105, 0xbfb8aa3b, v105
	v_mul_f32_e32 v111, 0xbfb8aa3b, v111
	v_mul_f32_e32 v113, 0xbfb8aa3b, v113
	v_mul_f32_e32 v97, 0xbfb8aa3b, v97
	v_exp_f32_e32 v105, v105
	v_exp_f32_e32 v111, v111
	v_exp_f32_e32 v113, v113
	v_exp_f32_e32 v97, v97
	v_add_f32_e32 v105, 1.0, v105
	v_add_f32_e32 v111, 1.0, v111
	v_add_f32_e32 v113, 1.0, v113
	v_add_f32_e32 v97, 1.0, v97
	v_rcp_f32_e32 v118, v105
	v_rcp_f32_e32 v119, v111
	v_rcp_f32_e32 v120, v113
	v_rcp_f32_e32 v121, v97
	v_mov_b32_e32 v105, 0
	s_waitcnt vmcnt(19)
	v_mov_b32_e32 v124, v176
	v_mov_b32_e32 v125, v177
	v_and_b32_e32 v139, 0xffff0000, v124
	v_lshlrev_b32_e32 v138, 16, v124
	v_and_b32_e32 v141, 0xffff0000, v125
	v_lshlrev_b32_e32 v140, 16, v125
	s_waitcnt vmcnt(18)
	v_mov_b32_e32 v114, v178
	v_mov_b32_e32 v115, v179
	v_mov_b32_e32 v116, v180
	v_mov_b32_e32 v117, v181
	v_pk_fma_f32 v[114:115], v[118:119], v[138:139], v[114:115]
	v_pk_fma_f32 v[116:117], v[120:121], v[140:141], v[116:117]
	global_store_dwordx4 v[126:127], v[114:117], off
	v_cvt_pk_bf16_f32 v118, v114, v115
	v_cvt_pk_bf16_f32 v119, v116, v117
	v_pk_mul_f32 v[114:115], v[114:115], v[114:115]
	v_pk_mul_f32 v[116:117], v[116:117], v[116:117]
	v_add_f32_e32 v97, v114, v115
	v_add_f32_e32 v97, v116, v97
	v_add_f32_e32 v97, v117, v97
	global_store_dwordx2 v[122:123], v[118:119], off
	s_nop 0
	v_add_f32_dpp v97, v97, v97 quad_perm:[1,0,3,2] row_mask:0xf bank_mask:0xf bound_ctrl:1
	s_nop 1
	v_add_f32_dpp v97, v97, v97 quad_perm:[2,3,0,1] row_mask:0xf bank_mask:0xf bound_ctrl:1
	s_nop 1
	v_add_f32_dpp v97, v97, v97 row_half_mirror row_mask:0xf bank_mask:0xf bound_ctrl:1
	s_nop 1
	v_mov_b32_dpp v105, v97 row_mirror row_mask:0xf bank_mask:0xf
	s_and_saveexec_b64 s[0:1], vcc
	s_cbranch_execz .LBB0_1651
	v_add_f32_e32 v105, v97, v105
	v_ashrrev_i32_e32 v97, 31, v96
	v_lshl_add_u64 v[96:97], v[96:97], 2, s[30:31]
	global_atomic_add_f32 v[96:97], v105, off
; __device__ __forceinline__ float bfs2f(short h) { return __uint_as_float(((unsigned)(u16)h) << 16); }
; __device__ __forceinline__ float sigm(float x) { return __builtin_amdgcn_rcpf(1.f + __expf(-x)); }
;   __device__ __forceinline__ void tile(const float* reg, int row0, int col0, int lane) const {
;     ...
;     rows4(reg, lane, [&](int it, int rr, int c4, float4 v) {
;       int row = row0 + rr, idx = row * 1024 + col0 + c4;
;       float rs = rsv[it];
;       float4 xo = *(const float4*)(xold + idx);
;       bf16x4 t = *(const bf16x4*)(tmp + idx);
;       v.x = fmaf(sigm(v.x * rs), bfs2f(t[0]), xo.x); v.y = fmaf(sigm(v.y * rs), bfs2f(t[1]), xo.y);
;       v.z = fmaf(sigm(v.z * rs), bfs2f(t[2]), xo.z); v.w = fmaf(sigm(v.w * rs), bfs2f(t[3]), xo.w);
;       *(float4*)(xnew + idx) = v;
;       *(bf16x4*)(xb + idx) = pack4(v.x, v.y, v.z, v.w);
;       float s = row16_sum(v.x * v.x + v.y * v.y + v.z * v.z + v.w * v.w);
;       if ((lane & 15) == 0) atomicAdd(ssqn + row, s);
;     });
.LBB0_1651:
	s_or_b64 exec, exec, s[0:1]
	v_or_b32_e32 v105, 20, v130
	v_add_u32_e32 v96, v105, v129
	v_lshl_add_u32 v114, v96, 10, v128
	v_ashrrev_i32_e32 v115, 31, v114
	v_lshlrev_b64 v[122:123], 1, v[114:115]
	v_lshl_add_u64 v[116:117], s[18:19], 0, v[122:123]
	v_lshl_add_u64 v[126:127], v[114:115], 2, s[12:13]
	v_fmamk_f32 v97, v106, 0x3a800000, v135
	v_mul_f32_e32 v106, 0x4b800000, v97
	v_cmp_gt_f32_e64 s[10:11], s52, v97
	ds_read_b128 v[118:121], v98 offset:2176
	v_lshl_add_u64 v[122:123], s[26:27], 0, v[122:123]
	v_cndmask_b32_e64 v97, v97, v106, s[10:11]
	v_rsq_f32_e32 v97, v97
	s_waitcnt vmcnt(20)
	v_mov_b32_e32 v124, v182
	v_mov_b32_e32 v125, v183
	v_and_b32_e32 v139, 0xffff0000, v124
	v_mul_f32_e32 v106, 0x45800000, v97
	v_cndmask_b32_e64 v97, v97, v106, s[10:11]
	s_waitcnt lgkmcnt(0)
	v_mul_f32_e32 v106, v97, v118
	v_mul_f32_e32 v111, v97, v119
	v_mul_f32_e32 v113, v97, v120
	v_mul_f32_e32 v97, v97, v121
	v_mul_f32_e32 v106, 0xbfb8aa3b, v106
	v_mul_f32_e32 v111, 0xbfb8aa3b, v111
	v_mul_f32_e32 v113, 0xbfb8aa3b, v113
	v_mul_f32_e32 v97, 0xbfb8aa3b, v97
	v_exp_f32_e32 v106, v106
	v_exp_f32_e32 v111, v111
	v_exp_f32_e32 v113, v113
	v_exp_f32_e32 v97, v97
	v_add_f32_e32 v106, 1.0, v106
	v_add_f32_e32 v111, 1.0, v111
	v_add_f32_e32 v113, 1.0, v113
	v_add_f32_e32 v97, 1.0, v97
	v_rcp_f32_e32 v118, v106
	v_rcp_f32_e32 v119, v111
	v_rcp_f32_e32 v120, v113
	v_rcp_f32_e32 v121, v97
	v_lshlrev_b32_e32 v138, 16, v124
	v_and_b32_e32 v141, 0xffff0000, v125
	v_lshlrev_b32_e32 v140, 16, v125
	s_waitcnt vmcnt(19)
	v_mov_b32_e32 v114, v184
	v_mov_b32_e32 v115, v185
	v_mov_b32_e32 v116, v186
	v_mov_b32_e32 v117, v187
	v_pk_fma_f32 v[114:115], v[118:119], v[138:139], v[114:115]
	v_pk_fma_f32 v[116:117], v[120:121], v[140:141], v[116:117]
	global_store_dwordx4 v[126:127], v[114:117], off
	v_cvt_pk_bf16_f32 v118, v114, v115
	v_cvt_pk_bf16_f32 v119, v116, v117
	v_pk_mul_f32 v[114:115], v[114:115], v[114:115]
	v_pk_mul_f32 v[116:117], v[116:117], v[116:117]
	v_add_f32_e32 v97, v114, v115
	v_add_f32_e32 v97, v116, v97
	v_add_f32_e32 v97, v117, v97
	v_mov_b32_e32 v106, 0
	global_store_dwordx2 v[122:123], v[118:119], off
	v_add_f32_dpp v97, v97, v97 quad_perm:[1,0,3,2] row_mask:0xf bank_mask:0xf bound_ctrl:1
	s_nop 1
	v_add_f32_dpp v97, v97, v97 quad_perm:[2,3,0,1] row_mask:0xf bank_mask:0xf bound_ctrl:1
	s_nop 1
	v_add_f32_dpp v97, v97, v97 row_half_mirror row_mask:0xf bank_mask:0xf bound_ctrl:1
	s_nop 1
	v_mov_b32_dpp v106, v97 row_mirror row_mask:0xf bank_mask:0xf
	s_and_saveexec_b64 s[0:1], vcc
	s_cbranch_execz .LBB0_1653
	v_add_f32_e32 v106, v97, v106
	v_ashrrev_i32_e32 v97, 31, v96
	v_lshl_add_u64 v[96:97], v[96:97], 2, s[30:31]
	global_atomic_add_f32 v[96:97], v106, off
.LBB0_1653:
	s_or_b64 exec, exec, s[0:1]
	v_or_b32_e32 v106, 24, v130
	v_add_u32_e32 v96, v106, v129
	v_lshl_add_u32 v114, v96, 10, v128
	v_ashrrev_i32_e32 v115, 31, v114
	v_lshlrev_b64 v[122:123], 1, v[114:115]
	v_lshl_add_u64 v[116:117], s[18:19], 0, v[122:123]
	v_lshl_add_u64 v[126:127], v[114:115], 2, s[12:13]
	v_fmamk_f32 v97, v107, 0x3a800000, v135
	v_mul_f32_e32 v107, 0x4b800000, v97
	v_cmp_gt_f32_e64 s[10:11], s52, v97
	ds_read_b128 v[118:121], v98 offset:3264
	v_lshl_add_u64 v[122:123], s[26:27], 0, v[122:123]
	v_cndmask_b32_e64 v97, v97, v107, s[10:11]
	v_rsq_f32_e32 v97, v97
	s_waitcnt vmcnt(21)
	v_mov_b32_e32 v124, v188
	v_mov_b32_e32 v125, v189
	v_and_b32_e32 v139, 0xffff0000, v124
	v_mul_f32_e32 v107, 0x45800000, v97
	v_cndmask_b32_e64 v97, v97, v107, s[10:11]
	s_waitcnt lgkmcnt(0)
	v_mul_f32_e32 v107, v97, v118
	v_mul_f32_e32 v111, v97, v119
	v_mul_f32_e32 v113, v97, v120
	v_mul_f32_e32 v97, v97, v121
	v_mul_f32_e32 v107, 0xbfb8aa3b, v107
	v_mul_f32_e32 v111, 0xbfb8aa3b, v111
	v_mul_f32_e32 v113, 0xbfb8aa3b, v113
	v_mul_f32_e32 v97, 0xbfb8aa3b, v97
	v_exp_f32_e32 v107, v107
	v_exp_f32_e32 v111, v111
	v_exp_f32_e32 v113, v113
	v_exp_f32_e32 v97, v97
	v_add_f32_e32 v107, 1.0, v107
	v_add_f32_e32 v111, 1.0, v111
	v_add_f32_e32 v113, 1.0, v113
	v_add_f32_e32 v97, 1.0, v97
	v_rcp_f32_e32 v118, v107
	v_rcp_f32_e32 v119, v111
	v_rcp_f32_e32 v120, v113
	v_rcp_f32_e32 v121, v97
	v_lshlrev_b32_e32 v138, 16, v124
	v_and_b32_e32 v141, 0xffff0000, v125
	v_lshlrev_b32_e32 v140, 16, v125
	s_waitcnt vmcnt(20)
	v_mov_b32_e32 v114, v190
	v_mov_b32_e32 v115, v191
	v_mov_b32_e32 v116, v192
	v_mov_b32_e32 v117, v193
	v_pk_fma_f32 v[114:115], v[118:119], v[138:139], v[114:115]
	v_pk_fma_f32 v[116:117], v[120:121], v[140:141], v[116:117]
	global_store_dwordx4 v[126:127], v[114:117], off
	v_cvt_pk_bf16_f32 v118, v114, v115
	v_cvt_pk_bf16_f32 v119, v116, v117
	v_pk_mul_f32 v[114:115], v[114:115], v[114:115]
	v_pk_mul_f32 v[116:117], v[116:117], v[116:117]
	v_add_f32_e32 v97, v114, v115
	v_add_f32_e32 v97, v116, v97
	v_add_f32_e32 v97, v117, v97
	v_mov_b32_e32 v107, 0
	global_store_dwordx2 v[122:123], v[118:119], off
	v_add_f32_dpp v97, v97, v97 quad_perm:[1,0,3,2] row_mask:0xf bank_mask:0xf bound_ctrl:1
	s_nop 1
	v_add_f32_dpp v97, v97, v97 quad_perm:[2,3,0,1] row_mask:0xf bank_mask:0xf bound_ctrl:1
	s_nop 1
	v_add_f32_dpp v97, v97, v97 row_half_mirror row_mask:0xf bank_mask:0xf bound_ctrl:1
	s_nop 1
	v_mov_b32_dpp v107, v97 row_mirror row_mask:0xf bank_mask:0xf
	s_and_saveexec_b64 s[0:1], vcc
	s_cbranch_execz .LBB0_1655
	v_add_f32_e32 v107, v97, v107
	v_ashrrev_i32_e32 v97, 31, v96
	v_lshl_add_u64 v[96:97], v[96:97], 2, s[30:31]
	global_atomic_add_f32 v[96:97], v107, off
; __device__ __forceinline__ float bfs2f(short h) { return __uint_as_float(((unsigned)(u16)h) << 16); }
; __device__ __forceinline__ float sigm(float x) { return __builtin_amdgcn_rcpf(1.f + __expf(-x)); }
;   __device__ __forceinline__ void tile(const float* reg, int row0, int col0, int lane) const {
;     ...
;     rows4(reg, lane, [&](int it, int rr, int c4, float4 v) {
;       int row = row0 + rr, idx = row * 1024 + col0 + c4;
;       float rs = rsv[it];
;       float4 xo = *(const float4*)(xold + idx);
;       bf16x4 t = *(const bf16x4*)(tmp + idx);
;       v.x = fmaf(sigm(v.x * rs), bfs2f(t[0]), xo.x); v.y = fmaf(sigm(v.y * rs), bfs2f(t[1]), xo.y);
;       v.z = fmaf(sigm(v.z * rs), bfs2f(t[2]), xo.z); v.w = fmaf(sigm(v.w * rs), bfs2f(t[3]), xo.w);
;       *(float4*)(xnew + idx) = v;
;       *(bf16x4*)(xb + idx) = pack4(v.x, v.y, v.z, v.w);
;       float s = row16_sum(v.x * v.x + v.y * v.y + v.z * v.z + v.w * v.w);
;       if ((lane & 15) == 0) atomicAdd(ssqn + row, s);
;     });
; template <int MF, class Epi>
; __device__ __forceinline__ void staged_epilogue(f32x4 (&acc)[MF][4], int row0, int col0, const Epi& epi) {
;     ...
;     for (int mm = 0; mm < 2; ++mm)
; #pragma unroll
;       for (int n = 0; n < 4; ++n)
; #pragma unroll
;         for (int j = 0; j < 4; ++j) reg[(mm * 16 + fq * 4 + j) * 68 + n * 16 + fr] = acc[mp * 2 + mm][n][j];
.LBB0_1655:
	s_or_b64 exec, exec, s[0:1]
	v_or_b32_e32 v107, 28, v130
	v_add_u32_e32 v96, v107, v129
	v_lshl_add_u32 v114, v96, 10, v128
	v_ashrrev_i32_e32 v115, 31, v114
	v_lshlrev_b64 v[122:123], 1, v[114:115]
	v_lshl_add_u64 v[116:117], s[18:19], 0, v[122:123]
	v_lshl_add_u64 v[126:127], v[114:115], 2, s[12:13]
	v_fmamk_f32 v97, v110, 0x3a800000, v135
	v_mul_f32_e32 v110, 0x4b800000, v97
	v_cmp_gt_f32_e64 s[10:11], s52, v97
	ds_read_b128 v[118:121], v98 offset:4352
	s_waitcnt vmcnt(22)
	v_mov_b32_e32 v124, v194
	v_mov_b32_e32 v125, v195
	v_and_b32_e32 v139, 0xffff0000, v125
	v_cndmask_b32_e64 v97, v97, v110, s[10:11]
	v_rsq_f32_e32 v97, v97
	v_lshl_add_u64 v[110:111], s[26:27], 0, v[122:123]
	v_and_b32_e32 v123, 0xffff0000, v124
	v_lshlrev_b32_e32 v122, 16, v124
	v_mul_f32_e32 v113, 0x45800000, v97
	v_cndmask_b32_e64 v97, v97, v113, s[10:11]
	s_waitcnt lgkmcnt(0)
	v_mul_f32_e32 v113, v97, v118
	v_mul_f32_e32 v118, v97, v119
	v_mul_f32_e32 v119, v97, v120
	v_mul_f32_e32 v97, v97, v121
	v_mul_f32_e32 v113, 0xbfb8aa3b, v113
	v_mul_f32_e32 v118, 0xbfb8aa3b, v118
	v_mul_f32_e32 v119, 0xbfb8aa3b, v119
	v_mul_f32_e32 v97, 0xbfb8aa3b, v97
	v_exp_f32_e32 v113, v113
	v_exp_f32_e32 v118, v118
	v_exp_f32_e32 v119, v119
	v_exp_f32_e32 v97, v97
	v_add_f32_e32 v113, 1.0, v113
	v_add_f32_e32 v120, 1.0, v118
	v_add_f32_e32 v121, 1.0, v119
	v_add_f32_e32 v97, 1.0, v97
	v_rcp_f32_e32 v118, v113
	v_rcp_f32_e32 v119, v120
	v_rcp_f32_e32 v120, v121
	v_rcp_f32_e32 v121, v97
	v_lshlrev_b32_e32 v138, 16, v125
	s_waitcnt vmcnt(21)
	v_mov_b32_e32 v114, v196
	v_mov_b32_e32 v115, v197
	v_mov_b32_e32 v116, v198
	v_mov_b32_e32 v117, v199
	v_pk_fma_f32 v[114:115], v[118:119], v[122:123], v[114:115]
	v_pk_fma_f32 v[116:117], v[120:121], v[138:139], v[116:117]
	global_store_dwordx4 v[126:127], v[114:117], off
	v_cvt_pk_bf16_f32 v118, v114, v115
	v_cvt_pk_bf16_f32 v119, v116, v117
	v_pk_mul_f32 v[114:115], v[114:115], v[114:115]
	v_pk_mul_f32 v[116:117], v[116:117], v[116:117]
	v_add_f32_e32 v97, v114, v115
	v_add_f32_e32 v97, v116, v97
	v_add_f32_e32 v97, v117, v97
	global_store_dwordx2 v[110:111], v[118:119], off
	v_mov_b32_e32 v110, 0
	v_add_f32_dpp v97, v97, v97 quad_perm:[1,0,3,2] row_mask:0xf bank_mask:0xf bound_ctrl:1
	s_nop 1
	v_add_f32_dpp v97, v97, v97 quad_perm:[2,3,0,1] row_mask:0xf bank_mask:0xf bound_ctrl:1
	s_nop 1
	v_add_f32_dpp v97, v97, v97 row_half_mirror row_mask:0xf bank_mask:0xf bound_ctrl:1
	s_nop 1
	v_mov_b32_dpp v110, v97 row_mirror row_mask:0xf bank_mask:0xf
	s_and_saveexec_b64 s[0:1], vcc
	s_cbranch_execz .LBB0_1657
	v_add_f32_e32 v110, v97, v110
	v_ashrrev_i32_e32 v97, 31, v96
	v_lshl_add_u64 v[96:97], v[96:97], 2, s[30:31]
	global_atomic_add_f32 v[96:97], v110, off
.LBB0_1657:
	s_or_b64 exec, exec, s[0:1]
	ds_write2_b32 v131, v88, v92 offset1:16
	ds_write2_b32 v131, v89, v93 offset0:68 offset1:84
	ds_write2_b32 v131, v90, v94 offset0:136 offset1:152
	ds_write2_b32 v131, v91, v95 offset0:204 offset1:220
	ds_write2_b32 v131, v80, v84 offset0:32 offset1:48
	ds_write2_b32 v131, v81, v85 offset0:100 offset1:116
	ds_write2_b32 v131, v82, v86 offset0:168 offset1:184
	ds_write2_b32 v131, v83, v87 offset0:236 offset1:252
	ds_write2_b32 v112, v72, v76 offset0:64 offset1:80
	ds_write2_b32 v112, v73, v77 offset0:132 offset1:148
	ds_write2_b32 v112, v74, v78 offset0:200 offset1:216
	ds_write2_b32 v104, v75, v79 offset0:12 offset1:28
	ds_write2_b32 v112, v64, v68 offset0:96 offset1:112
	ds_write2_b32 v112, v65, v69 offset0:164 offset1:180
	ds_write2_b32 v112, v66, v70 offset0:232 offset1:248
	ds_write2_b32 v104, v67, v71 offset0:44 offset1:60
	v_add_u32_e32 v210, 32, v129
	v_add_u32_e32 v200, v130, v210
	v_ashrrev_i32_e32 v201, 31, v200
	v_lshl_add_u64 v[202:203], v[200:201], 2, s[28:29]
	global_load_dword v144, v[202:203], off
	v_add_u32_e32 v211, 32, v129
	v_add_u32_e32 v210, v130, v211
	v_add_u32_e32 v200, 4, v210
	v_ashrrev_i32_e32 v201, 31, v200
	v_lshl_add_u64 v[200:201], v[200:201], 2, s[28:29]
	global_load_dword v145, v[200:201], off
	v_add_u32_e32 v211, 32, v129
	v_add_u32_e32 v210, v130, v211
	v_add_u32_e32 v200, 8, v210
	v_ashrrev_i32_e32 v201, 31, v200
	v_lshl_add_u64 v[200:201], v[200:201], 2, s[28:29]
	global_load_dword v146, v[200:201], off
	v_add_u32_e32 v211, 32, v129
	v_add_u32_e32 v210, v130, v211
	v_add_u32_e32 v200, 12, v210
	v_ashrrev_i32_e32 v201, 31, v200
	v_lshl_add_u64 v[202:203], v[200:201], 2, s[28:29]
	global_load_dword v147, v[202:203], off
	v_add_u32_e32 v211, 32, v129
	v_add_u32_e32 v210, v130, v211
	v_add_u32_e32 v200, 16, v210
	v_ashrrev_i32_e32 v201, 31, v200
	v_lshl_add_u64 v[202:203], v[200:201], 2, s[28:29]
	global_load_dword v148, v[202:203], off
	v_add_u32_e32 v211, 32, v129
	v_add_u32_e32 v210, v130, v211
	v_add_u32_e32 v200, 20, v210
	v_ashrrev_i32_e32 v201, 31, v200
	v_lshl_add_u64 v[202:203], v[200:201], 2, s[28:29]
	global_load_dword v149, v[202:203], off
	v_add_u32_e32 v211, 32, v129
	v_add_u32_e32 v210, v130, v211
	v_add_u32_e32 v200, 24, v210
	v_ashrrev_i32_e32 v201, 31, v200
	v_lshl_add_u64 v[202:203], v[200:201], 2, s[28:29]
	global_load_dword v150, v[202:203], off
	v_add_u32_e32 v211, 32, v129
	v_add_u32_e32 v210, v130, v211
	v_add_u32_e32 v200, 28, v210
	v_ashrrev_i32_e32 v201, 31, v200
	v_lshl_add_u64 v[202:203], v[200:201], 2, s[28:29]
	global_load_dword v151, v[202:203], off
	v_add_u32_e32 v211, 32, v129
	v_add_u32_e32 v210, v130, v211
	v_lshl_add_u32 v200, v210, 10, v128
	v_ashrrev_i32_e32 v201, 31, v200
	v_lshlrev_b64 v[206:207], 1, v[200:201]
	v_lshl_add_u64 v[202:203], s[18:19], 0, v[206:207]
	global_load_dwordx2 v[152:153], v[202:203], off
	v_add_u32_e32 v211, 32, v129
	v_add_u32_e32 v210, v130, v211
; __device__ __forceinline__ float bfs2f(short h) { return __uint_as_float(((unsigned)(u16)h) << 16); }
; __device__ __forceinline__ float sigm(float x) { return __builtin_amdgcn_rcpf(1.f + __expf(-x)); }
; __device__ __forceinline__ float rs_of(float ss) { return rsqrtf(ss * (1.f / 1024) + EPS); }
;   __device__ __forceinline__ void tile(const float* reg, int row0, int col0, int lane) const {
;     float rsv[8];
; #pragma unroll
;     for (int i = 0; i < 8; ++i) rsv[i] = rs_of(ssq[row0 + i * 4 + (lane >> 4)]);
;     rows4(reg, lane, [&](int it, int rr, int c4, float4 v) {
;       int row = row0 + rr, idx = row * 1024 + col0 + c4;
;       float rs = rsv[it];
;       float4 xo = *(const float4*)(xold + idx);
;       bf16x4 t = *(const bf16x4*)(tmp + idx);
;       v.x = fmaf(sigm(v.x * rs), bfs2f(t[0]), xo.x); v.y = fmaf(sigm(v.y * rs), bfs2f(t[1]), xo.y);
;       v.z = fmaf(sigm(v.z * rs), bfs2f(t[2]), xo.z); v.w = fmaf(sigm(v.w * rs), bfs2f(t[3]), xo.w);
;       *(float4*)(xnew + idx) = v;
;       *(bf16x4*)(xb + idx) = pack4(v.x, v.y, v.z, v.w);
;       float s = row16_sum(v.x * v.x + v.y * v.y + v.z * v.z + v.w * v.w);
;       if ((lane & 15) == 0) atomicAdd(ssqn + row, s);
;     });
	v_lshl_add_u32 v200, v210, 10, v128
	v_ashrrev_i32_e32 v201, 31, v200
	v_lshl_add_u64 v[202:203], v[200:201], 2, s[12:13]
	global_load_dwordx4 v[154:157], v[202:203], off
	v_add_u32_e32 v211, 32, v129
	v_add_u32_e32 v210, v99, v211
	v_lshl_add_u32 v200, v210, 10, v128
	v_ashrrev_i32_e32 v201, 31, v200
	v_lshlrev_b64 v[206:207], 1, v[200:201]
	v_lshl_add_u64 v[202:203], s[18:19], 0, v[206:207]
	global_load_dwordx2 v[158:159], v[202:203], off
	v_add_u32_e32 v211, 32, v129
	v_add_u32_e32 v210, v99, v211
	v_lshl_add_u32 v200, v210, 10, v128
	v_ashrrev_i32_e32 v201, 31, v200
	v_lshl_add_u64 v[202:203], v[200:201], 2, s[12:13]
	global_load_dwordx4 v[160:163], v[202:203], off
	v_add_u32_e32 v211, 32, v129
	v_add_u32_e32 v210, v100, v211
	v_lshl_add_u32 v200, v210, 10, v128
	v_ashrrev_i32_e32 v201, 31, v200
	v_lshlrev_b64 v[206:207], 1, v[200:201]
	v_lshl_add_u64 v[202:203], s[18:19], 0, v[206:207]
	global_load_dwordx2 v[164:165], v[202:203], off
	v_add_u32_e32 v211, 32, v129
	v_add_u32_e32 v210, v100, v211
	v_lshl_add_u32 v200, v210, 10, v128
	v_ashrrev_i32_e32 v201, 31, v200
	v_lshl_add_u64 v[202:203], v[200:201], 2, s[12:13]
	global_load_dwordx4 v[166:169], v[202:203], off
	v_add_u32_e32 v211, 32, v129
	v_add_u32_e32 v210, v101, v211
	v_lshl_add_u32 v200, v210, 10, v128
	v_ashrrev_i32_e32 v201, 31, v200
	v_lshlrev_b64 v[206:207], 1, v[200:201]
	v_lshl_add_u64 v[202:203], s[18:19], 0, v[206:207]
	global_load_dwordx2 v[170:171], v[202:203], off
	v_add_u32_e32 v211, 32, v129
	v_add_u32_e32 v210, v101, v211
	v_lshl_add_u32 v200, v210, 10, v128
	v_ashrrev_i32_e32 v201, 31, v200
	v_lshl_add_u64 v[202:203], v[200:201], 2, s[12:13]
	global_load_dwordx4 v[172:175], v[202:203], off
	v_add_u32_e32 v211, 32, v129
	v_add_u32_e32 v210, v108, v211
	v_lshl_add_u32 v200, v210, 10, v128
	v_ashrrev_i32_e32 v201, 31, v200
	v_lshlrev_b64 v[206:207], 1, v[200:201]
	v_lshl_add_u64 v[202:203], s[18:19], 0, v[206:207]
	global_load_dwordx2 v[176:177], v[202:203], off
	v_add_u32_e32 v211, 32, v129
	v_add_u32_e32 v210, v108, v211
	v_lshl_add_u32 v200, v210, 10, v128
	v_ashrrev_i32_e32 v201, 31, v200
	v_lshl_add_u64 v[202:203], v[200:201], 2, s[12:13]
	global_load_dwordx4 v[178:181], v[202:203], off
	v_add_u32_e32 v211, 32, v129
	v_add_u32_e32 v210, v105, v211
	v_lshl_add_u32 v200, v210, 10, v128
	v_ashrrev_i32_e32 v201, 31, v200
	v_lshlrev_b64 v[206:207], 1, v[200:201]
	v_lshl_add_u64 v[202:203], s[18:19], 0, v[206:207]
	global_load_dwordx2 v[182:183], v[202:203], off
	v_add_u32_e32 v211, 32, v129
	v_add_u32_e32 v210, v105, v211
	v_lshl_add_u32 v200, v210, 10, v128
	v_ashrrev_i32_e32 v201, 31, v200
	v_lshl_add_u64 v[202:203], v[200:201], 2, s[12:13]
	global_load_dwordx4 v[184:187], v[202:203], off
	v_add_u32_e32 v211, 32, v129
	v_add_u32_e32 v210, v106, v211
	v_lshl_add_u32 v200, v210, 10, v128
	v_ashrrev_i32_e32 v201, 31, v200
	v_lshlrev_b64 v[206:207], 1, v[200:201]
	v_lshl_add_u64 v[202:203], s[18:19], 0, v[206:207]
	global_load_dwordx2 v[188:189], v[202:203], off
	v_add_u32_e32 v211, 32, v129
	v_add_u32_e32 v210, v106, v211
	v_lshl_add_u32 v200, v210, 10, v128
	v_ashrrev_i32_e32 v201, 31, v200
	v_lshl_add_u64 v[202:203], v[200:201], 2, s[12:13]
	global_load_dwordx4 v[190:193], v[202:203], off
	v_add_u32_e32 v211, 32, v129
	v_add_u32_e32 v210, v107, v211
	v_lshl_add_u32 v200, v210, 10, v128
	v_ashrrev_i32_e32 v201, 31, v200
	v_lshlrev_b64 v[206:207], 1, v[200:201]
	v_lshl_add_u64 v[202:203], s[18:19], 0, v[206:207]
	global_load_dwordx2 v[194:195], v[202:203], off
	v_add_u32_e32 v211, 32, v129
	v_add_u32_e32 v210, v107, v211
	v_lshl_add_u32 v200, v210, 10, v128
	v_ashrrev_i32_e32 v201, 31, v200
	v_lshl_add_u64 v[202:203], v[200:201], 2, s[12:13]
	global_load_dwordx4 v[196:199], v[202:203], off
	v_add_u32_e32 v67, 32, v129
	v_add_u32_e32 v64, v130, v67
	v_add_u32_e32 v72, 12, v64
	v_ashrrev_i32_e32 v73, 31, v72
	v_lshl_add_u64 v[76:77], v[72:73], 2, s[28:29]
	v_add_u32_e32 v72, 16, v64
	v_ashrrev_i32_e32 v73, 31, v72
	v_ashrrev_i32_e32 v65, 31, v64
	v_lshl_add_u64 v[78:79], v[72:73], 2, s[28:29]
	v_add_u32_e32 v72, 20, v64
	v_lshl_add_u64 v[68:69], v[64:65], 2, s[28:29]
	v_ashrrev_i32_e32 v73, 31, v72
	v_lshl_add_u64 v[80:81], v[72:73], 2, s[28:29]
	v_add_u32_e32 v72, 24, v64
	v_add_u32_e32 v68, 4, v64
	v_add_u32_e32 v70, 8, v64
	v_ashrrev_i32_e32 v73, 31, v72
	v_ashrrev_i32_e32 v69, 31, v68
	v_ashrrev_i32_e32 v71, 31, v70
	v_lshl_add_u64 v[82:83], v[72:73], 2, s[28:29]
	v_add_u32_e32 v72, 28, v64
	v_lshl_add_u64 v[68:69], v[68:69], 2, s[28:29]
	v_lshl_add_u64 v[70:71], v[70:71], 2, s[28:29]
	v_ashrrev_i32_e32 v73, 31, v72
	v_lshl_add_u64 v[84:85], v[72:73], 2, s[28:29]
	s_nop 0
	s_waitcnt vmcnt(23)
	v_mov_b32_e32 v66, v144
	v_fmamk_f32 v66, v66, 0x3a800000, v135
	v_mul_f32_e32 v75, 0x4b800000, v66
	v_cmp_gt_f32_e64 s[10:11], s52, v66
	s_nop 1
	v_cndmask_b32_e64 v66, v66, v75, s[10:11]
	v_rsq_f32_e32 v66, v66
	s_nop 0
	v_mul_f32_e32 v75, 0x45800000, v66
	v_cndmask_b32_e64 v75, v66, v75, s[10:11]
	v_lshl_add_u32 v76, v64, 10, v128
	v_ashrrev_i32_e32 v77, 31, v76
	v_lshlrev_b64 v[84:85], 1, v[76:77]
	v_lshl_add_u64 v[78:79], s[18:19], 0, v[84:85]
	v_lshl_add_u64 v[88:89], v[76:77], 2, s[12:13]
	v_add_u32_e32 v66, v136, v109
	ds_read_b128 v[80:83], v66
	v_lshl_add_u64 v[84:85], s[26:27], 0, v[84:85]
	s_waitcnt lgkmcnt(0)
	v_mul_f32_e32 v80, v75, v80
	v_mul_f32_e32 v81, v75, v81
	v_mul_f32_e32 v82, v75, v82
	v_mul_f32_e32 v75, v75, v83
	v_mul_f32_e32 v80, 0xbfb8aa3b, v80
	v_mul_f32_e32 v81, 0xbfb8aa3b, v81
	v_mul_f32_e32 v82, 0xbfb8aa3b, v82
	v_mul_f32_e32 v75, 0xbfb8aa3b, v75
	v_exp_f32_e32 v80, v80
	v_exp_f32_e32 v81, v81
	v_exp_f32_e32 v82, v82
	v_exp_f32_e32 v75, v75
	v_add_f32_e32 v80, 1.0, v80
	v_add_f32_e32 v81, 1.0, v81
	v_add_f32_e32 v82, 1.0, v82
	v_add_f32_e32 v75, 1.0, v75
	v_rcp_f32_e32 v80, v80
	v_rcp_f32_e32 v81, v81
	v_rcp_f32_e32 v82, v82
	v_rcp_f32_e32 v83, v75
	s_waitcnt vmcnt(15)
; __device__ __forceinline__ float bfs2f(short h) { return __uint_as_float(((unsigned)(u16)h) << 16); }
; __device__ __forceinline__ float sigm(float x) { return __builtin_amdgcn_rcpf(1.f + __expf(-x)); }
;   __device__ __forceinline__ void tile(const float* reg, int row0, int col0, int lane) const {
;     ...
;     rows4(reg, lane, [&](int it, int rr, int c4, float4 v) {
;       int row = row0 + rr, idx = row * 1024 + col0 + c4;
;       float rs = rsv[it];
;       float4 xo = *(const float4*)(xold + idx);
;       bf16x4 t = *(const bf16x4*)(tmp + idx);
;       v.x = fmaf(sigm(v.x * rs), bfs2f(t[0]), xo.x); v.y = fmaf(sigm(v.y * rs), bfs2f(t[1]), xo.y);
;       v.z = fmaf(sigm(v.z * rs), bfs2f(t[2]), xo.z); v.w = fmaf(sigm(v.w * rs), bfs2f(t[3]), xo.w);
;       *(float4*)(xnew + idx) = v;
;       *(bf16x4*)(xb + idx) = pack4(v.x, v.y, v.z, v.w);
;       float s = row16_sum(v.x * v.x + v.y * v.y + v.z * v.z + v.w * v.w);
;       if ((lane & 15) == 0) atomicAdd(ssqn + row, s);
;     });
	v_mov_b32_e32 v74, v145
	v_mov_b32_e32 v73, v146
	v_mov_b32_e32 v72, v147
	v_mov_b32_e32 v71, v148
	v_mov_b32_e32 v70, v149
	v_mov_b32_e32 v69, v150
	v_mov_b32_e32 v68, v151
	v_mov_b32_e32 v86, v152
	v_mov_b32_e32 v87, v153
	v_and_b32_e32 v91, 0xffff0000, v86
	v_lshlrev_b32_e32 v90, 16, v86
	v_and_b32_e32 v93, 0xffff0000, v87
	v_lshlrev_b32_e32 v92, 16, v87
	s_waitcnt vmcnt(14)
	v_mov_b32_e32 v76, v154
	v_mov_b32_e32 v77, v155
	v_mov_b32_e32 v78, v156
	v_mov_b32_e32 v79, v157
	v_pk_fma_f32 v[76:77], v[80:81], v[90:91], v[76:77]
	v_pk_fma_f32 v[78:79], v[82:83], v[92:93], v[78:79]
	global_store_dwordx4 v[88:89], v[76:79], off
	v_cvt_pk_bf16_f32 v80, v76, v77
	v_cvt_pk_bf16_f32 v81, v78, v79
	v_pk_mul_f32 v[76:77], v[76:77], v[76:77]
	v_pk_mul_f32 v[78:79], v[78:79], v[78:79]
	v_add_f32_e32 v75, v76, v77
	v_add_f32_e32 v75, v78, v75
	v_add_f32_e32 v75, v79, v75
	v_mov_b32_e32 v76, 0
	global_store_dwordx2 v[84:85], v[80:81], off
	v_add_f32_dpp v75, v75, v75 quad_perm:[1,0,3,2] row_mask:0xf bank_mask:0xf bound_ctrl:1
	s_nop 1
	v_add_f32_dpp v75, v75, v75 quad_perm:[2,3,0,1] row_mask:0xf bank_mask:0xf bound_ctrl:1
	s_nop 1
	v_add_f32_dpp v75, v75, v75 row_half_mirror row_mask:0xf bank_mask:0xf bound_ctrl:1
	s_nop 1
	v_mov_b32_dpp v76, v75 row_mirror row_mask:0xf bank_mask:0xf
	s_and_saveexec_b64 s[0:1], vcc
	s_cbranch_execz .LBB0_1659
	v_add_f32_e32 v75, v75, v76
	v_lshl_add_u64 v[64:65], v[64:65], 2, s[30:31]
	global_atomic_add_f32 v[64:65], v75, off
.LBB0_1659:
	s_or_b64 exec, exec, s[0:1]
	v_add_u32_e32 v64, v99, v67
	v_lshl_add_u32 v76, v64, 10, v128
	v_ashrrev_i32_e32 v77, 31, v76
	v_lshlrev_b64 v[84:85], 1, v[76:77]
	v_lshl_add_u64 v[78:79], s[18:19], 0, v[84:85]
	v_lshl_add_u64 v[88:89], v[76:77], 2, s[12:13]
	v_fmamk_f32 v65, v74, 0x3a800000, v135
	v_mul_f32_e32 v74, 0x4b800000, v65
	v_cmp_gt_f32_e64 s[10:11], s52, v65
	ds_read_b128 v[80:83], v102
	v_lshl_add_u64 v[84:85], s[26:27], 0, v[84:85]
	v_cndmask_b32_e64 v65, v65, v74, s[10:11]
	v_rsq_f32_e32 v65, v65
	s_waitcnt vmcnt(16)
	v_mov_b32_e32 v86, v158
	v_mov_b32_e32 v87, v159
	v_and_b32_e32 v91, 0xffff0000, v87
	v_mul_f32_e32 v74, 0x45800000, v65
	v_cndmask_b32_e64 v65, v65, v74, s[10:11]
	s_waitcnt lgkmcnt(0)
	v_mul_f32_e32 v74, v65, v80
	v_mul_f32_e32 v75, v65, v81
	v_mul_f32_e32 v80, v65, v82
	v_mul_f32_e32 v65, v65, v83
	v_mul_f32_e32 v74, 0xbfb8aa3b, v74
	v_mul_f32_e32 v75, 0xbfb8aa3b, v75
	v_mul_f32_e32 v80, 0xbfb8aa3b, v80
	v_mul_f32_e32 v65, 0xbfb8aa3b, v65
	v_exp_f32_e32 v74, v74
	v_exp_f32_e32 v75, v75
	v_exp_f32_e32 v80, v80
	v_exp_f32_e32 v65, v65
	v_add_f32_e32 v74, 1.0, v74
	v_add_f32_e32 v75, 1.0, v75
	v_add_f32_e32 v80, 1.0, v80
	v_add_f32_e32 v65, 1.0, v65
	v_rcp_f32_e32 v74, v74
	v_rcp_f32_e32 v75, v75
	v_rcp_f32_e32 v80, v80
	v_rcp_f32_e32 v81, v65
	v_and_b32_e32 v83, 0xffff0000, v86
	v_lshlrev_b32_e32 v82, 16, v86
	v_lshlrev_b32_e32 v90, 16, v87
	s_waitcnt vmcnt(15)
	v_mov_b32_e32 v76, v160
	v_mov_b32_e32 v77, v161
	v_mov_b32_e32 v78, v162
	v_mov_b32_e32 v79, v163
	v_pk_fma_f32 v[74:75], v[74:75], v[82:83], v[76:77]
	v_pk_fma_f32 v[76:77], v[80:81], v[90:91], v[78:79]
	global_store_dwordx4 v[88:89], v[74:77], off
	v_cvt_pk_bf16_f32 v78, v74, v75
	v_cvt_pk_bf16_f32 v79, v76, v77
	v_pk_mul_f32 v[74:75], v[74:75], v[74:75]
	v_pk_mul_f32 v[76:77], v[76:77], v[76:77]
	v_add_f32_e32 v65, v74, v75
	v_add_f32_e32 v65, v76, v65
	v_add_f32_e32 v65, v77, v65
	v_mov_b32_e32 v74, 0
	global_store_dwordx2 v[84:85], v[78:79], off
	v_add_f32_dpp v65, v65, v65 quad_perm:[1,0,3,2] row_mask:0xf bank_mask:0xf bound_ctrl:1
	s_nop 1
	v_add_f32_dpp v65, v65, v65 quad_perm:[2,3,0,1] row_mask:0xf bank_mask:0xf bound_ctrl:1
	s_nop 1
	v_add_f32_dpp v65, v65, v65 row_half_mirror row_mask:0xf bank_mask:0xf bound_ctrl:1
	s_nop 1
	v_mov_b32_dpp v74, v65 row_mirror row_mask:0xf bank_mask:0xf
	s_and_saveexec_b64 s[0:1], vcc
	s_cbranch_execz .LBB0_1661
	v_add_f32_e32 v74, v65, v74
	v_ashrrev_i32_e32 v65, 31, v64
	v_lshl_add_u64 v[64:65], v[64:65], 2, s[30:31]
	global_atomic_add_f32 v[64:65], v74, off
.LBB0_1661:
	s_or_b64 exec, exec, s[0:1]
	v_add_u32_e32 v64, v100, v67
	v_lshl_add_u32 v74, v64, 10, v128
	v_ashrrev_i32_e32 v75, 31, v74
	v_lshlrev_b64 v[82:83], 1, v[74:75]
	v_lshl_add_u64 v[76:77], s[18:19], 0, v[82:83]
	v_lshl_add_u64 v[86:87], v[74:75], 2, s[12:13]
	v_fmamk_f32 v65, v73, 0x3a800000, v135
	v_mul_f32_e32 v73, 0x4b800000, v65
	v_cmp_gt_f32_e64 s[10:11], s52, v65
	ds_read_b128 v[78:81], v103
	v_lshl_add_u64 v[82:83], s[26:27], 0, v[82:83]
	v_cndmask_b32_e64 v65, v65, v73, s[10:11]
	v_rsq_f32_e32 v65, v65
	s_waitcnt vmcnt(17)
	v_mov_b32_e32 v84, v164
	v_mov_b32_e32 v85, v165
	v_and_b32_e32 v89, 0xffff0000, v84
	v_mul_f32_e32 v73, 0x45800000, v65
	v_cndmask_b32_e64 v65, v65, v73, s[10:11]
	s_waitcnt lgkmcnt(0)
	v_mul_f32_e32 v73, v65, v78
	v_mul_f32_e32 v78, v65, v79
	v_mul_f32_e32 v79, v65, v80
	v_mul_f32_e32 v65, v65, v81
	v_mul_f32_e32 v73, 0xbfb8aa3b, v73
	v_mul_f32_e32 v78, 0xbfb8aa3b, v78
	v_mul_f32_e32 v79, 0xbfb8aa3b, v79
	v_mul_f32_e32 v65, 0xbfb8aa3b, v65
	v_exp_f32_e32 v73, v73
	v_exp_f32_e32 v78, v78
	v_exp_f32_e32 v79, v79
	v_exp_f32_e32 v65, v65
	v_add_f32_e32 v73, 1.0, v73
	v_add_f32_e32 v80, 1.0, v78
	v_add_f32_e32 v81, 1.0, v79
	v_add_f32_e32 v65, 1.0, v65
	v_rcp_f32_e32 v78, v73
	v_rcp_f32_e32 v79, v80
	v_rcp_f32_e32 v80, v81
	v_rcp_f32_e32 v81, v65
	v_lshlrev_b32_e32 v88, 16, v84
	v_and_b32_e32 v91, 0xffff0000, v85
	v_lshlrev_b32_e32 v90, 16, v85
	s_waitcnt vmcnt(16)
	v_mov_b32_e32 v74, v166
	v_mov_b32_e32 v75, v167
	v_mov_b32_e32 v76, v168
	v_mov_b32_e32 v77, v169
	v_pk_fma_f32 v[74:75], v[78:79], v[88:89], v[74:75]
	v_pk_fma_f32 v[76:77], v[80:81], v[90:91], v[76:77]
	global_store_dwordx4 v[86:87], v[74:77], off
	v_cvt_pk_bf16_f32 v78, v74, v75
	v_cvt_pk_bf16_f32 v79, v76, v77
	v_pk_mul_f32 v[74:75], v[74:75], v[74:75]
	v_pk_mul_f32 v[76:77], v[76:77], v[76:77]
	v_add_f32_e32 v65, v74, v75
	v_add_f32_e32 v65, v76, v65
	v_add_f32_e32 v65, v77, v65
	v_mov_b32_e32 v73, 0
	global_store_dwordx2 v[82:83], v[78:79], off
	v_add_f32_dpp v65, v65, v65 quad_perm:[1,0,3,2] row_mask:0xf bank_mask:0xf bound_ctrl:1
	s_nop 1
	v_add_f32_dpp v65, v65, v65 quad_perm:[2,3,0,1] row_mask:0xf bank_mask:0xf bound_ctrl:1
	s_nop 1
	v_add_f32_dpp v65, v65, v65 row_half_mirror row_mask:0xf bank_mask:0xf bound_ctrl:1
	s_nop 1
	v_mov_b32_dpp v73, v65 row_mirror row_mask:0xf bank_mask:0xf
	s_and_saveexec_b64 s[0:1], vcc
	s_cbranch_execz .LBB0_1663
	v_add_f32_e32 v73, v65, v73
	v_ashrrev_i32_e32 v65, 31, v64
	v_lshl_add_u64 v[64:65], v[64:65], 2, s[30:31]
	global_atomic_add_f32 v[64:65], v73, off
; __device__ __forceinline__ float bfs2f(short h) { return __uint_as_float(((unsigned)(u16)h) << 16); }
; __device__ __forceinline__ float sigm(float x) { return __builtin_amdgcn_rcpf(1.f + __expf(-x)); }
;   __device__ __forceinline__ void tile(const float* reg, int row0, int col0, int lane) const {
;     ...
;     rows4(reg, lane, [&](int it, int rr, int c4, float4 v) {
;       int row = row0 + rr, idx = row * 1024 + col0 + c4;
;       float rs = rsv[it];
;       float4 xo = *(const float4*)(xold + idx);
;       bf16x4 t = *(const bf16x4*)(tmp + idx);
;       v.x = fmaf(sigm(v.x * rs), bfs2f(t[0]), xo.x); v.y = fmaf(sigm(v.y * rs), bfs2f(t[1]), xo.y);
;       v.z = fmaf(sigm(v.z * rs), bfs2f(t[2]), xo.z); v.w = fmaf(sigm(v.w * rs), bfs2f(t[3]), xo.w);
;       *(float4*)(xnew + idx) = v;
;       *(bf16x4*)(xb + idx) = pack4(v.x, v.y, v.z, v.w);
;       float s = row16_sum(v.x * v.x + v.y * v.y + v.z * v.z + v.w * v.w);
;       if ((lane & 15) == 0) atomicAdd(ssqn + row, s);
;     });
.LBB0_1663:
	s_or_b64 exec, exec, s[0:1]
	v_add_u32_e32 v64, v101, v67
	v_lshl_add_u32 v74, v64, 10, v128
	v_ashrrev_i32_e32 v75, 31, v74
	v_lshlrev_b64 v[82:83], 1, v[74:75]
	v_lshl_add_u64 v[76:77], s[18:19], 0, v[82:83]
	v_lshl_add_u64 v[86:87], v[74:75], 2, s[12:13]
	v_fmamk_f32 v65, v72, 0x3a800000, v135
	v_mul_f32_e32 v72, 0x4b800000, v65
	v_cmp_gt_f32_e64 s[10:11], s52, v65
	ds_read_b128 v[78:81], v98
	v_lshl_add_u64 v[82:83], s[26:27], 0, v[82:83]
	v_cndmask_b32_e64 v65, v65, v72, s[10:11]
	v_rsq_f32_e32 v65, v65
	s_waitcnt vmcnt(18)
	v_mov_b32_e32 v84, v170
	v_mov_b32_e32 v85, v171
	v_and_b32_e32 v89, 0xffff0000, v85
	v_mul_f32_e32 v72, 0x45800000, v65
	v_cndmask_b32_e64 v65, v65, v72, s[10:11]
	s_waitcnt lgkmcnt(0)
	v_mul_f32_e32 v72, v65, v78
	v_mul_f32_e32 v73, v65, v79
	v_mul_f32_e32 v78, v65, v80
	v_mul_f32_e32 v65, v65, v81
	v_mul_f32_e32 v72, 0xbfb8aa3b, v72
	v_mul_f32_e32 v73, 0xbfb8aa3b, v73
	v_mul_f32_e32 v78, 0xbfb8aa3b, v78
	v_mul_f32_e32 v65, 0xbfb8aa3b, v65
	v_exp_f32_e32 v72, v72
	v_exp_f32_e32 v73, v73
	v_exp_f32_e32 v78, v78
	v_exp_f32_e32 v65, v65
	v_add_f32_e32 v72, 1.0, v72
	v_add_f32_e32 v73, 1.0, v73
	v_add_f32_e32 v78, 1.0, v78
	v_add_f32_e32 v65, 1.0, v65
	v_rcp_f32_e32 v72, v72
	v_rcp_f32_e32 v73, v73
	v_rcp_f32_e32 v78, v78
	v_rcp_f32_e32 v79, v65
	v_and_b32_e32 v81, 0xffff0000, v84
	v_lshlrev_b32_e32 v80, 16, v84
	v_lshlrev_b32_e32 v88, 16, v85
	s_waitcnt vmcnt(17)
	v_mov_b32_e32 v74, v172
	v_mov_b32_e32 v75, v173
	v_mov_b32_e32 v76, v174
	v_mov_b32_e32 v77, v175
	v_pk_fma_f32 v[72:73], v[72:73], v[80:81], v[74:75]
	v_pk_fma_f32 v[74:75], v[78:79], v[88:89], v[76:77]
	global_store_dwordx4 v[86:87], v[72:75], off
	v_cvt_pk_bf16_f32 v76, v72, v73
	v_cvt_pk_bf16_f32 v77, v74, v75
	v_pk_mul_f32 v[72:73], v[72:73], v[72:73]
	v_pk_mul_f32 v[74:75], v[74:75], v[74:75]
	v_add_f32_e32 v65, v72, v73
	v_add_f32_e32 v65, v74, v65
	v_add_f32_e32 v65, v75, v65
	v_mov_b32_e32 v72, 0
	global_store_dwordx2 v[82:83], v[76:77], off
	v_add_f32_dpp v65, v65, v65 quad_perm:[1,0,3,2] row_mask:0xf bank_mask:0xf bound_ctrl:1
	s_nop 1
	v_add_f32_dpp v65, v65, v65 quad_perm:[2,3,0,1] row_mask:0xf bank_mask:0xf bound_ctrl:1
	s_nop 1
	v_add_f32_dpp v65, v65, v65 row_half_mirror row_mask:0xf bank_mask:0xf bound_ctrl:1
	s_nop 1
	v_mov_b32_dpp v72, v65 row_mirror row_mask:0xf bank_mask:0xf
	s_and_saveexec_b64 s[0:1], vcc
	s_cbranch_execz .LBB0_1665
	v_add_f32_e32 v72, v65, v72
	v_ashrrev_i32_e32 v65, 31, v64
	v_lshl_add_u64 v[64:65], v[64:65], 2, s[30:31]
	global_atomic_add_f32 v[64:65], v72, off
.LBB0_1665:
	s_or_b64 exec, exec, s[0:1]
	v_fmamk_f32 v64, v71, 0x3a800000, v135
	v_mul_f32_e32 v65, 0x4b800000, v64
	v_cmp_gt_f32_e64 s[10:11], s52, v64
	s_nop 1
	v_cndmask_b32_e64 v64, v64, v65, s[10:11]
	v_rsq_f32_e32 v64, v64
	s_nop 0
	v_mul_f32_e32 v65, 0x45800000, v64
	v_cndmask_b32_e64 v65, v64, v65, s[10:11]
	v_add_u32_e32 v64, v108, v67
	v_lshl_add_u32 v72, v64, 10, v128
	v_ashrrev_i32_e32 v73, 31, v72
	v_lshlrev_b64 v[80:81], 1, v[72:73]
	v_lshl_add_u64 v[74:75], s[18:19], 0, v[80:81]
	v_lshl_add_u64 v[84:85], v[72:73], 2, s[12:13]
	ds_read_b128 v[76:79], v98 offset:1088
	v_lshl_add_u64 v[80:81], s[26:27], 0, v[80:81]
	s_waitcnt lgkmcnt(0)
	v_mul_f32_e32 v71, v65, v76
	v_mul_f32_e32 v76, v65, v77
	v_mul_f32_e32 v77, v65, v78
	v_mul_f32_e32 v65, v65, v79
	v_mul_f32_e32 v71, 0xbfb8aa3b, v71
	v_mul_f32_e32 v76, 0xbfb8aa3b, v76
	v_mul_f32_e32 v77, 0xbfb8aa3b, v77
	v_mul_f32_e32 v65, 0xbfb8aa3b, v65
	v_exp_f32_e32 v71, v71
	v_exp_f32_e32 v76, v76
	v_exp_f32_e32 v77, v77
	v_exp_f32_e32 v65, v65
	v_add_f32_e32 v71, 1.0, v71
	v_add_f32_e32 v78, 1.0, v76
	v_add_f32_e32 v79, 1.0, v77
	v_add_f32_e32 v65, 1.0, v65
	v_rcp_f32_e32 v76, v71
	v_rcp_f32_e32 v77, v78
	v_rcp_f32_e32 v78, v79
	v_rcp_f32_e32 v79, v65
	v_mov_b32_e32 v71, 0
	s_waitcnt vmcnt(19)
	v_mov_b32_e32 v82, v176
	v_mov_b32_e32 v83, v177
	v_and_b32_e32 v87, 0xffff0000, v82
	v_lshlrev_b32_e32 v86, 16, v82
	v_and_b32_e32 v89, 0xffff0000, v83
	v_lshlrev_b32_e32 v88, 16, v83
	s_waitcnt vmcnt(18)
	v_mov_b32_e32 v72, v178
	v_mov_b32_e32 v73, v179
	v_mov_b32_e32 v74, v180
	v_mov_b32_e32 v75, v181
	v_pk_fma_f32 v[72:73], v[76:77], v[86:87], v[72:73]
	v_pk_fma_f32 v[74:75], v[78:79], v[88:89], v[74:75]
	global_store_dwordx4 v[84:85], v[72:75], off
	v_cvt_pk_bf16_f32 v76, v72, v73
	v_cvt_pk_bf16_f32 v77, v74, v75
	v_pk_mul_f32 v[72:73], v[72:73], v[72:73]
	v_pk_mul_f32 v[74:75], v[74:75], v[74:75]
	v_add_f32_e32 v65, v72, v73
	v_add_f32_e32 v65, v74, v65
	v_add_f32_e32 v65, v75, v65
	global_store_dwordx2 v[80:81], v[76:77], off
	s_nop 0
	v_add_f32_dpp v65, v65, v65 quad_perm:[1,0,3,2] row_mask:0xf bank_mask:0xf bound_ctrl:1
	s_nop 1
	v_add_f32_dpp v65, v65, v65 quad_perm:[2,3,0,1] row_mask:0xf bank_mask:0xf bound_ctrl:1
	s_nop 1
	v_add_f32_dpp v65, v65, v65 row_half_mirror row_mask:0xf bank_mask:0xf bound_ctrl:1
	s_nop 1
	v_mov_b32_dpp v71, v65 row_mirror row_mask:0xf bank_mask:0xf
	s_and_saveexec_b64 s[0:1], vcc
	s_cbranch_execz .LBB0_1667
	v_add_f32_e32 v71, v65, v71
	v_ashrrev_i32_e32 v65, 31, v64
	v_lshl_add_u64 v[64:65], v[64:65], 2, s[30:31]
	global_atomic_add_f32 v[64:65], v71, off
; __device__ __forceinline__ float bfs2f(short h) { return __uint_as_float(((unsigned)(u16)h) << 16); }
; __device__ __forceinline__ float sigm(float x) { return __builtin_amdgcn_rcpf(1.f + __expf(-x)); }
;   __device__ __forceinline__ void tile(const float* reg, int row0, int col0, int lane) const {
;     ...
;     rows4(reg, lane, [&](int it, int rr, int c4, float4 v) {
;       int row = row0 + rr, idx = row * 1024 + col0 + c4;
;       float rs = rsv[it];
;       float4 xo = *(const float4*)(xold + idx);
;       bf16x4 t = *(const bf16x4*)(tmp + idx);
;       v.x = fmaf(sigm(v.x * rs), bfs2f(t[0]), xo.x); v.y = fmaf(sigm(v.y * rs), bfs2f(t[1]), xo.y);
;       v.z = fmaf(sigm(v.z * rs), bfs2f(t[2]), xo.z); v.w = fmaf(sigm(v.w * rs), bfs2f(t[3]), xo.w);
;       *(float4*)(xnew + idx) = v;
;       *(bf16x4*)(xb + idx) = pack4(v.x, v.y, v.z, v.w);
;       float s = row16_sum(v.x * v.x + v.y * v.y + v.z * v.z + v.w * v.w);
;       if ((lane & 15) == 0) atomicAdd(ssqn + row, s);
;     });
.LBB0_1667:
	s_or_b64 exec, exec, s[0:1]
	v_add_u32_e32 v64, v105, v67
	v_lshl_add_u32 v72, v64, 10, v128
	v_ashrrev_i32_e32 v73, 31, v72
	v_lshlrev_b64 v[80:81], 1, v[72:73]
	v_lshl_add_u64 v[74:75], s[18:19], 0, v[80:81]
	v_lshl_add_u64 v[84:85], v[72:73], 2, s[12:13]
	v_fmamk_f32 v65, v70, 0x3a800000, v135
	v_mul_f32_e32 v70, 0x4b800000, v65
	v_cmp_gt_f32_e64 s[10:11], s52, v65
	ds_read_b128 v[76:79], v98 offset:2176
	v_lshl_add_u64 v[80:81], s[26:27], 0, v[80:81]
	v_cndmask_b32_e64 v65, v65, v70, s[10:11]
	v_rsq_f32_e32 v65, v65
	s_waitcnt vmcnt(20)
	v_mov_b32_e32 v82, v182
	v_mov_b32_e32 v83, v183
	v_and_b32_e32 v87, 0xffff0000, v83
	v_mul_f32_e32 v70, 0x45800000, v65
	v_cndmask_b32_e64 v65, v65, v70, s[10:11]
	s_waitcnt lgkmcnt(0)
	v_mul_f32_e32 v70, v65, v76
	v_mul_f32_e32 v71, v65, v77
	v_mul_f32_e32 v76, v65, v78
	v_mul_f32_e32 v65, v65, v79
	v_mul_f32_e32 v70, 0xbfb8aa3b, v70
	v_mul_f32_e32 v71, 0xbfb8aa3b, v71
	v_mul_f32_e32 v76, 0xbfb8aa3b, v76
	v_mul_f32_e32 v65, 0xbfb8aa3b, v65
	v_exp_f32_e32 v70, v70
	v_exp_f32_e32 v71, v71
	v_exp_f32_e32 v76, v76
	v_exp_f32_e32 v65, v65
	v_add_f32_e32 v70, 1.0, v70
	v_add_f32_e32 v71, 1.0, v71
	v_add_f32_e32 v76, 1.0, v76
	v_add_f32_e32 v65, 1.0, v65
	v_rcp_f32_e32 v70, v70
	v_rcp_f32_e32 v71, v71
	v_rcp_f32_e32 v76, v76
	v_rcp_f32_e32 v77, v65
	v_and_b32_e32 v79, 0xffff0000, v82
	v_lshlrev_b32_e32 v78, 16, v82
	v_lshlrev_b32_e32 v86, 16, v83
	s_waitcnt vmcnt(19)
	v_mov_b32_e32 v72, v184
	v_mov_b32_e32 v73, v185
	v_mov_b32_e32 v74, v186
	v_mov_b32_e32 v75, v187
	v_pk_fma_f32 v[70:71], v[70:71], v[78:79], v[72:73]
	v_pk_fma_f32 v[72:73], v[76:77], v[86:87], v[74:75]
	global_store_dwordx4 v[84:85], v[70:73], off
	v_cvt_pk_bf16_f32 v74, v70, v71
	v_cvt_pk_bf16_f32 v75, v72, v73
	v_pk_mul_f32 v[70:71], v[70:71], v[70:71]
	v_pk_mul_f32 v[72:73], v[72:73], v[72:73]
	v_add_f32_e32 v65, v70, v71
	v_add_f32_e32 v65, v72, v65
	v_add_f32_e32 v65, v73, v65
	v_mov_b32_e32 v70, 0
	global_store_dwordx2 v[80:81], v[74:75], off
	v_add_f32_dpp v65, v65, v65 quad_perm:[1,0,3,2] row_mask:0xf bank_mask:0xf bound_ctrl:1
	s_nop 1
	v_add_f32_dpp v65, v65, v65 quad_perm:[2,3,0,1] row_mask:0xf bank_mask:0xf bound_ctrl:1
	s_nop 1
	v_add_f32_dpp v65, v65, v65 row_half_mirror row_mask:0xf bank_mask:0xf bound_ctrl:1
	s_nop 1
	v_mov_b32_dpp v70, v65 row_mirror row_mask:0xf bank_mask:0xf
	s_and_saveexec_b64 s[0:1], vcc
	s_cbranch_execz .LBB0_1669
	v_add_f32_e32 v70, v65, v70
	v_ashrrev_i32_e32 v65, 31, v64
	v_lshl_add_u64 v[64:65], v[64:65], 2, s[30:31]
	global_atomic_add_f32 v[64:65], v70, off
.LBB0_1669:
	s_or_b64 exec, exec, s[0:1]
	v_add_u32_e32 v64, v106, v67
	v_lshl_add_u32 v70, v64, 10, v128
	v_ashrrev_i32_e32 v71, 31, v70
	v_lshlrev_b64 v[78:79], 1, v[70:71]
	v_lshl_add_u64 v[72:73], s[18:19], 0, v[78:79]
	v_lshl_add_u64 v[82:83], v[70:71], 2, s[12:13]
	v_fmamk_f32 v65, v69, 0x3a800000, v135
	v_mul_f32_e32 v69, 0x4b800000, v65
	v_cmp_gt_f32_e64 s[10:11], s52, v65
	ds_read_b128 v[74:77], v98 offset:3264
	v_lshl_add_u64 v[78:79], s[26:27], 0, v[78:79]
	v_cndmask_b32_e64 v65, v65, v69, s[10:11]
	v_rsq_f32_e32 v65, v65
	s_waitcnt vmcnt(21)
	v_mov_b32_e32 v80, v188
	v_mov_b32_e32 v81, v189
	v_and_b32_e32 v85, 0xffff0000, v80
	v_mul_f32_e32 v69, 0x45800000, v65
	v_cndmask_b32_e64 v65, v65, v69, s[10:11]
	s_waitcnt lgkmcnt(0)
	v_mul_f32_e32 v69, v65, v74
	v_mul_f32_e32 v74, v65, v75
	v_mul_f32_e32 v75, v65, v76
	v_mul_f32_e32 v65, v65, v77
	v_mul_f32_e32 v69, 0xbfb8aa3b, v69
	v_mul_f32_e32 v74, 0xbfb8aa3b, v74
	v_mul_f32_e32 v75, 0xbfb8aa3b, v75
	v_mul_f32_e32 v65, 0xbfb8aa3b, v65
	v_exp_f32_e32 v69, v69
	v_exp_f32_e32 v74, v74
	v_exp_f32_e32 v75, v75
	v_exp_f32_e32 v65, v65
	v_add_f32_e32 v69, 1.0, v69
	v_add_f32_e32 v76, 1.0, v74
	v_add_f32_e32 v77, 1.0, v75
	v_add_f32_e32 v65, 1.0, v65
	v_rcp_f32_e32 v74, v69
	v_rcp_f32_e32 v75, v76
	v_rcp_f32_e32 v76, v77
	v_rcp_f32_e32 v77, v65
	v_lshlrev_b32_e32 v84, 16, v80
	v_and_b32_e32 v87, 0xffff0000, v81
	v_lshlrev_b32_e32 v86, 16, v81
	s_waitcnt vmcnt(20)
	v_mov_b32_e32 v70, v190
	v_mov_b32_e32 v71, v191
	v_mov_b32_e32 v72, v192
	v_mov_b32_e32 v73, v193
	v_pk_fma_f32 v[70:71], v[74:75], v[84:85], v[70:71]
	v_pk_fma_f32 v[72:73], v[76:77], v[86:87], v[72:73]
	global_store_dwordx4 v[82:83], v[70:73], off
	v_cvt_pk_bf16_f32 v74, v70, v71
	v_cvt_pk_bf16_f32 v75, v72, v73
	v_pk_mul_f32 v[70:71], v[70:71], v[70:71]
	v_pk_mul_f32 v[72:73], v[72:73], v[72:73]
	v_add_f32_e32 v65, v70, v71
	v_add_f32_e32 v65, v72, v65
	v_add_f32_e32 v65, v73, v65
	v_mov_b32_e32 v69, 0
	global_store_dwordx2 v[78:79], v[74:75], off
	v_add_f32_dpp v65, v65, v65 quad_perm:[1,0,3,2] row_mask:0xf bank_mask:0xf bound_ctrl:1
	s_nop 1
	v_add_f32_dpp v65, v65, v65 quad_perm:[2,3,0,1] row_mask:0xf bank_mask:0xf bound_ctrl:1
	s_nop 1
	v_add_f32_dpp v65, v65, v65 row_half_mirror row_mask:0xf bank_mask:0xf bound_ctrl:1
	s_nop 1
	v_mov_b32_dpp v69, v65 row_mirror row_mask:0xf bank_mask:0xf
	s_and_saveexec_b64 s[0:1], vcc
	s_cbranch_execz .LBB0_1671
	v_add_f32_e32 v69, v65, v69
	v_ashrrev_i32_e32 v65, 31, v64
	v_lshl_add_u64 v[64:65], v[64:65], 2, s[30:31]
	global_atomic_add_f32 v[64:65], v69, off
; __device__ __forceinline__ float bfs2f(short h) { return __uint_as_float(((unsigned)(u16)h) << 16); }
; __device__ __forceinline__ float sigm(float x) { return __builtin_amdgcn_rcpf(1.f + __expf(-x)); }
; __device__ __forceinline__ float rs_of(float ss) { return rsqrtf(ss * (1.f / 1024) + EPS); }
;   __device__ __forceinline__ void tile(const float* reg, int row0, int col0, int lane) const {
;     float rsv[8];
; #pragma unroll
;     for (int i = 0; i < 8; ++i) rsv[i] = rs_of(ssq[row0 + i * 4 + (lane >> 4)]);
;     rows4(reg, lane, [&](int it, int rr, int c4, float4 v) {
;       int row = row0 + rr, idx = row * 1024 + col0 + c4;
;       float rs = rsv[it];
;       float4 xo = *(const float4*)(xold + idx);
;       bf16x4 t = *(const bf16x4*)(tmp + idx);
;       v.x = fmaf(sigm(v.x * rs), bfs2f(t[0]), xo.x); v.y = fmaf(sigm(v.y * rs), bfs2f(t[1]), xo.y);
;       v.z = fmaf(sigm(v.z * rs), bfs2f(t[2]), xo.z); v.w = fmaf(sigm(v.w * rs), bfs2f(t[3]), xo.w);
;       *(float4*)(xnew + idx) = v;
;       *(bf16x4*)(xb + idx) = pack4(v.x, v.y, v.z, v.w);
;       float s = row16_sum(v.x * v.x + v.y * v.y + v.z * v.z + v.w * v.w);
;       if ((lane & 15) == 0) atomicAdd(ssqn + row, s);
;     });
; template <int MF, class Epi>
; __device__ __forceinline__ void staged_epilogue(f32x4 (&acc)[MF][4], int row0, int col0, const Epi& epi) {
;     ...
;     for (int mm = 0; mm < 2; ++mm)
; #pragma unroll
;       for (int n = 0; n < 4; ++n)
; #pragma unroll
;         for (int j = 0; j < 4; ++j) reg[(mm * 16 + fq * 4 + j) * 68 + n * 16 + fr] = acc[mp * 2 + mm][n][j];
;     __builtin_amdgcn_fence(__ATOMIC_ACQ_REL, "wavefront");
.LBB0_1671:
	s_or_b64 exec, exec, s[0:1]
	v_add_u32_e32 v64, v107, v67
	v_lshl_add_u32 v70, v64, 10, v128
	v_ashrrev_i32_e32 v71, 31, v70
	v_lshlrev_b64 v[78:79], 1, v[70:71]
	v_lshl_add_u64 v[72:73], s[18:19], 0, v[78:79]
	v_lshl_add_u64 v[82:83], v[70:71], 2, s[12:13]
	v_fmamk_f32 v65, v68, 0x3a800000, v135
	v_mul_f32_e32 v67, 0x4b800000, v65
	v_cmp_gt_f32_e64 s[10:11], s52, v65
	ds_read_b128 v[74:77], v98 offset:4352
	v_lshl_add_u64 v[78:79], s[26:27], 0, v[78:79]
	v_cndmask_b32_e64 v65, v65, v67, s[10:11]
	v_rsq_f32_e32 v65, v65
	s_waitcnt vmcnt(22)
	v_mov_b32_e32 v80, v194
	v_mov_b32_e32 v81, v195
	v_and_b32_e32 v85, 0xffff0000, v81
	v_mul_f32_e32 v67, 0x45800000, v65
	v_cndmask_b32_e64 v65, v65, v67, s[10:11]
	s_waitcnt lgkmcnt(0)
	v_mul_f32_e32 v67, v65, v74
	v_mul_f32_e32 v68, v65, v75
	v_mul_f32_e32 v69, v65, v76
	v_mul_f32_e32 v65, v65, v77
	v_mul_f32_e32 v67, 0xbfb8aa3b, v67
	v_mul_f32_e32 v68, 0xbfb8aa3b, v68
	v_mul_f32_e32 v69, 0xbfb8aa3b, v69
	v_mul_f32_e32 v65, 0xbfb8aa3b, v65
	v_exp_f32_e32 v67, v67
	v_exp_f32_e32 v68, v68
	v_exp_f32_e32 v69, v69
	v_exp_f32_e32 v65, v65
	v_add_f32_e32 v67, 1.0, v67
	v_add_f32_e32 v74, 1.0, v68
	v_add_f32_e32 v75, 1.0, v69
	v_add_f32_e32 v65, 1.0, v65
	v_rcp_f32_e32 v68, v67
	v_rcp_f32_e32 v69, v74
	v_rcp_f32_e32 v74, v75
	v_rcp_f32_e32 v75, v65
	v_and_b32_e32 v77, 0xffff0000, v80
	v_lshlrev_b32_e32 v76, 16, v80
	v_lshlrev_b32_e32 v84, 16, v81
	s_waitcnt vmcnt(21)
	v_mov_b32_e32 v70, v196
	v_mov_b32_e32 v71, v197
	v_mov_b32_e32 v72, v198
	v_mov_b32_e32 v73, v199
	v_pk_fma_f32 v[68:69], v[68:69], v[76:77], v[70:71]
	v_pk_fma_f32 v[70:71], v[74:75], v[84:85], v[72:73]
	global_store_dwordx4 v[82:83], v[68:71], off
	v_cvt_pk_bf16_f32 v72, v68, v69
	v_cvt_pk_bf16_f32 v73, v70, v71
	v_pk_mul_f32 v[68:69], v[68:69], v[68:69]
	v_pk_mul_f32 v[70:71], v[70:71], v[70:71]
	v_add_f32_e32 v65, v68, v69
	v_add_f32_e32 v65, v70, v65
	v_add_f32_e32 v65, v71, v65
	v_mov_b32_e32 v67, 0
	global_store_dwordx2 v[78:79], v[72:73], off
	v_add_f32_dpp v65, v65, v65 quad_perm:[1,0,3,2] row_mask:0xf bank_mask:0xf bound_ctrl:1
	s_nop 1
	v_add_f32_dpp v65, v65, v65 quad_perm:[2,3,0,1] row_mask:0xf bank_mask:0xf bound_ctrl:1
	s_nop 1
	v_add_f32_dpp v65, v65, v65 row_half_mirror row_mask:0xf bank_mask:0xf bound_ctrl:1
	s_nop 1
	v_mov_b32_dpp v67, v65 row_mirror row_mask:0xf bank_mask:0xf
	s_and_saveexec_b64 s[0:1], vcc
	s_cbranch_execz .LBB0_1673
	v_add_f32_e32 v67, v65, v67
	v_ashrrev_i32_e32 v65, 31, v64
	v_lshl_add_u64 v[64:65], v[64:65], 2, s[30:31]
	global_atomic_add_f32 v[64:65], v67, off
.LBB0_1673:
	s_or_b64 exec, exec, s[0:1]
	ds_write2_b32 v131, v56, v60 offset1:16
	ds_write2_b32 v131, v57, v61 offset0:68 offset1:84
	ds_write2_b32 v131, v58, v62 offset0:136 offset1:152
	ds_write2_b32 v131, v59, v63 offset0:204 offset1:220
	ds_write2_b32 v131, v48, v52 offset0:32 offset1:48
	ds_write2_b32 v131, v49, v53 offset0:100 offset1:116
	ds_write2_b32 v131, v50, v54 offset0:168 offset1:184
	ds_write2_b32 v131, v51, v55 offset0:236 offset1:252
	ds_write2_b32 v112, v40, v44 offset0:64 offset1:80
	ds_write2_b32 v112, v41, v45 offset0:132 offset1:148
	ds_write2_b32 v112, v42, v46 offset0:200 offset1:216
	ds_write2_b32 v104, v43, v47 offset0:12 offset1:28
	ds_write2_b32 v112, v32, v36 offset0:96 offset1:112
	ds_write2_b32 v112, v33, v37 offset0:164 offset1:180
	ds_write2_b32 v112, v34, v38 offset0:232 offset1:248
	ds_write2_b32 v104, v35, v39 offset0:44 offset1:60
	v_add_u32_e32 v210, 64, v129
	v_add_u32_e32 v200, v130, v210
	v_ashrrev_i32_e32 v201, 31, v200
	v_lshl_add_u64 v[202:203], v[200:201], 2, s[28:29]
	global_load_dword v144, v[202:203], off
	v_add_u32_e32 v211, 64, v129
	v_add_u32_e32 v210, v130, v211
	v_add_u32_e32 v200, 4, v210
	v_ashrrev_i32_e32 v201, 31, v200
	v_lshl_add_u64 v[200:201], v[200:201], 2, s[28:29]
	global_load_dword v145, v[200:201], off
	v_add_u32_e32 v211, 64, v129
	v_add_u32_e32 v210, v130, v211
	v_add_u32_e32 v200, 8, v210
	v_ashrrev_i32_e32 v201, 31, v200
	v_lshl_add_u64 v[200:201], v[200:201], 2, s[28:29]
	global_load_dword v146, v[200:201], off
	v_add_u32_e32 v211, 64, v129
	v_add_u32_e32 v210, v130, v211
	v_add_u32_e32 v200, 12, v210
	v_ashrrev_i32_e32 v201, 31, v200
	v_lshl_add_u64 v[202:203], v[200:201], 2, s[28:29]
	global_load_dword v147, v[202:203], off
	v_add_u32_e32 v211, 64, v129
	v_add_u32_e32 v210, v130, v211
	v_add_u32_e32 v200, 16, v210
	v_ashrrev_i32_e32 v201, 31, v200
	v_lshl_add_u64 v[202:203], v[200:201], 2, s[28:29]
	global_load_dword v148, v[202:203], off
	v_add_u32_e32 v211, 64, v129
	v_add_u32_e32 v210, v130, v211
	v_add_u32_e32 v200, 20, v210
	v_ashrrev_i32_e32 v201, 31, v200
	v_lshl_add_u64 v[202:203], v[200:201], 2, s[28:29]
	global_load_dword v149, v[202:203], off
	v_add_u32_e32 v211, 64, v129
	v_add_u32_e32 v210, v130, v211
	v_add_u32_e32 v200, 24, v210
	v_ashrrev_i32_e32 v201, 31, v200
	v_lshl_add_u64 v[202:203], v[200:201], 2, s[28:29]
	global_load_dword v150, v[202:203], off
	v_add_u32_e32 v211, 64, v129
	v_add_u32_e32 v210, v130, v211
	v_add_u32_e32 v200, 28, v210
	v_ashrrev_i32_e32 v201, 31, v200
	v_lshl_add_u64 v[202:203], v[200:201], 2, s[28:29]
	global_load_dword v151, v[202:203], off
	v_add_u32_e32 v211, 64, v129
	v_add_u32_e32 v210, v130, v211
	v_lshl_add_u32 v200, v210, 10, v128
	v_ashrrev_i32_e32 v201, 31, v200
	v_lshlrev_b64 v[206:207], 1, v[200:201]
	v_lshl_add_u64 v[202:203], s[18:19], 0, v[206:207]
	global_load_dwordx2 v[152:153], v[202:203], off
	v_add_u32_e32 v211, 64, v129
	v_add_u32_e32 v210, v130, v211
	v_lshl_add_u32 v200, v210, 10, v128
	v_ashrrev_i32_e32 v201, 31, v200
	v_lshl_add_u64 v[202:203], v[200:201], 2, s[12:13]
; __device__ __forceinline__ float bfs2f(short h) { return __uint_as_float(((unsigned)(u16)h) << 16); }
; __device__ __forceinline__ float sigm(float x) { return __builtin_amdgcn_rcpf(1.f + __expf(-x)); }
; __device__ __forceinline__ float rs_of(float ss) { return rsqrtf(ss * (1.f / 1024) + EPS); }
;   __device__ __forceinline__ void tile(const float* reg, int row0, int col0, int lane) const {
;     ...
;     for (int i = 0; i < 8; ++i) rsv[i] = rs_of(ssq[row0 + i * 4 + (lane >> 4)]);
;     rows4(reg, lane, [&](int it, int rr, int c4, float4 v) {
;       int row = row0 + rr, idx = row * 1024 + col0 + c4;
;       float rs = rsv[it];
;       float4 xo = *(const float4*)(xold + idx);
;       bf16x4 t = *(const bf16x4*)(tmp + idx);
;       v.x = fmaf(sigm(v.x * rs), bfs2f(t[0]), xo.x); v.y = fmaf(sigm(v.y * rs), bfs2f(t[1]), xo.y);
;       v.z = fmaf(sigm(v.z * rs), bfs2f(t[2]), xo.z); v.w = fmaf(sigm(v.w * rs), bfs2f(t[3]), xo.w);
;       *(float4*)(xnew + idx) = v;
;       *(bf16x4*)(xb + idx) = pack4(v.x, v.y, v.z, v.w);
;       float s = row16_sum(v.x * v.x + v.y * v.y + v.z * v.z + v.w * v.w);
;       if ((lane & 15) == 0) atomicAdd(ssqn + row, s);
	global_load_dwordx4 v[154:157], v[202:203], off
	v_add_u32_e32 v211, 64, v129
	v_add_u32_e32 v210, v99, v211
	v_lshl_add_u32 v200, v210, 10, v128
	v_ashrrev_i32_e32 v201, 31, v200
	v_lshlrev_b64 v[206:207], 1, v[200:201]
	v_lshl_add_u64 v[202:203], s[18:19], 0, v[206:207]
	global_load_dwordx2 v[158:159], v[202:203], off
	v_add_u32_e32 v211, 64, v129
	v_add_u32_e32 v210, v99, v211
	v_lshl_add_u32 v200, v210, 10, v128
	v_ashrrev_i32_e32 v201, 31, v200
	v_lshl_add_u64 v[202:203], v[200:201], 2, s[12:13]
	global_load_dwordx4 v[160:163], v[202:203], off
	v_add_u32_e32 v211, 64, v129
	v_add_u32_e32 v210, v100, v211
	v_lshl_add_u32 v200, v210, 10, v128
	v_ashrrev_i32_e32 v201, 31, v200
	v_lshlrev_b64 v[206:207], 1, v[200:201]
	v_lshl_add_u64 v[202:203], s[18:19], 0, v[206:207]
	global_load_dwordx2 v[164:165], v[202:203], off
	v_add_u32_e32 v211, 64, v129
	v_add_u32_e32 v210, v100, v211
	v_lshl_add_u32 v200, v210, 10, v128
	v_ashrrev_i32_e32 v201, 31, v200
	v_lshl_add_u64 v[202:203], v[200:201], 2, s[12:13]
	global_load_dwordx4 v[166:169], v[202:203], off
	v_add_u32_e32 v211, 64, v129
	v_add_u32_e32 v210, v101, v211
	v_lshl_add_u32 v200, v210, 10, v128
	v_ashrrev_i32_e32 v201, 31, v200
	v_lshlrev_b64 v[206:207], 1, v[200:201]
	v_lshl_add_u64 v[202:203], s[18:19], 0, v[206:207]
	global_load_dwordx2 v[170:171], v[202:203], off
	v_add_u32_e32 v211, 64, v129
	v_add_u32_e32 v210, v101, v211
	v_lshl_add_u32 v200, v210, 10, v128
	v_ashrrev_i32_e32 v201, 31, v200
	v_lshl_add_u64 v[202:203], v[200:201], 2, s[12:13]
	global_load_dwordx4 v[172:175], v[202:203], off
	v_add_u32_e32 v211, 64, v129
	v_add_u32_e32 v210, v108, v211
	v_lshl_add_u32 v200, v210, 10, v128
	v_ashrrev_i32_e32 v201, 31, v200
	v_lshlrev_b64 v[206:207], 1, v[200:201]
	v_lshl_add_u64 v[202:203], s[18:19], 0, v[206:207]
	global_load_dwordx2 v[176:177], v[202:203], off
	v_add_u32_e32 v211, 64, v129
	v_add_u32_e32 v210, v108, v211
	v_lshl_add_u32 v200, v210, 10, v128
	v_ashrrev_i32_e32 v201, 31, v200
	v_lshl_add_u64 v[202:203], v[200:201], 2, s[12:13]
	global_load_dwordx4 v[178:181], v[202:203], off
	v_add_u32_e32 v211, 64, v129
	v_add_u32_e32 v210, v105, v211
	v_lshl_add_u32 v200, v210, 10, v128
	v_ashrrev_i32_e32 v201, 31, v200
	v_lshlrev_b64 v[206:207], 1, v[200:201]
	v_lshl_add_u64 v[202:203], s[18:19], 0, v[206:207]
	global_load_dwordx2 v[182:183], v[202:203], off
	v_add_u32_e32 v211, 64, v129
	v_add_u32_e32 v210, v105, v211
	v_lshl_add_u32 v200, v210, 10, v128
	v_ashrrev_i32_e32 v201, 31, v200
	v_lshl_add_u64 v[202:203], v[200:201], 2, s[12:13]
	global_load_dwordx4 v[184:187], v[202:203], off
	v_add_u32_e32 v211, 64, v129
	v_add_u32_e32 v210, v106, v211
	v_lshl_add_u32 v200, v210, 10, v128
	v_ashrrev_i32_e32 v201, 31, v200
	v_lshlrev_b64 v[206:207], 1, v[200:201]
	v_lshl_add_u64 v[202:203], s[18:19], 0, v[206:207]
	global_load_dwordx2 v[188:189], v[202:203], off
	v_add_u32_e32 v211, 64, v129
	v_add_u32_e32 v210, v106, v211
	v_lshl_add_u32 v200, v210, 10, v128
	v_ashrrev_i32_e32 v201, 31, v200
	v_lshl_add_u64 v[202:203], v[200:201], 2, s[12:13]
	global_load_dwordx4 v[190:193], v[202:203], off
	v_add_u32_e32 v211, 64, v129
	v_add_u32_e32 v210, v107, v211
	v_lshl_add_u32 v200, v210, 10, v128
	v_ashrrev_i32_e32 v201, 31, v200
	v_lshlrev_b64 v[206:207], 1, v[200:201]
	v_lshl_add_u64 v[202:203], s[18:19], 0, v[206:207]
	global_load_dwordx2 v[194:195], v[202:203], off
	v_add_u32_e32 v211, 64, v129
	v_add_u32_e32 v210, v107, v211
	v_lshl_add_u32 v200, v210, 10, v128
	v_ashrrev_i32_e32 v201, 31, v200
	v_lshl_add_u64 v[202:203], v[200:201], 2, s[12:13]
	global_load_dwordx4 v[196:199], v[202:203], off
	v_add_u32_e32 v34, 64, v129
	v_add_u32_e32 v32, v130, v34
	v_add_u32_e32 v40, 12, v32
	v_ashrrev_i32_e32 v41, 31, v40
	v_lshl_add_u64 v[42:43], v[40:41], 2, s[28:29]
	v_add_u32_e32 v40, 16, v32
	v_ashrrev_i32_e32 v41, 31, v40
	v_lshl_add_u64 v[44:45], v[40:41], 2, s[28:29]
	v_add_u32_e32 v40, 20, v32
	v_ashrrev_i32_e32 v33, 31, v32
	v_ashrrev_i32_e32 v41, 31, v40
	v_lshl_add_u64 v[36:37], v[32:33], 2, s[28:29]
	v_lshl_add_u64 v[46:47], v[40:41], 2, s[28:29]
	v_add_u32_e32 v40, 24, v32
	v_add_u32_e32 v36, 4, v32
	v_add_u32_e32 v38, 8, v32
	v_ashrrev_i32_e32 v41, 31, v40
	v_ashrrev_i32_e32 v37, 31, v36
	v_ashrrev_i32_e32 v39, 31, v38
	v_lshl_add_u64 v[48:49], v[40:41], 2, s[28:29]
	v_add_u32_e32 v40, 28, v32
	v_lshl_add_u64 v[36:37], v[36:37], 2, s[28:29]
	v_lshl_add_u64 v[38:39], v[38:39], 2, s[28:29]
	v_ashrrev_i32_e32 v41, 31, v40
	v_lshl_add_u64 v[50:51], v[40:41], 2, s[28:29]
	s_nop 0
	s_waitcnt vmcnt(23)
	v_mov_b32_e32 v52, v144
	v_fmamk_f32 v42, v52, 0x3a800000, v135
	v_mul_f32_e32 v43, 0x4b800000, v42
	v_cmp_gt_f32_e64 s[10:11], s52, v42
	s_nop 1
	v_cndmask_b32_e64 v42, v42, v43, s[10:11]
	v_rsq_f32_e32 v42, v42
	s_nop 0
	v_mul_f32_e32 v43, 0x45800000, v42
	v_cndmask_b32_e64 v56, v42, v43, s[10:11]
	v_lshl_add_u32 v42, v32, 10, v128
	v_ashrrev_i32_e32 v43, 31, v42
	v_lshlrev_b64 v[50:51], 1, v[42:43]
	v_lshl_add_u64 v[44:45], s[18:19], 0, v[50:51]
	v_lshl_add_u64 v[54:55], v[42:43], 2, s[12:13]
	ds_read_b128 v[46:49], v66
	v_lshl_add_u64 v[50:51], s[26:27], 0, v[50:51]
	s_waitcnt lgkmcnt(0)
	v_mul_f32_e32 v46, v56, v46
	v_mul_f32_e32 v47, v56, v47
	v_mul_f32_e32 v48, v56, v48
	v_mul_f32_e32 v49, v56, v49
	v_mul_f32_e32 v46, 0xbfb8aa3b, v46
	v_mul_f32_e32 v47, 0xbfb8aa3b, v47
	v_mul_f32_e32 v48, 0xbfb8aa3b, v48
	v_mul_f32_e32 v49, 0xbfb8aa3b, v49
	v_exp_f32_e32 v46, v46
	v_exp_f32_e32 v47, v47
	v_exp_f32_e32 v48, v48
	v_exp_f32_e32 v49, v49
	v_add_f32_e32 v46, 1.0, v46
	v_add_f32_e32 v47, 1.0, v47
	v_add_f32_e32 v48, 1.0, v48
	v_add_f32_e32 v49, 1.0, v49
	v_rcp_f32_e32 v46, v46
	v_rcp_f32_e32 v47, v47
	v_rcp_f32_e32 v48, v48
	v_rcp_f32_e32 v49, v49
	s_waitcnt vmcnt(15)
; __device__ __forceinline__ float bfs2f(short h) { return __uint_as_float(((unsigned)(u16)h) << 16); }
; __device__ __forceinline__ float sigm(float x) { return __builtin_amdgcn_rcpf(1.f + __expf(-x)); }
;   __device__ __forceinline__ void tile(const float* reg, int row0, int col0, int lane) const {
;     ...
;     rows4(reg, lane, [&](int it, int rr, int c4, float4 v) {
;       int row = row0 + rr, idx = row * 1024 + col0 + c4;
;       float rs = rsv[it];
;       float4 xo = *(const float4*)(xold + idx);
;       bf16x4 t = *(const bf16x4*)(tmp + idx);
;       v.x = fmaf(sigm(v.x * rs), bfs2f(t[0]), xo.x); v.y = fmaf(sigm(v.y * rs), bfs2f(t[1]), xo.y);
;       v.z = fmaf(sigm(v.z * rs), bfs2f(t[2]), xo.z); v.w = fmaf(sigm(v.w * rs), bfs2f(t[3]), xo.w);
;       *(float4*)(xnew + idx) = v;
;       *(bf16x4*)(xb + idx) = pack4(v.x, v.y, v.z, v.w);
;       float s = row16_sum(v.x * v.x + v.y * v.y + v.z * v.z + v.w * v.w);
;       if ((lane & 15) == 0) atomicAdd(ssqn + row, s);
;     });
	v_mov_b32_e32 v41, v145
	v_mov_b32_e32 v40, v146
	v_mov_b32_e32 v39, v147
	v_mov_b32_e32 v38, v148
	v_mov_b32_e32 v37, v149
	v_mov_b32_e32 v36, v150
	v_mov_b32_e32 v35, v151
	v_mov_b32_e32 v52, v152
	v_mov_b32_e32 v53, v153
	v_and_b32_e32 v57, 0xffff0000, v52
	v_lshlrev_b32_e32 v56, 16, v52
	v_and_b32_e32 v59, 0xffff0000, v53
	v_lshlrev_b32_e32 v58, 16, v53
	s_waitcnt vmcnt(14)
	v_mov_b32_e32 v42, v154
	v_mov_b32_e32 v43, v155
	v_mov_b32_e32 v44, v156
	v_mov_b32_e32 v45, v157
	v_pk_fma_f32 v[42:43], v[46:47], v[56:57], v[42:43]
	v_pk_fma_f32 v[44:45], v[48:49], v[58:59], v[44:45]
	global_store_dwordx4 v[54:55], v[42:45], off
	v_cvt_pk_bf16_f32 v46, v42, v43
	v_cvt_pk_bf16_f32 v47, v44, v45
	v_pk_mul_f32 v[42:43], v[42:43], v[42:43]
	v_pk_mul_f32 v[44:45], v[44:45], v[44:45]
	v_add_f32_e32 v42, v42, v43
	v_add_f32_e32 v42, v44, v42
	v_add_f32_e32 v42, v45, v42
	v_mov_b32_e32 v43, 0
	global_store_dwordx2 v[50:51], v[46:47], off
	v_add_f32_dpp v42, v42, v42 quad_perm:[1,0,3,2] row_mask:0xf bank_mask:0xf bound_ctrl:1
	s_nop 1
	v_add_f32_dpp v42, v42, v42 quad_perm:[2,3,0,1] row_mask:0xf bank_mask:0xf bound_ctrl:1
	s_nop 1
	v_add_f32_dpp v42, v42, v42 row_half_mirror row_mask:0xf bank_mask:0xf bound_ctrl:1
	s_nop 1
	v_mov_b32_dpp v43, v42 row_mirror row_mask:0xf bank_mask:0xf
	s_and_saveexec_b64 s[0:1], vcc
	s_cbranch_execz .LBB0_1675
	v_add_f32_e32 v42, v42, v43
	v_lshl_add_u64 v[32:33], v[32:33], 2, s[30:31]
	global_atomic_add_f32 v[32:33], v42, off
.LBB0_1675:
	s_or_b64 exec, exec, s[0:1]
	v_add_u32_e32 v32, v99, v34
	v_lshl_add_u32 v42, v32, 10, v128
	v_ashrrev_i32_e32 v43, 31, v42
	v_lshlrev_b64 v[50:51], 1, v[42:43]
	v_lshl_add_u64 v[44:45], s[18:19], 0, v[50:51]
	v_lshl_add_u64 v[54:55], v[42:43], 2, s[12:13]
	v_fmamk_f32 v33, v41, 0x3a800000, v135
	v_mul_f32_e32 v41, 0x4b800000, v33
	v_cmp_gt_f32_e64 s[10:11], s52, v33
	ds_read_b128 v[46:49], v102
	v_lshl_add_u64 v[50:51], s[26:27], 0, v[50:51]
	v_cndmask_b32_e64 v33, v33, v41, s[10:11]
	v_rsq_f32_e32 v33, v33
	s_waitcnt vmcnt(16)
	v_mov_b32_e32 v52, v158
	v_mov_b32_e32 v53, v159
	v_and_b32_e32 v57, 0xffff0000, v52
	v_mul_f32_e32 v41, 0x45800000, v33
	v_cndmask_b32_e64 v33, v33, v41, s[10:11]
	s_waitcnt lgkmcnt(0)
	v_mul_f32_e32 v41, v33, v46
	v_mul_f32_e32 v46, v33, v47
	v_mul_f32_e32 v47, v33, v48
	v_mul_f32_e32 v33, v33, v49
	v_mul_f32_e32 v41, 0xbfb8aa3b, v41
	v_mul_f32_e32 v46, 0xbfb8aa3b, v46
	v_mul_f32_e32 v47, 0xbfb8aa3b, v47
	v_mul_f32_e32 v33, 0xbfb8aa3b, v33
	v_exp_f32_e32 v41, v41
	v_exp_f32_e32 v46, v46
	v_exp_f32_e32 v47, v47
	v_exp_f32_e32 v33, v33
	v_add_f32_e32 v41, 1.0, v41
	v_add_f32_e32 v48, 1.0, v46
	v_add_f32_e32 v49, 1.0, v47
	v_add_f32_e32 v33, 1.0, v33
	v_rcp_f32_e32 v46, v41
	v_rcp_f32_e32 v47, v48
	v_rcp_f32_e32 v48, v49
	v_rcp_f32_e32 v49, v33
	v_lshlrev_b32_e32 v56, 16, v52
	v_and_b32_e32 v59, 0xffff0000, v53
	v_lshlrev_b32_e32 v58, 16, v53
	s_waitcnt vmcnt(15)
	v_mov_b32_e32 v42, v160
	v_mov_b32_e32 v43, v161
	v_mov_b32_e32 v44, v162
	v_mov_b32_e32 v45, v163
	v_pk_fma_f32 v[42:43], v[46:47], v[56:57], v[42:43]
	v_pk_fma_f32 v[44:45], v[48:49], v[58:59], v[44:45]
	global_store_dwordx4 v[54:55], v[42:45], off
	v_cvt_pk_bf16_f32 v46, v42, v43
	v_cvt_pk_bf16_f32 v47, v44, v45
	v_pk_mul_f32 v[42:43], v[42:43], v[42:43]
	v_pk_mul_f32 v[44:45], v[44:45], v[44:45]
	v_add_f32_e32 v33, v42, v43
	v_add_f32_e32 v33, v44, v33
	v_add_f32_e32 v33, v45, v33
	v_mov_b32_e32 v41, 0
	global_store_dwordx2 v[50:51], v[46:47], off
	v_add_f32_dpp v33, v33, v33 quad_perm:[1,0,3,2] row_mask:0xf bank_mask:0xf bound_ctrl:1
	s_nop 1
	v_add_f32_dpp v33, v33, v33 quad_perm:[2,3,0,1] row_mask:0xf bank_mask:0xf bound_ctrl:1
	s_nop 1
	v_add_f32_dpp v33, v33, v33 row_half_mirror row_mask:0xf bank_mask:0xf bound_ctrl:1
	s_nop 1
	v_mov_b32_dpp v41, v33 row_mirror row_mask:0xf bank_mask:0xf
	s_and_saveexec_b64 s[0:1], vcc
	s_cbranch_execz .LBB0_1677
	v_add_f32_e32 v41, v33, v41
	v_ashrrev_i32_e32 v33, 31, v32
	v_lshl_add_u64 v[32:33], v[32:33], 2, s[30:31]
	global_atomic_add_f32 v[32:33], v41, off
.LBB0_1677:
	s_or_b64 exec, exec, s[0:1]
	v_add_u32_e32 v32, v100, v34
	v_lshl_add_u32 v42, v32, 10, v128
	v_ashrrev_i32_e32 v43, 31, v42
	v_lshlrev_b64 v[50:51], 1, v[42:43]
	v_lshl_add_u64 v[44:45], s[18:19], 0, v[50:51]
	v_lshl_add_u64 v[54:55], v[42:43], 2, s[12:13]
	v_fmamk_f32 v33, v40, 0x3a800000, v135
	v_mul_f32_e32 v40, 0x4b800000, v33
	v_cmp_gt_f32_e64 s[10:11], s52, v33
	ds_read_b128 v[46:49], v103
	v_lshl_add_u64 v[50:51], s[26:27], 0, v[50:51]
	v_cndmask_b32_e64 v33, v33, v40, s[10:11]
	v_rsq_f32_e32 v33, v33
	s_waitcnt vmcnt(17)
	v_mov_b32_e32 v52, v164
	v_mov_b32_e32 v53, v165
	v_and_b32_e32 v57, 0xffff0000, v53
	v_mul_f32_e32 v40, 0x45800000, v33
	v_cndmask_b32_e64 v33, v33, v40, s[10:11]
	s_waitcnt lgkmcnt(0)
	v_mul_f32_e32 v40, v33, v46
	v_mul_f32_e32 v41, v33, v47
	v_mul_f32_e32 v46, v33, v48
	v_mul_f32_e32 v33, v33, v49
	v_mul_f32_e32 v40, 0xbfb8aa3b, v40
	v_mul_f32_e32 v41, 0xbfb8aa3b, v41
	v_mul_f32_e32 v46, 0xbfb8aa3b, v46
	v_mul_f32_e32 v33, 0xbfb8aa3b, v33
	v_exp_f32_e32 v40, v40
	v_exp_f32_e32 v41, v41
	v_exp_f32_e32 v46, v46
	v_exp_f32_e32 v33, v33
	v_add_f32_e32 v40, 1.0, v40
	v_add_f32_e32 v41, 1.0, v41
	v_add_f32_e32 v46, 1.0, v46
	v_add_f32_e32 v33, 1.0, v33
	v_rcp_f32_e32 v40, v40
	v_rcp_f32_e32 v41, v41
	v_rcp_f32_e32 v46, v46
	v_rcp_f32_e32 v47, v33
	v_and_b32_e32 v49, 0xffff0000, v52
	v_lshlrev_b32_e32 v48, 16, v52
	v_lshlrev_b32_e32 v56, 16, v53
	s_waitcnt vmcnt(16)
	v_mov_b32_e32 v42, v166
	v_mov_b32_e32 v43, v167
	v_mov_b32_e32 v44, v168
	v_mov_b32_e32 v45, v169
	v_pk_fma_f32 v[40:41], v[40:41], v[48:49], v[42:43]
	v_pk_fma_f32 v[42:43], v[46:47], v[56:57], v[44:45]
	global_store_dwordx4 v[54:55], v[40:43], off
	v_cvt_pk_bf16_f32 v44, v40, v41
	v_cvt_pk_bf16_f32 v45, v42, v43
	v_pk_mul_f32 v[40:41], v[40:41], v[40:41]
	v_pk_mul_f32 v[42:43], v[42:43], v[42:43]
	v_add_f32_e32 v33, v40, v41
	v_add_f32_e32 v33, v42, v33
	v_add_f32_e32 v33, v43, v33
	v_mov_b32_e32 v40, 0
	global_store_dwordx2 v[50:51], v[44:45], off
	v_add_f32_dpp v33, v33, v33 quad_perm:[1,0,3,2] row_mask:0xf bank_mask:0xf bound_ctrl:1
	s_nop 1
	v_add_f32_dpp v33, v33, v33 quad_perm:[2,3,0,1] row_mask:0xf bank_mask:0xf bound_ctrl:1
	s_nop 1
	v_add_f32_dpp v33, v33, v33 row_half_mirror row_mask:0xf bank_mask:0xf bound_ctrl:1
	s_nop 1
	v_mov_b32_dpp v40, v33 row_mirror row_mask:0xf bank_mask:0xf
	s_and_saveexec_b64 s[0:1], vcc
	s_cbranch_execz .LBB0_1679
	v_add_f32_e32 v40, v33, v40
	v_ashrrev_i32_e32 v33, 31, v32
	v_lshl_add_u64 v[32:33], v[32:33], 2, s[30:31]
	global_atomic_add_f32 v[32:33], v40, off
; __device__ __forceinline__ float bfs2f(short h) { return __uint_as_float(((unsigned)(u16)h) << 16); }
; __device__ __forceinline__ float sigm(float x) { return __builtin_amdgcn_rcpf(1.f + __expf(-x)); }
;   __device__ __forceinline__ void tile(const float* reg, int row0, int col0, int lane) const {
;     ...
;     rows4(reg, lane, [&](int it, int rr, int c4, float4 v) {
;       int row = row0 + rr, idx = row * 1024 + col0 + c4;
;       float rs = rsv[it];
;       float4 xo = *(const float4*)(xold + idx);
;       bf16x4 t = *(const bf16x4*)(tmp + idx);
;       v.x = fmaf(sigm(v.x * rs), bfs2f(t[0]), xo.x); v.y = fmaf(sigm(v.y * rs), bfs2f(t[1]), xo.y);
;       v.z = fmaf(sigm(v.z * rs), bfs2f(t[2]), xo.z); v.w = fmaf(sigm(v.w * rs), bfs2f(t[3]), xo.w);
;       *(float4*)(xnew + idx) = v;
;       *(bf16x4*)(xb + idx) = pack4(v.x, v.y, v.z, v.w);
;       float s = row16_sum(v.x * v.x + v.y * v.y + v.z * v.z + v.w * v.w);
;       if ((lane & 15) == 0) atomicAdd(ssqn + row, s);
;     });
.LBB0_1679:
	s_or_b64 exec, exec, s[0:1]
	v_add_u32_e32 v32, v101, v34
	v_lshl_add_u32 v40, v32, 10, v128
	v_ashrrev_i32_e32 v41, 31, v40
	v_lshlrev_b64 v[48:49], 1, v[40:41]
	v_lshl_add_u64 v[42:43], s[18:19], 0, v[48:49]
	v_lshl_add_u64 v[52:53], v[40:41], 2, s[12:13]
	v_fmamk_f32 v33, v39, 0x3a800000, v135
	v_mul_f32_e32 v39, 0x4b800000, v33
	v_cmp_gt_f32_e64 s[10:11], s52, v33
	ds_read_b128 v[44:47], v98
	v_lshl_add_u64 v[48:49], s[26:27], 0, v[48:49]
	v_cndmask_b32_e64 v33, v33, v39, s[10:11]
	v_rsq_f32_e32 v33, v33
	s_waitcnt vmcnt(18)
	v_mov_b32_e32 v50, v170
	v_mov_b32_e32 v51, v171
	v_and_b32_e32 v55, 0xffff0000, v50
	v_mul_f32_e32 v39, 0x45800000, v33
	v_cndmask_b32_e64 v33, v33, v39, s[10:11]
	s_waitcnt lgkmcnt(0)
	v_mul_f32_e32 v39, v33, v44
	v_mul_f32_e32 v44, v33, v45
	v_mul_f32_e32 v45, v33, v46
	v_mul_f32_e32 v33, v33, v47
	v_mul_f32_e32 v39, 0xbfb8aa3b, v39
	v_mul_f32_e32 v44, 0xbfb8aa3b, v44
	v_mul_f32_e32 v45, 0xbfb8aa3b, v45
	v_mul_f32_e32 v33, 0xbfb8aa3b, v33
	v_exp_f32_e32 v39, v39
	v_exp_f32_e32 v44, v44
	v_exp_f32_e32 v45, v45
	v_exp_f32_e32 v33, v33
	v_add_f32_e32 v39, 1.0, v39
	v_add_f32_e32 v46, 1.0, v44
	v_add_f32_e32 v47, 1.0, v45
	v_add_f32_e32 v33, 1.0, v33
	v_rcp_f32_e32 v44, v39
	v_rcp_f32_e32 v45, v46
	v_rcp_f32_e32 v46, v47
	v_rcp_f32_e32 v47, v33
	v_lshlrev_b32_e32 v54, 16, v50
	v_and_b32_e32 v57, 0xffff0000, v51
	v_lshlrev_b32_e32 v56, 16, v51
	s_waitcnt vmcnt(17)
	v_mov_b32_e32 v40, v172
	v_mov_b32_e32 v41, v173
	v_mov_b32_e32 v42, v174
	v_mov_b32_e32 v43, v175
	v_pk_fma_f32 v[40:41], v[44:45], v[54:55], v[40:41]
	v_pk_fma_f32 v[42:43], v[46:47], v[56:57], v[42:43]
	global_store_dwordx4 v[52:53], v[40:43], off
	v_cvt_pk_bf16_f32 v44, v40, v41
	v_cvt_pk_bf16_f32 v45, v42, v43
	v_pk_mul_f32 v[40:41], v[40:41], v[40:41]
	v_pk_mul_f32 v[42:43], v[42:43], v[42:43]
	v_add_f32_e32 v33, v40, v41
	v_add_f32_e32 v33, v42, v33
	v_add_f32_e32 v33, v43, v33
	v_mov_b32_e32 v39, 0
	global_store_dwordx2 v[48:49], v[44:45], off
	v_add_f32_dpp v33, v33, v33 quad_perm:[1,0,3,2] row_mask:0xf bank_mask:0xf bound_ctrl:1
	s_nop 1
	v_add_f32_dpp v33, v33, v33 quad_perm:[2,3,0,1] row_mask:0xf bank_mask:0xf bound_ctrl:1
	s_nop 1
	v_add_f32_dpp v33, v33, v33 row_half_mirror row_mask:0xf bank_mask:0xf bound_ctrl:1
	s_nop 1
	v_mov_b32_dpp v39, v33 row_mirror row_mask:0xf bank_mask:0xf
	s_and_saveexec_b64 s[0:1], vcc
	s_cbranch_execz .LBB0_1681
	v_add_f32_e32 v39, v33, v39
	v_ashrrev_i32_e32 v33, 31, v32
	v_lshl_add_u64 v[32:33], v[32:33], 2, s[30:31]
	global_atomic_add_f32 v[32:33], v39, off
.LBB0_1681:
	s_or_b64 exec, exec, s[0:1]
	v_fmamk_f32 v32, v38, 0x3a800000, v135
	v_mul_f32_e32 v33, 0x4b800000, v32
	v_cmp_gt_f32_e64 s[10:11], s52, v32
	s_nop 1
	v_cndmask_b32_e64 v32, v32, v33, s[10:11]
	v_rsq_f32_e32 v32, v32
	s_nop 0
	v_mul_f32_e32 v33, 0x45800000, v32
	v_cndmask_b32_e64 v33, v32, v33, s[10:11]
	v_add_u32_e32 v32, v108, v34
	v_lshl_add_u32 v38, v32, 10, v128
	v_ashrrev_i32_e32 v39, 31, v38
	v_lshlrev_b64 v[46:47], 1, v[38:39]
	v_lshl_add_u64 v[40:41], s[18:19], 0, v[46:47]
	v_lshl_add_u64 v[50:51], v[38:39], 2, s[12:13]
	ds_read_b128 v[42:45], v98 offset:1088
	v_lshl_add_u64 v[46:47], s[26:27], 0, v[46:47]
	s_waitcnt lgkmcnt(0)
	v_mul_f32_e32 v42, v33, v42
	v_mul_f32_e32 v43, v33, v43
	v_mul_f32_e32 v44, v33, v44
	v_mul_f32_e32 v33, v33, v45
	v_mul_f32_e32 v42, 0xbfb8aa3b, v42
	v_mul_f32_e32 v43, 0xbfb8aa3b, v43
	v_mul_f32_e32 v44, 0xbfb8aa3b, v44
	v_mul_f32_e32 v33, 0xbfb8aa3b, v33
	v_exp_f32_e32 v42, v42
	v_exp_f32_e32 v43, v43
	v_exp_f32_e32 v44, v44
	v_exp_f32_e32 v33, v33
	v_add_f32_e32 v42, 1.0, v42
	v_add_f32_e32 v43, 1.0, v43
	v_add_f32_e32 v44, 1.0, v44
	v_add_f32_e32 v33, 1.0, v33
	v_rcp_f32_e32 v42, v42
	v_rcp_f32_e32 v43, v43
	v_rcp_f32_e32 v44, v44
	v_rcp_f32_e32 v45, v33
	s_waitcnt vmcnt(19)
	v_mov_b32_e32 v48, v176
	v_mov_b32_e32 v49, v177
	v_and_b32_e32 v53, 0xffff0000, v48
	v_lshlrev_b32_e32 v52, 16, v48
	v_and_b32_e32 v55, 0xffff0000, v49
	v_lshlrev_b32_e32 v54, 16, v49
	s_waitcnt vmcnt(18)
	v_mov_b32_e32 v38, v178
	v_mov_b32_e32 v39, v179
	v_mov_b32_e32 v40, v180
	v_mov_b32_e32 v41, v181
	v_pk_fma_f32 v[38:39], v[42:43], v[52:53], v[38:39]
	v_pk_fma_f32 v[40:41], v[44:45], v[54:55], v[40:41]
	global_store_dwordx4 v[50:51], v[38:41], off
	v_cvt_pk_bf16_f32 v42, v38, v39
	v_cvt_pk_bf16_f32 v43, v40, v41
	v_pk_mul_f32 v[38:39], v[38:39], v[38:39]
	v_pk_mul_f32 v[40:41], v[40:41], v[40:41]
	v_add_f32_e32 v33, v38, v39
	v_add_f32_e32 v33, v40, v33
	v_add_f32_e32 v33, v41, v33
	v_mov_b32_e32 v38, 0
	global_store_dwordx2 v[46:47], v[42:43], off
	v_add_f32_dpp v33, v33, v33 quad_perm:[1,0,3,2] row_mask:0xf bank_mask:0xf bound_ctrl:1
	s_nop 1
	v_add_f32_dpp v33, v33, v33 quad_perm:[2,3,0,1] row_mask:0xf bank_mask:0xf bound_ctrl:1
	s_nop 1
	v_add_f32_dpp v33, v33, v33 row_half_mirror row_mask:0xf bank_mask:0xf bound_ctrl:1
	s_nop 1
	v_mov_b32_dpp v38, v33 row_mirror row_mask:0xf bank_mask:0xf
	s_and_saveexec_b64 s[0:1], vcc
	s_cbranch_execz .LBB0_1683
	v_add_f32_e32 v38, v33, v38
	v_ashrrev_i32_e32 v33, 31, v32
	v_lshl_add_u64 v[32:33], v[32:33], 2, s[30:31]
	global_atomic_add_f32 v[32:33], v38, off
; __device__ __forceinline__ float bfs2f(short h) { return __uint_as_float(((unsigned)(u16)h) << 16); }
; __device__ __forceinline__ float sigm(float x) { return __builtin_amdgcn_rcpf(1.f + __expf(-x)); }
;   __device__ __forceinline__ void tile(const float* reg, int row0, int col0, int lane) const {
;     ...
;     rows4(reg, lane, [&](int it, int rr, int c4, float4 v) {
;       int row = row0 + rr, idx = row * 1024 + col0 + c4;
;       float rs = rsv[it];
;       float4 xo = *(const float4*)(xold + idx);
;       bf16x4 t = *(const bf16x4*)(tmp + idx);
;       v.x = fmaf(sigm(v.x * rs), bfs2f(t[0]), xo.x); v.y = fmaf(sigm(v.y * rs), bfs2f(t[1]), xo.y);
;       v.z = fmaf(sigm(v.z * rs), bfs2f(t[2]), xo.z); v.w = fmaf(sigm(v.w * rs), bfs2f(t[3]), xo.w);
;       *(float4*)(xnew + idx) = v;
;       *(bf16x4*)(xb + idx) = pack4(v.x, v.y, v.z, v.w);
;       float s = row16_sum(v.x * v.x + v.y * v.y + v.z * v.z + v.w * v.w);
;       if ((lane & 15) == 0) atomicAdd(ssqn + row, s);
;     });
.LBB0_1683:
	s_or_b64 exec, exec, s[0:1]
	v_add_u32_e32 v32, v105, v34
	v_lshl_add_u32 v38, v32, 10, v128
	v_ashrrev_i32_e32 v39, 31, v38
	v_lshlrev_b64 v[46:47], 1, v[38:39]
	v_lshl_add_u64 v[40:41], s[18:19], 0, v[46:47]
	v_lshl_add_u64 v[50:51], v[38:39], 2, s[12:13]
	v_fmamk_f32 v33, v37, 0x3a800000, v135
	v_mul_f32_e32 v37, 0x4b800000, v33
	v_cmp_gt_f32_e64 s[10:11], s52, v33
	ds_read_b128 v[42:45], v98 offset:2176
	v_lshl_add_u64 v[46:47], s[26:27], 0, v[46:47]
	v_cndmask_b32_e64 v33, v33, v37, s[10:11]
	v_rsq_f32_e32 v33, v33
	s_waitcnt vmcnt(20)
	v_mov_b32_e32 v48, v182
	v_mov_b32_e32 v49, v183
	v_and_b32_e32 v53, 0xffff0000, v48
	v_mul_f32_e32 v37, 0x45800000, v33
	v_cndmask_b32_e64 v33, v33, v37, s[10:11]
	s_waitcnt lgkmcnt(0)
	v_mul_f32_e32 v37, v33, v42
	v_mul_f32_e32 v42, v33, v43
	v_mul_f32_e32 v43, v33, v44
	v_mul_f32_e32 v33, v33, v45
	v_mul_f32_e32 v37, 0xbfb8aa3b, v37
	v_mul_f32_e32 v42, 0xbfb8aa3b, v42
	v_mul_f32_e32 v43, 0xbfb8aa3b, v43
	v_mul_f32_e32 v33, 0xbfb8aa3b, v33
	v_exp_f32_e32 v37, v37
	v_exp_f32_e32 v42, v42
	v_exp_f32_e32 v43, v43
	v_exp_f32_e32 v33, v33
	v_add_f32_e32 v37, 1.0, v37
	v_add_f32_e32 v44, 1.0, v42
	v_add_f32_e32 v45, 1.0, v43
	v_add_f32_e32 v33, 1.0, v33
	v_rcp_f32_e32 v42, v37
	v_rcp_f32_e32 v43, v44
	v_rcp_f32_e32 v44, v45
	v_rcp_f32_e32 v45, v33
	v_lshlrev_b32_e32 v52, 16, v48
	v_and_b32_e32 v55, 0xffff0000, v49
	v_lshlrev_b32_e32 v54, 16, v49
	s_waitcnt vmcnt(19)
	v_mov_b32_e32 v38, v184
	v_mov_b32_e32 v39, v185
	v_mov_b32_e32 v40, v186
	v_mov_b32_e32 v41, v187
	v_pk_fma_f32 v[38:39], v[42:43], v[52:53], v[38:39]
	v_pk_fma_f32 v[40:41], v[44:45], v[54:55], v[40:41]
	global_store_dwordx4 v[50:51], v[38:41], off
	v_cvt_pk_bf16_f32 v42, v38, v39
	v_cvt_pk_bf16_f32 v43, v40, v41
	v_pk_mul_f32 v[38:39], v[38:39], v[38:39]
	v_pk_mul_f32 v[40:41], v[40:41], v[40:41]
	v_add_f32_e32 v33, v38, v39
	v_add_f32_e32 v33, v40, v33
	v_add_f32_e32 v33, v41, v33
	v_mov_b32_e32 v37, 0
	global_store_dwordx2 v[46:47], v[42:43], off
	v_add_f32_dpp v33, v33, v33 quad_perm:[1,0,3,2] row_mask:0xf bank_mask:0xf bound_ctrl:1
	s_nop 1
	v_add_f32_dpp v33, v33, v33 quad_perm:[2,3,0,1] row_mask:0xf bank_mask:0xf bound_ctrl:1
	s_nop 1
	v_add_f32_dpp v33, v33, v33 row_half_mirror row_mask:0xf bank_mask:0xf bound_ctrl:1
	s_nop 1
	v_mov_b32_dpp v37, v33 row_mirror row_mask:0xf bank_mask:0xf
	s_and_saveexec_b64 s[0:1], vcc
	s_cbranch_execz .LBB0_1685
	v_add_f32_e32 v37, v33, v37
	v_ashrrev_i32_e32 v33, 31, v32
	v_lshl_add_u64 v[32:33], v[32:33], 2, s[30:31]
	global_atomic_add_f32 v[32:33], v37, off
; __device__ __forceinline__ float bfs2f(short h) { return __uint_as_float(((unsigned)(u16)h) << 16); }
; __device__ __forceinline__ float sigm(float x) { return __builtin_amdgcn_rcpf(1.f + __expf(-x)); }
;   __device__ __forceinline__ void tile(const float* reg, int row0, int col0, int lane) const {
;     ...
;     rows4(reg, lane, [&](int it, int rr, int c4, float4 v) {
;       int row = row0 + rr, idx = row * 1024 + col0 + c4;
;       float rs = rsv[it];
;       float4 xo = *(const float4*)(xold + idx);
;       bf16x4 t = *(const bf16x4*)(tmp + idx);
;       v.x = fmaf(sigm(v.x * rs), bfs2f(t[0]), xo.x); v.y = fmaf(sigm(v.y * rs), bfs2f(t[1]), xo.y);
;       v.z = fmaf(sigm(v.z * rs), bfs2f(t[2]), xo.z); v.w = fmaf(sigm(v.w * rs), bfs2f(t[3]), xo.w);
;       *(float4*)(xnew + idx) = v;
;       *(bf16x4*)(xb + idx) = pack4(v.x, v.y, v.z, v.w);
;       float s = row16_sum(v.x * v.x + v.y * v.y + v.z * v.z + v.w * v.w);
;       if ((lane & 15) == 0) atomicAdd(ssqn + row, s);
;     });
.LBB0_1685:
	s_or_b64 exec, exec, s[0:1]
	v_add_u32_e32 v32, v106, v34
	v_lshl_add_u32 v38, v32, 10, v128
	v_ashrrev_i32_e32 v39, 31, v38
	v_lshlrev_b64 v[46:47], 1, v[38:39]
	v_lshl_add_u64 v[40:41], s[18:19], 0, v[46:47]
	v_lshl_add_u64 v[50:51], v[38:39], 2, s[12:13]
	v_fmamk_f32 v33, v36, 0x3a800000, v135
	v_mul_f32_e32 v36, 0x4b800000, v33
	v_cmp_gt_f32_e64 s[10:11], s52, v33
	ds_read_b128 v[42:45], v98 offset:3264
	v_lshl_add_u64 v[46:47], s[26:27], 0, v[46:47]
	v_cndmask_b32_e64 v33, v33, v36, s[10:11]
	v_rsq_f32_e32 v33, v33
	s_waitcnt vmcnt(21)
	v_mov_b32_e32 v48, v188
	v_mov_b32_e32 v49, v189
	v_and_b32_e32 v53, 0xffff0000, v49
	v_mul_f32_e32 v36, 0x45800000, v33
	v_cndmask_b32_e64 v33, v33, v36, s[10:11]
	s_waitcnt lgkmcnt(0)
	v_mul_f32_e32 v36, v33, v42
	v_mul_f32_e32 v37, v33, v43
	v_mul_f32_e32 v42, v33, v44
	v_mul_f32_e32 v33, v33, v45
	v_mul_f32_e32 v36, 0xbfb8aa3b, v36
	v_mul_f32_e32 v37, 0xbfb8aa3b, v37
	v_mul_f32_e32 v42, 0xbfb8aa3b, v42
	v_mul_f32_e32 v33, 0xbfb8aa3b, v33
	v_exp_f32_e32 v36, v36
	v_exp_f32_e32 v37, v37
	v_exp_f32_e32 v42, v42
	v_exp_f32_e32 v33, v33
	v_add_f32_e32 v36, 1.0, v36
	v_add_f32_e32 v37, 1.0, v37
	v_add_f32_e32 v42, 1.0, v42
	v_add_f32_e32 v33, 1.0, v33
	v_rcp_f32_e32 v36, v36
	v_rcp_f32_e32 v37, v37
	v_rcp_f32_e32 v42, v42
	v_rcp_f32_e32 v43, v33
	v_and_b32_e32 v45, 0xffff0000, v48
	v_lshlrev_b32_e32 v44, 16, v48
	v_lshlrev_b32_e32 v52, 16, v49
	s_waitcnt vmcnt(20)
	v_mov_b32_e32 v38, v190
	v_mov_b32_e32 v39, v191
	v_mov_b32_e32 v40, v192
	v_mov_b32_e32 v41, v193
	v_pk_fma_f32 v[36:37], v[36:37], v[44:45], v[38:39]
	v_pk_fma_f32 v[38:39], v[42:43], v[52:53], v[40:41]
	global_store_dwordx4 v[50:51], v[36:39], off
	v_cvt_pk_bf16_f32 v40, v36, v37
	v_cvt_pk_bf16_f32 v41, v38, v39
	v_pk_mul_f32 v[36:37], v[36:37], v[36:37]
	v_pk_mul_f32 v[38:39], v[38:39], v[38:39]
	v_add_f32_e32 v33, v36, v37
	v_add_f32_e32 v33, v38, v33
	v_add_f32_e32 v33, v39, v33
	v_mov_b32_e32 v36, 0
	global_store_dwordx2 v[46:47], v[40:41], off
	v_add_f32_dpp v33, v33, v33 quad_perm:[1,0,3,2] row_mask:0xf bank_mask:0xf bound_ctrl:1
	s_nop 1
	v_add_f32_dpp v33, v33, v33 quad_perm:[2,3,0,1] row_mask:0xf bank_mask:0xf bound_ctrl:1
	s_nop 1
	v_add_f32_dpp v33, v33, v33 row_half_mirror row_mask:0xf bank_mask:0xf bound_ctrl:1
	s_nop 1
	v_mov_b32_dpp v36, v33 row_mirror row_mask:0xf bank_mask:0xf
	s_and_saveexec_b64 s[0:1], vcc
	s_cbranch_execz .LBB0_1687
	v_add_f32_e32 v36, v33, v36
	v_ashrrev_i32_e32 v33, 31, v32
	v_lshl_add_u64 v[32:33], v[32:33], 2, s[30:31]
	global_atomic_add_f32 v[32:33], v36, off
.LBB0_1687:
	s_or_b64 exec, exec, s[0:1]
	v_add_u32_e32 v32, v107, v34
	v_lshl_add_u32 v36, v32, 10, v128
	v_ashrrev_i32_e32 v37, 31, v36
	v_lshlrev_b64 v[44:45], 1, v[36:37]
	v_lshl_add_u64 v[38:39], s[18:19], 0, v[44:45]
	v_lshl_add_u64 v[48:49], v[36:37], 2, s[12:13]
	v_fmamk_f32 v33, v35, 0x3a800000, v135
	v_mul_f32_e32 v34, 0x4b800000, v33
	v_cmp_gt_f32_e64 s[10:11], s52, v33
	ds_read_b128 v[40:43], v98 offset:4352
	v_lshl_add_u64 v[44:45], s[26:27], 0, v[44:45]
	v_cndmask_b32_e64 v33, v33, v34, s[10:11]
	v_rsq_f32_e32 v33, v33
	s_waitcnt vmcnt(22)
	v_mov_b32_e32 v46, v194
	v_mov_b32_e32 v47, v195
	v_and_b32_e32 v51, 0xffff0000, v47
	v_mul_f32_e32 v34, 0x45800000, v33
	v_cndmask_b32_e64 v33, v33, v34, s[10:11]
	s_waitcnt lgkmcnt(0)
	v_mul_f32_e32 v34, v33, v40
	v_mul_f32_e32 v35, v33, v41
	v_mul_f32_e32 v40, v33, v42
	v_mul_f32_e32 v33, v33, v43
	v_mul_f32_e32 v34, 0xbfb8aa3b, v34
	v_mul_f32_e32 v35, 0xbfb8aa3b, v35
	v_mul_f32_e32 v40, 0xbfb8aa3b, v40
	v_mul_f32_e32 v33, 0xbfb8aa3b, v33
	v_exp_f32_e32 v34, v34
	v_exp_f32_e32 v35, v35
	v_exp_f32_e32 v40, v40
	v_exp_f32_e32 v33, v33
	v_add_f32_e32 v34, 1.0, v34
	v_add_f32_e32 v35, 1.0, v35
	v_add_f32_e32 v40, 1.0, v40
	v_add_f32_e32 v33, 1.0, v33
	v_rcp_f32_e32 v34, v34
	v_rcp_f32_e32 v35, v35
	v_rcp_f32_e32 v40, v40
	v_rcp_f32_e32 v41, v33
	v_and_b32_e32 v43, 0xffff0000, v46
	v_lshlrev_b32_e32 v42, 16, v46
	v_lshlrev_b32_e32 v50, 16, v47
	s_waitcnt vmcnt(21)
	v_mov_b32_e32 v36, v196
	v_mov_b32_e32 v37, v197
	v_mov_b32_e32 v38, v198
	v_mov_b32_e32 v39, v199
	v_pk_fma_f32 v[34:35], v[34:35], v[42:43], v[36:37]
	v_pk_fma_f32 v[36:37], v[40:41], v[50:51], v[38:39]
	global_store_dwordx4 v[48:49], v[34:37], off
	v_cvt_pk_bf16_f32 v38, v34, v35
	v_cvt_pk_bf16_f32 v39, v36, v37
	v_pk_mul_f32 v[34:35], v[34:35], v[34:35]
	v_pk_mul_f32 v[36:37], v[36:37], v[36:37]
	v_add_f32_e32 v33, v34, v35
	v_add_f32_e32 v33, v36, v33
	v_add_f32_e32 v33, v37, v33
	v_mov_b32_e32 v34, 0
	global_store_dwordx2 v[44:45], v[38:39], off
	v_add_f32_dpp v33, v33, v33 quad_perm:[1,0,3,2] row_mask:0xf bank_mask:0xf bound_ctrl:1
	s_nop 1
	v_add_f32_dpp v33, v33, v33 quad_perm:[2,3,0,1] row_mask:0xf bank_mask:0xf bound_ctrl:1
	s_nop 1
	v_add_f32_dpp v33, v33, v33 row_half_mirror row_mask:0xf bank_mask:0xf bound_ctrl:1
	s_nop 1
	v_mov_b32_dpp v34, v33 row_mirror row_mask:0xf bank_mask:0xf
	s_and_saveexec_b64 s[0:1], vcc
	s_cbranch_execz .LBB0_1689
	v_add_f32_e32 v34, v33, v34
	v_ashrrev_i32_e32 v33, 31, v32
	v_lshl_add_u64 v[32:33], v[32:33], 2, s[30:31]
	global_atomic_add_f32 v[32:33], v34, off

; __device__ __forceinline__ float bfs2f(short h) { return __uint_as_float(((unsigned)(u16)h) << 16); }
;   __device__ __forceinline__ void tile(const float* reg, int row0, int col0, int lane) const {
;     rows4(reg, lane, [&](int it, int rr, int c4, float4 v) {
;       int idx = (row0 + rr) * 1024 + col0 + c4;
;       bf16x4 gt = *(const bf16x4*)(gate + idx);
;       *(bf16x4*)(merged + idx) = pack4(bfs2f(gt[0]) * v.x, bfs2f(gt[1]) * v.y, bfs2f(gt[2]) * v.z, bfs2f(gt[3]) * v.w);
;     });
; template <int MF, class Epi>
; __device__ __forceinline__ void staged_epilogue(f32x4 (&acc)[MF][4], int row0, int col0, const Epi& epi) {
;   const int lane = tidx() & 63, wid = tidx() >> 6, fr = lane & 15, fq = lane >> 4;
;   float* reg = (float*)(g_shm + 65536 + wid * 8704);
; #pragma unroll
;   for (int mp = 0; mp < MF / 2; ++mp) {
;     __builtin_amdgcn_sched_barrier(0);
; #pragma unroll
;     for (int mm = 0; mm < 2; ++mm)
; #pragma unroll
;       for (int n = 0; n < 4; ++n)
; #pragma unroll
;         for (int j = 0; j < 4; ++j) reg[(mm * 16 + fq * 4 + j) * 68 + n * 16 + fr] = acc[mp * 2 + mm][n][j];
;     __builtin_amdgcn_fence(__ATOMIC_ACQ_REL, "wavefront");
;     epi.tile(reg, row0 + mp * 32, col0, lane);
.LBB0_3009:
	v_mov_b32_e32 v128, v204
	v_mov_b32_e32 v130, v204
	s_nop 0
	v_lshrrev_b32_e32 v130, 6, v130
	v_mul_lo_u32 v130, v130, s52
	v_and_b32_e32 v131, 15, v128
	v_add_u32_e32 v130, 0x10000, v130
	v_lshrrev_b32_e32 v134, 2, v128
	v_bfe_u32 v140, v128, 4, 2
	v_lshlrev_b32_e32 v128, 2, v128
	v_lshl_or_b32 v142, v131, 2, v130
	v_and_b32_e32 v131, 60, v128
	v_lshl_or_b32 v128, v131, 2, v130
	v_and_b32_e32 v141, 12, v134
	v_mad_u32_u24 v128, v140, s53, v128
	v_add_u32_e32 v129, v131, v129
	v_or_b32_e32 v139, 4, v140
	v_or_b32_e32 v138, 8, v140
	v_or_b32_e32 v137, 12, v140
	v_or_b32_e32 v136, 16, v140
	v_or_b32_e32 v134, 20, v140
	v_or_b32_e32 v131, 24, v140
	v_or_b32_e32 v130, 28, v140
	v_mad_u32_u24 v141, v141, s53, v142
	ds_write2_b32 v141, v120, v124 offset1:16
	ds_write2_b32 v141, v121, v125 offset0:68 offset1:84
	ds_write2_b32 v141, v122, v126 offset0:136 offset1:152
	ds_write2_b32 v141, v123, v127 offset0:204 offset1:220
	ds_write2_b32 v141, v112, v116 offset0:32 offset1:48
	ds_write2_b32 v141, v113, v117 offset0:100 offset1:116
	ds_write2_b32 v141, v114, v118 offset0:168 offset1:184
	ds_write2_b32 v141, v115, v119 offset0:236 offset1:252
	v_add_u32_e32 v112, 0x1000, v141
	ds_write2_b32 v112, v104, v108 offset0:64 offset1:80
	ds_write2_b32 v112, v105, v109 offset0:132 offset1:148
	ds_write2_b32 v112, v106, v110 offset0:200 offset1:216
	v_add_u32_e32 v104, 0x1400, v141
	ds_write2_b32 v104, v107, v111 offset0:12 offset1:28
	ds_write2_b32 v112, v96, v100 offset0:96 offset1:112
	ds_write2_b32 v112, v97, v101 offset0:164 offset1:180
	ds_write2_b32 v112, v98, v102 offset0:232 offset1:248
	ds_write2_b32 v104, v99, v103 offset0:44 offset1:60
	v_add_u32_e32 v176, v140, v135
	v_lshl_add_u32 v176, v176, 10, v129
	v_ashrrev_i32_e32 v177, 31, v176
	v_lshlrev_b64 v[178:179], 1, v[176:177]
	v_lshl_add_u64 v[176:177], s[14:15], 0, v[178:179]
	global_load_dwordx2 v[144:145], v[176:177], off
	v_add_u32_e32 v184, v139, v135
	v_lshl_add_u32 v176, v184, 10, v129
	v_ashrrev_i32_e32 v177, 31, v176
	v_lshlrev_b64 v[176:177], 1, v[176:177]
	v_lshl_add_u64 v[178:179], s[14:15], 0, v[176:177]
	global_load_dwordx2 v[146:147], v[178:179], off
	v_add_u32_e32 v176, v138, v135
	v_lshl_add_u32 v176, v176, 10, v129
	v_ashrrev_i32_e32 v177, 31, v176
	v_lshlrev_b64 v[178:179], 1, v[176:177]
	v_lshl_add_u64 v[180:181], s[14:15], 0, v[178:179]
	global_load_dwordx2 v[148:149], v[180:181], off
	v_add_u32_e32 v184, v137, v135
	v_lshl_add_u32 v176, v184, 10, v129
	v_ashrrev_i32_e32 v177, 31, v176
	v_lshlrev_b64 v[176:177], 1, v[176:177]
	v_lshl_add_u64 v[178:179], s[14:15], 0, v[176:177]
	global_load_dwordx2 v[150:151], v[178:179], off
	v_add_u32_e32 v176, v136, v135
	v_lshl_add_u32 v176, v176, 10, v129
	v_ashrrev_i32_e32 v177, 31, v176
	v_lshlrev_b64 v[178:179], 1, v[176:177]
	v_lshl_add_u64 v[176:177], s[14:15], 0, v[178:179]
	global_load_dwordx2 v[152:153], v[176:177], off
	v_add_u32_e32 v184, v134, v135
	v_lshl_add_u32 v176, v184, 10, v129
	v_ashrrev_i32_e32 v177, 31, v176
	v_lshlrev_b64 v[176:177], 1, v[176:177]
	v_lshl_add_u64 v[178:179], s[14:15], 0, v[176:177]
	global_load_dwordx2 v[154:155], v[178:179], off
	v_add_u32_e32 v176, v131, v135
	v_lshl_add_u32 v176, v176, 10, v129
	v_ashrrev_i32_e32 v177, 31, v176
	v_lshlrev_b64 v[178:179], 1, v[176:177]
	v_lshl_add_u64 v[180:181], s[14:15], 0, v[178:179]
	global_load_dwordx2 v[156:157], v[180:181], off
	v_add_u32_e32 v184, v130, v135
	v_lshl_add_u32 v176, v184, 10, v129
	v_ashrrev_i32_e32 v177, 31, v176
	v_lshlrev_b64 v[176:177], 1, v[176:177]
	v_lshl_add_u64 v[178:179], s[14:15], 0, v[176:177]
	global_load_dwordx2 v[158:159], v[178:179], off
	v_add_u32_e32 v96, v140, v135
	v_lshl_add_u32 v96, v96, 10, v129
	v_ashrrev_i32_e32 v97, 31, v96
	v_lshlrev_b64 v[106:107], 1, v[96:97]
	v_lshl_add_u64 v[96:97], s[14:15], 0, v[106:107]
	s_waitcnt vmcnt(7)
	v_mov_b32_e32 v108, v144
	v_mov_b32_e32 v109, v145
	ds_read_b128 v[96:99], v128
	ds_read_b128 v[100:103], v128 offset:1088
	v_add_u32_e32 v105, v139, v135
	v_lshl_add_u32 v110, v105, 10, v129
	v_ashrrev_i32_e32 v111, 31, v110
	v_lshlrev_b64 v[110:111], 1, v[110:111]
	v_lshl_add_u64 v[106:107], s[12:13], 0, v[106:107]
	v_lshl_add_u64 v[114:115], s[14:15], 0, v[110:111]
	v_add_u32_e32 v105, v137, v135
	v_and_b32_e32 v117, 0xffff0000, v108
	v_lshlrev_b32_e32 v116, 16, v108
	v_and_b32_e32 v119, 0xffff0000, v109
	v_lshlrev_b32_e32 v118, 16, v109
	s_waitcnt lgkmcnt(0)
	v_pk_mul_f32 v[96:97], v[96:97], v[116:117]
	v_pk_mul_f32 v[98:99], v[98:99], v[118:119]
	v_cvt_pk_bf16_f32 v96, v96, v97
	v_cvt_pk_bf16_f32 v97, v98, v99
	global_store_dwordx2 v[106:107], v[96:97], off
	v_add_u32_e32 v98, v138, v135
	v_lshl_add_u32 v98, v98, 10, v129
	v_ashrrev_i32_e32 v99, 31, v98
	v_lshlrev_b64 v[106:107], 1, v[98:99]
	v_lshl_add_u64 v[98:99], s[12:13], 0, v[110:111]
	v_lshl_add_u64 v[108:109], s[14:15], 0, v[106:107]
	v_lshl_add_u64 v[106:107], s[12:13], 0, v[106:107]
	s_waitcnt vmcnt(7)
	v_mov_b32_e32 v96, v146
	v_mov_b32_e32 v97, v147
	v_and_b32_e32 v111, 0xffff0000, v96
	v_lshlrev_b32_e32 v110, 16, v96
	v_and_b32_e32 v115, 0xffff0000, v97
	v_lshlrev_b32_e32 v114, 16, v97
	v_pk_mul_f32 v[96:97], v[100:101], v[110:111]
	v_pk_mul_f32 v[100:101], v[102:103], v[114:115]
	v_cvt_pk_bf16_f32 v96, v96, v97
	v_cvt_pk_bf16_f32 v97, v100, v101
	global_store_dwordx2 v[98:99], v[96:97], off
	ds_read_b128 v[96:99], v128 offset:2176
	ds_read_b128 v[100:103], v128 offset:3264
	v_lshl_add_u32 v110, v105, 10, v129
	v_ashrrev_i32_e32 v111, 31, v110
	v_lshlrev_b64 v[110:111], 1, v[110:111]
	v_lshl_add_u64 v[114:115], s[14:15], 0, v[110:111]
	s_waitcnt vmcnt(7)
; __device__ __forceinline__ float bfs2f(short h) { return __uint_as_float(((unsigned)(u16)h) << 16); }
;   __device__ __forceinline__ void tile(const float* reg, int row0, int col0, int lane) const {
;     rows4(reg, lane, [&](int it, int rr, int c4, float4 v) {
;       int idx = (row0 + rr) * 1024 + col0 + c4;
;       bf16x4 gt = *(const bf16x4*)(gate + idx);
;       *(bf16x4*)(merged + idx) = pack4(bfs2f(gt[0]) * v.x, bfs2f(gt[1]) * v.y, bfs2f(gt[2]) * v.z, bfs2f(gt[3]) * v.w);
;     });
; template <int MF, class Epi>
; __device__ __forceinline__ void staged_epilogue(f32x4 (&acc)[MF][4], int row0, int col0, const Epi& epi) {
;     ...
;     for (int mm = 0; mm < 2; ++mm)
; #pragma unroll
;       for (int n = 0; n < 4; ++n)
; #pragma unroll
;         for (int j = 0; j < 4; ++j) reg[(mm * 16 + fq * 4 + j) * 68 + n * 16 + fr] = acc[mp * 2 + mm][n][j];
	v_mov_b32_e32 v108, v148
	v_mov_b32_e32 v109, v149
	v_and_b32_e32 v117, 0xffff0000, v108
	v_lshlrev_b32_e32 v116, 16, v108
	v_and_b32_e32 v119, 0xffff0000, v109
	v_lshlrev_b32_e32 v118, 16, v109
	s_waitcnt lgkmcnt(1)
	v_pk_mul_f32 v[96:97], v[96:97], v[116:117]
	v_pk_mul_f32 v[98:99], v[98:99], v[118:119]
	v_cvt_pk_bf16_f32 v96, v96, v97
	v_cvt_pk_bf16_f32 v97, v98, v99
	global_store_dwordx2 v[106:107], v[96:97], off
	s_waitcnt vmcnt(7)
	v_mov_b32_e32 v96, v150
	v_mov_b32_e32 v97, v151
	v_and_b32_e32 v99, 0xffff0000, v96
	v_lshlrev_b32_e32 v98, 16, v96
	v_and_b32_e32 v107, 0xffff0000, v97
	v_lshlrev_b32_e32 v106, 16, v97
	s_waitcnt lgkmcnt(0)
	v_pk_mul_f32 v[96:97], v[100:101], v[98:99]
	v_pk_mul_f32 v[98:99], v[102:103], v[106:107]
	v_cvt_pk_bf16_f32 v96, v96, v97
	v_cvt_pk_bf16_f32 v97, v98, v99
	v_lshl_add_u64 v[98:99], s[12:13], 0, v[110:111]
	global_store_dwordx2 v[98:99], v[96:97], off
	v_add_u32_e32 v96, v136, v135
	v_lshl_add_u32 v96, v96, 10, v129
	v_ashrrev_i32_e32 v97, 31, v96
	v_lshlrev_b64 v[106:107], 1, v[96:97]
	v_lshl_add_u64 v[96:97], s[14:15], 0, v[106:107]
	ds_read_b128 v[96:99], v128 offset:4352
	ds_read_b128 v[100:103], v128 offset:5440
	v_add_u32_e32 v105, v134, v135
	v_lshl_add_u32 v110, v105, 10, v129
	v_ashrrev_i32_e32 v111, 31, v110
	v_lshlrev_b64 v[110:111], 1, v[110:111]
	v_lshl_add_u64 v[106:107], s[12:13], 0, v[106:107]
	v_lshl_add_u64 v[114:115], s[14:15], 0, v[110:111]
	v_add_u32_e32 v105, v130, v135
	s_waitcnt vmcnt(7)
	v_mov_b32_e32 v108, v152
	v_mov_b32_e32 v109, v153
	v_and_b32_e32 v117, 0xffff0000, v108
	v_lshlrev_b32_e32 v116, 16, v108
	v_and_b32_e32 v119, 0xffff0000, v109
	v_lshlrev_b32_e32 v118, 16, v109
	s_waitcnt lgkmcnt(1)
	v_pk_mul_f32 v[96:97], v[96:97], v[116:117]
	v_pk_mul_f32 v[98:99], v[98:99], v[118:119]
	v_cvt_pk_bf16_f32 v96, v96, v97
	v_cvt_pk_bf16_f32 v97, v98, v99
	global_store_dwordx2 v[106:107], v[96:97], off
	v_add_u32_e32 v98, v131, v135
	v_lshl_add_u32 v98, v98, 10, v129
	v_ashrrev_i32_e32 v99, 31, v98
	v_lshlrev_b64 v[106:107], 1, v[98:99]
	v_lshl_add_u64 v[98:99], s[12:13], 0, v[110:111]
	v_lshl_add_u64 v[108:109], s[14:15], 0, v[106:107]
	v_lshl_add_u64 v[106:107], s[12:13], 0, v[106:107]
	s_waitcnt vmcnt(7)
	v_mov_b32_e32 v96, v154
	v_mov_b32_e32 v97, v155
	v_and_b32_e32 v111, 0xffff0000, v96
	v_lshlrev_b32_e32 v110, 16, v96
	v_and_b32_e32 v115, 0xffff0000, v97
	v_lshlrev_b32_e32 v114, 16, v97
	s_waitcnt lgkmcnt(0)
	v_pk_mul_f32 v[96:97], v[100:101], v[110:111]
	v_pk_mul_f32 v[100:101], v[102:103], v[114:115]
	v_cvt_pk_bf16_f32 v96, v96, v97
	v_cvt_pk_bf16_f32 v97, v100, v101
	global_store_dwordx2 v[98:99], v[96:97], off
	ds_read_b128 v[96:99], v128 offset:6528
	ds_read_b128 v[100:103], v128 offset:7616
	v_lshl_add_u32 v110, v105, 10, v129
	v_ashrrev_i32_e32 v111, 31, v110
	v_lshlrev_b64 v[110:111], 1, v[110:111]
	v_lshl_add_u64 v[114:115], s[14:15], 0, v[110:111]
	s_waitcnt vmcnt(7)
	v_mov_b32_e32 v108, v156
	v_mov_b32_e32 v109, v157
	v_and_b32_e32 v117, 0xffff0000, v108
	v_lshlrev_b32_e32 v116, 16, v108
	v_and_b32_e32 v119, 0xffff0000, v109
	v_lshlrev_b32_e32 v118, 16, v109
	s_waitcnt lgkmcnt(1)
	v_pk_mul_f32 v[96:97], v[96:97], v[116:117]
	v_pk_mul_f32 v[98:99], v[98:99], v[118:119]
	v_cvt_pk_bf16_f32 v96, v96, v97
	v_cvt_pk_bf16_f32 v97, v98, v99
	global_store_dwordx2 v[106:107], v[96:97], off
	v_lshl_add_u64 v[98:99], s[12:13], 0, v[110:111]
	s_waitcnt vmcnt(7)
	v_mov_b32_e32 v96, v158
	v_mov_b32_e32 v97, v159
	v_and_b32_e32 v107, 0xffff0000, v96
	v_lshlrev_b32_e32 v106, 16, v96
	v_and_b32_e32 v109, 0xffff0000, v97
	v_lshlrev_b32_e32 v108, 16, v97
	s_waitcnt lgkmcnt(0)
	v_pk_mul_f32 v[96:97], v[100:101], v[106:107]
	v_pk_mul_f32 v[100:101], v[102:103], v[108:109]
	v_cvt_pk_bf16_f32 v96, v96, v97
	v_cvt_pk_bf16_f32 v97, v100, v101
	global_store_dwordx2 v[98:99], v[96:97], off
	ds_write2_b32 v141, v88, v92 offset1:16
	ds_write2_b32 v141, v89, v93 offset0:68 offset1:84
	ds_write2_b32 v141, v90, v94 offset0:136 offset1:152
	ds_write2_b32 v141, v91, v95 offset0:204 offset1:220
	ds_write2_b32 v141, v80, v84 offset0:32 offset1:48
	ds_write2_b32 v141, v81, v85 offset0:100 offset1:116
	ds_write2_b32 v141, v82, v86 offset0:168 offset1:184
	ds_write2_b32 v141, v83, v87 offset0:236 offset1:252
	ds_write2_b32 v112, v72, v76 offset0:64 offset1:80
	ds_write2_b32 v112, v73, v77 offset0:132 offset1:148
	ds_write2_b32 v112, v74, v78 offset0:200 offset1:216
	ds_write2_b32 v104, v75, v79 offset0:12 offset1:28
	ds_write2_b32 v112, v64, v68 offset0:96 offset1:112
	ds_write2_b32 v112, v65, v69 offset0:164 offset1:180
	ds_write2_b32 v112, v66, v70 offset0:232 offset1:248
	ds_write2_b32 v104, v67, v71 offset0:44 offset1:60
	v_add_u32_e32 v184, 32, v135
	v_add_u32_e32 v176, v140, v184
	v_lshl_add_u32 v176, v176, 10, v129
	v_ashrrev_i32_e32 v177, 31, v176
	v_lshlrev_b64 v[178:179], 1, v[176:177]
	v_lshl_add_u64 v[176:177], s[14:15], 0, v[178:179]
	global_load_dwordx2 v[144:145], v[176:177], off
	v_add_u32_e32 v184, 32, v135
	v_add_u32_e32 v176, v139, v184
	v_lshl_add_u32 v176, v176, 10, v129
	v_ashrrev_i32_e32 v177, 31, v176
	v_lshlrev_b64 v[176:177], 1, v[176:177]
	v_lshl_add_u64 v[178:179], s[14:15], 0, v[176:177]
	global_load_dwordx2 v[146:147], v[178:179], off
	v_add_u32_e32 v184, 32, v135
	v_add_u32_e32 v176, v138, v184
	v_lshl_add_u32 v176, v176, 10, v129
	v_ashrrev_i32_e32 v177, 31, v176
	v_lshlrev_b64 v[178:179], 1, v[176:177]
	v_lshl_add_u64 v[180:181], s[14:15], 0, v[178:179]
	global_load_dwordx2 v[148:149], v[180:181], off
	v_add_u32_e32 v184, 32, v135
	v_add_u32_e32 v176, v137, v184
	v_lshl_add_u32 v176, v176, 10, v129
	v_ashrrev_i32_e32 v177, 31, v176
	v_lshlrev_b64 v[176:177], 1, v[176:177]
; __device__ __forceinline__ float bfs2f(short h) { return __uint_as_float(((unsigned)(u16)h) << 16); }
;   __device__ __forceinline__ void tile(const float* reg, int row0, int col0, int lane) const {
;     rows4(reg, lane, [&](int it, int rr, int c4, float4 v) {
;       int idx = (row0 + rr) * 1024 + col0 + c4;
;       bf16x4 gt = *(const bf16x4*)(gate + idx);
;       *(bf16x4*)(merged + idx) = pack4(bfs2f(gt[0]) * v.x, bfs2f(gt[1]) * v.y, bfs2f(gt[2]) * v.z, bfs2f(gt[3]) * v.w);
;     });
	v_lshl_add_u64 v[178:179], s[14:15], 0, v[176:177]
	global_load_dwordx2 v[150:151], v[178:179], off
	v_add_u32_e32 v184, 32, v135
	v_add_u32_e32 v176, v136, v184
	v_lshl_add_u32 v176, v176, 10, v129
	v_ashrrev_i32_e32 v177, 31, v176
	v_lshlrev_b64 v[178:179], 1, v[176:177]
	v_lshl_add_u64 v[176:177], s[14:15], 0, v[178:179]
	global_load_dwordx2 v[152:153], v[176:177], off
	v_add_u32_e32 v184, 32, v135
	v_add_u32_e32 v176, v134, v184
	v_lshl_add_u32 v176, v176, 10, v129
	v_ashrrev_i32_e32 v177, 31, v176
	v_lshlrev_b64 v[176:177], 1, v[176:177]
	v_lshl_add_u64 v[178:179], s[14:15], 0, v[176:177]
	global_load_dwordx2 v[154:155], v[178:179], off
	v_add_u32_e32 v184, 32, v135
	v_add_u32_e32 v176, v131, v184
	v_lshl_add_u32 v176, v176, 10, v129
	v_ashrrev_i32_e32 v177, 31, v176
	v_lshlrev_b64 v[178:179], 1, v[176:177]
	v_lshl_add_u64 v[180:181], s[14:15], 0, v[178:179]
	global_load_dwordx2 v[156:157], v[180:181], off
	v_add_u32_e32 v184, 32, v135
	v_add_u32_e32 v176, v130, v184
	v_lshl_add_u32 v176, v176, 10, v129
	v_ashrrev_i32_e32 v177, 31, v176
	v_lshlrev_b64 v[176:177], 1, v[176:177]
	v_lshl_add_u64 v[178:179], s[14:15], 0, v[176:177]
	global_load_dwordx2 v[158:159], v[178:179], off
	v_add_u32_e32 v84, 32, v135
	v_add_u32_e32 v64, v140, v84
	v_lshl_add_u32 v64, v64, 10, v129
	v_ashrrev_i32_e32 v65, 31, v64
	v_lshlrev_b64 v[72:73], 1, v[64:65]
	v_lshl_add_u64 v[64:65], s[14:15], 0, v[72:73]
	ds_read_b128 v[64:67], v128
	ds_read_b128 v[68:71], v128 offset:1088
	v_add_u32_e32 v76, v139, v84
	v_lshl_add_u32 v76, v76, 10, v129
	v_ashrrev_i32_e32 v77, 31, v76
	v_lshlrev_b64 v[76:77], 1, v[76:77]
	v_lshl_add_u64 v[72:73], s[12:13], 0, v[72:73]
	v_lshl_add_u64 v[78:79], s[14:15], 0, v[76:77]
	s_waitcnt vmcnt(7)
	v_mov_b32_e32 v74, v144
	v_mov_b32_e32 v75, v145
	v_and_b32_e32 v81, 0xffff0000, v74
	v_lshlrev_b32_e32 v80, 16, v74
	v_and_b32_e32 v83, 0xffff0000, v75
	v_lshlrev_b32_e32 v82, 16, v75
	s_waitcnt lgkmcnt(1)
	v_pk_mul_f32 v[64:65], v[64:65], v[80:81]
	v_pk_mul_f32 v[66:67], v[66:67], v[82:83]
	v_cvt_pk_bf16_f32 v64, v64, v65
	v_cvt_pk_bf16_f32 v65, v66, v67
	global_store_dwordx2 v[72:73], v[64:65], off
	v_add_u32_e32 v66, v138, v84
	v_lshl_add_u32 v66, v66, 10, v129
	v_ashrrev_i32_e32 v67, 31, v66
	v_lshlrev_b64 v[72:73], 1, v[66:67]
	v_lshl_add_u64 v[66:67], s[12:13], 0, v[76:77]
	v_lshl_add_u64 v[74:75], s[14:15], 0, v[72:73]
	v_lshl_add_u64 v[72:73], s[12:13], 0, v[72:73]
	s_waitcnt vmcnt(7)
	v_mov_b32_e32 v64, v146
	v_mov_b32_e32 v65, v147
	v_and_b32_e32 v77, 0xffff0000, v64
	v_lshlrev_b32_e32 v76, 16, v64
	v_and_b32_e32 v79, 0xffff0000, v65
	v_lshlrev_b32_e32 v78, 16, v65
	s_waitcnt lgkmcnt(0)
	v_pk_mul_f32 v[64:65], v[68:69], v[76:77]
	v_pk_mul_f32 v[68:69], v[70:71], v[78:79]
	v_cvt_pk_bf16_f32 v64, v64, v65
	v_cvt_pk_bf16_f32 v65, v68, v69
	global_store_dwordx2 v[66:67], v[64:65], off
	ds_read_b128 v[64:67], v128 offset:2176
	ds_read_b128 v[68:71], v128 offset:3264
	v_add_u32_e32 v76, v137, v84
	v_lshl_add_u32 v76, v76, 10, v129
	v_ashrrev_i32_e32 v77, 31, v76
	v_lshlrev_b64 v[76:77], 1, v[76:77]
	v_lshl_add_u64 v[78:79], s[14:15], 0, v[76:77]
	s_waitcnt vmcnt(7)
	v_mov_b32_e32 v74, v148
	v_mov_b32_e32 v75, v149
	v_and_b32_e32 v81, 0xffff0000, v74
	v_lshlrev_b32_e32 v80, 16, v74
	v_and_b32_e32 v83, 0xffff0000, v75
	v_lshlrev_b32_e32 v82, 16, v75
	s_waitcnt lgkmcnt(1)
	v_pk_mul_f32 v[64:65], v[64:65], v[80:81]
	v_pk_mul_f32 v[66:67], v[66:67], v[82:83]
	v_cvt_pk_bf16_f32 v64, v64, v65
	v_cvt_pk_bf16_f32 v65, v66, v67
	global_store_dwordx2 v[72:73], v[64:65], off
	s_waitcnt vmcnt(7)
	v_mov_b32_e32 v64, v150
	v_mov_b32_e32 v65, v151
	v_and_b32_e32 v67, 0xffff0000, v64
	v_lshlrev_b32_e32 v66, 16, v64
	v_and_b32_e32 v73, 0xffff0000, v65
	v_lshlrev_b32_e32 v72, 16, v65
	s_waitcnt lgkmcnt(0)
	v_pk_mul_f32 v[64:65], v[68:69], v[66:67]
	v_pk_mul_f32 v[66:67], v[70:71], v[72:73]
	v_cvt_pk_bf16_f32 v64, v64, v65
	v_cvt_pk_bf16_f32 v65, v66, v67
	v_lshl_add_u64 v[66:67], s[12:13], 0, v[76:77]
	global_store_dwordx2 v[66:67], v[64:65], off
	v_add_u32_e32 v64, v136, v84
	v_lshl_add_u32 v64, v64, 10, v129
	v_ashrrev_i32_e32 v65, 31, v64
	v_lshlrev_b64 v[72:73], 1, v[64:65]
	v_lshl_add_u64 v[64:65], s[14:15], 0, v[72:73]
	ds_read_b128 v[64:67], v128 offset:4352
	ds_read_b128 v[68:71], v128 offset:5440
	v_add_u32_e32 v76, v134, v84
	v_lshl_add_u32 v76, v76, 10, v129
	v_ashrrev_i32_e32 v77, 31, v76
	v_lshlrev_b64 v[76:77], 1, v[76:77]
	v_lshl_add_u64 v[72:73], s[12:13], 0, v[72:73]
	v_lshl_add_u64 v[78:79], s[14:15], 0, v[76:77]
	s_waitcnt vmcnt(7)
	v_mov_b32_e32 v74, v152
	v_mov_b32_e32 v75, v153
	v_and_b32_e32 v81, 0xffff0000, v74
	v_lshlrev_b32_e32 v80, 16, v74
	v_and_b32_e32 v83, 0xffff0000, v75
	v_lshlrev_b32_e32 v82, 16, v75
	s_waitcnt lgkmcnt(1)
	v_pk_mul_f32 v[64:65], v[64:65], v[80:81]
	v_pk_mul_f32 v[66:67], v[66:67], v[82:83]
	v_cvt_pk_bf16_f32 v64, v64, v65
	v_cvt_pk_bf16_f32 v65, v66, v67
	global_store_dwordx2 v[72:73], v[64:65], off
	v_add_u32_e32 v66, v131, v84
	v_lshl_add_u32 v66, v66, 10, v129
	v_ashrrev_i32_e32 v67, 31, v66
	v_lshlrev_b64 v[72:73], 1, v[66:67]
	v_lshl_add_u64 v[66:67], s[12:13], 0, v[76:77]
	v_lshl_add_u64 v[74:75], s[14:15], 0, v[72:73]
	v_lshl_add_u64 v[72:73], s[12:13], 0, v[72:73]
	s_waitcnt vmcnt(7)
	v_mov_b32_e32 v64, v154
	v_mov_b32_e32 v65, v155
	v_and_b32_e32 v77, 0xffff0000, v64
	v_lshlrev_b32_e32 v76, 16, v64
	v_and_b32_e32 v79, 0xffff0000, v65
	v_lshlrev_b32_e32 v78, 16, v65
	s_waitcnt lgkmcnt(0)
; __device__ __forceinline__ float bfs2f(short h) { return __uint_as_float(((unsigned)(u16)h) << 16); }
;   __device__ __forceinline__ void tile(const float* reg, int row0, int col0, int lane) const {
;     rows4(reg, lane, [&](int it, int rr, int c4, float4 v) {
;       int idx = (row0 + rr) * 1024 + col0 + c4;
;       bf16x4 gt = *(const bf16x4*)(gate + idx);
;       *(bf16x4*)(merged + idx) = pack4(bfs2f(gt[0]) * v.x, bfs2f(gt[1]) * v.y, bfs2f(gt[2]) * v.z, bfs2f(gt[3]) * v.w);
;     });
; template <int MF, class Epi>
; __device__ __forceinline__ void staged_epilogue(f32x4 (&acc)[MF][4], int row0, int col0, const Epi& epi) {
;     ...
;     for (int mm = 0; mm < 2; ++mm)
; #pragma unroll
;       for (int n = 0; n < 4; ++n)
; #pragma unroll
;         for (int j = 0; j < 4; ++j) reg[(mm * 16 + fq * 4 + j) * 68 + n * 16 + fr] = acc[mp * 2 + mm][n][j];
	v_pk_mul_f32 v[64:65], v[68:69], v[76:77]
	v_pk_mul_f32 v[68:69], v[70:71], v[78:79]
	v_cvt_pk_bf16_f32 v64, v64, v65
	v_cvt_pk_bf16_f32 v65, v68, v69
	global_store_dwordx2 v[66:67], v[64:65], off
	ds_read_b128 v[64:67], v128 offset:6528
	ds_read_b128 v[68:71], v128 offset:7616
	v_add_u32_e32 v76, v130, v84
	v_lshl_add_u32 v76, v76, 10, v129
	v_ashrrev_i32_e32 v77, 31, v76
	v_lshlrev_b64 v[76:77], 1, v[76:77]
	v_lshl_add_u64 v[78:79], s[14:15], 0, v[76:77]
	s_waitcnt vmcnt(7)
	v_mov_b32_e32 v74, v156
	v_mov_b32_e32 v75, v157
	v_and_b32_e32 v81, 0xffff0000, v74
	v_lshlrev_b32_e32 v80, 16, v74
	v_and_b32_e32 v83, 0xffff0000, v75
	v_lshlrev_b32_e32 v82, 16, v75
	s_waitcnt lgkmcnt(1)
	v_pk_mul_f32 v[64:65], v[64:65], v[80:81]
	v_pk_mul_f32 v[66:67], v[66:67], v[82:83]
	v_cvt_pk_bf16_f32 v64, v64, v65
	v_cvt_pk_bf16_f32 v65, v66, v67
	global_store_dwordx2 v[72:73], v[64:65], off
	v_lshl_add_u64 v[66:67], s[12:13], 0, v[76:77]
	s_waitcnt vmcnt(7)
	v_mov_b32_e32 v64, v158
	v_mov_b32_e32 v65, v159
	v_and_b32_e32 v73, 0xffff0000, v64
	v_lshlrev_b32_e32 v72, 16, v64
	v_and_b32_e32 v75, 0xffff0000, v65
	v_lshlrev_b32_e32 v74, 16, v65
	s_waitcnt lgkmcnt(0)
	v_pk_mul_f32 v[64:65], v[68:69], v[72:73]
	v_pk_mul_f32 v[68:69], v[70:71], v[74:75]
	v_cvt_pk_bf16_f32 v64, v64, v65
	v_cvt_pk_bf16_f32 v65, v68, v69
	global_store_dwordx2 v[66:67], v[64:65], off
	ds_write2_b32 v141, v56, v60 offset1:16
	ds_write2_b32 v141, v57, v61 offset0:68 offset1:84
	ds_write2_b32 v141, v58, v62 offset0:136 offset1:152
	ds_write2_b32 v141, v59, v63 offset0:204 offset1:220
	ds_write2_b32 v141, v48, v52 offset0:32 offset1:48
	ds_write2_b32 v141, v49, v53 offset0:100 offset1:116
	ds_write2_b32 v141, v50, v54 offset0:168 offset1:184
	ds_write2_b32 v141, v51, v55 offset0:236 offset1:252
	ds_write2_b32 v112, v40, v44 offset0:64 offset1:80
	ds_write2_b32 v112, v41, v45 offset0:132 offset1:148
	ds_write2_b32 v112, v42, v46 offset0:200 offset1:216
	ds_write2_b32 v104, v43, v47 offset0:12 offset1:28
	ds_write2_b32 v112, v32, v36 offset0:96 offset1:112
	ds_write2_b32 v112, v33, v37 offset0:164 offset1:180
	ds_write2_b32 v112, v34, v38 offset0:232 offset1:248
	ds_write2_b32 v104, v35, v39 offset0:44 offset1:60
	v_add_u32_e32 v184, 64, v135
	v_add_u32_e32 v176, v140, v184
	v_lshl_add_u32 v176, v176, 10, v129
	v_ashrrev_i32_e32 v177, 31, v176
	v_lshlrev_b64 v[178:179], 1, v[176:177]
	v_lshl_add_u64 v[176:177], s[14:15], 0, v[178:179]
	global_load_dwordx2 v[144:145], v[176:177], off
	v_add_u32_e32 v184, 64, v135
	v_add_u32_e32 v176, v139, v184
	v_lshl_add_u32 v176, v176, 10, v129
	v_ashrrev_i32_e32 v177, 31, v176
	v_lshlrev_b64 v[176:177], 1, v[176:177]
	v_lshl_add_u64 v[178:179], s[14:15], 0, v[176:177]
	global_load_dwordx2 v[146:147], v[178:179], off
	v_add_u32_e32 v184, 64, v135
	v_add_u32_e32 v176, v138, v184
	v_lshl_add_u32 v176, v176, 10, v129
	v_ashrrev_i32_e32 v177, 31, v176
	v_lshlrev_b64 v[178:179], 1, v[176:177]
	v_lshl_add_u64 v[180:181], s[14:15], 0, v[178:179]
	global_load_dwordx2 v[148:149], v[180:181], off
	v_add_u32_e32 v184, 64, v135
	v_add_u32_e32 v176, v137, v184
	v_lshl_add_u32 v176, v176, 10, v129
	v_ashrrev_i32_e32 v177, 31, v176
	v_lshlrev_b64 v[176:177], 1, v[176:177]
	v_lshl_add_u64 v[178:179], s[14:15], 0, v[176:177]
	global_load_dwordx2 v[150:151], v[178:179], off
	v_add_u32_e32 v184, 64, v135
	v_add_u32_e32 v176, v136, v184
	v_lshl_add_u32 v176, v176, 10, v129
	v_ashrrev_i32_e32 v177, 31, v176
	v_lshlrev_b64 v[178:179], 1, v[176:177]
	v_lshl_add_u64 v[176:177], s[14:15], 0, v[178:179]
	global_load_dwordx2 v[152:153], v[176:177], off
	v_add_u32_e32 v184, 64, v135
	v_add_u32_e32 v176, v134, v184
	v_lshl_add_u32 v176, v176, 10, v129
	v_ashrrev_i32_e32 v177, 31, v176
	v_lshlrev_b64 v[176:177], 1, v[176:177]
	v_lshl_add_u64 v[178:179], s[14:15], 0, v[176:177]
	global_load_dwordx2 v[154:155], v[178:179], off
	v_add_u32_e32 v184, 64, v135
	v_add_u32_e32 v176, v131, v184
	v_lshl_add_u32 v176, v176, 10, v129
	v_ashrrev_i32_e32 v177, 31, v176
	v_lshlrev_b64 v[178:179], 1, v[176:177]
	v_lshl_add_u64 v[180:181], s[14:15], 0, v[178:179]
	global_load_dwordx2 v[156:157], v[180:181], off
	v_add_u32_e32 v184, 64, v135
	v_add_u32_e32 v176, v130, v184
	v_lshl_add_u32 v176, v176, 10, v129
	v_ashrrev_i32_e32 v177, 31, v176
	v_lshlrev_b64 v[176:177], 1, v[176:177]
	v_lshl_add_u64 v[178:179], s[14:15], 0, v[176:177]
	global_load_dwordx2 v[158:159], v[178:179], off
	v_add_u32_e32 v52, 64, v135
	v_add_u32_e32 v32, v140, v52
	v_lshl_add_u32 v32, v32, 10, v129
	v_ashrrev_i32_e32 v33, 31, v32
	v_lshlrev_b64 v[40:41], 1, v[32:33]
	v_lshl_add_u64 v[32:33], s[14:15], 0, v[40:41]
	ds_read_b128 v[32:35], v128
	ds_read_b128 v[36:39], v128 offset:1088
	v_add_u32_e32 v44, v139, v52
	v_lshl_add_u32 v44, v44, 10, v129
	v_ashrrev_i32_e32 v45, 31, v44
	v_lshlrev_b64 v[44:45], 1, v[44:45]
	v_lshl_add_u64 v[40:41], s[12:13], 0, v[40:41]
	v_lshl_add_u64 v[46:47], s[14:15], 0, v[44:45]
	s_waitcnt vmcnt(7)
	v_mov_b32_e32 v42, v144
	v_mov_b32_e32 v43, v145
	v_and_b32_e32 v49, 0xffff0000, v42
	v_lshlrev_b32_e32 v48, 16, v42
	v_and_b32_e32 v51, 0xffff0000, v43
	v_lshlrev_b32_e32 v50, 16, v43
	s_waitcnt lgkmcnt(1)
	v_pk_mul_f32 v[32:33], v[32:33], v[48:49]
	v_pk_mul_f32 v[34:35], v[34:35], v[50:51]
	v_cvt_pk_bf16_f32 v32, v32, v33
	v_cvt_pk_bf16_f32 v33, v34, v35
	global_store_dwordx2 v[40:41], v[32:33], off
	v_add_u32_e32 v34, v138, v52
	v_lshl_add_u32 v34, v34, 10, v129
	v_ashrrev_i32_e32 v35, 31, v34
	v_lshlrev_b64 v[40:41], 1, v[34:35]
	v_lshl_add_u64 v[34:35], s[12:13], 0, v[44:45]
	v_lshl_add_u64 v[42:43], s[14:15], 0, v[40:41]
	v_lshl_add_u64 v[40:41], s[12:13], 0, v[40:41]
	s_waitcnt vmcnt(7)
; __device__ __forceinline__ float bfs2f(short h) { return __uint_as_float(((unsigned)(u16)h) << 16); }
;   __device__ __forceinline__ void tile(const float* reg, int row0, int col0, int lane) const {
;     rows4(reg, lane, [&](int it, int rr, int c4, float4 v) {
;       int idx = (row0 + rr) * 1024 + col0 + c4;
;       bf16x4 gt = *(const bf16x4*)(gate + idx);
;       *(bf16x4*)(merged + idx) = pack4(bfs2f(gt[0]) * v.x, bfs2f(gt[1]) * v.y, bfs2f(gt[2]) * v.z, bfs2f(gt[3]) * v.w);
;     });
; template <int MF, class Epi>
; __device__ __forceinline__ void staged_epilogue(f32x4 (&acc)[MF][4], int row0, int col0, const Epi& epi) {
;     ...
;     for (int mm = 0; mm < 2; ++mm)
; #pragma unroll
;       for (int n = 0; n < 4; ++n)
; #pragma unroll
;         for (int j = 0; j < 4; ++j) reg[(mm * 16 + fq * 4 + j) * 68 + n * 16 + fr] = acc[mp * 2 + mm][n][j];
	v_mov_b32_e32 v32, v146
	v_mov_b32_e32 v33, v147
	v_and_b32_e32 v45, 0xffff0000, v32
	v_lshlrev_b32_e32 v44, 16, v32
	v_and_b32_e32 v47, 0xffff0000, v33
	v_lshlrev_b32_e32 v46, 16, v33
	s_waitcnt lgkmcnt(0)
	v_pk_mul_f32 v[32:33], v[36:37], v[44:45]
	v_pk_mul_f32 v[36:37], v[38:39], v[46:47]
	v_cvt_pk_bf16_f32 v32, v32, v33
	v_cvt_pk_bf16_f32 v33, v36, v37
	global_store_dwordx2 v[34:35], v[32:33], off
	ds_read_b128 v[32:35], v128 offset:2176
	ds_read_b128 v[36:39], v128 offset:3264
	v_add_u32_e32 v44, v137, v52
	v_lshl_add_u32 v44, v44, 10, v129
	v_ashrrev_i32_e32 v45, 31, v44
	v_lshlrev_b64 v[44:45], 1, v[44:45]
	v_lshl_add_u64 v[46:47], s[14:15], 0, v[44:45]
	s_waitcnt vmcnt(7)
	v_mov_b32_e32 v42, v148
	v_mov_b32_e32 v43, v149
	v_and_b32_e32 v49, 0xffff0000, v42
	v_lshlrev_b32_e32 v48, 16, v42
	v_and_b32_e32 v51, 0xffff0000, v43
	v_lshlrev_b32_e32 v50, 16, v43
	s_waitcnt lgkmcnt(1)
	v_pk_mul_f32 v[32:33], v[32:33], v[48:49]
	v_pk_mul_f32 v[34:35], v[34:35], v[50:51]
	v_cvt_pk_bf16_f32 v32, v32, v33
	v_cvt_pk_bf16_f32 v33, v34, v35
	global_store_dwordx2 v[40:41], v[32:33], off
	s_waitcnt vmcnt(7)
	v_mov_b32_e32 v32, v150
	v_mov_b32_e32 v33, v151
	v_and_b32_e32 v35, 0xffff0000, v32
	v_lshlrev_b32_e32 v34, 16, v32
	v_and_b32_e32 v41, 0xffff0000, v33
	v_lshlrev_b32_e32 v40, 16, v33
	s_waitcnt lgkmcnt(0)
	v_pk_mul_f32 v[32:33], v[36:37], v[34:35]
	v_pk_mul_f32 v[34:35], v[38:39], v[40:41]
	v_cvt_pk_bf16_f32 v32, v32, v33
	v_cvt_pk_bf16_f32 v33, v34, v35
	v_lshl_add_u64 v[34:35], s[12:13], 0, v[44:45]
	global_store_dwordx2 v[34:35], v[32:33], off
	v_add_u32_e32 v32, v136, v52
	v_lshl_add_u32 v32, v32, 10, v129
	v_ashrrev_i32_e32 v33, 31, v32
	v_lshlrev_b64 v[40:41], 1, v[32:33]
	v_lshl_add_u64 v[32:33], s[14:15], 0, v[40:41]
	ds_read_b128 v[32:35], v128 offset:4352
	ds_read_b128 v[36:39], v128 offset:5440
	v_add_u32_e32 v44, v134, v52
	v_lshl_add_u32 v44, v44, 10, v129
	v_ashrrev_i32_e32 v45, 31, v44
	v_lshlrev_b64 v[44:45], 1, v[44:45]
	v_lshl_add_u64 v[40:41], s[12:13], 0, v[40:41]
	v_lshl_add_u64 v[46:47], s[14:15], 0, v[44:45]
	s_waitcnt vmcnt(7)
	v_mov_b32_e32 v42, v152
	v_mov_b32_e32 v43, v153
	v_and_b32_e32 v49, 0xffff0000, v42
	v_lshlrev_b32_e32 v48, 16, v42
	v_and_b32_e32 v51, 0xffff0000, v43
	v_lshlrev_b32_e32 v50, 16, v43
	s_waitcnt lgkmcnt(1)
	v_pk_mul_f32 v[32:33], v[32:33], v[48:49]
	v_pk_mul_f32 v[34:35], v[34:35], v[50:51]
	v_cvt_pk_bf16_f32 v32, v32, v33
	v_cvt_pk_bf16_f32 v33, v34, v35
	global_store_dwordx2 v[40:41], v[32:33], off
	v_add_u32_e32 v34, v131, v52
	v_lshl_add_u32 v34, v34, 10, v129
	v_ashrrev_i32_e32 v35, 31, v34
	v_lshlrev_b64 v[40:41], 1, v[34:35]
	v_lshl_add_u64 v[34:35], s[12:13], 0, v[44:45]
	v_lshl_add_u64 v[42:43], s[14:15], 0, v[40:41]
	v_lshl_add_u64 v[40:41], s[12:13], 0, v[40:41]
	s_waitcnt vmcnt(7)
	v_mov_b32_e32 v32, v154
	v_mov_b32_e32 v33, v155
	v_and_b32_e32 v45, 0xffff0000, v32
	v_lshlrev_b32_e32 v44, 16, v32
	v_and_b32_e32 v47, 0xffff0000, v33
	v_lshlrev_b32_e32 v46, 16, v33
	s_waitcnt lgkmcnt(0)
	v_pk_mul_f32 v[32:33], v[36:37], v[44:45]
	v_pk_mul_f32 v[36:37], v[38:39], v[46:47]
	v_cvt_pk_bf16_f32 v32, v32, v33
	v_cvt_pk_bf16_f32 v33, v36, v37
	global_store_dwordx2 v[34:35], v[32:33], off
	ds_read_b128 v[32:35], v128 offset:6528
	ds_read_b128 v[36:39], v128 offset:7616
	v_add_u32_e32 v44, v130, v52
	v_lshl_add_u32 v44, v44, 10, v129
	v_ashrrev_i32_e32 v45, 31, v44
	v_lshlrev_b64 v[44:45], 1, v[44:45]
	v_lshl_add_u64 v[46:47], s[14:15], 0, v[44:45]
	s_waitcnt vmcnt(7)
	v_mov_b32_e32 v42, v156
	v_mov_b32_e32 v43, v157
	v_and_b32_e32 v49, 0xffff0000, v42
	v_lshlrev_b32_e32 v48, 16, v42
	v_and_b32_e32 v51, 0xffff0000, v43
	v_lshlrev_b32_e32 v50, 16, v43
	s_waitcnt lgkmcnt(1)
	v_pk_mul_f32 v[32:33], v[32:33], v[48:49]
	v_pk_mul_f32 v[34:35], v[34:35], v[50:51]
	v_cvt_pk_bf16_f32 v32, v32, v33
	v_cvt_pk_bf16_f32 v33, v34, v35
	global_store_dwordx2 v[40:41], v[32:33], off
	v_lshl_add_u64 v[34:35], s[12:13], 0, v[44:45]
	s_waitcnt vmcnt(7)
	v_mov_b32_e32 v32, v158
	v_mov_b32_e32 v33, v159
	v_and_b32_e32 v41, 0xffff0000, v32
	v_lshlrev_b32_e32 v40, 16, v32
	v_and_b32_e32 v43, 0xffff0000, v33
	v_lshlrev_b32_e32 v42, 16, v33
	s_waitcnt lgkmcnt(0)
	v_pk_mul_f32 v[32:33], v[36:37], v[40:41]
	v_pk_mul_f32 v[36:37], v[38:39], v[42:43]
	v_cvt_pk_bf16_f32 v32, v32, v33
	v_cvt_pk_bf16_f32 v33, v36, v37
	global_store_dwordx2 v[34:35], v[32:33], off
	ds_write2_b32 v141, v24, v28 offset1:16
	ds_write2_b32 v141, v25, v29 offset0:68 offset1:84
	ds_write2_b32 v141, v26, v30 offset0:136 offset1:152
	ds_write2_b32 v141, v27, v31 offset0:204 offset1:220
	ds_write2_b32 v141, v16, v20 offset0:32 offset1:48
	ds_write2_b32 v141, v17, v21 offset0:100 offset1:116
	ds_write2_b32 v141, v18, v22 offset0:168 offset1:184
	ds_write2_b32 v141, v19, v23 offset0:236 offset1:252
	ds_write2_b32 v112, v4, v8 offset0:64 offset1:80
	ds_write2_b32 v112, v5, v9 offset0:132 offset1:148
	ds_write2_b32 v112, v6, v10 offset0:200 offset1:216
	ds_write2_b32 v104, v7, v11 offset0:12 offset1:28
	ds_write2_b32 v112, v0, v12 offset0:96 offset1:112
	ds_write2_b32 v112, v1, v13 offset0:164 offset1:180
	ds_write2_b32 v112, v2, v14 offset0:232 offset1:248
	ds_write2_b32 v104, v3, v15 offset0:44 offset1:60
	v_add_u32_e32 v184, 0x60, v135
	v_add_u32_e32 v176, v140, v184
	v_lshl_add_u32 v176, v176, 10, v129
	v_ashrrev_i32_e32 v177, 31, v176
	v_lshlrev_b64 v[178:179], 1, v[176:177]
	v_lshl_add_u64 v[176:177], s[14:15], 0, v[178:179]
	global_load_dwordx2 v[144:145], v[176:177], off
	v_add_u32_e32 v184, 0x60, v135
	v_add_u32_e32 v176, v139, v184
	v_lshl_add_u32 v176, v176, 10, v129
	v_ashrrev_i32_e32 v177, 31, v176
	v_lshlrev_b64 v[176:177], 1, v[176:177]
; __device__ __forceinline__ float bfs2f(short h) { return __uint_as_float(((unsigned)(u16)h) << 16); }
;   __device__ __forceinline__ void tile(const float* reg, int row0, int col0, int lane) const {
;     rows4(reg, lane, [&](int it, int rr, int c4, float4 v) {
;       int idx = (row0 + rr) * 1024 + col0 + c4;
;       bf16x4 gt = *(const bf16x4*)(gate + idx);
;       *(bf16x4*)(merged + idx) = pack4(bfs2f(gt[0]) * v.x, bfs2f(gt[1]) * v.y, bfs2f(gt[2]) * v.z, bfs2f(gt[3]) * v.w);
;     });
	v_lshl_add_u64 v[178:179], s[14:15], 0, v[176:177]
	global_load_dwordx2 v[146:147], v[178:179], off
	v_add_u32_e32 v184, 0x60, v135
	v_add_u32_e32 v176, v138, v184
	v_lshl_add_u32 v176, v176, 10, v129
	v_ashrrev_i32_e32 v177, 31, v176
	v_lshlrev_b64 v[178:179], 1, v[176:177]
	v_lshl_add_u64 v[180:181], s[14:15], 0, v[178:179]
	global_load_dwordx2 v[148:149], v[180:181], off
	v_add_u32_e32 v184, 0x60, v135
	v_add_u32_e32 v176, v137, v184
	v_lshl_add_u32 v176, v176, 10, v129
	v_ashrrev_i32_e32 v177, 31, v176
	v_lshlrev_b64 v[176:177], 1, v[176:177]
	v_lshl_add_u64 v[178:179], s[14:15], 0, v[176:177]
	global_load_dwordx2 v[150:151], v[178:179], off
	v_add_u32_e32 v184, 0x60, v135
	v_add_u32_e32 v176, v136, v184
	v_lshl_add_u32 v176, v176, 10, v129
	v_ashrrev_i32_e32 v177, 31, v176
	v_lshlrev_b64 v[178:179], 1, v[176:177]
	v_lshl_add_u64 v[176:177], s[14:15], 0, v[178:179]
	global_load_dwordx2 v[152:153], v[176:177], off
	v_add_u32_e32 v184, 0x60, v135
	v_add_u32_e32 v176, v134, v184
	v_lshl_add_u32 v176, v176, 10, v129
	v_ashrrev_i32_e32 v177, 31, v176
	v_lshlrev_b64 v[176:177], 1, v[176:177]
	v_lshl_add_u64 v[178:179], s[14:15], 0, v[176:177]
	global_load_dwordx2 v[154:155], v[178:179], off
	v_add_u32_e32 v184, 0x60, v135
	v_add_u32_e32 v176, v131, v184
	v_lshl_add_u32 v176, v176, 10, v129
	v_ashrrev_i32_e32 v177, 31, v176
	v_lshlrev_b64 v[178:179], 1, v[176:177]
	v_lshl_add_u64 v[180:181], s[14:15], 0, v[178:179]
	global_load_dwordx2 v[156:157], v[180:181], off
	v_add_u32_e32 v184, 0x60, v135
	v_add_u32_e32 v176, v130, v184
	v_lshl_add_u32 v176, v176, 10, v129
	v_ashrrev_i32_e32 v177, 31, v176
	v_lshlrev_b64 v[176:177], 1, v[176:177]
	v_lshl_add_u64 v[178:179], s[14:15], 0, v[176:177]
	global_load_dwordx2 v[158:159], v[178:179], off
	v_add_u32_e32 v20, 0x60, v135
	v_add_u32_e32 v0, v140, v20
	v_lshl_add_u32 v0, v0, 10, v129
	v_ashrrev_i32_e32 v1, 31, v0
	v_lshlrev_b64 v[8:9], 1, v[0:1]
	v_lshl_add_u64 v[0:1], s[14:15], 0, v[8:9]
	ds_read_b128 v[0:3], v128
	ds_read_b128 v[4:7], v128 offset:1088
	v_add_u32_e32 v12, v139, v20
	v_lshl_add_u32 v12, v12, 10, v129
	v_ashrrev_i32_e32 v13, 31, v12
	v_lshlrev_b64 v[12:13], 1, v[12:13]
	v_lshl_add_u64 v[8:9], s[12:13], 0, v[8:9]
	v_lshl_add_u64 v[14:15], s[14:15], 0, v[12:13]
	s_waitcnt vmcnt(7)
	v_mov_b32_e32 v10, v144
	v_mov_b32_e32 v11, v145
	v_and_b32_e32 v17, 0xffff0000, v10
	v_lshlrev_b32_e32 v16, 16, v10
	v_and_b32_e32 v19, 0xffff0000, v11
	v_lshlrev_b32_e32 v18, 16, v11
	s_waitcnt lgkmcnt(1)
	v_pk_mul_f32 v[0:1], v[0:1], v[16:17]
	v_pk_mul_f32 v[2:3], v[2:3], v[18:19]
	v_cvt_pk_bf16_f32 v0, v0, v1
	v_cvt_pk_bf16_f32 v1, v2, v3
	global_store_dwordx2 v[8:9], v[0:1], off
	v_add_u32_e32 v2, v138, v20
	v_lshl_add_u32 v2, v2, 10, v129
	v_ashrrev_i32_e32 v3, 31, v2
	v_lshlrev_b64 v[8:9], 1, v[2:3]
	v_lshl_add_u64 v[2:3], s[12:13], 0, v[12:13]
	v_lshl_add_u64 v[10:11], s[14:15], 0, v[8:9]
	v_lshl_add_u64 v[8:9], s[12:13], 0, v[8:9]
	s_waitcnt vmcnt(7)
	v_mov_b32_e32 v0, v146
	v_mov_b32_e32 v1, v147
	v_and_b32_e32 v13, 0xffff0000, v0
	v_lshlrev_b32_e32 v12, 16, v0
	v_and_b32_e32 v15, 0xffff0000, v1
	v_lshlrev_b32_e32 v14, 16, v1
	s_waitcnt lgkmcnt(0)
	v_pk_mul_f32 v[0:1], v[4:5], v[12:13]
	v_pk_mul_f32 v[4:5], v[6:7], v[14:15]
	v_cvt_pk_bf16_f32 v0, v0, v1
	v_cvt_pk_bf16_f32 v1, v4, v5
	global_store_dwordx2 v[2:3], v[0:1], off
	ds_read_b128 v[0:3], v128 offset:2176
	ds_read_b128 v[4:7], v128 offset:3264
	v_add_u32_e32 v12, v137, v20
	v_lshl_add_u32 v12, v12, 10, v129
	v_ashrrev_i32_e32 v13, 31, v12
	v_lshlrev_b64 v[12:13], 1, v[12:13]
	v_lshl_add_u64 v[14:15], s[14:15], 0, v[12:13]
	s_waitcnt vmcnt(7)
; __device__ __forceinline__ float bfs2f(short h) { return __uint_as_float(((unsigned)(u16)h) << 16); }
;   __device__ __forceinline__ void tile(const float* reg, int row0, int col0, int lane) const {
;     rows4(reg, lane, [&](int it, int rr, int c4, float4 v) {
;       int idx = (row0 + rr) * 1024 + col0 + c4;
;       bf16x4 gt = *(const bf16x4*)(gate + idx);
;       *(bf16x4*)(merged + idx) = pack4(bfs2f(gt[0]) * v.x, bfs2f(gt[1]) * v.y, bfs2f(gt[2]) * v.z, bfs2f(gt[3]) * v.w);
;     });
; template <class Epi>
; __device__ __forceinline__ void gemm_phase(const u16* A, const u16* Bt, int K, int N, const Epi& epiP, const Epi& epiS) {
;     ...
;   for (; t < nwg; t += gridDim.x) {
;     f32x4 acc[8][4] = {};
;     gemm_mainloop<false>(A + (size_t)brow * K, Bt + (size_t)bcol * K, K, acc);
;     int er0 = brow + wr * 128, ec0 = bcol + wc * 64;
;     asm volatile("" : "+v"(er0), "+v"(ec0));
;     if (t + (int)gridDim.x < nwg) {
;       tile_coords(t + gridDim.x, 128, nN, brow, bcol);
;       gemm_prefetch0(A + (size_t)brow * K, Bt + (size_t)bcol * K, K);
;     }
;     staged_epilogue<8>(acc, er0, ec0, epiP);
;   }
	v_mov_b32_e32 v10, v148
	v_mov_b32_e32 v11, v149
	v_and_b32_e32 v17, 0xffff0000, v10
	v_lshlrev_b32_e32 v16, 16, v10
	v_and_b32_e32 v19, 0xffff0000, v11
	v_lshlrev_b32_e32 v18, 16, v11
	s_waitcnt lgkmcnt(1)
	v_pk_mul_f32 v[0:1], v[0:1], v[16:17]
	v_pk_mul_f32 v[2:3], v[2:3], v[18:19]
	v_cvt_pk_bf16_f32 v0, v0, v1
	v_cvt_pk_bf16_f32 v1, v2, v3
	global_store_dwordx2 v[8:9], v[0:1], off
	s_waitcnt vmcnt(7)
	v_mov_b32_e32 v0, v150
	v_mov_b32_e32 v1, v151
	v_and_b32_e32 v3, 0xffff0000, v0
	v_lshlrev_b32_e32 v2, 16, v0
	v_and_b32_e32 v9, 0xffff0000, v1
	v_lshlrev_b32_e32 v8, 16, v1
	s_waitcnt lgkmcnt(0)
	v_pk_mul_f32 v[0:1], v[4:5], v[2:3]
	v_pk_mul_f32 v[2:3], v[6:7], v[8:9]
	v_cvt_pk_bf16_f32 v0, v0, v1
	v_cvt_pk_bf16_f32 v1, v2, v3
	v_lshl_add_u64 v[2:3], s[12:13], 0, v[12:13]
	global_store_dwordx2 v[2:3], v[0:1], off
	v_add_u32_e32 v0, v136, v20
	v_lshl_add_u32 v0, v0, 10, v129
	v_ashrrev_i32_e32 v1, 31, v0
	v_lshlrev_b64 v[8:9], 1, v[0:1]
	v_lshl_add_u64 v[0:1], s[14:15], 0, v[8:9]
	ds_read_b128 v[0:3], v128 offset:4352
	ds_read_b128 v[4:7], v128 offset:5440
	v_add_u32_e32 v12, v134, v20
	v_lshl_add_u32 v12, v12, 10, v129
	v_ashrrev_i32_e32 v13, 31, v12
	v_lshlrev_b64 v[12:13], 1, v[12:13]
	v_lshl_add_u64 v[8:9], s[12:13], 0, v[8:9]
	v_lshl_add_u64 v[14:15], s[14:15], 0, v[12:13]
	s_andn2_b64 vcc, exec, s[46:47]
	s_waitcnt vmcnt(7)
	v_mov_b32_e32 v10, v152
	v_mov_b32_e32 v11, v153
	v_and_b32_e32 v17, 0xffff0000, v10
	v_lshlrev_b32_e32 v16, 16, v10
	v_and_b32_e32 v19, 0xffff0000, v11
	v_lshlrev_b32_e32 v18, 16, v11
	s_waitcnt lgkmcnt(1)
	v_pk_mul_f32 v[0:1], v[0:1], v[16:17]
	v_pk_mul_f32 v[2:3], v[2:3], v[18:19]
	v_cvt_pk_bf16_f32 v0, v0, v1
	v_cvt_pk_bf16_f32 v1, v2, v3
	global_store_dwordx2 v[8:9], v[0:1], off
	v_add_u32_e32 v2, v131, v20
	v_lshl_add_u32 v2, v2, 10, v129
	v_ashrrev_i32_e32 v3, 31, v2
	v_lshlrev_b64 v[8:9], 1, v[2:3]
	v_lshl_add_u64 v[2:3], s[12:13], 0, v[12:13]
	v_lshl_add_u64 v[10:11], s[14:15], 0, v[8:9]
	v_lshl_add_u64 v[8:9], s[12:13], 0, v[8:9]
	s_waitcnt vmcnt(7)
	v_mov_b32_e32 v0, v154
	v_mov_b32_e32 v1, v155
	v_and_b32_e32 v13, 0xffff0000, v0
	v_lshlrev_b32_e32 v12, 16, v0
	v_and_b32_e32 v15, 0xffff0000, v1
	v_lshlrev_b32_e32 v14, 16, v1
	s_waitcnt lgkmcnt(0)
	v_pk_mul_f32 v[0:1], v[4:5], v[12:13]
	v_pk_mul_f32 v[4:5], v[6:7], v[14:15]
	v_cvt_pk_bf16_f32 v0, v0, v1
	v_cvt_pk_bf16_f32 v1, v4, v5
	global_store_dwordx2 v[2:3], v[0:1], off
	ds_read_b128 v[0:3], v128 offset:6528
	ds_read_b128 v[4:7], v128 offset:7616
	v_add_u32_e32 v12, v130, v20
	v_lshl_add_u32 v12, v12, 10, v129
	v_ashrrev_i32_e32 v13, 31, v12
	v_lshlrev_b64 v[12:13], 1, v[12:13]
	v_lshl_add_u64 v[14:15], s[14:15], 0, v[12:13]
	s_waitcnt vmcnt(7)
	v_mov_b32_e32 v10, v156
	v_mov_b32_e32 v11, v157
	v_and_b32_e32 v17, 0xffff0000, v10
	v_lshlrev_b32_e32 v16, 16, v10
	v_and_b32_e32 v19, 0xffff0000, v11
	v_lshlrev_b32_e32 v18, 16, v11
	s_waitcnt lgkmcnt(1)
	v_pk_mul_f32 v[0:1], v[0:1], v[16:17]
	v_pk_mul_f32 v[2:3], v[2:3], v[18:19]
	v_cvt_pk_bf16_f32 v0, v0, v1
	v_cvt_pk_bf16_f32 v1, v2, v3
	global_store_dwordx2 v[8:9], v[0:1], off
	v_lshl_add_u64 v[2:3], s[12:13], 0, v[12:13]
	s_waitcnt vmcnt(7)
	v_mov_b32_e32 v0, v158
	v_mov_b32_e32 v1, v159
	v_and_b32_e32 v9, 0xffff0000, v0
	v_lshlrev_b32_e32 v8, 16, v0
	v_and_b32_e32 v11, 0xffff0000, v1
	v_lshlrev_b32_e32 v10, 16, v1
	s_waitcnt lgkmcnt(0)
	v_pk_mul_f32 v[0:1], v[4:5], v[8:9]
	v_pk_mul_f32 v[4:5], v[6:7], v[10:11]
	v_cvt_pk_bf16_f32 v0, v0, v1
	v_cvt_pk_bf16_f32 v1, v4, v5
	global_store_dwordx2 v[2:3], v[0:1], off
	s_cbranch_vccz .LBB0_3014

; __device__ __forceinline__ float bfs2f(short h) { return __uint_as_float(((unsigned)(u16)h) << 16); }
;   __device__ __forceinline__ void tile(const float* reg, int row0, int col0, int lane) const {
;     rows4(reg, lane, [&](int it, int rr, int c4, float4 v) {
;       int idx = (row0 + rr) * 1024 + col0 + c4;
;       bf16x4 gt = *(const bf16x4*)(gate + idx), mo = *(const bf16x4*)(merged + idx);
;       *(bf16x4*)(merged + idx) = pack4(fmaf(bfs2f(gt[0]), v.x, bfs2f(mo[0])), fmaf(bfs2f(gt[1]), v.y, bfs2f(mo[1])),
;                                        fmaf(bfs2f(gt[2]), v.z, bfs2f(mo[2])), fmaf(bfs2f(gt[3]), v.w, bfs2f(mo[3])));
;     });
; template <int MF, class Epi>
; __device__ __forceinline__ void staged_epilogue(f32x4 (&acc)[MF][4], int row0, int col0, const Epi& epi) {
;   const int lane = tidx() & 63, wid = tidx() >> 6, fr = lane & 15, fq = lane >> 4;
;   float* reg = (float*)(g_shm + 65536 + wid * 8704);
; #pragma unroll
;   for (int mp = 0; mp < MF / 2; ++mp) {
;     __builtin_amdgcn_sched_barrier(0);
; #pragma unroll
;     for (int mm = 0; mm < 2; ++mm)
; #pragma unroll
;       for (int n = 0; n < 4; ++n)
; #pragma unroll
;         for (int j = 0; j < 4; ++j) reg[(mm * 16 + fq * 4 + j) * 68 + n * 16 + fr] = acc[mp * 2 + mm][n][j];
;     __builtin_amdgcn_fence(__ATOMIC_ACQ_REL, "wavefront");
;     epi.tile(reg, row0 + mp * 32, col0, lane);
.LBB0_3021:
	v_mov_b32_e32 v128, v204
	v_mov_b32_e32 v130, v204
	s_nop 0
	v_lshrrev_b32_e32 v130, 6, v130
	v_mul_lo_u32 v130, v130, s56
	v_and_b32_e32 v131, 15, v128
	v_add_u32_e32 v130, 0x10000, v130
	v_lshrrev_b32_e32 v134, 2, v128
	v_bfe_u32 v140, v128, 4, 2
	v_lshlrev_b32_e32 v128, 2, v128
	v_lshl_or_b32 v142, v131, 2, v130
	v_and_b32_e32 v131, 60, v128
	v_lshl_or_b32 v128, v131, 2, v130
	v_and_b32_e32 v141, 12, v134
	v_mad_u32_u24 v128, v140, s57, v128
	v_add_u32_e32 v129, v131, v129
	v_or_b32_e32 v139, 4, v140
	v_or_b32_e32 v138, 8, v140
	v_or_b32_e32 v137, 12, v140
	v_or_b32_e32 v135, 16, v140
	v_or_b32_e32 v134, 20, v140
	v_or_b32_e32 v131, 24, v140
	v_or_b32_e32 v130, 28, v140
	v_mad_u32_u24 v141, v141, s57, v142
	ds_write2_b32 v141, v120, v124 offset1:16
	ds_write2_b32 v141, v121, v125 offset0:68 offset1:84
	ds_write2_b32 v141, v122, v126 offset0:136 offset1:152
	ds_write2_b32 v141, v123, v127 offset0:204 offset1:220
	ds_write2_b32 v141, v112, v116 offset0:32 offset1:48
	ds_write2_b32 v141, v113, v117 offset0:100 offset1:116
	ds_write2_b32 v141, v114, v118 offset0:168 offset1:184
	ds_write2_b32 v141, v115, v119 offset0:236 offset1:252
	v_add_u32_e32 v112, 0x1000, v141
	ds_write2_b32 v112, v104, v108 offset0:64 offset1:80
	ds_write2_b32 v112, v105, v109 offset0:132 offset1:148
	ds_write2_b32 v112, v106, v110 offset0:200 offset1:216
	v_add_u32_e32 v104, 0x1400, v141
	ds_write2_b32 v104, v107, v111 offset0:12 offset1:28
	ds_write2_b32 v112, v96, v100 offset0:96 offset1:112
	ds_write2_b32 v112, v97, v101 offset0:164 offset1:180
	ds_write2_b32 v112, v98, v102 offset0:232 offset1:248
	ds_write2_b32 v104, v99, v103 offset0:44 offset1:60
	v_add_u32_e32 v176, v140, v136
	v_lshl_add_u32 v176, v176, 10, v129
	v_ashrrev_i32_e32 v177, 31, v176
	v_lshlrev_b64 v[176:177], 1, v[176:177]
	v_lshl_add_u64 v[178:179], s[18:19], 0, v[176:177]
	global_load_dwordx2 v[144:145], v[178:179], off
	v_add_u32_e32 v176, v140, v136
	v_lshl_add_u32 v176, v176, 10, v129
	v_ashrrev_i32_e32 v177, 31, v176
	v_lshlrev_b64 v[176:177], 1, v[176:177]
	v_lshl_add_u64 v[178:179], s[12:13], 0, v[176:177]
	global_load_dwordx2 v[146:147], v[178:179], off
	v_add_u32_e32 v184, v139, v136
	v_lshl_add_u32 v176, v184, 10, v129
	v_ashrrev_i32_e32 v177, 31, v176
	v_lshlrev_b64 v[176:177], 1, v[176:177]
	v_lshl_add_u64 v[178:179], s[18:19], 0, v[176:177]
	global_load_dwordx2 v[148:149], v[178:179], off
	v_add_u32_e32 v184, v139, v136
	v_lshl_add_u32 v178, v184, 10, v129
	v_ashrrev_i32_e32 v179, 31, v178
	v_lshlrev_b64 v[178:179], 1, v[178:179]
	v_lshl_add_u64 v[176:177], s[12:13], 0, v[178:179]
	global_load_dwordx2 v[150:151], v[176:177], off
	v_add_u32_e32 v184, v138, v136
	v_lshl_add_u32 v176, v184, 10, v129
	v_ashrrev_i32_e32 v177, 31, v176
	v_lshlrev_b64 v[176:177], 1, v[176:177]
	v_lshl_add_u64 v[178:179], s[18:19], 0, v[176:177]
	global_load_dwordx2 v[152:153], v[178:179], off
	v_add_u32_e32 v184, v138, v136
	v_lshl_add_u32 v176, v184, 10, v129
	v_ashrrev_i32_e32 v177, 31, v176
	v_lshlrev_b64 v[176:177], 1, v[176:177]
	v_lshl_add_u64 v[176:177], s[12:13], 0, v[176:177]
	global_load_dwordx2 v[154:155], v[176:177], off
	v_add_u32_e32 v184, v137, v136
	v_lshl_add_u32 v176, v184, 10, v129
	v_ashrrev_i32_e32 v177, 31, v176
	v_lshlrev_b64 v[176:177], 1, v[176:177]
	v_lshl_add_u64 v[178:179], s[18:19], 0, v[176:177]
	global_load_dwordx2 v[156:157], v[178:179], off
	v_add_u32_e32 v184, v137, v136
	v_lshl_add_u32 v178, v184, 10, v129
	v_ashrrev_i32_e32 v179, 31, v178
	v_lshlrev_b64 v[178:179], 1, v[178:179]
	v_lshl_add_u64 v[176:177], s[12:13], 0, v[178:179]
	global_load_dwordx2 v[158:159], v[176:177], off
	v_add_u32_e32 v176, v135, v136
	v_lshl_add_u32 v176, v176, 10, v129
	v_ashrrev_i32_e32 v177, 31, v176
	v_lshlrev_b64 v[176:177], 1, v[176:177]
	v_lshl_add_u64 v[178:179], s[18:19], 0, v[176:177]
	global_load_dwordx2 v[160:161], v[178:179], off
	v_add_u32_e32 v176, v135, v136
	v_lshl_add_u32 v176, v176, 10, v129
	v_ashrrev_i32_e32 v177, 31, v176
	v_lshlrev_b64 v[176:177], 1, v[176:177]
	v_lshl_add_u64 v[178:179], s[12:13], 0, v[176:177]
	global_load_dwordx2 v[162:163], v[178:179], off
	v_add_u32_e32 v184, v134, v136
	v_lshl_add_u32 v176, v184, 10, v129
	v_ashrrev_i32_e32 v177, 31, v176
	v_lshlrev_b64 v[176:177], 1, v[176:177]
	v_lshl_add_u64 v[178:179], s[18:19], 0, v[176:177]
	global_load_dwordx2 v[164:165], v[178:179], off
	v_add_u32_e32 v184, v134, v136
	v_lshl_add_u32 v178, v184, 10, v129
	v_ashrrev_i32_e32 v179, 31, v178
	v_lshlrev_b64 v[178:179], 1, v[178:179]
	v_lshl_add_u64 v[176:177], s[12:13], 0, v[178:179]
	global_load_dwordx2 v[166:167], v[176:177], off
	v_add_u32_e32 v184, v131, v136
	v_lshl_add_u32 v176, v184, 10, v129
	v_ashrrev_i32_e32 v177, 31, v176
	v_lshlrev_b64 v[176:177], 1, v[176:177]
	v_lshl_add_u64 v[178:179], s[18:19], 0, v[176:177]
	global_load_dwordx2 v[168:169], v[178:179], off
	v_add_u32_e32 v184, v131, v136
	v_lshl_add_u32 v176, v184, 10, v129
	v_ashrrev_i32_e32 v177, 31, v176
	v_lshlrev_b64 v[176:177], 1, v[176:177]
	v_lshl_add_u64 v[176:177], s[12:13], 0, v[176:177]
	global_load_dwordx2 v[170:171], v[176:177], off
	v_add_u32_e32 v184, v130, v136
	v_lshl_add_u32 v176, v184, 10, v129
	v_ashrrev_i32_e32 v177, 31, v176
	v_lshlrev_b64 v[176:177], 1, v[176:177]
	v_lshl_add_u64 v[178:179], s[18:19], 0, v[176:177]
	global_load_dwordx2 v[172:173], v[178:179], off
	v_add_u32_e32 v184, v130, v136
	v_lshl_add_u32 v178, v184, 10, v129
	v_ashrrev_i32_e32 v179, 31, v178
	v_lshlrev_b64 v[178:179], 1, v[178:179]
	v_lshl_add_u64 v[176:177], s[12:13], 0, v[178:179]
	global_load_dwordx2 v[174:175], v[176:177], off
	v_add_u32_e32 v96, v140, v136
	v_lshl_add_u32 v96, v96, 10, v129
	v_ashrrev_i32_e32 v97, 31, v96
	v_lshlrev_b64 v[96:97], 1, v[96:97]
	v_lshl_add_u64 v[98:99], s[18:19], 0, v[96:97]
	v_lshl_add_u64 v[108:109], s[12:13], 0, v[96:97]
	s_waitcnt vmcnt(14)
; __device__ __forceinline__ float bfs2f(short h) { return __uint_as_float(((unsigned)(u16)h) << 16); }
;   __device__ __forceinline__ void tile(const float* reg, int row0, int col0, int lane) const {
;     rows4(reg, lane, [&](int it, int rr, int c4, float4 v) {
;       int idx = (row0 + rr) * 1024 + col0 + c4;
;       bf16x4 gt = *(const bf16x4*)(gate + idx), mo = *(const bf16x4*)(merged + idx);
;       *(bf16x4*)(merged + idx) = pack4(fmaf(bfs2f(gt[0]), v.x, bfs2f(mo[0])), fmaf(bfs2f(gt[1]), v.y, bfs2f(mo[1])),
;                                        fmaf(bfs2f(gt[2]), v.z, bfs2f(mo[2])), fmaf(bfs2f(gt[3]), v.w, bfs2f(mo[3])));
;     });
	v_mov_b32_e32 v106, v144
	v_mov_b32_e32 v107, v145
	v_mov_b32_e32 v110, v146
	v_mov_b32_e32 v111, v147
	ds_read_b128 v[96:99], v128
	ds_read_b128 v[100:103], v128 offset:1088
	v_add_u32_e32 v105, v139, v136
	v_lshl_add_u32 v114, v105, 10, v129
	v_ashrrev_i32_e32 v115, 31, v114
	v_lshlrev_b64 v[114:115], 1, v[114:115]
	v_lshl_add_u64 v[116:117], s[18:19], 0, v[114:115]
	v_add_u32_e32 v105, v138, v136
	v_and_b32_e32 v119, 0xffff0000, v106
	v_lshlrev_b32_e32 v118, 16, v106
	v_and_b32_e32 v121, 0xffff0000, v110
	v_lshlrev_b32_e32 v120, 16, v110
	v_and_b32_e32 v123, 0xffff0000, v107
	v_lshlrev_b32_e32 v122, 16, v107
	v_and_b32_e32 v107, 0xffff0000, v111
	v_lshlrev_b32_e32 v106, 16, v111
	s_waitcnt lgkmcnt(0)
	v_pk_fma_f32 v[96:97], v[118:119], v[96:97], v[120:121]
	v_pk_fma_f32 v[98:99], v[122:123], v[98:99], v[106:107]
	v_cvt_pk_bf16_f32 v96, v96, v97
	v_cvt_pk_bf16_f32 v97, v98, v99
	global_store_dwordx2 v[108:109], v[96:97], off
	v_lshl_add_u64 v[98:99], s[12:13], 0, v[114:115]
	v_lshl_add_u32 v108, v105, 10, v129
	v_ashrrev_i32_e32 v109, 31, v108
	v_lshlrev_b64 v[108:109], 1, v[108:109]
	v_lshl_add_u64 v[110:111], s[18:19], 0, v[108:109]
	v_lshl_add_u64 v[108:109], s[12:13], 0, v[108:109]
	v_add_u32_e32 v105, v137, v136
	s_waitcnt vmcnt(14)
	v_mov_b32_e32 v96, v148
	v_mov_b32_e32 v97, v149
	v_and_b32_e32 v115, 0xffff0000, v96
	v_lshlrev_b32_e32 v114, 16, v96
	s_waitcnt vmcnt(13)
	v_mov_b32_e32 v106, v150
	v_mov_b32_e32 v107, v151
	v_and_b32_e32 v117, 0xffff0000, v106
	v_lshlrev_b32_e32 v116, 16, v106
	v_and_b32_e32 v119, 0xffff0000, v97
	v_lshlrev_b32_e32 v118, 16, v97
	v_and_b32_e32 v97, 0xffff0000, v107
	v_lshlrev_b32_e32 v96, 16, v107
	v_pk_fma_f32 v[100:101], v[114:115], v[100:101], v[116:117]
	v_pk_fma_f32 v[96:97], v[118:119], v[102:103], v[96:97]
	v_cvt_pk_bf16_f32 v100, v100, v101
	v_cvt_pk_bf16_f32 v101, v96, v97
	global_store_dwordx2 v[98:99], v[100:101], off
	v_lshl_add_u32 v114, v105, 10, v129
	ds_read_b128 v[96:99], v128 offset:2176
	ds_read_b128 v[100:103], v128 offset:3264
	v_ashrrev_i32_e32 v115, 31, v114
	v_lshlrev_b64 v[114:115], 1, v[114:115]
	v_lshl_add_u64 v[116:117], s[18:19], 0, v[114:115]
	s_waitcnt vmcnt(13)
	v_mov_b32_e32 v106, v152
	v_mov_b32_e32 v107, v153
	v_and_b32_e32 v119, 0xffff0000, v106
	v_lshlrev_b32_e32 v118, 16, v106
	s_waitcnt vmcnt(12)
	v_mov_b32_e32 v110, v154
	v_mov_b32_e32 v111, v155
	v_and_b32_e32 v121, 0xffff0000, v110
	v_lshlrev_b32_e32 v120, 16, v110
	v_and_b32_e32 v123, 0xffff0000, v107
	v_lshlrev_b32_e32 v122, 16, v107
	v_and_b32_e32 v107, 0xffff0000, v111
	v_lshlrev_b32_e32 v106, 16, v111
	s_waitcnt lgkmcnt(1)
	v_pk_fma_f32 v[96:97], v[118:119], v[96:97], v[120:121]
	v_pk_fma_f32 v[98:99], v[122:123], v[98:99], v[106:107]
	v_cvt_pk_bf16_f32 v96, v96, v97
	v_cvt_pk_bf16_f32 v97, v98, v99
	global_store_dwordx2 v[108:109], v[96:97], off
	v_lshl_add_u64 v[98:99], s[12:13], 0, v[114:115]
	s_waitcnt vmcnt(12)
	v_mov_b32_e32 v96, v156
	v_mov_b32_e32 v97, v157
	v_and_b32_e32 v109, 0xffff0000, v96
	v_lshlrev_b32_e32 v108, 16, v96
	s_waitcnt vmcnt(11)
	v_mov_b32_e32 v106, v158
	v_mov_b32_e32 v107, v159
	v_and_b32_e32 v111, 0xffff0000, v106
	v_lshlrev_b32_e32 v110, 16, v106
	v_and_b32_e32 v115, 0xffff0000, v97
	v_lshlrev_b32_e32 v114, 16, v97
	v_and_b32_e32 v97, 0xffff0000, v107
	v_lshlrev_b32_e32 v96, 16, v107
	s_waitcnt lgkmcnt(0)
	v_pk_fma_f32 v[100:101], v[108:109], v[100:101], v[110:111]
	v_pk_fma_f32 v[96:97], v[114:115], v[102:103], v[96:97]
	v_cvt_pk_bf16_f32 v100, v100, v101
	v_cvt_pk_bf16_f32 v101, v96, v97
	global_store_dwordx2 v[98:99], v[100:101], off
	v_add_u32_e32 v96, v135, v136
	v_lshl_add_u32 v96, v96, 10, v129
	v_ashrrev_i32_e32 v97, 31, v96
	v_lshlrev_b64 v[96:97], 1, v[96:97]
	v_lshl_add_u64 v[98:99], s[18:19], 0, v[96:97]
	v_lshl_add_u64 v[108:109], s[12:13], 0, v[96:97]
	ds_read_b128 v[96:99], v128 offset:4352
	ds_read_b128 v[100:103], v128 offset:5440
	v_add_u32_e32 v105, v134, v136
	v_lshl_add_u32 v114, v105, 10, v129
	v_ashrrev_i32_e32 v115, 31, v114
	v_lshlrev_b64 v[114:115], 1, v[114:115]
	v_lshl_add_u64 v[116:117], s[18:19], 0, v[114:115]
	v_add_u32_e32 v105, v131, v136
	s_waitcnt vmcnt(11)
	v_mov_b32_e32 v106, v160
	v_mov_b32_e32 v107, v161
	v_and_b32_e32 v119, 0xffff0000, v106
	v_lshlrev_b32_e32 v118, 16, v106
	s_waitcnt vmcnt(10)
	v_mov_b32_e32 v110, v162
	v_mov_b32_e32 v111, v163
	v_and_b32_e32 v121, 0xffff0000, v110
	v_lshlrev_b32_e32 v120, 16, v110
	v_and_b32_e32 v123, 0xffff0000, v107
	v_lshlrev_b32_e32 v122, 16, v107
	v_and_b32_e32 v107, 0xffff0000, v111
	v_lshlrev_b32_e32 v106, 16, v111
	s_waitcnt lgkmcnt(1)
	v_pk_fma_f32 v[96:97], v[118:119], v[96:97], v[120:121]
	v_pk_fma_f32 v[98:99], v[122:123], v[98:99], v[106:107]
	v_cvt_pk_bf16_f32 v96, v96, v97
	v_cvt_pk_bf16_f32 v97, v98, v99
	global_store_dwordx2 v[108:109], v[96:97], off
	v_lshl_add_u64 v[98:99], s[12:13], 0, v[114:115]
	v_lshl_add_u32 v108, v105, 10, v129
	v_ashrrev_i32_e32 v109, 31, v108
	v_lshlrev_b64 v[108:109], 1, v[108:109]
	v_lshl_add_u64 v[110:111], s[18:19], 0, v[108:109]
	v_lshl_add_u64 v[108:109], s[12:13], 0, v[108:109]
	v_add_u32_e32 v105, v130, v136
	s_waitcnt vmcnt(10)
	v_mov_b32_e32 v96, v164
	v_mov_b32_e32 v97, v165
	v_and_b32_e32 v115, 0xffff0000, v96
	v_lshlrev_b32_e32 v114, 16, v96
	s_waitcnt vmcnt(9)
	v_mov_b32_e32 v106, v166
	v_mov_b32_e32 v107, v167
	v_and_b32_e32 v117, 0xffff0000, v106
	v_lshlrev_b32_e32 v116, 16, v106
	v_and_b32_e32 v119, 0xffff0000, v97
	v_lshlrev_b32_e32 v118, 16, v97
	v_and_b32_e32 v97, 0xffff0000, v107
	v_lshlrev_b32_e32 v96, 16, v107
	s_waitcnt lgkmcnt(0)
; __device__ __forceinline__ float bfs2f(short h) { return __uint_as_float(((unsigned)(u16)h) << 16); }
;   __device__ __forceinline__ void tile(const float* reg, int row0, int col0, int lane) const {
;     rows4(reg, lane, [&](int it, int rr, int c4, float4 v) {
;       int idx = (row0 + rr) * 1024 + col0 + c4;
;       bf16x4 gt = *(const bf16x4*)(gate + idx), mo = *(const bf16x4*)(merged + idx);
;       *(bf16x4*)(merged + idx) = pack4(fmaf(bfs2f(gt[0]), v.x, bfs2f(mo[0])), fmaf(bfs2f(gt[1]), v.y, bfs2f(mo[1])),
;                                        fmaf(bfs2f(gt[2]), v.z, bfs2f(mo[2])), fmaf(bfs2f(gt[3]), v.w, bfs2f(mo[3])));
;     });
; template <int MF, class Epi>
; __device__ __forceinline__ void staged_epilogue(f32x4 (&acc)[MF][4], int row0, int col0, const Epi& epi) {
;     ...
;     for (int mm = 0; mm < 2; ++mm)
; #pragma unroll
;       for (int n = 0; n < 4; ++n)
; #pragma unroll
;         for (int j = 0; j < 4; ++j) reg[(mm * 16 + fq * 4 + j) * 68 + n * 16 + fr] = acc[mp * 2 + mm][n][j];
	v_pk_fma_f32 v[100:101], v[114:115], v[100:101], v[116:117]
	v_pk_fma_f32 v[96:97], v[118:119], v[102:103], v[96:97]
	v_cvt_pk_bf16_f32 v100, v100, v101
	v_cvt_pk_bf16_f32 v101, v96, v97
	global_store_dwordx2 v[98:99], v[100:101], off
	v_lshl_add_u32 v114, v105, 10, v129
	ds_read_b128 v[96:99], v128 offset:6528
	ds_read_b128 v[100:103], v128 offset:7616
	v_ashrrev_i32_e32 v115, 31, v114
	v_lshlrev_b64 v[114:115], 1, v[114:115]
	v_lshl_add_u64 v[116:117], s[18:19], 0, v[114:115]
	s_waitcnt vmcnt(9)
	v_mov_b32_e32 v106, v168
	v_mov_b32_e32 v107, v169
	v_and_b32_e32 v119, 0xffff0000, v106
	v_lshlrev_b32_e32 v118, 16, v106
	s_waitcnt vmcnt(8)
	v_mov_b32_e32 v110, v170
	v_mov_b32_e32 v111, v171
	v_and_b32_e32 v121, 0xffff0000, v110
	v_lshlrev_b32_e32 v120, 16, v110
	v_and_b32_e32 v123, 0xffff0000, v107
	v_lshlrev_b32_e32 v122, 16, v107
	v_and_b32_e32 v107, 0xffff0000, v111
	v_lshlrev_b32_e32 v106, 16, v111
	s_waitcnt lgkmcnt(1)
	v_pk_fma_f32 v[96:97], v[118:119], v[96:97], v[120:121]
	v_pk_fma_f32 v[98:99], v[122:123], v[98:99], v[106:107]
	v_cvt_pk_bf16_f32 v96, v96, v97
	v_cvt_pk_bf16_f32 v97, v98, v99
	global_store_dwordx2 v[108:109], v[96:97], off
	v_lshl_add_u64 v[98:99], s[12:13], 0, v[114:115]
	s_waitcnt vmcnt(8)
	v_mov_b32_e32 v96, v172
	v_mov_b32_e32 v97, v173
	v_and_b32_e32 v109, 0xffff0000, v96
	v_lshlrev_b32_e32 v108, 16, v96
	s_waitcnt vmcnt(7)
	v_mov_b32_e32 v106, v174
	v_mov_b32_e32 v107, v175
	v_and_b32_e32 v111, 0xffff0000, v106
	v_lshlrev_b32_e32 v110, 16, v106
	v_and_b32_e32 v115, 0xffff0000, v97
	v_lshlrev_b32_e32 v114, 16, v97
	v_and_b32_e32 v97, 0xffff0000, v107
	v_lshlrev_b32_e32 v96, 16, v107
	s_waitcnt lgkmcnt(0)
	v_pk_fma_f32 v[100:101], v[108:109], v[100:101], v[110:111]
	v_pk_fma_f32 v[96:97], v[114:115], v[102:103], v[96:97]
	v_cvt_pk_bf16_f32 v100, v100, v101
	v_cvt_pk_bf16_f32 v101, v96, v97
	global_store_dwordx2 v[98:99], v[100:101], off
	ds_write2_b32 v141, v88, v92 offset1:16
	ds_write2_b32 v141, v89, v93 offset0:68 offset1:84
	ds_write2_b32 v141, v90, v94 offset0:136 offset1:152
	ds_write2_b32 v141, v91, v95 offset0:204 offset1:220
	ds_write2_b32 v141, v80, v84 offset0:32 offset1:48
	ds_write2_b32 v141, v81, v85 offset0:100 offset1:116
	ds_write2_b32 v141, v82, v86 offset0:168 offset1:184
	ds_write2_b32 v141, v83, v87 offset0:236 offset1:252
	ds_write2_b32 v112, v72, v76 offset0:64 offset1:80
	ds_write2_b32 v112, v73, v77 offset0:132 offset1:148
	ds_write2_b32 v112, v74, v78 offset0:200 offset1:216
	ds_write2_b32 v104, v75, v79 offset0:12 offset1:28
	ds_write2_b32 v112, v64, v68 offset0:96 offset1:112
	ds_write2_b32 v112, v65, v69 offset0:164 offset1:180
	ds_write2_b32 v112, v66, v70 offset0:232 offset1:248
	ds_write2_b32 v104, v67, v71 offset0:44 offset1:60
	v_add_u32_e32 v184, 32, v136
	v_add_u32_e32 v176, v140, v184
	v_lshl_add_u32 v176, v176, 10, v129
	v_ashrrev_i32_e32 v177, 31, v176
	v_lshlrev_b64 v[176:177], 1, v[176:177]
	v_lshl_add_u64 v[178:179], s[18:19], 0, v[176:177]
	global_load_dwordx2 v[144:145], v[178:179], off
	v_add_u32_e32 v184, 32, v136
	v_add_u32_e32 v176, v140, v184
	v_lshl_add_u32 v176, v176, 10, v129
	v_ashrrev_i32_e32 v177, 31, v176
	v_lshlrev_b64 v[176:177], 1, v[176:177]
	v_lshl_add_u64 v[178:179], s[12:13], 0, v[176:177]
	global_load_dwordx2 v[146:147], v[178:179], off
	v_add_u32_e32 v184, 32, v136
	v_add_u32_e32 v176, v139, v184
	v_lshl_add_u32 v176, v176, 10, v129
	v_ashrrev_i32_e32 v177, 31, v176
	v_lshlrev_b64 v[176:177], 1, v[176:177]
	v_lshl_add_u64 v[178:179], s[18:19], 0, v[176:177]
	global_load_dwordx2 v[148:149], v[178:179], off
	v_add_u32_e32 v184, 32, v136
	v_add_u32_e32 v178, v139, v184
	v_lshl_add_u32 v178, v178, 10, v129
	v_ashrrev_i32_e32 v179, 31, v178
	v_lshlrev_b64 v[178:179], 1, v[178:179]
	v_lshl_add_u64 v[176:177], s[12:13], 0, v[178:179]
	global_load_dwordx2 v[150:151], v[176:177], off
	v_add_u32_e32 v184, 32, v136
	v_add_u32_e32 v176, v138, v184
	v_lshl_add_u32 v176, v176, 10, v129
	v_ashrrev_i32_e32 v177, 31, v176
	v_lshlrev_b64 v[176:177], 1, v[176:177]
	v_lshl_add_u64 v[178:179], s[18:19], 0, v[176:177]
	global_load_dwordx2 v[152:153], v[178:179], off
	v_add_u32_e32 v184, 32, v136
	v_add_u32_e32 v176, v138, v184
	v_lshl_add_u32 v176, v176, 10, v129
	v_ashrrev_i32_e32 v177, 31, v176
	v_lshlrev_b64 v[176:177], 1, v[176:177]
	v_lshl_add_u64 v[176:177], s[12:13], 0, v[176:177]
	global_load_dwordx2 v[154:155], v[176:177], off
	v_add_u32_e32 v184, 32, v136
	v_add_u32_e32 v176, v137, v184
	v_lshl_add_u32 v176, v176, 10, v129
	v_ashrrev_i32_e32 v177, 31, v176
	v_lshlrev_b64 v[176:177], 1, v[176:177]
	v_lshl_add_u64 v[178:179], s[18:19], 0, v[176:177]
	global_load_dwordx2 v[156:157], v[178:179], off
	v_add_u32_e32 v184, 32, v136
	v_add_u32_e32 v178, v137, v184
	v_lshl_add_u32 v178, v178, 10, v129
	v_ashrrev_i32_e32 v179, 31, v178
	v_lshlrev_b64 v[178:179], 1, v[178:179]
	v_lshl_add_u64 v[176:177], s[12:13], 0, v[178:179]
	global_load_dwordx2 v[158:159], v[176:177], off
	v_add_u32_e32 v184, 32, v136
	v_add_u32_e32 v176, v135, v184
	v_lshl_add_u32 v176, v176, 10, v129
	v_ashrrev_i32_e32 v177, 31, v176
	v_lshlrev_b64 v[176:177], 1, v[176:177]
	v_lshl_add_u64 v[178:179], s[18:19], 0, v[176:177]
	global_load_dwordx2 v[160:161], v[178:179], off
	v_add_u32_e32 v184, 32, v136
	v_add_u32_e32 v176, v135, v184
	v_lshl_add_u32 v176, v176, 10, v129
	v_ashrrev_i32_e32 v177, 31, v176
	v_lshlrev_b64 v[176:177], 1, v[176:177]
	v_lshl_add_u64 v[178:179], s[12:13], 0, v[176:177]
	global_load_dwordx2 v[162:163], v[178:179], off
	v_add_u32_e32 v184, 32, v136
	v_add_u32_e32 v176, v134, v184
	v_lshl_add_u32 v176, v176, 10, v129
	v_ashrrev_i32_e32 v177, 31, v176
; __device__ __forceinline__ float bfs2f(short h) { return __uint_as_float(((unsigned)(u16)h) << 16); }
;   __device__ __forceinline__ void tile(const float* reg, int row0, int col0, int lane) const {
;     rows4(reg, lane, [&](int it, int rr, int c4, float4 v) {
;       int idx = (row0 + rr) * 1024 + col0 + c4;
;       bf16x4 gt = *(const bf16x4*)(gate + idx), mo = *(const bf16x4*)(merged + idx);
;       *(bf16x4*)(merged + idx) = pack4(fmaf(bfs2f(gt[0]), v.x, bfs2f(mo[0])), fmaf(bfs2f(gt[1]), v.y, bfs2f(mo[1])),
;                                        fmaf(bfs2f(gt[2]), v.z, bfs2f(mo[2])), fmaf(bfs2f(gt[3]), v.w, bfs2f(mo[3])));
;     });
	v_lshlrev_b64 v[176:177], 1, v[176:177]
	v_lshl_add_u64 v[178:179], s[18:19], 0, v[176:177]
	global_load_dwordx2 v[164:165], v[178:179], off
	v_add_u32_e32 v184, 32, v136
	v_add_u32_e32 v178, v134, v184
	v_lshl_add_u32 v178, v178, 10, v129
	v_ashrrev_i32_e32 v179, 31, v178
	v_lshlrev_b64 v[178:179], 1, v[178:179]
	v_lshl_add_u64 v[176:177], s[12:13], 0, v[178:179]
	global_load_dwordx2 v[166:167], v[176:177], off
	v_add_u32_e32 v184, 32, v136
	v_add_u32_e32 v176, v131, v184
	v_lshl_add_u32 v176, v176, 10, v129
	v_ashrrev_i32_e32 v177, 31, v176
	v_lshlrev_b64 v[176:177], 1, v[176:177]
	v_lshl_add_u64 v[178:179], s[18:19], 0, v[176:177]
	global_load_dwordx2 v[168:169], v[178:179], off
	v_add_u32_e32 v184, 32, v136
	v_add_u32_e32 v176, v131, v184
	v_lshl_add_u32 v176, v176, 10, v129
	v_ashrrev_i32_e32 v177, 31, v176
	v_lshlrev_b64 v[176:177], 1, v[176:177]
	v_lshl_add_u64 v[176:177], s[12:13], 0, v[176:177]
	global_load_dwordx2 v[170:171], v[176:177], off
	v_add_u32_e32 v184, 32, v136
	v_add_u32_e32 v176, v130, v184
	v_lshl_add_u32 v176, v176, 10, v129
	v_ashrrev_i32_e32 v177, 31, v176
	v_lshlrev_b64 v[176:177], 1, v[176:177]
	v_lshl_add_u64 v[178:179], s[18:19], 0, v[176:177]
	global_load_dwordx2 v[172:173], v[178:179], off
	v_add_u32_e32 v184, 32, v136
	v_add_u32_e32 v178, v130, v184
	v_lshl_add_u32 v178, v178, 10, v129
	v_ashrrev_i32_e32 v179, 31, v178
	v_lshlrev_b64 v[178:179], 1, v[178:179]
	v_lshl_add_u64 v[176:177], s[12:13], 0, v[178:179]
	global_load_dwordx2 v[174:175], v[176:177], off
	v_add_u32_e32 v88, 32, v136
	v_add_u32_e32 v64, v140, v88
	v_lshl_add_u32 v64, v64, 10, v129
	v_ashrrev_i32_e32 v65, 31, v64
	v_lshlrev_b64 v[64:65], 1, v[64:65]
	v_lshl_add_u64 v[66:67], s[18:19], 0, v[64:65]
	v_lshl_add_u64 v[74:75], s[12:13], 0, v[64:65]
	ds_read_b128 v[64:67], v128
	ds_read_b128 v[68:71], v128 offset:1088
	v_add_u32_e32 v78, v139, v88
	v_lshl_add_u32 v78, v78, 10, v129
	v_ashrrev_i32_e32 v79, 31, v78
	v_lshlrev_b64 v[78:79], 1, v[78:79]
	v_lshl_add_u64 v[80:81], s[18:19], 0, v[78:79]
	s_waitcnt vmcnt(15)
	v_mov_b32_e32 v72, v144
	v_mov_b32_e32 v73, v145
	v_and_b32_e32 v83, 0xffff0000, v72
	v_lshlrev_b32_e32 v82, 16, v72
	s_waitcnt vmcnt(14)
	v_mov_b32_e32 v76, v146
	v_mov_b32_e32 v77, v147
	v_and_b32_e32 v85, 0xffff0000, v76
	v_lshlrev_b32_e32 v84, 16, v76
	v_and_b32_e32 v87, 0xffff0000, v73
	v_lshlrev_b32_e32 v86, 16, v73
	v_and_b32_e32 v73, 0xffff0000, v77
	v_lshlrev_b32_e32 v72, 16, v77
	s_waitcnt lgkmcnt(1)
	v_pk_fma_f32 v[64:65], v[82:83], v[64:65], v[84:85]
	v_pk_fma_f32 v[66:67], v[86:87], v[66:67], v[72:73]
	v_cvt_pk_bf16_f32 v64, v64, v65
	v_cvt_pk_bf16_f32 v65, v66, v67
	global_store_dwordx2 v[74:75], v[64:65], off
	v_lshl_add_u64 v[66:67], s[12:13], 0, v[78:79]
	v_add_u32_e32 v74, v138, v88
	v_lshl_add_u32 v74, v74, 10, v129
	v_ashrrev_i32_e32 v75, 31, v74
	v_lshlrev_b64 v[74:75], 1, v[74:75]
	v_lshl_add_u64 v[76:77], s[18:19], 0, v[74:75]
	v_lshl_add_u64 v[74:75], s[12:13], 0, v[74:75]
	s_waitcnt vmcnt(14)
	v_mov_b32_e32 v64, v148
	v_mov_b32_e32 v65, v149
	v_and_b32_e32 v79, 0xffff0000, v64
	v_lshlrev_b32_e32 v78, 16, v64
	s_waitcnt vmcnt(13)
	v_mov_b32_e32 v72, v150
	v_mov_b32_e32 v73, v151
	v_and_b32_e32 v81, 0xffff0000, v72
	v_lshlrev_b32_e32 v80, 16, v72
	v_and_b32_e32 v83, 0xffff0000, v65
	v_lshlrev_b32_e32 v82, 16, v65
	v_and_b32_e32 v65, 0xffff0000, v73
	v_lshlrev_b32_e32 v64, 16, v73
	s_waitcnt lgkmcnt(0)
	v_pk_fma_f32 v[68:69], v[78:79], v[68:69], v[80:81]
	v_pk_fma_f32 v[64:65], v[82:83], v[70:71], v[64:65]
	v_cvt_pk_bf16_f32 v68, v68, v69
	v_cvt_pk_bf16_f32 v69, v64, v65
	global_store_dwordx2 v[66:67], v[68:69], off
	v_add_u32_e32 v78, v137, v88
	ds_read_b128 v[64:67], v128 offset:2176
	ds_read_b128 v[68:71], v128 offset:3264
	v_lshl_add_u32 v78, v78, 10, v129
	v_ashrrev_i32_e32 v79, 31, v78
	v_lshlrev_b64 v[78:79], 1, v[78:79]
	v_lshl_add_u64 v[80:81], s[18:19], 0, v[78:79]
	s_waitcnt vmcnt(13)
	v_mov_b32_e32 v72, v152
	v_mov_b32_e32 v73, v153
	v_and_b32_e32 v83, 0xffff0000, v72
	v_lshlrev_b32_e32 v82, 16, v72
	s_waitcnt vmcnt(12)
	v_mov_b32_e32 v76, v154
	v_mov_b32_e32 v77, v155
	v_and_b32_e32 v85, 0xffff0000, v76
	v_lshlrev_b32_e32 v84, 16, v76
	v_and_b32_e32 v87, 0xffff0000, v73
	v_lshlrev_b32_e32 v86, 16, v73
	v_and_b32_e32 v73, 0xffff0000, v77
	v_lshlrev_b32_e32 v72, 16, v77
	s_waitcnt lgkmcnt(1)
	v_pk_fma_f32 v[64:65], v[82:83], v[64:65], v[84:85]
	v_pk_fma_f32 v[66:67], v[86:87], v[66:67], v[72:73]
	v_cvt_pk_bf16_f32 v64, v64, v65
	v_cvt_pk_bf16_f32 v65, v66, v67
	global_store_dwordx2 v[74:75], v[64:65], off
	v_lshl_add_u64 v[66:67], s[12:13], 0, v[78:79]
	s_waitcnt vmcnt(12)
	v_mov_b32_e32 v64, v156
	v_mov_b32_e32 v65, v157
	v_and_b32_e32 v75, 0xffff0000, v64
	v_lshlrev_b32_e32 v74, 16, v64
	s_waitcnt vmcnt(11)
	v_mov_b32_e32 v72, v158
	v_mov_b32_e32 v73, v159
	v_and_b32_e32 v77, 0xffff0000, v72
	v_lshlrev_b32_e32 v76, 16, v72
	v_and_b32_e32 v79, 0xffff0000, v65
	v_lshlrev_b32_e32 v78, 16, v65
	v_and_b32_e32 v65, 0xffff0000, v73
	v_lshlrev_b32_e32 v64, 16, v73
	s_waitcnt lgkmcnt(0)
	v_pk_fma_f32 v[68:69], v[74:75], v[68:69], v[76:77]
	v_pk_fma_f32 v[64:65], v[78:79], v[70:71], v[64:65]
	v_cvt_pk_bf16_f32 v68, v68, v69
	v_cvt_pk_bf16_f32 v69, v64, v65
	global_store_dwordx2 v[66:67], v[68:69], off
	v_add_u32_e32 v64, v135, v88
	v_lshl_add_u32 v64, v64, 10, v129
	v_ashrrev_i32_e32 v65, 31, v64
	v_lshlrev_b64 v[64:65], 1, v[64:65]
	v_lshl_add_u64 v[66:67], s[18:19], 0, v[64:65]
	v_lshl_add_u64 v[74:75], s[12:13], 0, v[64:65]
	ds_read_b128 v[64:67], v128 offset:4352
	ds_read_b128 v[68:71], v128 offset:5440
	v_add_u32_e32 v78, v134, v88
	v_lshl_add_u32 v78, v78, 10, v129
	v_ashrrev_i32_e32 v79, 31, v78
	v_lshlrev_b64 v[78:79], 1, v[78:79]
	v_lshl_add_u64 v[80:81], s[18:19], 0, v[78:79]
	s_waitcnt vmcnt(11)
; __device__ __forceinline__ float bfs2f(short h) { return __uint_as_float(((unsigned)(u16)h) << 16); }
;   __device__ __forceinline__ void tile(const float* reg, int row0, int col0, int lane) const {
;     rows4(reg, lane, [&](int it, int rr, int c4, float4 v) {
;       int idx = (row0 + rr) * 1024 + col0 + c4;
;       bf16x4 gt = *(const bf16x4*)(gate + idx), mo = *(const bf16x4*)(merged + idx);
;       *(bf16x4*)(merged + idx) = pack4(fmaf(bfs2f(gt[0]), v.x, bfs2f(mo[0])), fmaf(bfs2f(gt[1]), v.y, bfs2f(mo[1])),
;                                        fmaf(bfs2f(gt[2]), v.z, bfs2f(mo[2])), fmaf(bfs2f(gt[3]), v.w, bfs2f(mo[3])));
;     });
; template <int MF, class Epi>
; __device__ __forceinline__ void staged_epilogue(f32x4 (&acc)[MF][4], int row0, int col0, const Epi& epi) {
;     ...
;     for (int mm = 0; mm < 2; ++mm)
; #pragma unroll
;       for (int n = 0; n < 4; ++n)
; #pragma unroll
;         for (int j = 0; j < 4; ++j) reg[(mm * 16 + fq * 4 + j) * 68 + n * 16 + fr] = acc[mp * 2 + mm][n][j];
	v_mov_b32_e32 v72, v160
	v_mov_b32_e32 v73, v161
	v_and_b32_e32 v83, 0xffff0000, v72
	v_lshlrev_b32_e32 v82, 16, v72
	s_waitcnt vmcnt(10)
	v_mov_b32_e32 v76, v162
	v_mov_b32_e32 v77, v163
	v_and_b32_e32 v85, 0xffff0000, v76
	v_lshlrev_b32_e32 v84, 16, v76
	v_and_b32_e32 v87, 0xffff0000, v73
	v_lshlrev_b32_e32 v86, 16, v73
	v_and_b32_e32 v73, 0xffff0000, v77
	v_lshlrev_b32_e32 v72, 16, v77
	s_waitcnt lgkmcnt(1)
	v_pk_fma_f32 v[64:65], v[82:83], v[64:65], v[84:85]
	v_pk_fma_f32 v[66:67], v[86:87], v[66:67], v[72:73]
	v_cvt_pk_bf16_f32 v64, v64, v65
	v_cvt_pk_bf16_f32 v65, v66, v67
	global_store_dwordx2 v[74:75], v[64:65], off
	v_lshl_add_u64 v[66:67], s[12:13], 0, v[78:79]
	v_add_u32_e32 v74, v131, v88
	v_lshl_add_u32 v74, v74, 10, v129
	v_ashrrev_i32_e32 v75, 31, v74
	v_lshlrev_b64 v[74:75], 1, v[74:75]
	v_lshl_add_u64 v[76:77], s[18:19], 0, v[74:75]
	v_lshl_add_u64 v[74:75], s[12:13], 0, v[74:75]
	s_waitcnt vmcnt(10)
	v_mov_b32_e32 v64, v164
	v_mov_b32_e32 v65, v165
	v_and_b32_e32 v79, 0xffff0000, v64
	v_lshlrev_b32_e32 v78, 16, v64
	s_waitcnt vmcnt(9)
	v_mov_b32_e32 v72, v166
	v_mov_b32_e32 v73, v167
	v_and_b32_e32 v81, 0xffff0000, v72
	v_lshlrev_b32_e32 v80, 16, v72
	v_and_b32_e32 v83, 0xffff0000, v65
	v_lshlrev_b32_e32 v82, 16, v65
	v_and_b32_e32 v65, 0xffff0000, v73
	v_lshlrev_b32_e32 v64, 16, v73
	s_waitcnt lgkmcnt(0)
	v_pk_fma_f32 v[68:69], v[78:79], v[68:69], v[80:81]
	v_pk_fma_f32 v[64:65], v[82:83], v[70:71], v[64:65]
	v_cvt_pk_bf16_f32 v68, v68, v69
	v_cvt_pk_bf16_f32 v69, v64, v65
	global_store_dwordx2 v[66:67], v[68:69], off
	v_add_u32_e32 v78, v130, v88
	ds_read_b128 v[64:67], v128 offset:6528
	ds_read_b128 v[68:71], v128 offset:7616
	v_lshl_add_u32 v78, v78, 10, v129
	v_ashrrev_i32_e32 v79, 31, v78
	v_lshlrev_b64 v[78:79], 1, v[78:79]
	v_lshl_add_u64 v[80:81], s[18:19], 0, v[78:79]
	s_waitcnt vmcnt(9)
	v_mov_b32_e32 v72, v168
	v_mov_b32_e32 v73, v169
	v_and_b32_e32 v83, 0xffff0000, v72
	v_lshlrev_b32_e32 v82, 16, v72
	s_waitcnt vmcnt(8)
	v_mov_b32_e32 v76, v170
	v_mov_b32_e32 v77, v171
	v_and_b32_e32 v85, 0xffff0000, v76
	v_lshlrev_b32_e32 v84, 16, v76
	v_and_b32_e32 v87, 0xffff0000, v73
	v_lshlrev_b32_e32 v86, 16, v73
	v_and_b32_e32 v73, 0xffff0000, v77
	v_lshlrev_b32_e32 v72, 16, v77
	s_waitcnt lgkmcnt(1)
	v_pk_fma_f32 v[64:65], v[82:83], v[64:65], v[84:85]
	v_pk_fma_f32 v[66:67], v[86:87], v[66:67], v[72:73]
	v_cvt_pk_bf16_f32 v64, v64, v65
	v_cvt_pk_bf16_f32 v65, v66, v67
	global_store_dwordx2 v[74:75], v[64:65], off
	v_lshl_add_u64 v[66:67], s[12:13], 0, v[78:79]
	s_waitcnt vmcnt(8)
	v_mov_b32_e32 v64, v172
	v_mov_b32_e32 v65, v173
	v_and_b32_e32 v75, 0xffff0000, v64
	v_lshlrev_b32_e32 v74, 16, v64
	s_waitcnt vmcnt(7)
	v_mov_b32_e32 v72, v174
	v_mov_b32_e32 v73, v175
	v_and_b32_e32 v77, 0xffff0000, v72
	v_lshlrev_b32_e32 v76, 16, v72
	v_and_b32_e32 v79, 0xffff0000, v65
	v_lshlrev_b32_e32 v78, 16, v65
	v_and_b32_e32 v65, 0xffff0000, v73
	v_lshlrev_b32_e32 v64, 16, v73
	s_waitcnt lgkmcnt(0)
	v_pk_fma_f32 v[68:69], v[74:75], v[68:69], v[76:77]
	v_pk_fma_f32 v[64:65], v[78:79], v[70:71], v[64:65]
	v_cvt_pk_bf16_f32 v68, v68, v69
	v_cvt_pk_bf16_f32 v69, v64, v65
	global_store_dwordx2 v[66:67], v[68:69], off
	ds_write2_b32 v141, v56, v60 offset1:16
	ds_write2_b32 v141, v57, v61 offset0:68 offset1:84
	ds_write2_b32 v141, v58, v62 offset0:136 offset1:152
	ds_write2_b32 v141, v59, v63 offset0:204 offset1:220
	ds_write2_b32 v141, v48, v52 offset0:32 offset1:48
	ds_write2_b32 v141, v49, v53 offset0:100 offset1:116
	ds_write2_b32 v141, v50, v54 offset0:168 offset1:184
	ds_write2_b32 v141, v51, v55 offset0:236 offset1:252
	ds_write2_b32 v112, v40, v44 offset0:64 offset1:80
	ds_write2_b32 v112, v41, v45 offset0:132 offset1:148
	ds_write2_b32 v112, v42, v46 offset0:200 offset1:216
	ds_write2_b32 v104, v43, v47 offset0:12 offset1:28
	ds_write2_b32 v112, v32, v36 offset0:96 offset1:112
	ds_write2_b32 v112, v33, v37 offset0:164 offset1:180
	ds_write2_b32 v112, v34, v38 offset0:232 offset1:248
	ds_write2_b32 v104, v35, v39 offset0:44 offset1:60
	v_add_u32_e32 v184, 64, v136
	v_add_u32_e32 v176, v140, v184
	v_lshl_add_u32 v176, v176, 10, v129
	v_ashrrev_i32_e32 v177, 31, v176
	v_lshlrev_b64 v[176:177], 1, v[176:177]
	v_lshl_add_u64 v[178:179], s[18:19], 0, v[176:177]
	global_load_dwordx2 v[144:145], v[178:179], off
	v_add_u32_e32 v184, 64, v136
	v_add_u32_e32 v176, v140, v184
	v_lshl_add_u32 v176, v176, 10, v129
	v_ashrrev_i32_e32 v177, 31, v176
	v_lshlrev_b64 v[176:177], 1, v[176:177]
	v_lshl_add_u64 v[178:179], s[12:13], 0, v[176:177]
	global_load_dwordx2 v[146:147], v[178:179], off
	v_add_u32_e32 v184, 64, v136
	v_add_u32_e32 v176, v139, v184
	v_lshl_add_u32 v176, v176, 10, v129
	v_ashrrev_i32_e32 v177, 31, v176
	v_lshlrev_b64 v[176:177], 1, v[176:177]
	v_lshl_add_u64 v[178:179], s[18:19], 0, v[176:177]
	global_load_dwordx2 v[148:149], v[178:179], off
	v_add_u32_e32 v184, 64, v136
	v_add_u32_e32 v178, v139, v184
	v_lshl_add_u32 v178, v178, 10, v129
	v_ashrrev_i32_e32 v179, 31, v178
	v_lshlrev_b64 v[178:179], 1, v[178:179]
	v_lshl_add_u64 v[176:177], s[12:13], 0, v[178:179]
	global_load_dwordx2 v[150:151], v[176:177], off
	v_add_u32_e32 v184, 64, v136
	v_add_u32_e32 v176, v138, v184
	v_lshl_add_u32 v176, v176, 10, v129
	v_ashrrev_i32_e32 v177, 31, v176
	v_lshlrev_b64 v[176:177], 1, v[176:177]
	v_lshl_add_u64 v[178:179], s[18:19], 0, v[176:177]
	global_load_dwordx2 v[152:153], v[178:179], off
	v_add_u32_e32 v184, 64, v136
	v_add_u32_e32 v176, v138, v184
	v_lshl_add_u32 v176, v176, 10, v129
	v_ashrrev_i32_e32 v177, 31, v176
	v_lshlrev_b64 v[176:177], 1, v[176:177]
	v_lshl_add_u64 v[176:177], s[12:13], 0, v[176:177]
; __device__ __forceinline__ float bfs2f(short h) { return __uint_as_float(((unsigned)(u16)h) << 16); }
;   __device__ __forceinline__ void tile(const float* reg, int row0, int col0, int lane) const {
;     rows4(reg, lane, [&](int it, int rr, int c4, float4 v) {
;       int idx = (row0 + rr) * 1024 + col0 + c4;
;       bf16x4 gt = *(const bf16x4*)(gate + idx), mo = *(const bf16x4*)(merged + idx);
;       *(bf16x4*)(merged + idx) = pack4(fmaf(bfs2f(gt[0]), v.x, bfs2f(mo[0])), fmaf(bfs2f(gt[1]), v.y, bfs2f(mo[1])),
;                                        fmaf(bfs2f(gt[2]), v.z, bfs2f(mo[2])), fmaf(bfs2f(gt[3]), v.w, bfs2f(mo[3])));
;     });
	global_load_dwordx2 v[154:155], v[176:177], off
	v_add_u32_e32 v184, 64, v136
	v_add_u32_e32 v176, v137, v184
	v_lshl_add_u32 v176, v176, 10, v129
	v_ashrrev_i32_e32 v177, 31, v176
	v_lshlrev_b64 v[176:177], 1, v[176:177]
	v_lshl_add_u64 v[178:179], s[18:19], 0, v[176:177]
	global_load_dwordx2 v[156:157], v[178:179], off
	v_add_u32_e32 v184, 64, v136
	v_add_u32_e32 v178, v137, v184
	v_lshl_add_u32 v178, v178, 10, v129
	v_ashrrev_i32_e32 v179, 31, v178
	v_lshlrev_b64 v[178:179], 1, v[178:179]
	v_lshl_add_u64 v[176:177], s[12:13], 0, v[178:179]
	global_load_dwordx2 v[158:159], v[176:177], off
	v_add_u32_e32 v184, 64, v136
	v_add_u32_e32 v176, v135, v184
	v_lshl_add_u32 v176, v176, 10, v129
	v_ashrrev_i32_e32 v177, 31, v176
	v_lshlrev_b64 v[176:177], 1, v[176:177]
	v_lshl_add_u64 v[178:179], s[18:19], 0, v[176:177]
	global_load_dwordx2 v[160:161], v[178:179], off
	v_add_u32_e32 v184, 64, v136
	v_add_u32_e32 v176, v135, v184
	v_lshl_add_u32 v176, v176, 10, v129
	v_ashrrev_i32_e32 v177, 31, v176
	v_lshlrev_b64 v[176:177], 1, v[176:177]
	v_lshl_add_u64 v[178:179], s[12:13], 0, v[176:177]
	global_load_dwordx2 v[162:163], v[178:179], off
	v_add_u32_e32 v184, 64, v136
	v_add_u32_e32 v176, v134, v184
	v_lshl_add_u32 v176, v176, 10, v129
	v_ashrrev_i32_e32 v177, 31, v176
	v_lshlrev_b64 v[176:177], 1, v[176:177]
	v_lshl_add_u64 v[178:179], s[18:19], 0, v[176:177]
	global_load_dwordx2 v[164:165], v[178:179], off
	v_add_u32_e32 v184, 64, v136
	v_add_u32_e32 v178, v134, v184
	v_lshl_add_u32 v178, v178, 10, v129
	v_ashrrev_i32_e32 v179, 31, v178
	v_lshlrev_b64 v[178:179], 1, v[178:179]
	v_lshl_add_u64 v[176:177], s[12:13], 0, v[178:179]
	global_load_dwordx2 v[166:167], v[176:177], off
	v_add_u32_e32 v184, 64, v136
	v_add_u32_e32 v176, v131, v184
	v_lshl_add_u32 v176, v176, 10, v129
	v_ashrrev_i32_e32 v177, 31, v176
	v_lshlrev_b64 v[176:177], 1, v[176:177]
	v_lshl_add_u64 v[178:179], s[18:19], 0, v[176:177]
	global_load_dwordx2 v[168:169], v[178:179], off
	v_add_u32_e32 v184, 64, v136
	v_add_u32_e32 v176, v131, v184
	v_lshl_add_u32 v176, v176, 10, v129
	v_ashrrev_i32_e32 v177, 31, v176
	v_lshlrev_b64 v[176:177], 1, v[176:177]
	v_lshl_add_u64 v[176:177], s[12:13], 0, v[176:177]
	global_load_dwordx2 v[170:171], v[176:177], off
	v_add_u32_e32 v184, 64, v136
	v_add_u32_e32 v176, v130, v184
	v_lshl_add_u32 v176, v176, 10, v129
	v_ashrrev_i32_e32 v177, 31, v176
	v_lshlrev_b64 v[176:177], 1, v[176:177]
	v_lshl_add_u64 v[178:179], s[18:19], 0, v[176:177]
	global_load_dwordx2 v[172:173], v[178:179], off
	v_add_u32_e32 v184, 64, v136
	v_add_u32_e32 v178, v130, v184
	v_lshl_add_u32 v178, v178, 10, v129
	v_ashrrev_i32_e32 v179, 31, v178
	v_lshlrev_b64 v[178:179], 1, v[178:179]
	v_lshl_add_u64 v[176:177], s[12:13], 0, v[178:179]
	global_load_dwordx2 v[174:175], v[176:177], off
	v_add_u32_e32 v56, 64, v136
	v_add_u32_e32 v32, v140, v56
	v_lshl_add_u32 v32, v32, 10, v129
	v_ashrrev_i32_e32 v33, 31, v32
	v_lshlrev_b64 v[32:33], 1, v[32:33]
	v_lshl_add_u64 v[34:35], s[18:19], 0, v[32:33]
	v_lshl_add_u64 v[42:43], s[12:13], 0, v[32:33]
	ds_read_b128 v[32:35], v128
	ds_read_b128 v[36:39], v128 offset:1088
	v_add_u32_e32 v46, v139, v56
	v_lshl_add_u32 v46, v46, 10, v129
	v_ashrrev_i32_e32 v47, 31, v46
	v_lshlrev_b64 v[46:47], 1, v[46:47]
	v_lshl_add_u64 v[48:49], s[18:19], 0, v[46:47]
	s_waitcnt vmcnt(15)
	v_mov_b32_e32 v40, v144
	v_mov_b32_e32 v41, v145
	v_and_b32_e32 v51, 0xffff0000, v40
	v_lshlrev_b32_e32 v50, 16, v40
	s_waitcnt vmcnt(14)
	v_mov_b32_e32 v44, v146
	v_mov_b32_e32 v45, v147
	v_and_b32_e32 v53, 0xffff0000, v44
	v_lshlrev_b32_e32 v52, 16, v44
	v_and_b32_e32 v55, 0xffff0000, v41
	v_lshlrev_b32_e32 v54, 16, v41
	v_and_b32_e32 v41, 0xffff0000, v45
	v_lshlrev_b32_e32 v40, 16, v45
	s_waitcnt lgkmcnt(1)
	v_pk_fma_f32 v[32:33], v[50:51], v[32:33], v[52:53]
	v_pk_fma_f32 v[34:35], v[54:55], v[34:35], v[40:41]
	v_cvt_pk_bf16_f32 v32, v32, v33
	v_cvt_pk_bf16_f32 v33, v34, v35
	global_store_dwordx2 v[42:43], v[32:33], off
	v_lshl_add_u64 v[34:35], s[12:13], 0, v[46:47]
	v_add_u32_e32 v42, v138, v56
	v_lshl_add_u32 v42, v42, 10, v129
	v_ashrrev_i32_e32 v43, 31, v42
	v_lshlrev_b64 v[42:43], 1, v[42:43]
	v_lshl_add_u64 v[44:45], s[18:19], 0, v[42:43]
	v_lshl_add_u64 v[42:43], s[12:13], 0, v[42:43]
	s_waitcnt vmcnt(14)
	v_mov_b32_e32 v32, v148
	v_mov_b32_e32 v33, v149
	v_and_b32_e32 v47, 0xffff0000, v32
	v_lshlrev_b32_e32 v46, 16, v32
	s_waitcnt vmcnt(13)
	v_mov_b32_e32 v40, v150
	v_mov_b32_e32 v41, v151
	v_and_b32_e32 v49, 0xffff0000, v40
	v_lshlrev_b32_e32 v48, 16, v40
	v_and_b32_e32 v51, 0xffff0000, v33
	v_lshlrev_b32_e32 v50, 16, v33
	v_and_b32_e32 v33, 0xffff0000, v41
	v_lshlrev_b32_e32 v32, 16, v41
	s_waitcnt lgkmcnt(0)
	v_pk_fma_f32 v[36:37], v[46:47], v[36:37], v[48:49]
	v_pk_fma_f32 v[32:33], v[50:51], v[38:39], v[32:33]
	v_cvt_pk_bf16_f32 v36, v36, v37
	v_cvt_pk_bf16_f32 v37, v32, v33
	global_store_dwordx2 v[34:35], v[36:37], off
	v_add_u32_e32 v46, v137, v56
	ds_read_b128 v[32:35], v128 offset:2176
	ds_read_b128 v[36:39], v128 offset:3264
	v_lshl_add_u32 v46, v46, 10, v129
	v_ashrrev_i32_e32 v47, 31, v46
	v_lshlrev_b64 v[46:47], 1, v[46:47]
	v_lshl_add_u64 v[48:49], s[18:19], 0, v[46:47]
	s_waitcnt vmcnt(13)
	v_mov_b32_e32 v40, v152
	v_mov_b32_e32 v41, v153
	v_and_b32_e32 v51, 0xffff0000, v40
	v_lshlrev_b32_e32 v50, 16, v40
	s_waitcnt vmcnt(12)
	v_mov_b32_e32 v44, v154
	v_mov_b32_e32 v45, v155
	v_and_b32_e32 v53, 0xffff0000, v44
	v_lshlrev_b32_e32 v52, 16, v44
	v_and_b32_e32 v55, 0xffff0000, v41
	v_lshlrev_b32_e32 v54, 16, v41
	v_and_b32_e32 v41, 0xffff0000, v45
	v_lshlrev_b32_e32 v40, 16, v45
	s_waitcnt lgkmcnt(1)
; __device__ __forceinline__ float bfs2f(short h) { return __uint_as_float(((unsigned)(u16)h) << 16); }
;   __device__ __forceinline__ void tile(const float* reg, int row0, int col0, int lane) const {
;     rows4(reg, lane, [&](int it, int rr, int c4, float4 v) {
;       int idx = (row0 + rr) * 1024 + col0 + c4;
;       bf16x4 gt = *(const bf16x4*)(gate + idx), mo = *(const bf16x4*)(merged + idx);
;       *(bf16x4*)(merged + idx) = pack4(fmaf(bfs2f(gt[0]), v.x, bfs2f(mo[0])), fmaf(bfs2f(gt[1]), v.y, bfs2f(mo[1])),
;                                        fmaf(bfs2f(gt[2]), v.z, bfs2f(mo[2])), fmaf(bfs2f(gt[3]), v.w, bfs2f(mo[3])));
;     });
	v_pk_fma_f32 v[32:33], v[50:51], v[32:33], v[52:53]
	v_pk_fma_f32 v[34:35], v[54:55], v[34:35], v[40:41]
	v_cvt_pk_bf16_f32 v32, v32, v33
	v_cvt_pk_bf16_f32 v33, v34, v35
	global_store_dwordx2 v[42:43], v[32:33], off
	v_lshl_add_u64 v[34:35], s[12:13], 0, v[46:47]
	s_waitcnt vmcnt(12)
	v_mov_b32_e32 v32, v156
	v_mov_b32_e32 v33, v157
	v_and_b32_e32 v43, 0xffff0000, v32
	v_lshlrev_b32_e32 v42, 16, v32
	s_waitcnt vmcnt(11)
	v_mov_b32_e32 v40, v158
	v_mov_b32_e32 v41, v159
	v_and_b32_e32 v45, 0xffff0000, v40
	v_lshlrev_b32_e32 v44, 16, v40
	v_and_b32_e32 v47, 0xffff0000, v33
	v_lshlrev_b32_e32 v46, 16, v33
	v_and_b32_e32 v33, 0xffff0000, v41
	v_lshlrev_b32_e32 v32, 16, v41
	s_waitcnt lgkmcnt(0)
	v_pk_fma_f32 v[36:37], v[42:43], v[36:37], v[44:45]
	v_pk_fma_f32 v[32:33], v[46:47], v[38:39], v[32:33]
	v_cvt_pk_bf16_f32 v36, v36, v37
	v_cvt_pk_bf16_f32 v37, v32, v33
	global_store_dwordx2 v[34:35], v[36:37], off
	v_add_u32_e32 v32, v135, v56
	v_lshl_add_u32 v32, v32, 10, v129
	v_ashrrev_i32_e32 v33, 31, v32
	v_lshlrev_b64 v[32:33], 1, v[32:33]
	v_lshl_add_u64 v[34:35], s[18:19], 0, v[32:33]
	v_lshl_add_u64 v[42:43], s[12:13], 0, v[32:33]
	ds_read_b128 v[32:35], v128 offset:4352
	ds_read_b128 v[36:39], v128 offset:5440
	v_add_u32_e32 v46, v134, v56
	v_lshl_add_u32 v46, v46, 10, v129
	v_ashrrev_i32_e32 v47, 31, v46
	v_lshlrev_b64 v[46:47], 1, v[46:47]
	v_lshl_add_u64 v[48:49], s[18:19], 0, v[46:47]
	s_waitcnt vmcnt(11)
	v_mov_b32_e32 v40, v160
	v_mov_b32_e32 v41, v161
	v_and_b32_e32 v51, 0xffff0000, v40
	v_lshlrev_b32_e32 v50, 16, v40
	s_waitcnt vmcnt(10)
	v_mov_b32_e32 v44, v162
	v_mov_b32_e32 v45, v163
	v_and_b32_e32 v53, 0xffff0000, v44
	v_lshlrev_b32_e32 v52, 16, v44
	v_and_b32_e32 v55, 0xffff0000, v41
	v_lshlrev_b32_e32 v54, 16, v41
	v_and_b32_e32 v41, 0xffff0000, v45
	v_lshlrev_b32_e32 v40, 16, v45
	s_waitcnt lgkmcnt(1)
	v_pk_fma_f32 v[32:33], v[50:51], v[32:33], v[52:53]
	v_pk_fma_f32 v[34:35], v[54:55], v[34:35], v[40:41]
	v_cvt_pk_bf16_f32 v32, v32, v33
	v_cvt_pk_bf16_f32 v33, v34, v35
	global_store_dwordx2 v[42:43], v[32:33], off
	v_lshl_add_u64 v[34:35], s[12:13], 0, v[46:47]
	v_add_u32_e32 v42, v131, v56
	v_lshl_add_u32 v42, v42, 10, v129
	v_ashrrev_i32_e32 v43, 31, v42
	v_lshlrev_b64 v[42:43], 1, v[42:43]
	v_lshl_add_u64 v[44:45], s[18:19], 0, v[42:43]
	v_lshl_add_u64 v[42:43], s[12:13], 0, v[42:43]
	s_waitcnt vmcnt(10)
	v_mov_b32_e32 v32, v164
	v_mov_b32_e32 v33, v165
	v_and_b32_e32 v47, 0xffff0000, v32
	v_lshlrev_b32_e32 v46, 16, v32
	s_waitcnt vmcnt(9)
	v_mov_b32_e32 v40, v166
	v_mov_b32_e32 v41, v167
	v_and_b32_e32 v49, 0xffff0000, v40
	v_lshlrev_b32_e32 v48, 16, v40
	v_and_b32_e32 v51, 0xffff0000, v33
	v_lshlrev_b32_e32 v50, 16, v33
	v_and_b32_e32 v33, 0xffff0000, v41
	v_lshlrev_b32_e32 v32, 16, v41
	s_waitcnt lgkmcnt(0)
	v_pk_fma_f32 v[36:37], v[46:47], v[36:37], v[48:49]
	v_pk_fma_f32 v[32:33], v[50:51], v[38:39], v[32:33]
	v_cvt_pk_bf16_f32 v36, v36, v37
	v_cvt_pk_bf16_f32 v37, v32, v33
	global_store_dwordx2 v[34:35], v[36:37], off
	v_add_u32_e32 v46, v130, v56
	ds_read_b128 v[32:35], v128 offset:6528
	ds_read_b128 v[36:39], v128 offset:7616
	v_lshl_add_u32 v46, v46, 10, v129
	v_ashrrev_i32_e32 v47, 31, v46
	v_lshlrev_b64 v[46:47], 1, v[46:47]
	v_lshl_add_u64 v[48:49], s[18:19], 0, v[46:47]
	s_waitcnt vmcnt(9)
	v_mov_b32_e32 v40, v168
	v_mov_b32_e32 v41, v169
	v_and_b32_e32 v51, 0xffff0000, v40
	v_lshlrev_b32_e32 v50, 16, v40
	s_waitcnt vmcnt(8)
	v_mov_b32_e32 v44, v170
	v_mov_b32_e32 v45, v171
	v_and_b32_e32 v53, 0xffff0000, v44
	v_lshlrev_b32_e32 v52, 16, v44
	v_and_b32_e32 v55, 0xffff0000, v41
	v_lshlrev_b32_e32 v54, 16, v41
	v_and_b32_e32 v41, 0xffff0000, v45
	v_lshlrev_b32_e32 v40, 16, v45
	s_waitcnt lgkmcnt(1)
	v_pk_fma_f32 v[32:33], v[50:51], v[32:33], v[52:53]
	v_pk_fma_f32 v[34:35], v[54:55], v[34:35], v[40:41]
	v_cvt_pk_bf16_f32 v32, v32, v33
	v_cvt_pk_bf16_f32 v33, v34, v35
	global_store_dwordx2 v[42:43], v[32:33], off
	v_lshl_add_u64 v[34:35], s[12:13], 0, v[46:47]
	s_waitcnt vmcnt(8)
	v_mov_b32_e32 v32, v172
	v_mov_b32_e32 v33, v173
	v_and_b32_e32 v43, 0xffff0000, v32
	v_lshlrev_b32_e32 v42, 16, v32
	s_waitcnt vmcnt(7)
	v_mov_b32_e32 v40, v174
	v_mov_b32_e32 v41, v175
	v_and_b32_e32 v45, 0xffff0000, v40
	v_lshlrev_b32_e32 v44, 16, v40
	v_and_b32_e32 v47, 0xffff0000, v33
	v_lshlrev_b32_e32 v46, 16, v33
	v_and_b32_e32 v33, 0xffff0000, v41
	v_lshlrev_b32_e32 v32, 16, v41
	s_waitcnt lgkmcnt(0)
; __device__ __forceinline__ float bfs2f(short h) { return __uint_as_float(((unsigned)(u16)h) << 16); }
;   __device__ __forceinline__ void tile(const float* reg, int row0, int col0, int lane) const {
;     rows4(reg, lane, [&](int it, int rr, int c4, float4 v) {
;       int idx = (row0 + rr) * 1024 + col0 + c4;
;       bf16x4 gt = *(const bf16x4*)(gate + idx), mo = *(const bf16x4*)(merged + idx);
;       *(bf16x4*)(merged + idx) = pack4(fmaf(bfs2f(gt[0]), v.x, bfs2f(mo[0])), fmaf(bfs2f(gt[1]), v.y, bfs2f(mo[1])),
;                                        fmaf(bfs2f(gt[2]), v.z, bfs2f(mo[2])), fmaf(bfs2f(gt[3]), v.w, bfs2f(mo[3])));
;     });
;   }
; template <int MF, class Epi>
; __device__ __forceinline__ void staged_epilogue(f32x4 (&acc)[MF][4], int row0, int col0, const Epi& epi) {
;     ...
; #pragma unroll
;   for (int mp = 0; mp < MF / 2; ++mp) {
;     __builtin_amdgcn_sched_barrier(0);
; #pragma unroll
;     for (int mm = 0; mm < 2; ++mm)
; #pragma unroll
;       for (int n = 0; n < 4; ++n)
; #pragma unroll
;         for (int j = 0; j < 4; ++j) reg[(mm * 16 + fq * 4 + j) * 68 + n * 16 + fr] = acc[mp * 2 + mm][n][j];
;     __builtin_amdgcn_fence(__ATOMIC_ACQ_REL, "wavefront");
;     epi.tile(reg, row0 + mp * 32, col0, lane);
;     __builtin_amdgcn_fence(__ATOMIC_ACQ_REL, "wavefront");
	v_pk_fma_f32 v[36:37], v[42:43], v[36:37], v[44:45]
	v_pk_fma_f32 v[32:33], v[46:47], v[38:39], v[32:33]
	v_cvt_pk_bf16_f32 v36, v36, v37
	v_cvt_pk_bf16_f32 v37, v32, v33
	global_store_dwordx2 v[34:35], v[36:37], off
	ds_write2_b32 v141, v24, v28 offset1:16
	ds_write2_b32 v141, v25, v29 offset0:68 offset1:84
	ds_write2_b32 v141, v26, v30 offset0:136 offset1:152
	ds_write2_b32 v141, v27, v31 offset0:204 offset1:220
	ds_write2_b32 v141, v16, v20 offset0:32 offset1:48
	ds_write2_b32 v141, v17, v21 offset0:100 offset1:116
	ds_write2_b32 v141, v18, v22 offset0:168 offset1:184
	ds_write2_b32 v141, v19, v23 offset0:236 offset1:252
	ds_write2_b32 v112, v4, v8 offset0:64 offset1:80
	ds_write2_b32 v112, v5, v9 offset0:132 offset1:148
	ds_write2_b32 v112, v6, v10 offset0:200 offset1:216
	ds_write2_b32 v104, v7, v11 offset0:12 offset1:28
	ds_write2_b32 v112, v0, v12 offset0:96 offset1:112
	ds_write2_b32 v112, v1, v13 offset0:164 offset1:180
	ds_write2_b32 v112, v2, v14 offset0:232 offset1:248
	ds_write2_b32 v104, v3, v15 offset0:44 offset1:60
	v_add_u32_e32 v184, 0x60, v136
	v_add_u32_e32 v176, v140, v184
	v_lshl_add_u32 v176, v176, 10, v129
	v_ashrrev_i32_e32 v177, 31, v176
	v_lshlrev_b64 v[176:177], 1, v[176:177]
	v_lshl_add_u64 v[178:179], s[18:19], 0, v[176:177]
	global_load_dwordx2 v[144:145], v[178:179], off
	v_add_u32_e32 v184, 0x60, v136
	v_add_u32_e32 v176, v140, v184
	v_lshl_add_u32 v176, v176, 10, v129
	v_ashrrev_i32_e32 v177, 31, v176
	v_lshlrev_b64 v[176:177], 1, v[176:177]
	v_lshl_add_u64 v[178:179], s[12:13], 0, v[176:177]
	global_load_dwordx2 v[146:147], v[178:179], off
	v_add_u32_e32 v184, 0x60, v136
	v_add_u32_e32 v176, v139, v184
	v_lshl_add_u32 v176, v176, 10, v129
	v_ashrrev_i32_e32 v177, 31, v176
	v_lshlrev_b64 v[176:177], 1, v[176:177]
	v_lshl_add_u64 v[178:179], s[18:19], 0, v[176:177]
	global_load_dwordx2 v[148:149], v[178:179], off
	v_add_u32_e32 v184, 0x60, v136
	v_add_u32_e32 v178, v139, v184
	v_lshl_add_u32 v178, v178, 10, v129
	v_ashrrev_i32_e32 v179, 31, v178
	v_lshlrev_b64 v[178:179], 1, v[178:179]
	v_lshl_add_u64 v[176:177], s[12:13], 0, v[178:179]
	global_load_dwordx2 v[150:151], v[176:177], off
	v_add_u32_e32 v184, 0x60, v136
	v_add_u32_e32 v176, v138, v184
	v_lshl_add_u32 v176, v176, 10, v129
	v_ashrrev_i32_e32 v177, 31, v176
	v_lshlrev_b64 v[176:177], 1, v[176:177]
	v_lshl_add_u64 v[178:179], s[18:19], 0, v[176:177]
	global_load_dwordx2 v[152:153], v[178:179], off
	v_add_u32_e32 v184, 0x60, v136
	v_add_u32_e32 v176, v138, v184
	v_lshl_add_u32 v176, v176, 10, v129
	v_ashrrev_i32_e32 v177, 31, v176
	v_lshlrev_b64 v[176:177], 1, v[176:177]
	v_lshl_add_u64 v[176:177], s[12:13], 0, v[176:177]
	global_load_dwordx2 v[154:155], v[176:177], off
	v_add_u32_e32 v184, 0x60, v136
	v_add_u32_e32 v176, v137, v184
	v_lshl_add_u32 v176, v176, 10, v129
	v_ashrrev_i32_e32 v177, 31, v176
	v_lshlrev_b64 v[176:177], 1, v[176:177]
	v_lshl_add_u64 v[178:179], s[18:19], 0, v[176:177]
	global_load_dwordx2 v[156:157], v[178:179], off
	v_add_u32_e32 v184, 0x60, v136
	v_add_u32_e32 v178, v137, v184
	v_lshl_add_u32 v178, v178, 10, v129
	v_ashrrev_i32_e32 v179, 31, v178
	v_lshlrev_b64 v[178:179], 1, v[178:179]
	v_lshl_add_u64 v[176:177], s[12:13], 0, v[178:179]
	global_load_dwordx2 v[158:159], v[176:177], off
	v_add_u32_e32 v184, 0x60, v136
	v_add_u32_e32 v176, v135, v184
	v_lshl_add_u32 v176, v176, 10, v129
	v_ashrrev_i32_e32 v177, 31, v176
	v_lshlrev_b64 v[176:177], 1, v[176:177]
	v_lshl_add_u64 v[178:179], s[18:19], 0, v[176:177]
	global_load_dwordx2 v[160:161], v[178:179], off
	v_add_u32_e32 v184, 0x60, v136
	v_add_u32_e32 v176, v135, v184
	v_lshl_add_u32 v176, v176, 10, v129
	v_ashrrev_i32_e32 v177, 31, v176
	v_lshlrev_b64 v[176:177], 1, v[176:177]
	v_lshl_add_u64 v[178:179], s[12:13], 0, v[176:177]
	global_load_dwordx2 v[162:163], v[178:179], off
	v_add_u32_e32 v184, 0x60, v136
	v_add_u32_e32 v176, v134, v184
	v_lshl_add_u32 v176, v176, 10, v129
	v_ashrrev_i32_e32 v177, 31, v176
	v_lshlrev_b64 v[176:177], 1, v[176:177]
	v_lshl_add_u64 v[178:179], s[18:19], 0, v[176:177]
	global_load_dwordx2 v[164:165], v[178:179], off
	v_add_u32_e32 v184, 0x60, v136
	v_add_u32_e32 v178, v134, v184
	v_lshl_add_u32 v178, v178, 10, v129
	v_ashrrev_i32_e32 v179, 31, v178
	v_lshlrev_b64 v[178:179], 1, v[178:179]
	v_lshl_add_u64 v[176:177], s[12:13], 0, v[178:179]
	global_load_dwordx2 v[166:167], v[176:177], off
	v_add_u32_e32 v184, 0x60, v136
	v_add_u32_e32 v176, v131, v184
	v_lshl_add_u32 v176, v176, 10, v129
	v_ashrrev_i32_e32 v177, 31, v176
	v_lshlrev_b64 v[176:177], 1, v[176:177]
	v_lshl_add_u64 v[178:179], s[18:19], 0, v[176:177]
	global_load_dwordx2 v[168:169], v[178:179], off
	v_add_u32_e32 v184, 0x60, v136
	v_add_u32_e32 v176, v131, v184
	v_lshl_add_u32 v176, v176, 10, v129
	v_ashrrev_i32_e32 v177, 31, v176
	v_lshlrev_b64 v[176:177], 1, v[176:177]
	v_lshl_add_u64 v[176:177], s[12:13], 0, v[176:177]
	global_load_dwordx2 v[170:171], v[176:177], off
	v_add_u32_e32 v184, 0x60, v136
	v_add_u32_e32 v176, v130, v184
	v_lshl_add_u32 v176, v176, 10, v129
	v_ashrrev_i32_e32 v177, 31, v176
	v_lshlrev_b64 v[176:177], 1, v[176:177]
	v_lshl_add_u64 v[178:179], s[18:19], 0, v[176:177]
	global_load_dwordx2 v[172:173], v[178:179], off
	v_add_u32_e32 v184, 0x60, v136
	v_add_u32_e32 v178, v130, v184
	v_lshl_add_u32 v178, v178, 10, v129
	v_ashrrev_i32_e32 v179, 31, v178
	v_lshlrev_b64 v[178:179], 1, v[178:179]
	v_lshl_add_u64 v[176:177], s[12:13], 0, v[178:179]
	global_load_dwordx2 v[174:175], v[176:177], off
	v_add_u32_e32 v24, 0x60, v136
	v_add_u32_e32 v0, v140, v24
	v_lshl_add_u32 v0, v0, 10, v129
	v_ashrrev_i32_e32 v1, 31, v0
	v_lshlrev_b64 v[0:1], 1, v[0:1]
	v_lshl_add_u64 v[2:3], s[18:19], 0, v[0:1]
	v_lshl_add_u64 v[10:11], s[12:13], 0, v[0:1]
	ds_read_b128 v[0:3], v128
	ds_read_b128 v[4:7], v128 offset:1088
	v_add_u32_e32 v14, v139, v24
	v_lshl_add_u32 v14, v14, 10, v129
	v_ashrrev_i32_e32 v15, 31, v14
	v_lshlrev_b64 v[14:15], 1, v[14:15]
	v_lshl_add_u64 v[16:17], s[18:19], 0, v[14:15]
	s_waitcnt vmcnt(15)
; __device__ __forceinline__ float bfs2f(short h) { return __uint_as_float(((unsigned)(u16)h) << 16); }
;   __device__ __forceinline__ void tile(const float* reg, int row0, int col0, int lane) const {
;     rows4(reg, lane, [&](int it, int rr, int c4, float4 v) {
;       int idx = (row0 + rr) * 1024 + col0 + c4;
;       bf16x4 gt = *(const bf16x4*)(gate + idx), mo = *(const bf16x4*)(merged + idx);
;       *(bf16x4*)(merged + idx) = pack4(fmaf(bfs2f(gt[0]), v.x, bfs2f(mo[0])), fmaf(bfs2f(gt[1]), v.y, bfs2f(mo[1])),
;                                        fmaf(bfs2f(gt[2]), v.z, bfs2f(mo[2])), fmaf(bfs2f(gt[3]), v.w, bfs2f(mo[3])));
;     });
	v_mov_b32_e32 v8, v144
	v_mov_b32_e32 v9, v145
	v_and_b32_e32 v19, 0xffff0000, v8
	v_lshlrev_b32_e32 v18, 16, v8
	s_waitcnt vmcnt(14)
	v_mov_b32_e32 v12, v146
	v_mov_b32_e32 v13, v147
	v_and_b32_e32 v21, 0xffff0000, v12
	v_lshlrev_b32_e32 v20, 16, v12
	v_and_b32_e32 v23, 0xffff0000, v9
	v_lshlrev_b32_e32 v22, 16, v9
	v_and_b32_e32 v9, 0xffff0000, v13
	v_lshlrev_b32_e32 v8, 16, v13
	s_waitcnt lgkmcnt(1)
	v_pk_fma_f32 v[0:1], v[18:19], v[0:1], v[20:21]
	v_pk_fma_f32 v[2:3], v[22:23], v[2:3], v[8:9]
	v_cvt_pk_bf16_f32 v0, v0, v1
	v_cvt_pk_bf16_f32 v1, v2, v3
	global_store_dwordx2 v[10:11], v[0:1], off
	v_lshl_add_u64 v[2:3], s[12:13], 0, v[14:15]
	v_add_u32_e32 v10, v138, v24
	v_lshl_add_u32 v10, v10, 10, v129
	v_ashrrev_i32_e32 v11, 31, v10
	v_lshlrev_b64 v[10:11], 1, v[10:11]
	v_lshl_add_u64 v[12:13], s[18:19], 0, v[10:11]
	v_lshl_add_u64 v[10:11], s[12:13], 0, v[10:11]
	s_waitcnt vmcnt(14)
	v_mov_b32_e32 v0, v148
	v_mov_b32_e32 v1, v149
	v_and_b32_e32 v15, 0xffff0000, v0
	v_lshlrev_b32_e32 v14, 16, v0
	s_waitcnt vmcnt(13)
	v_mov_b32_e32 v8, v150
	v_mov_b32_e32 v9, v151
	v_and_b32_e32 v17, 0xffff0000, v8
	v_lshlrev_b32_e32 v16, 16, v8
	v_and_b32_e32 v19, 0xffff0000, v1
	v_lshlrev_b32_e32 v18, 16, v1
	v_and_b32_e32 v1, 0xffff0000, v9
	v_lshlrev_b32_e32 v0, 16, v9
	s_waitcnt lgkmcnt(0)
	v_pk_fma_f32 v[4:5], v[14:15], v[4:5], v[16:17]
	v_pk_fma_f32 v[0:1], v[18:19], v[6:7], v[0:1]
	v_cvt_pk_bf16_f32 v4, v4, v5
	v_cvt_pk_bf16_f32 v5, v0, v1
	global_store_dwordx2 v[2:3], v[4:5], off
	v_add_u32_e32 v14, v137, v24
	ds_read_b128 v[0:3], v128 offset:2176
	ds_read_b128 v[4:7], v128 offset:3264
	v_lshl_add_u32 v14, v14, 10, v129
	v_ashrrev_i32_e32 v15, 31, v14
	v_lshlrev_b64 v[14:15], 1, v[14:15]
	v_lshl_add_u64 v[16:17], s[18:19], 0, v[14:15]
	s_waitcnt vmcnt(13)
	v_mov_b32_e32 v8, v152
	v_mov_b32_e32 v9, v153
	v_and_b32_e32 v19, 0xffff0000, v8
	v_lshlrev_b32_e32 v18, 16, v8
	s_waitcnt vmcnt(12)
	v_mov_b32_e32 v12, v154
	v_mov_b32_e32 v13, v155
	v_and_b32_e32 v21, 0xffff0000, v12
	v_lshlrev_b32_e32 v20, 16, v12
	v_and_b32_e32 v23, 0xffff0000, v9
	v_lshlrev_b32_e32 v22, 16, v9
	v_and_b32_e32 v9, 0xffff0000, v13
	v_lshlrev_b32_e32 v8, 16, v13
	s_waitcnt lgkmcnt(1)
	v_pk_fma_f32 v[0:1], v[18:19], v[0:1], v[20:21]
	v_pk_fma_f32 v[2:3], v[22:23], v[2:3], v[8:9]
	v_cvt_pk_bf16_f32 v0, v0, v1
	v_cvt_pk_bf16_f32 v1, v2, v3
	global_store_dwordx2 v[10:11], v[0:1], off
	v_lshl_add_u64 v[2:3], s[12:13], 0, v[14:15]
	s_waitcnt vmcnt(12)
	v_mov_b32_e32 v0, v156
	v_mov_b32_e32 v1, v157
	v_and_b32_e32 v11, 0xffff0000, v0
	v_lshlrev_b32_e32 v10, 16, v0
	s_waitcnt vmcnt(11)
	v_mov_b32_e32 v8, v158
	v_mov_b32_e32 v9, v159
	v_and_b32_e32 v13, 0xffff0000, v8
	v_lshlrev_b32_e32 v12, 16, v8
	v_and_b32_e32 v15, 0xffff0000, v1
	v_lshlrev_b32_e32 v14, 16, v1
	v_and_b32_e32 v1, 0xffff0000, v9
	v_lshlrev_b32_e32 v0, 16, v9
	s_waitcnt lgkmcnt(0)
	v_pk_fma_f32 v[4:5], v[10:11], v[4:5], v[12:13]
	v_pk_fma_f32 v[0:1], v[14:15], v[6:7], v[0:1]
	v_cvt_pk_bf16_f32 v4, v4, v5
	v_cvt_pk_bf16_f32 v5, v0, v1
	global_store_dwordx2 v[2:3], v[4:5], off
	v_add_u32_e32 v0, v135, v24
	v_lshl_add_u32 v0, v0, 10, v129
	v_ashrrev_i32_e32 v1, 31, v0
	v_lshlrev_b64 v[0:1], 1, v[0:1]
	v_lshl_add_u64 v[2:3], s[18:19], 0, v[0:1]
	v_lshl_add_u64 v[10:11], s[12:13], 0, v[0:1]
	ds_read_b128 v[0:3], v128 offset:4352
	ds_read_b128 v[4:7], v128 offset:5440
	v_add_u32_e32 v14, v134, v24
	v_lshl_add_u32 v14, v14, 10, v129
	v_ashrrev_i32_e32 v15, 31, v14
	v_lshlrev_b64 v[14:15], 1, v[14:15]
	v_lshl_add_u64 v[16:17], s[18:19], 0, v[14:15]
	s_andn2_b64 vcc, exec, s[50:51]
	s_waitcnt vmcnt(11)
	v_mov_b32_e32 v8, v160
	v_mov_b32_e32 v9, v161
	v_and_b32_e32 v19, 0xffff0000, v8
	v_lshlrev_b32_e32 v18, 16, v8
	s_waitcnt vmcnt(10)
	v_mov_b32_e32 v12, v162
	v_mov_b32_e32 v13, v163
	v_and_b32_e32 v21, 0xffff0000, v12
	v_lshlrev_b32_e32 v20, 16, v12
	v_and_b32_e32 v23, 0xffff0000, v9
	v_lshlrev_b32_e32 v22, 16, v9
	v_and_b32_e32 v9, 0xffff0000, v13
	v_lshlrev_b32_e32 v8, 16, v13
	s_waitcnt lgkmcnt(1)
	v_pk_fma_f32 v[0:1], v[18:19], v[0:1], v[20:21]
	v_pk_fma_f32 v[2:3], v[22:23], v[2:3], v[8:9]
	v_cvt_pk_bf16_f32 v0, v0, v1
	v_cvt_pk_bf16_f32 v1, v2, v3
	global_store_dwordx2 v[10:11], v[0:1], off
	v_lshl_add_u64 v[2:3], s[12:13], 0, v[14:15]
	v_add_u32_e32 v10, v131, v24
	v_lshl_add_u32 v10, v10, 10, v129
	v_ashrrev_i32_e32 v11, 31, v10
	v_lshlrev_b64 v[10:11], 1, v[10:11]
	v_lshl_add_u64 v[12:13], s[18:19], 0, v[10:11]
	v_lshl_add_u64 v[10:11], s[12:13], 0, v[10:11]
	s_waitcnt vmcnt(10)
	v_mov_b32_e32 v0, v164
	v_mov_b32_e32 v1, v165
	v_and_b32_e32 v15, 0xffff0000, v0
	v_lshlrev_b32_e32 v14, 16, v0
	s_waitcnt vmcnt(9)
	v_mov_b32_e32 v8, v166
	v_mov_b32_e32 v9, v167
	v_and_b32_e32 v17, 0xffff0000, v8
	v_lshlrev_b32_e32 v16, 16, v8
	v_and_b32_e32 v19, 0xffff0000, v1
	v_lshlrev_b32_e32 v18, 16, v1
	v_and_b32_e32 v1, 0xffff0000, v9
	v_lshlrev_b32_e32 v0, 16, v9
	s_waitcnt lgkmcnt(0)
	v_pk_fma_f32 v[4:5], v[14:15], v[4:5], v[16:17]
	v_pk_fma_f32 v[0:1], v[18:19], v[6:7], v[0:1]
	v_cvt_pk_bf16_f32 v4, v4, v5
	v_cvt_pk_bf16_f32 v5, v0, v1
	global_store_dwordx2 v[2:3], v[4:5], off
	v_add_u32_e32 v14, v130, v24
	ds_read_b128 v[0:3], v128 offset:6528
	ds_read_b128 v[4:7], v128 offset:7616
	v_lshl_add_u32 v14, v14, 10, v129
	v_ashrrev_i32_e32 v15, 31, v14
	v_lshlrev_b64 v[14:15], 1, v[14:15]
	v_lshl_add_u64 v[16:17], s[18:19], 0, v[14:15]
	s_waitcnt vmcnt(9)
	v_mov_b32_e32 v8, v168
	v_mov_b32_e32 v9, v169
	v_and_b32_e32 v19, 0xffff0000, v8
	v_lshlrev_b32_e32 v18, 16, v8
	s_waitcnt vmcnt(8)
	v_mov_b32_e32 v12, v170
	v_mov_b32_e32 v13, v171
	v_and_b32_e32 v21, 0xffff0000, v12
	v_lshlrev_b32_e32 v20, 16, v12
	v_and_b32_e32 v23, 0xffff0000, v9
	v_lshlrev_b32_e32 v22, 16, v9
	v_and_b32_e32 v9, 0xffff0000, v13
	v_lshlrev_b32_e32 v8, 16, v13
	s_waitcnt lgkmcnt(1)
	v_pk_fma_f32 v[0:1], v[18:19], v[0:1], v[20:21]
	v_pk_fma_f32 v[2:3], v[22:23], v[2:3], v[8:9]
	v_cvt_pk_bf16_f32 v0, v0, v1
	v_cvt_pk_bf16_f32 v1, v2, v3
	global_store_dwordx2 v[10:11], v[0:1], off
	v_lshl_add_u64 v[2:3], s[12:13], 0, v[14:15]
	s_waitcnt vmcnt(8)
	v_mov_b32_e32 v0, v172
	v_mov_b32_e32 v1, v173
	v_and_b32_e32 v11, 0xffff0000, v0
	v_lshlrev_b32_e32 v10, 16, v0
	s_waitcnt vmcnt(7)
	v_mov_b32_e32 v8, v174
	v_mov_b32_e32 v9, v175
	v_and_b32_e32 v13, 0xffff0000, v8
	v_lshlrev_b32_e32 v12, 16, v8
	v_and_b32_e32 v15, 0xffff0000, v1
	v_lshlrev_b32_e32 v14, 16, v1
	v_and_b32_e32 v1, 0xffff0000, v9
	v_lshlrev_b32_e32 v0, 16, v9
	s_waitcnt lgkmcnt(0)
	v_pk_fma_f32 v[4:5], v[10:11], v[4:5], v[12:13]
	v_pk_fma_f32 v[0:1], v[14:15], v[6:7], v[0:1]
	v_cvt_pk_bf16_f32 v4, v4, v5
	v_cvt_pk_bf16_f32 v5, v0, v1
	global_store_dwordx2 v[2:3], v[4:5], off
	s_cbranch_vccz .LBB0_3026

; template <class Epi>
; __device__ __forceinline__ void small_gemm(const u16* __restrict__ A, const u16* __restrict__ Bt, int K, int N, const Epi& epi) {
;     ...
;   for (int piece = blockIdx.x; piece < npieces; piece += gridDim.x) {
;     int row0 = (piece & 3) * 32, col0 = (piece >> 2) * 64;
;     f32x4 acc[2][4] = {};
;     int kper = K >> 3, k0 = wid * kper;
;     for (int kk = k0; kk < k0 + kper; kk += 32) {
;       bf16x8 a[2], b[4];
; #pragma unroll
;       for (int m = 0; m < 2; ++m) a[m] = *(const bf16x8*)(A + (size_t)(row0 + m * 16 + fr) * K + kk + fq * 8);
; #pragma unroll
;       for (int n = 0; n < 4; ++n) b[n] = *(const bf16x8*)(Bt + (size_t)(col0 + n * 16 + fr) * K + kk + fq * 8);
; #pragma unroll
;       for (int m = 0; m < 2; ++m)
; #pragma unroll
;         for (int n = 0; n < 4; ++n) acc[m][n] = __builtin_amdgcn_mfma_f32_16x16x32_bf16(a[m], b[n], acc[m][n], 0, 0, 0);
;     }
;     __syncthreads();
; #pragma unroll
;     for (int m = 0; m < 2; ++m)
; #pragma unroll
;       for (int n = 0; n < 4; ++n) red[(wid * 8 + m * 4 + n) * 64 + lane] = acc[m][n];
;     __syncthreads();
.LBB0_3031:
	s_and_b32 s19, s2, 0xffffffc0
	v_or_b32_e32 v30, s19, v22
	s_and_b32 s18, s3, 0x60
	v_ashrrev_i32_e32 v31, 31, v30
	v_or_b32_e32 v0, s18, v22
	v_lshlrev_b64 v[16:17], 11, v[30:31]
	v_or_b32_e32 v26, 16, v30
	v_or_b32_e32 v32, s2, v24
	v_or_b32_e32 v30, 32, v30
	v_lshlrev_b32_e32 v0, 11, v0
	v_ashrrev_i32_e32 v27, 31, v26
	v_ashrrev_i32_e32 v33, 31, v32
	v_ashrrev_i32_e32 v31, 31, v30
	v_lshl_add_u64 v[20:21], v[2:3], 0, v[0:1]
	v_lshlrev_b64 v[26:27], 11, v[26:27]
	v_lshlrev_b64 v[42:43], 11, v[32:33]
	v_lshlrev_b64 v[34:35], 11, v[30:31]
	v_or_b32_e32 v0, 0x8000, v0
	v_lshl_add_u64 v[74:75], v[4:5], 0, v[16:17]
	v_lshl_add_u64 v[82:83], v[4:5], 0, v[26:27]
	v_lshl_add_u64 v[90:91], v[4:5], 0, v[34:35]
	v_lshl_add_u64 v[102:103], v[4:5], 0, v[42:43]
	v_lshl_add_u64 v[66:67], v[2:3], 0, v[0:1]
	global_load_dwordx4 v[12:15], v[20:21], off
	global_load_dwordx4 v[16:19], v[74:75], off
	global_load_dwordx4 v[26:29], v[82:83], off
	global_load_dwordx4 v[30:33], v[20:21], off offset:64
	global_load_dwordx4 v[38:41], v[90:91], off
	global_load_dwordx4 v[42:45], v[74:75], off offset:192
	global_load_dwordx4 v[50:53], v[102:103], off
	global_load_dwordx4 v[54:57], v[82:83], off offset:192
	global_load_dwordx4 v[62:65], v[90:91], off offset:192
	v_lshl_add_u64 v[104:105], v[6:7], 0, v[0:1]
	global_load_dwordx4 v[66:69], v[66:67], off
	s_waitcnt vmcnt(8)
	v_mfma_f32_16x16x32_bf16 v[34:37], v[12:15], v[16:19], 0
	s_waitcnt vmcnt(7)
	v_mfma_f32_16x16x32_bf16 v[46:49], v[12:15], v[26:29], 0
	s_waitcnt vmcnt(5)
	v_mfma_f32_16x16x32_bf16 v[58:61], v[12:15], v[38:41], 0
	s_waitcnt vmcnt(3)
	v_mfma_f32_16x16x32_bf16 v[12:15], v[12:15], v[50:53], 0
	s_waitcnt vmcnt(0)
	v_mfma_f32_16x16x32_bf16 v[16:19], v[66:69], v[16:19], 0
	v_mfma_f32_16x16x32_bf16 v[26:29], v[66:69], v[26:29], 0
	v_mfma_f32_16x16x32_bf16 v[38:41], v[66:69], v[38:41], 0
	v_mfma_f32_16x16x32_bf16 v[50:53], v[66:69], v[50:53], 0
	global_load_dwordx4 v[66:69], v[74:75], off offset:64
	global_load_dwordx4 v[70:73], v[74:75], off offset:128
	s_nop 0
	global_load_dwordx4 v[74:77], v[82:83], off offset:64
	global_load_dwordx4 v[78:81], v[82:83], off offset:128
	s_nop 0
	global_load_dwordx4 v[82:85], v[90:91], off offset:64
	global_load_dwordx4 v[86:89], v[90:91], off offset:128
	global_load_dwordx4 v[94:97], v[102:103], off offset:128
	s_waitcnt vmcnt(6)
	v_mfma_f32_16x16x32_bf16 v[34:37], v[30:33], v[66:69], v[34:37]
	global_load_dwordx4 v[90:93], v[102:103], off offset:64
	s_waitcnt vmcnt(5)
	v_mfma_f32_16x16x32_bf16 v[46:49], v[30:33], v[74:77], v[46:49]
	s_waitcnt vmcnt(3)
	v_mfma_f32_16x16x32_bf16 v[58:61], v[30:33], v[82:85], v[58:61]
	s_waitcnt vmcnt(0)
	v_mfma_f32_16x16x32_bf16 v[12:15], v[30:33], v[90:93], v[12:15]
	global_load_dwordx4 v[30:33], v[104:105], off
	global_load_dwordx4 v[98:101], v[102:103], off offset:192
	s_waitcnt vmcnt(1)
	v_mfma_f32_16x16x32_bf16 v[16:19], v[30:33], v[66:69], v[16:19]
	v_mfma_f32_16x16x32_bf16 v[26:29], v[30:33], v[74:77], v[26:29]
	v_mfma_f32_16x16x32_bf16 v[38:41], v[30:33], v[82:85], v[38:41]
	v_mfma_f32_16x16x32_bf16 v[30:33], v[30:33], v[90:93], v[50:53]
	s_nop 2
	global_load_dwordx4 v[50:53], v[20:21], off offset:128
	global_load_dwordx4 v[66:69], v[20:21], off offset:192
	v_lshl_add_u64 v[20:21], v[8:9], 0, v[0:1]
	global_load_dwordx4 v[74:77], v[20:21], off
	v_lshl_add_u64 v[20:21], v[10:11], 0, v[0:1]
	s_waitcnt vmcnt(2)
	v_mfma_f32_16x16x32_bf16 v[34:37], v[50:53], v[70:73], v[34:37]
	v_mfma_f32_16x16x32_bf16 v[46:49], v[50:53], v[78:81], v[46:49]
	v_mfma_f32_16x16x32_bf16 v[58:61], v[50:53], v[86:89], v[58:61]
	v_mfma_f32_16x16x32_bf16 v[12:15], v[50:53], v[94:97], v[12:15]
	global_load_dwordx4 v[50:53], v[20:21], off
	s_barrier
	s_waitcnt vmcnt(1)
	v_mfma_f32_16x16x32_bf16 v[16:19], v[74:77], v[70:73], v[16:19]
	v_mfma_f32_16x16x32_bf16 v[26:29], v[74:77], v[78:81], v[26:29]
	v_mfma_f32_16x16x32_bf16 v[38:41], v[74:77], v[86:89], v[38:41]
	v_mfma_f32_16x16x32_bf16 v[34:37], v[66:69], v[42:45], v[34:37]
	v_mfma_f32_16x16x32_bf16 v[46:49], v[66:69], v[54:57], v[46:49]
	v_mfma_f32_16x16x32_bf16 v[58:61], v[66:69], v[62:65], v[58:61]
	s_nop 5
	ds_write_b128 v25, v[34:37]
	v_mfma_f32_16x16x32_bf16 v[30:33], v[74:77], v[94:97], v[30:33]
	v_mfma_f32_16x16x32_bf16 v[12:15], v[66:69], v[98:101], v[12:15]
	ds_write_b128 v25, v[46:49] offset:1024
	ds_write_b128 v25, v[58:61] offset:2048
	s_nop 5
	ds_write_b128 v25, v[12:15] offset:3072
	s_waitcnt vmcnt(0)
	v_mfma_f32_16x16x32_bf16 v[16:19], v[50:53], v[42:45], v[16:19]
	v_mfma_f32_16x16x32_bf16 v[26:29], v[50:53], v[54:57], v[26:29]
	v_mfma_f32_16x16x32_bf16 v[12:15], v[50:53], v[62:65], v[38:41]
	s_nop 5
	ds_write_b128 v25, v[16:19] offset:4096
	ds_write_b128 v25, v[26:29] offset:5120
	ds_write_b128 v25, v[12:15] offset:6144
	v_mfma_f32_16x16x32_bf16 v[12:15], v[50:53], v[98:101], v[30:33]
	s_nop 7
	ds_write_b128 v25, v[12:15] offset:7168
	s_waitcnt lgkmcnt(0)
	s_barrier
	s_and_saveexec_b64 s[0:1], vcc
	s_cbranch_execz .LBB0_3030
; template <class Epi>
; __device__ __forceinline__ void small_gemm(const u16* __restrict__ A, const u16* __restrict__ Bt, int K, int N, const Epi& epi) {
;     ...
;     if (wid == 0) {
; #pragma unroll
;       for (int m = 0; m < 2; ++m)
; #pragma unroll
;         for (int n = 0; n < 4; ++n) {
;           f32x4 s = red[(m * 4 + n) * 64 + lane];
; #pragma unroll
;           for (int w = 1; w < 8; ++w) s += red[(w * 8 + m * 4 + n) * 64 + lane];
;           acc[m][n] = s;
;         }
	ds_read_b128 v[12:15], v23
	ds_read_b128 v[16:19], v23 offset:8192
	ds_read_b128 v[26:29], v23 offset:16384
	ds_read_b128 v[30:33], v23 offset:1024
	ds_read_b128 v[34:37], v23 offset:9216
	v_mov_b32_e32 v0, v204
	s_waitcnt lgkmcnt(3)
	v_pk_add_f32 v[20:21], v[14:15], v[18:19]
	v_pk_add_f32 v[38:39], v[12:13], v[16:17]
	ds_read_b128 v[12:15], v23 offset:24576
	ds_read_b128 v[16:19], v23 offset:17408
	s_waitcnt lgkmcnt(4)
	v_pk_add_f32 v[20:21], v[20:21], v[28:29]
	v_pk_add_f32 v[42:43], v[38:39], v[26:27]
	ds_read_b128 v[26:29], v23 offset:32768
	ds_read_b128 v[38:41], v23 offset:25600
	s_waitcnt lgkmcnt(3)
	v_pk_add_f32 v[20:21], v[20:21], v[14:15]
	v_pk_add_f32 v[46:47], v[42:43], v[12:13]
	ds_read_b128 v[12:15], v23 offset:40960
	ds_read_b128 v[42:45], v23 offset:33792
	s_waitcnt lgkmcnt(3)
	v_pk_add_f32 v[20:21], v[20:21], v[28:29]
	v_pk_add_f32 v[50:51], v[46:47], v[26:27]
	ds_read_b128 v[26:29], v23 offset:49152
	ds_read_b128 v[46:49], v23 offset:41984
	s_waitcnt lgkmcnt(3)
	v_pk_add_f32 v[12:13], v[50:51], v[12:13]
	ds_read_b128 v[50:53], v23 offset:57344
	ds_read_b128 v[54:57], v23 offset:50176
	v_pk_add_f32 v[14:15], v[20:21], v[14:15]
	s_waitcnt lgkmcnt(3)
	v_pk_add_f32 v[20:21], v[12:13], v[26:27]
	v_pk_add_f32 v[14:15], v[14:15], v[28:29]
	ds_read_b128 v[26:29], v23 offset:58368
	s_waitcnt lgkmcnt(2)
	v_pk_add_f32 v[12:13], v[14:15], v[52:53]
	v_pk_add_f32 v[14:15], v[20:21], v[50:51]
	v_pk_add_f32 v[20:21], v[32:33], v[36:37]
	v_pk_add_f32 v[30:31], v[30:31], v[34:35]
	v_pk_add_f32 v[18:19], v[20:21], v[18:19]
	v_pk_add_f32 v[16:17], v[30:31], v[16:17]
	v_pk_add_f32 v[18:19], v[18:19], v[40:41]
	v_pk_add_f32 v[16:17], v[16:17], v[38:39]
	v_pk_add_f32 v[18:19], v[18:19], v[44:45]
	v_pk_add_f32 v[16:17], v[16:17], v[42:43]
	v_pk_add_f32 v[18:19], v[18:19], v[48:49]
	v_pk_add_f32 v[16:17], v[16:17], v[46:47]
	s_waitcnt lgkmcnt(1)
	v_pk_add_f32 v[18:19], v[18:19], v[56:57]
	v_pk_add_f32 v[20:21], v[16:17], v[54:55]
	s_waitcnt lgkmcnt(0)
	v_pk_add_f32 v[16:17], v[18:19], v[28:29]
	ds_read_b128 v[28:31], v23 offset:2048
	ds_read_b128 v[32:35], v23 offset:10240
	v_pk_add_f32 v[18:19], v[20:21], v[26:27]
	ds_read_b128 v[36:39], v23 offset:18432
	ds_read_b128 v[40:43], v23 offset:3072
	ds_read_b128 v[44:47], v23 offset:11264
	s_waitcnt lgkmcnt(3)
	v_pk_add_f32 v[20:21], v[30:31], v[34:35]
	v_pk_add_f32 v[34:35], v[28:29], v[32:33]
	ds_read_b128 v[26:29], v23 offset:26624
	ds_read_b128 v[30:33], v23 offset:19456
	s_waitcnt lgkmcnt(4)
	v_pk_add_f32 v[20:21], v[20:21], v[38:39]
	v_pk_add_f32 v[38:39], v[34:35], v[36:37]
	ds_read_b128 v[34:37], v23 offset:34816
	ds_read_b128 v[48:51], v23 offset:27648
	s_waitcnt lgkmcnt(3)
	v_pk_add_f32 v[20:21], v[20:21], v[28:29]
	v_pk_add_f32 v[38:39], v[38:39], v[26:27]
	ds_read_b128 v[26:29], v23 offset:43008
	ds_read_b128 v[52:55], v23 offset:35840
	s_waitcnt lgkmcnt(3)
	v_pk_add_f32 v[20:21], v[20:21], v[36:37]
	v_pk_add_f32 v[38:39], v[38:39], v[34:35]
	ds_read_b128 v[34:37], v23 offset:51200
	ds_read_b128 v[56:59], v23 offset:44032
	s_waitcnt lgkmcnt(3)
	v_pk_add_f32 v[20:21], v[20:21], v[28:29]
	v_pk_add_f32 v[38:39], v[38:39], v[26:27]
	ds_read_b128 v[26:29], v23 offset:59392
	ds_read_b128 v[60:63], v23 offset:52224
	s_waitcnt lgkmcnt(3)
	v_pk_add_f32 v[38:39], v[38:39], v[34:35]
	v_pk_add_f32 v[20:21], v[20:21], v[36:37]
	ds_read_b128 v[34:37], v23 offset:60416
	s_waitcnt lgkmcnt(2)
	v_pk_add_f32 v[64:65], v[38:39], v[26:27]
	v_pk_add_f32 v[26:27], v[42:43], v[46:47]
	v_pk_add_f32 v[20:21], v[20:21], v[28:29]
	v_pk_add_f32 v[28:29], v[40:41], v[44:45]
	v_pk_add_f32 v[26:27], v[26:27], v[32:33]
	v_pk_add_f32 v[28:29], v[28:29], v[30:31]
	v_pk_add_f32 v[26:27], v[26:27], v[50:51]
	v_pk_add_f32 v[28:29], v[28:29], v[48:49]
	v_pk_add_f32 v[26:27], v[26:27], v[54:55]
	v_pk_add_f32 v[28:29], v[28:29], v[52:53]
	v_pk_add_f32 v[26:27], v[26:27], v[58:59]
	v_pk_add_f32 v[28:29], v[28:29], v[56:57]
	s_waitcnt lgkmcnt(1)
	v_pk_add_f32 v[26:27], v[26:27], v[62:63]
	v_pk_add_f32 v[38:39], v[28:29], v[60:61]
	s_waitcnt lgkmcnt(0)
	v_pk_add_f32 v[62:63], v[26:27], v[36:37]
	ds_read_b128 v[26:29], v23 offset:4096
	ds_read_b128 v[30:33], v23 offset:12288
	v_pk_add_f32 v[66:67], v[38:39], v[34:35]
	ds_read_b128 v[34:37], v23 offset:20480
	ds_read_b128 v[38:41], v23 offset:5120
	ds_read_b128 v[42:45], v23 offset:13312
	s_waitcnt lgkmcnt(3)
	v_pk_add_f32 v[46:47], v[28:29], v[32:33]
	v_pk_add_f32 v[48:49], v[26:27], v[30:31]
	ds_read_b128 v[26:29], v23 offset:28672
	ds_read_b128 v[30:33], v23 offset:21504
	s_waitcnt lgkmcnt(4)
	v_pk_add_f32 v[50:51], v[46:47], v[36:37]
	v_pk_add_f32 v[52:53], v[48:49], v[34:35]
	ds_read_b128 v[34:37], v23 offset:36864
	ds_read_b128 v[46:49], v23 offset:29696
	s_waitcnt lgkmcnt(3)
	v_pk_add_f32 v[54:55], v[50:51], v[28:29]
	v_pk_add_f32 v[56:57], v[52:53], v[26:27]
	ds_read_b128 v[26:29], v23 offset:45056
	ds_read_b128 v[50:53], v23 offset:37888
	s_waitcnt lgkmcnt(3)
	v_pk_add_f32 v[58:59], v[54:55], v[36:37]
	v_pk_add_f32 v[60:61], v[56:57], v[34:35]
	ds_read_b128 v[34:37], v23 offset:53248
	ds_read_b128 v[54:57], v23 offset:46080
	s_waitcnt lgkmcnt(3)
	v_pk_add_f32 v[68:69], v[58:59], v[28:29]
	v_pk_add_f32 v[70:71], v[60:61], v[26:27]
	ds_read_b128 v[26:29], v23 offset:61440
	ds_read_b128 v[58:61], v23 offset:54272
	s_waitcnt lgkmcnt(3)
	v_pk_add_f32 v[70:71], v[70:71], v[34:35]
	v_pk_add_f32 v[68:69], v[68:69], v[36:37]
	ds_read_b128 v[34:37], v23 offset:62464
	s_waitcnt lgkmcnt(2)
; __device__ __forceinline__ float bfs2f(short h) { return __uint_as_float(((unsigned)(u16)h) << 16); }
;   __device__ __forceinline__ void tile(const float* reg, int row0, int col0, int lane) const {
;     rows4(reg, lane, [&](int it, int rr, int c4, float4 v) {
;       int idx = (row0 + rr) * 1024 + col0 + c4;
;       bf16x4 gt = *(const bf16x4*)(gate + idx), mo = *(const bf16x4*)(merged + idx);
;       *(bf16x4*)(merged + idx) = pack4(fmaf(bfs2f(gt[0]), v.x, bfs2f(mo[0])), fmaf(bfs2f(gt[1]), v.y, bfs2f(mo[1])),
;                                        fmaf(bfs2f(gt[2]), v.z, bfs2f(mo[2])), fmaf(bfs2f(gt[3]), v.w, bfs2f(mo[3])));
;     });
; template <class Epi>
; __device__ __forceinline__ void small_gemm(const u16* __restrict__ A, const u16* __restrict__ Bt, int K, int N, const Epi& epi) {
;     ...
;     if (wid == 0) {
; #pragma unroll
;       for (int m = 0; m < 2; ++m)
; #pragma unroll
;         for (int n = 0; n < 4; ++n) {
;           f32x4 s = red[(m * 4 + n) * 64 + lane];
; #pragma unroll
;           for (int w = 1; w < 8; ++w) s += red[(w * 8 + m * 4 + n) * 64 + lane];
;           acc[m][n] = s;
;         }
;       staged_epilogue<2>(acc, row0, col0, epi);
	v_pk_add_f32 v[70:71], v[70:71], v[26:27]
	v_pk_add_f32 v[26:27], v[40:41], v[44:45]
	v_pk_add_f32 v[68:69], v[68:69], v[28:29]
	v_pk_add_f32 v[28:29], v[38:39], v[42:43]
	v_pk_add_f32 v[26:27], v[26:27], v[32:33]
	v_pk_add_f32 v[28:29], v[28:29], v[30:31]
	v_pk_add_f32 v[26:27], v[26:27], v[48:49]
	v_pk_add_f32 v[28:29], v[28:29], v[46:47]
	v_pk_add_f32 v[26:27], v[26:27], v[52:53]
	v_pk_add_f32 v[28:29], v[28:29], v[50:51]
	v_pk_add_f32 v[26:27], v[26:27], v[56:57]
	v_pk_add_f32 v[28:29], v[28:29], v[54:55]
	s_waitcnt lgkmcnt(1)
	v_pk_add_f32 v[26:27], v[26:27], v[60:61]
	v_pk_add_f32 v[38:39], v[28:29], v[58:59]
	s_waitcnt lgkmcnt(0)
	v_pk_add_f32 v[72:73], v[26:27], v[36:37]
	ds_read_b128 v[26:29], v23 offset:6144
	ds_read_b128 v[30:33], v23 offset:14336
	v_pk_add_f32 v[74:75], v[38:39], v[34:35]
	ds_read_b128 v[34:37], v23 offset:22528
	ds_read_b128 v[38:41], v23 offset:7168
	ds_read_b128 v[42:45], v23 offset:15360
	s_waitcnt lgkmcnt(3)
	v_pk_add_f32 v[46:47], v[28:29], v[32:33]
	v_pk_add_f32 v[48:49], v[26:27], v[30:31]
	ds_read_b128 v[26:29], v23 offset:30720
	ds_read_b128 v[30:33], v23 offset:23552
	s_waitcnt lgkmcnt(4)
	v_pk_add_f32 v[50:51], v[46:47], v[36:37]
	v_pk_add_f32 v[52:53], v[48:49], v[34:35]
	ds_read_b128 v[34:37], v23 offset:38912
	ds_read_b128 v[46:49], v23 offset:31744
	s_waitcnt lgkmcnt(3)
	v_pk_add_f32 v[54:55], v[50:51], v[28:29]
	v_pk_add_f32 v[56:57], v[52:53], v[26:27]
	ds_read_b128 v[26:29], v23 offset:47104
	ds_read_b128 v[50:53], v23 offset:39936
	s_waitcnt lgkmcnt(3)
	v_pk_add_f32 v[58:59], v[54:55], v[36:37]
	v_pk_add_f32 v[60:61], v[56:57], v[34:35]
	ds_read_b128 v[34:37], v23 offset:55296
	ds_read_b128 v[54:57], v23 offset:48128
	s_waitcnt lgkmcnt(3)
	v_pk_add_f32 v[76:77], v[58:59], v[28:29]
	v_pk_add_f32 v[78:79], v[60:61], v[26:27]
	ds_read_b128 v[26:29], v23 offset:63488
	ds_read_b128 v[58:61], v23 offset:56320
	v_pk_add_f32 v[38:39], v[38:39], v[42:43]
	s_waitcnt lgkmcnt(3)
	v_pk_add_f32 v[76:77], v[76:77], v[36:37]
	v_pk_add_f32 v[78:79], v[78:79], v[34:35]
	ds_read_b128 v[34:37], v23 offset:64512
	v_pk_add_f32 v[30:31], v[38:39], v[30:31]
	v_pk_add_f32 v[40:41], v[40:41], v[44:45]
	v_pk_add_f32 v[30:31], v[30:31], v[46:47]
	v_pk_add_f32 v[32:33], v[40:41], v[32:33]
	v_pk_add_f32 v[30:31], v[30:31], v[50:51]
	v_pk_add_f32 v[32:33], v[32:33], v[48:49]
	s_waitcnt lgkmcnt(3)
	v_pk_add_f32 v[30:31], v[30:31], v[54:55]
	v_pk_add_f32 v[32:33], v[32:33], v[52:53]
	s_waitcnt lgkmcnt(1)
	v_pk_add_f32 v[30:31], v[30:31], v[58:59]
	v_pk_add_f32 v[32:33], v[32:33], v[56:57]
	s_waitcnt lgkmcnt(0)
	v_pk_add_f32 v[30:31], v[30:31], v[34:35]
	v_mov_b32_e32 v34, v204
	v_pk_add_f32 v[32:33], v[32:33], v[60:61]
	v_lshrrev_b32_e32 v34, 6, v34
	v_mul_lo_u32 v34, v34, s9
	v_pk_add_f32 v[32:33], v[32:33], v[36:37]
	v_and_b32_e32 v35, 15, v0
	v_add_u32_e32 v34, 0x10000, v34
	v_lshrrev_b32_e32 v36, 2, v0
	v_pk_add_f32 v[28:29], v[76:77], v[28:29]
	v_pk_add_f32 v[26:27], v[78:79], v[26:27]
	v_and_b32_e32 v36, 12, v36
	v_lshl_or_b32 v35, v35, 2, v34
	v_mad_u32_u24 v35, v36, s16, v35
	ds_write2_b32 v35, v14, v18 offset1:16
	ds_write2_b32 v35, v15, v19 offset0:68 offset1:84
	ds_write2_b32 v35, v12, v16 offset0:136 offset1:152
	ds_write2_b32 v35, v13, v17 offset0:204 offset1:220
	ds_write2_b32 v35, v64, v66 offset0:32 offset1:48
	ds_write2_b32 v35, v65, v67 offset0:100 offset1:116
	ds_write2_b32 v35, v20, v62 offset0:168 offset1:184
	ds_write2_b32 v35, v21, v63 offset0:236 offset1:252
	v_add_u32_e32 v12, 0x1000, v35
	v_add_u32_e32 v13, 0x1400, v35
	ds_write2_b32 v12, v70, v74 offset0:64 offset1:80
	ds_write2_b32 v12, v71, v75 offset0:132 offset1:148
	ds_write2_b32 v12, v68, v72 offset0:200 offset1:216
	ds_write2_b32 v13, v69, v73 offset0:12 offset1:28
	ds_write2_b32 v12, v26, v30 offset0:96 offset1:112
	ds_write2_b32 v12, v27, v31 offset0:164 offset1:180
	ds_write2_b32 v12, v28, v32 offset0:232 offset1:248
	ds_write2_b32 v13, v29, v33 offset0:44 offset1:60
	v_bfe_u32 v178, v0, 4, 2
	v_lshlrev_b32_e32 v184, 2, v0
	v_and_b32_e32 v184, 60, v184
	v_or_b32_e32 v176, s19, v184
	v_or_b32_e32 v185, s18, v178
	v_lshlrev_b32_e32 v177, 10, v185
	v_add_u32_e32 v176, v176, v177
	v_ashrrev_i32_e32 v177, 31, v176
	v_lshlrev_b64 v[176:177], 1, v[176:177]
	v_lshl_add_u64 v[178:179], s[12:13], 0, v[176:177]
	global_load_dwordx2 v[144:145], v[178:179], off
	v_bfe_u32 v186, v0, 4, 2
	v_lshlrev_b32_e32 v184, 2, v0
	v_and_b32_e32 v184, 60, v184
	v_or_b32_e32 v176, s19, v184
	v_or_b32_e32 v185, s18, v186
	v_lshlrev_b32_e32 v177, 10, v185
	v_add_u32_e32 v176, v176, v177
	v_ashrrev_i32_e32 v177, 31, v176
	v_lshlrev_b64 v[176:177], 1, v[176:177]
	v_lshl_add_u64 v[178:179], s[14:15], 0, v[176:177]
	global_load_dwordx2 v[146:147], v[178:179], off
	v_bfe_u32 v182, v0, 4, 2
	v_lshlrev_b32_e32 v184, 2, v0
	v_and_b32_e32 v184, 60, v184
	v_or_b32_e32 v186, s19, v184
	v_or_b32_e32 v185, s18, v182
	v_lshlrev_b32_e32 v187, 10, v185
	v_or_b32_e32 v176, 0x1000, v187
	v_add_u32_e32 v176, v176, v186
	v_ashrrev_i32_e32 v177, 31, v176
	v_lshlrev_b64 v[178:179], 1, v[176:177]
	v_lshl_add_u64 v[180:181], s[12:13], 0, v[178:179]
	global_load_dwordx2 v[148:149], v[180:181], off
	v_bfe_u32 v186, v0, 4, 2
	v_lshlrev_b32_e32 v184, 2, v0
	v_and_b32_e32 v184, 60, v184
	v_or_b32_e32 v178, s19, v184
	v_or_b32_e32 v185, s18, v186
	v_lshlrev_b32_e32 v179, 10, v185
	v_or_b32_e32 v176, 0x1000, v179
	v_add_u32_e32 v176, v176, v178
	v_ashrrev_i32_e32 v177, 31, v176
	v_lshlrev_b64 v[180:181], 1, v[176:177]
	v_lshl_add_u64 v[178:179], s[14:15], 0, v[180:181]
	global_load_dwordx2 v[150:151], v[178:179], off
	v_bfe_u32 v181, v0, 4, 2
	v_lshlrev_b32_e32 v184, 2, v0
	v_and_b32_e32 v184, 60, v184
; __device__ __forceinline__ float bfs2f(short h) { return __uint_as_float(((unsigned)(u16)h) << 16); }
;   __device__ __forceinline__ void tile(const float* reg, int row0, int col0, int lane) const {
;     rows4(reg, lane, [&](int it, int rr, int c4, float4 v) {
;       int idx = (row0 + rr) * 1024 + col0 + c4;
;       bf16x4 gt = *(const bf16x4*)(gate + idx), mo = *(const bf16x4*)(merged + idx);
;       *(bf16x4*)(merged + idx) = pack4(fmaf(bfs2f(gt[0]), v.x, bfs2f(mo[0])), fmaf(bfs2f(gt[1]), v.y, bfs2f(mo[1])),
;                                        fmaf(bfs2f(gt[2]), v.z, bfs2f(mo[2])), fmaf(bfs2f(gt[3]), v.w, bfs2f(mo[3])));
;     });
	v_or_b32_e32 v187, s19, v184
	v_or_b32_e32 v185, s18, v181
	v_lshlrev_b32_e32 v180, 10, v185
	v_or_b32_e32 v186, 0x2000, v180
	v_add_u32_e32 v176, v186, v187
	v_ashrrev_i32_e32 v177, 31, v176
	v_lshlrev_b64 v[176:177], 1, v[176:177]
	v_lshl_add_u64 v[178:179], s[12:13], 0, v[176:177]
	global_load_dwordx2 v[152:153], v[178:179], off
	v_bfe_u32 v179, v0, 4, 2
	v_lshlrev_b32_e32 v184, 2, v0
	v_and_b32_e32 v184, 60, v184
	v_or_b32_e32 v187, s19, v184
	v_or_b32_e32 v185, s18, v179
	v_lshlrev_b32_e32 v178, 10, v185
	v_or_b32_e32 v186, 0x2000, v178
	v_add_u32_e32 v176, v186, v187
	v_ashrrev_i32_e32 v177, 31, v176
	v_lshlrev_b64 v[176:177], 1, v[176:177]
	v_lshl_add_u64 v[176:177], s[14:15], 0, v[176:177]
	global_load_dwordx2 v[154:155], v[176:177], off
	v_bfe_u32 v181, v0, 4, 2
	v_lshlrev_b32_e32 v184, 2, v0
	v_and_b32_e32 v184, 60, v184
	v_or_b32_e32 v187, s19, v184
	v_or_b32_e32 v185, s18, v181
	v_lshlrev_b32_e32 v180, 10, v185
	v_or_b32_e32 v186, 0x3000, v180
	v_add_u32_e32 v176, v186, v187
	v_ashrrev_i32_e32 v177, 31, v176
	v_lshlrev_b64 v[176:177], 1, v[176:177]
	v_lshl_add_u64 v[178:179], s[12:13], 0, v[176:177]
	global_load_dwordx2 v[156:157], v[178:179], off
	v_bfe_u32 v187, v0, 4, 2
	v_lshlrev_b32_e32 v184, 2, v0
	v_and_b32_e32 v184, 60, v184
	v_or_b32_e32 v176, s19, v184
	v_or_b32_e32 v185, s18, v187
	v_lshlrev_b32_e32 v177, 10, v185
	v_or_b32_e32 v186, 0x3000, v177
	v_add_u32_e32 v178, v186, v176
	v_ashrrev_i32_e32 v179, 31, v178
	v_lshlrev_b64 v[178:179], 1, v[178:179]
	v_lshl_add_u64 v[176:177], s[14:15], 0, v[178:179]
	global_load_dwordx2 v[158:159], v[176:177], off
	v_bfe_u32 v186, v0, 4, 2
	v_lshlrev_b32_e32 v184, 2, v0
	v_and_b32_e32 v184, 60, v184
	v_or_b32_e32 v178, s19, v184
	v_or_b32_e32 v185, s18, v186
	v_lshlrev_b32_e32 v179, 10, v185
	v_or_b32_e32 v176, 0x4000, v179
	v_add_u32_e32 v180, v176, v178
	v_ashrrev_i32_e32 v181, 31, v180
	v_lshlrev_b64 v[176:177], 1, v[180:181]
	v_lshl_add_u64 v[178:179], s[12:13], 0, v[176:177]
	global_load_dwordx2 v[160:161], v[178:179], off
	v_bfe_u32 v182, v0, 4, 2
	v_lshlrev_b32_e32 v184, 2, v0
	v_and_b32_e32 v184, 60, v184
	v_or_b32_e32 v186, s19, v184
	v_or_b32_e32 v185, s18, v182
	v_lshlrev_b32_e32 v187, 10, v185
	v_or_b32_e32 v176, 0x4000, v187
	v_add_u32_e32 v178, v176, v186
	v_ashrrev_i32_e32 v179, 31, v178
	v_lshlrev_b64 v[176:177], 1, v[178:179]
	v_lshl_add_u64 v[180:181], s[14:15], 0, v[176:177]
	global_load_dwordx2 v[162:163], v[180:181], off
	v_bfe_u32 v181, v0, 4, 2
	v_lshlrev_b32_e32 v184, 2, v0
	v_and_b32_e32 v184, 60, v184
	v_or_b32_e32 v187, s19, v184
	v_or_b32_e32 v185, s18, v181
	v_lshlrev_b32_e32 v180, 10, v185
	v_or_b32_e32 v186, 0x5000, v180
	v_add_u32_e32 v176, v186, v187
	v_ashrrev_i32_e32 v177, 31, v176
	v_lshlrev_b64 v[176:177], 1, v[176:177]
	v_lshl_add_u64 v[178:179], s[12:13], 0, v[176:177]
	global_load_dwordx2 v[164:165], v[178:179], off
	v_bfe_u32 v187, v0, 4, 2
	v_lshlrev_b32_e32 v184, 2, v0
	v_and_b32_e32 v184, 60, v184
	v_or_b32_e32 v176, s19, v184
	v_or_b32_e32 v185, s18, v187
	v_lshlrev_b32_e32 v177, 10, v185
	v_or_b32_e32 v186, 0x5000, v177
	v_add_u32_e32 v178, v186, v176
	v_ashrrev_i32_e32 v179, 31, v178
	v_lshlrev_b64 v[178:179], 1, v[178:179]
	v_lshl_add_u64 v[176:177], s[14:15], 0, v[178:179]
	global_load_dwordx2 v[166:167], v[176:177], off
	v_bfe_u32 v187, v0, 4, 2
	v_lshlrev_b32_e32 v184, 2, v0
	v_and_b32_e32 v184, 60, v184
	v_or_b32_e32 v185, s19, v184
	v_or_b32_e32 v176, s18, v187
	v_lshlrev_b32_e32 v186, 10, v176
	v_or_b32_e32 v176, 0x6000, v186
	v_add_u32_e32 v176, v176, v185
	v_ashrrev_i32_e32 v177, 31, v176
	v_lshlrev_b64 v[176:177], 1, v[176:177]
	v_lshl_add_u64 v[178:179], s[12:13], 0, v[176:177]
	global_load_dwordx2 v[168:169], v[178:179], off
	v_bfe_u32 v178, v0, 4, 2
	v_lshlrev_b32_e32 v184, 2, v0
	v_and_b32_e32 v184, 60, v184
	v_or_b32_e32 v185, s19, v184
	v_or_b32_e32 v176, s18, v178
	v_lshlrev_b32_e32 v186, 10, v176
	v_or_b32_e32 v176, 0x6000, v186
	v_add_u32_e32 v176, v176, v185
	v_ashrrev_i32_e32 v177, 31, v176
	v_lshlrev_b64 v[176:177], 1, v[176:177]
	v_lshl_add_u64 v[178:179], s[14:15], 0, v[176:177]
	global_load_dwordx2 v[170:171], v[178:179], off
	v_bfe_u32 v187, v0, 4, 2
	v_lshlrev_b32_e32 v184, 2, v0
	v_and_b32_e32 v184, 60, v184
	v_or_b32_e32 v185, 28, v187
	v_or_b32_e32 v186, s19, v184
	v_or_b32_e32 v176, s18, v185
	v_lshl_add_u32 v176, v176, 10, v186
	v_ashrrev_i32_e32 v177, 31, v176
	v_lshlrev_b64 v[178:179], 1, v[176:177]
	v_lshl_add_u64 v[180:181], s[12:13], 0, v[178:179]
	global_load_dwordx2 v[172:173], v[180:181], off
	v_bfe_u32 v186, v0, 4, 2
	v_lshlrev_b32_e32 v184, 2, v0
	v_and_b32_e32 v184, 60, v184
	v_or_b32_e32 v178, 28, v186
	v_or_b32_e32 v185, s19, v184
	v_or_b32_e32 v176, s18, v178
	v_lshl_add_u32 v176, v176, 10, v185
	v_ashrrev_i32_e32 v177, 31, v176
	v_lshlrev_b64 v[180:181], 1, v[176:177]
	v_lshl_add_u64 v[178:179], s[14:15], 0, v[180:181]
	global_load_dwordx2 v[174:175], v[178:179], off
	v_bfe_u32 v26, v0, 4, 2
	v_lshlrev_b32_e32 v0, 2, v0
	v_and_b32_e32 v0, 60, v0
	v_or_b32_e32 v14, 28, v26
	v_or_b32_e32 v18, s19, v0
	v_lshl_or_b32 v0, v0, 2, v34
	v_or_b32_e32 v12, s18, v14
	v_mad_u32_u24 v52, v14, s16, v0
	v_or_b32_e32 v14, s18, v26
	v_lshlrev_b32_e32 v19, 10, v14
	v_or_b32_e32 v16, 0x5000, v19
	v_add_u32_e32 v20, v16, v18
	v_or_b32_e32 v16, 0x4000, v19
	v_add_u32_e32 v30, v16, v18
	v_or_b32_e32 v16, 0x3000, v19
	v_add_u32_e32 v32, v16, v18
	v_or_b32_e32 v16, 0x2000, v19
	v_or_b32_e32 v14, 0x6000, v19
	v_add_u32_e32 v34, v16, v18
	v_or_b32_e32 v16, 0x1000, v19
	v_lshl_add_u32 v12, v12, 10, v18
	v_add_u32_e32 v14, v14, v18
	v_add_u32_e32 v16, v16, v18
	v_add_u32_e32 v18, v18, v19
	v_ashrrev_i32_e32 v13, 31, v12
	v_ashrrev_i32_e32 v15, 31, v14
	v_add_u32_e32 v53, 0xfffffbc0, v52
	v_ashrrev_i32_e32 v21, 31, v20
	v_add_u32_e32 v54, 0xfffff780, v52
	v_ashrrev_i32_e32 v31, 31, v30
	v_add_u32_e32 v55, 0xfffff340, v52
	v_ashrrev_i32_e32 v33, 31, v32
	v_add_u32_e32 v56, 0xffffef00, v52
	v_ashrrev_i32_e32 v35, 31, v34
	v_add_u32_e32 v57, 0xffffeac0, v52
	v_ashrrev_i32_e32 v17, 31, v16
	v_add_u32_e32 v28, 0xffffe680, v52
	v_ashrrev_i32_e32 v19, 31, v18
	v_mad_u32_u24 v0, v26, s16, v0
	v_lshlrev_b64 v[18:19], 1, v[18:19]
	v_lshl_add_u64 v[26:27], s[12:13], 0, v[18:19]
	v_lshl_add_u64 v[38:39], s[14:15], 0, v[18:19]
	v_lshlrev_b64 v[42:43], 1, v[16:17]
	ds_read_b128 v[16:19], v0
	ds_read_b128 v[26:29], v28
	v_lshl_add_u64 v[44:45], s[12:13], 0, v[42:43]
	v_lshlrev_b64 v[34:35], 1, v[34:35]
	v_lshlrev_b64 v[32:33], 1, v[32:33]
	s_waitcnt vmcnt(15)
; __device__ __forceinline__ float bfs2f(short h) { return __uint_as_float(((unsigned)(u16)h) << 16); }
;   __device__ __forceinline__ void tile(const float* reg, int row0, int col0, int lane) const {
;     rows4(reg, lane, [&](int it, int rr, int c4, float4 v) {
;       int idx = (row0 + rr) * 1024 + col0 + c4;
;       bf16x4 gt = *(const bf16x4*)(gate + idx), mo = *(const bf16x4*)(merged + idx);
;       *(bf16x4*)(merged + idx) = pack4(fmaf(bfs2f(gt[0]), v.x, bfs2f(mo[0])), fmaf(bfs2f(gt[1]), v.y, bfs2f(mo[1])),
;                                        fmaf(bfs2f(gt[2]), v.z, bfs2f(mo[2])), fmaf(bfs2f(gt[3]), v.w, bfs2f(mo[3])));
;     });
	v_mov_b32_e32 v36, v144
	v_mov_b32_e32 v37, v145
	v_and_b32_e32 v47, 0xffff0000, v36
	v_lshlrev_b32_e32 v46, 16, v36
	s_waitcnt vmcnt(14)
	v_mov_b32_e32 v40, v146
	v_mov_b32_e32 v41, v147
	v_and_b32_e32 v49, 0xffff0000, v40
	v_lshlrev_b32_e32 v48, 16, v40
	v_and_b32_e32 v51, 0xffff0000, v37
	v_lshlrev_b32_e32 v50, 16, v37
	v_and_b32_e32 v37, 0xffff0000, v41
	v_lshlrev_b32_e32 v36, 16, v41
	s_waitcnt lgkmcnt(1)
	v_pk_fma_f32 v[16:17], v[46:47], v[16:17], v[48:49]
	v_pk_fma_f32 v[18:19], v[50:51], v[18:19], v[36:37]
	v_cvt_pk_bf16_f32 v16, v16, v17
	v_cvt_pk_bf16_f32 v17, v18, v19
	global_store_dwordx2 v[38:39], v[16:17], off
	v_lshl_add_u64 v[18:19], s[14:15], 0, v[42:43]
	v_lshl_add_u64 v[38:39], s[12:13], 0, v[34:35]
	v_lshl_add_u64 v[34:35], s[14:15], 0, v[34:35]
	s_waitcnt vmcnt(14)
	v_mov_b32_e32 v16, v148
	v_mov_b32_e32 v17, v149
	v_and_b32_e32 v41, 0xffff0000, v16
	v_lshlrev_b32_e32 v40, 16, v16
	s_waitcnt vmcnt(13)
	v_mov_b32_e32 v36, v150
	v_mov_b32_e32 v37, v151
	v_and_b32_e32 v43, 0xffff0000, v36
	v_lshlrev_b32_e32 v42, 16, v36
	v_and_b32_e32 v45, 0xffff0000, v17
	v_lshlrev_b32_e32 v44, 16, v17
	v_and_b32_e32 v17, 0xffff0000, v37
	v_lshlrev_b32_e32 v16, 16, v37
	s_waitcnt lgkmcnt(0)
	v_pk_fma_f32 v[26:27], v[40:41], v[26:27], v[42:43]
	v_pk_fma_f32 v[16:17], v[44:45], v[28:29], v[16:17]
	v_cvt_pk_bf16_f32 v26, v26, v27
	v_cvt_pk_bf16_f32 v27, v16, v17
	global_store_dwordx2 v[18:19], v[26:27], off
	v_lshl_add_u64 v[40:41], s[12:13], 0, v[32:33]
	ds_read_b128 v[16:19], v57
	ds_read_b128 v[26:29], v56
	s_waitcnt vmcnt(13)
	v_mov_b32_e32 v36, v152
	v_mov_b32_e32 v37, v153
	v_and_b32_e32 v43, 0xffff0000, v36
	v_lshlrev_b32_e32 v42, 16, v36
	s_waitcnt vmcnt(12)
	v_mov_b32_e32 v38, v154
	v_mov_b32_e32 v39, v155
	v_and_b32_e32 v45, 0xffff0000, v38
	v_lshlrev_b32_e32 v44, 16, v38
	v_and_b32_e32 v47, 0xffff0000, v37
	v_lshlrev_b32_e32 v46, 16, v37
	v_and_b32_e32 v37, 0xffff0000, v39
	v_lshlrev_b32_e32 v36, 16, v39
	s_waitcnt lgkmcnt(1)
	v_pk_fma_f32 v[16:17], v[42:43], v[16:17], v[44:45]
	v_pk_fma_f32 v[18:19], v[46:47], v[18:19], v[36:37]
	v_cvt_pk_bf16_f32 v16, v16, v17
	v_cvt_pk_bf16_f32 v17, v18, v19
	global_store_dwordx2 v[34:35], v[16:17], off
	v_lshl_add_u64 v[18:19], s[14:15], 0, v[32:33]
	s_waitcnt vmcnt(12)
	v_mov_b32_e32 v16, v156
	v_mov_b32_e32 v17, v157
	v_and_b32_e32 v35, 0xffff0000, v16
	v_lshlrev_b32_e32 v34, 16, v16
	s_waitcnt vmcnt(11)
	v_mov_b32_e32 v32, v158
	v_mov_b32_e32 v33, v159
	v_and_b32_e32 v37, 0xffff0000, v32
	v_lshlrev_b32_e32 v36, 16, v32
	v_and_b32_e32 v39, 0xffff0000, v17
	v_lshlrev_b32_e32 v38, 16, v17
	v_and_b32_e32 v17, 0xffff0000, v33
	v_lshlrev_b32_e32 v16, 16, v33
	s_waitcnt lgkmcnt(0)
	v_pk_fma_f32 v[26:27], v[34:35], v[26:27], v[36:37]
	v_pk_fma_f32 v[16:17], v[38:39], v[28:29], v[16:17]
	v_cvt_pk_bf16_f32 v26, v26, v27
	v_cvt_pk_bf16_f32 v27, v16, v17
	global_store_dwordx2 v[18:19], v[26:27], off
	v_lshlrev_b64 v[16:17], 1, v[30:31]
	v_lshl_add_u64 v[18:19], s[12:13], 0, v[16:17]
	v_lshl_add_u64 v[32:33], s[14:15], 0, v[16:17]
	ds_read_b128 v[16:19], v55
	ds_read_b128 v[26:29], v54
	v_lshlrev_b64 v[20:21], 1, v[20:21]
	v_lshl_add_u64 v[36:37], s[12:13], 0, v[20:21]
	v_lshlrev_b64 v[14:15], 1, v[14:15]
	s_waitcnt vmcnt(11)
	v_mov_b32_e32 v30, v160
	v_mov_b32_e32 v31, v161
	v_and_b32_e32 v39, 0xffff0000, v30
	v_lshlrev_b32_e32 v38, 16, v30
	s_waitcnt vmcnt(10)
	v_mov_b32_e32 v34, v162
	v_mov_b32_e32 v35, v163
	v_and_b32_e32 v41, 0xffff0000, v34
	v_lshlrev_b32_e32 v40, 16, v34
	v_and_b32_e32 v43, 0xffff0000, v31
	v_lshlrev_b32_e32 v42, 16, v31
	v_and_b32_e32 v31, 0xffff0000, v35
	v_lshlrev_b32_e32 v30, 16, v35
	s_waitcnt lgkmcnt(1)
	v_pk_fma_f32 v[16:17], v[38:39], v[16:17], v[40:41]
	v_pk_fma_f32 v[18:19], v[42:43], v[18:19], v[30:31]
	v_cvt_pk_bf16_f32 v16, v16, v17
	v_cvt_pk_bf16_f32 v17, v18, v19
	global_store_dwordx2 v[32:33], v[16:17], off
	v_lshl_add_u64 v[18:19], s[14:15], 0, v[20:21]
	v_lshl_add_u64 v[30:31], s[12:13], 0, v[14:15]
	s_waitcnt vmcnt(10)
	v_mov_b32_e32 v16, v164
	v_mov_b32_e32 v17, v165
	v_and_b32_e32 v33, 0xffff0000, v16
	v_lshlrev_b32_e32 v32, 16, v16
	s_waitcnt vmcnt(9)
	v_mov_b32_e32 v20, v166
	v_mov_b32_e32 v21, v167
	v_and_b32_e32 v35, 0xffff0000, v20
	v_lshlrev_b32_e32 v34, 16, v20
	v_and_b32_e32 v37, 0xffff0000, v17
	v_lshlrev_b32_e32 v36, 16, v17
	v_and_b32_e32 v17, 0xffff0000, v21
	v_lshlrev_b32_e32 v16, 16, v21
	s_waitcnt lgkmcnt(0)
	v_pk_fma_f32 v[20:21], v[32:33], v[26:27], v[34:35]
	v_pk_fma_f32 v[16:17], v[36:37], v[28:29], v[16:17]
	v_cvt_pk_bf16_f32 v20, v20, v21
	v_cvt_pk_bf16_f32 v21, v16, v17
	global_store_dwordx2 v[18:19], v[20:21], off
	v_lshl_add_u64 v[26:27], s[14:15], 0, v[14:15]
	v_lshlrev_b64 v[30:31], 1, v[12:13]
	ds_read_b128 v[12:15], v53
	ds_read_b128 v[16:19], v52
	v_lshl_add_u64 v[32:33], s[12:13], 0, v[30:31]
	s_waitcnt vmcnt(9)
	v_mov_b32_e32 v20, v168
	v_mov_b32_e32 v21, v169
	v_and_b32_e32 v35, 0xffff0000, v20
	v_lshlrev_b32_e32 v34, 16, v20
	s_waitcnt vmcnt(8)
	v_mov_b32_e32 v28, v170
	v_mov_b32_e32 v29, v171
	v_and_b32_e32 v37, 0xffff0000, v28
	v_lshlrev_b32_e32 v36, 16, v28
	v_and_b32_e32 v39, 0xffff0000, v21
	v_lshlrev_b32_e32 v38, 16, v21
	v_and_b32_e32 v21, 0xffff0000, v29
	v_lshlrev_b32_e32 v20, 16, v29
	s_waitcnt lgkmcnt(1)
	v_pk_fma_f32 v[12:13], v[34:35], v[12:13], v[36:37]
	v_pk_fma_f32 v[14:15], v[38:39], v[14:15], v[20:21]
	v_cvt_pk_bf16_f32 v12, v12, v13
	v_cvt_pk_bf16_f32 v13, v14, v15
	global_store_dwordx2 v[26:27], v[12:13], off
	v_lshl_add_u64 v[14:15], s[14:15], 0, v[30:31]
	s_waitcnt vmcnt(8)
	v_mov_b32_e32 v12, v172
	v_mov_b32_e32 v13, v173
	v_and_b32_e32 v27, 0xffff0000, v12
	v_lshlrev_b32_e32 v26, 16, v12
	s_waitcnt vmcnt(7)
	v_mov_b32_e32 v20, v174
	v_mov_b32_e32 v21, v175
	v_and_b32_e32 v29, 0xffff0000, v20
	v_lshlrev_b32_e32 v28, 16, v20
	v_and_b32_e32 v31, 0xffff0000, v13
	v_lshlrev_b32_e32 v30, 16, v13
	v_and_b32_e32 v13, 0xffff0000, v21
	v_lshlrev_b32_e32 v12, 16, v21
	s_waitcnt lgkmcnt(0)
	v_pk_fma_f32 v[16:17], v[26:27], v[16:17], v[28:29]
	v_pk_fma_f32 v[12:13], v[30:31], v[18:19], v[12:13]
	v_cvt_pk_bf16_f32 v16, v16, v17
	v_cvt_pk_bf16_f32 v17, v12, v13
	global_store_dwordx2 v[14:15], v[16:17], off
	s_branch .LBB0_3030

; __device__ __forceinline__ float bfs2f(short h) { return __uint_as_float(((unsigned)(u16)h) << 16); }
; __device__ __forceinline__ float sigm(float x) { return __builtin_amdgcn_rcpf(1.f + __expf(-x)); }
; __device__ __forceinline__ float rs_of(float ss) { return rsqrtf(ss * (1.f / 1024) + EPS); }
;   __device__ __forceinline__ void tile(const float* reg, int row0, int col0, int lane) const {
;     float rsv[8];
; #pragma unroll
;     for (int i = 0; i < 8; ++i) rsv[i] = rs_of(ssq[row0 + i * 4 + (lane >> 4)]);
;     rows4(reg, lane, [&](int it, int rr, int c4, float4 v) {
;       int row = row0 + rr, idx = row * 1024 + col0 + c4;
;       float rs = rsv[it];
;       float4 xo = *(const float4*)(xold + idx);
;       bf16x4 t = *(const bf16x4*)(tmp + idx);
;       v.x = fmaf(sigm(v.x * rs), bfs2f(t[0]), xo.x); v.y = fmaf(sigm(v.y * rs), bfs2f(t[1]), xo.y);
;       v.z = fmaf(sigm(v.z * rs), bfs2f(t[2]), xo.z); v.w = fmaf(sigm(v.w * rs), bfs2f(t[3]), xo.w);
;       *(float4*)(xnew + idx) = v;
;       *(bf16x4*)(xb + idx) = pack4(v.x, v.y, v.z, v.w);
;       float s = row16_sum(v.x * v.x + v.y * v.y + v.z * v.z + v.w * v.w);
;       if ((lane & 15) == 0) atomicAdd(ssqn + row, s);
;     });
; template <int MF, class Epi>
; __device__ __forceinline__ void staged_epilogue(f32x4 (&acc)[MF][4], int row0, int col0, const Epi& epi) {
;   const int lane = tidx() & 63, wid = tidx() >> 6, fr = lane & 15, fq = lane >> 4;
;   float* reg = (float*)(g_shm + 65536 + wid * 8704);
; #pragma unroll
;   for (int mp = 0; mp < MF / 2; ++mp) {
;     __builtin_amdgcn_sched_barrier(0);
; #pragma unroll
;     for (int mm = 0; mm < 2; ++mm)
; #pragma unroll
;       for (int n = 0; n < 4; ++n)
; #pragma unroll
;         for (int j = 0; j < 4; ++j) reg[(mm * 16 + fq * 4 + j) * 68 + n * 16 + fr] = acc[mp * 2 + mm][n][j];
;     __builtin_amdgcn_fence(__ATOMIC_ACQ_REL, "wavefront");
;     epi.tile(reg, row0 + mp * 32, col0, lane);
;     __builtin_amdgcn_fence(__ATOMIC_ACQ_REL, "wavefront");
.LBB0_3278:
	v_mov_b32_e32 v131, v204
	v_mov_b32_e32 v130, v204
	s_nop 0
	v_lshrrev_b32_e32 v130, 6, v130
	v_mul_lo_u32 v130, v130, s55
	v_add_u32_e32 v136, 0x10000, v130
	v_lshrrev_b32_e32 v130, 2, v131
	v_and_b32_e32 v137, 15, v131
	v_and_b32_e32 v138, 12, v130
	v_bfe_u32 v130, v131, 4, 2
	v_lshlrev_b32_e32 v131, 2, v131
	v_and_b32_e32 v131, 60, v131
	v_lshl_or_b32 v139, v137, 2, v136
	v_lshl_or_b32 v136, v131, 2, v136
	v_add_u32_e32 v128, v131, v128
	v_cmp_eq_u32_e32 vcc, 0, v137
	v_mad_u32_u24 v140, v130, s56, v136
	v_mad_u32_u24 v131, v138, s56, v139
	ds_write2_b32 v131, v120, v124 offset1:16
	ds_write2_b32 v131, v121, v125 offset0:68 offset1:84
	ds_write2_b32 v131, v122, v126 offset0:136 offset1:152
	ds_write2_b32 v131, v123, v127 offset0:204 offset1:220
	ds_write2_b32 v131, v112, v116 offset0:32 offset1:48
	ds_write2_b32 v131, v113, v117 offset0:100 offset1:116
	ds_write2_b32 v131, v114, v118 offset0:168 offset1:184
	ds_write2_b32 v131, v115, v119 offset0:236 offset1:252
	v_add_u32_e32 v112, 0x1000, v131
	ds_write2_b32 v112, v104, v108 offset0:64 offset1:80
	ds_write2_b32 v112, v105, v109 offset0:132 offset1:148
	ds_write2_b32 v112, v106, v110 offset0:200 offset1:216
	v_add_u32_e32 v104, 0x1400, v131
	ds_write2_b32 v104, v107, v111 offset0:12 offset1:28
	ds_write2_b32 v112, v96, v100 offset0:96 offset1:112
	ds_write2_b32 v112, v97, v101 offset0:164 offset1:180
	ds_write2_b32 v112, v98, v102 offset0:232 offset1:248
	ds_write2_b32 v104, v99, v103 offset0:44 offset1:60
	v_add_u32_e32 v200, v130, v129
	v_ashrrev_i32_e32 v201, 31, v200
	v_lshl_add_u64 v[202:203], v[200:201], 2, s[22:23]
	global_load_dword v144, v[202:203], off
	v_add_u32_e32 v210, v130, v129
	v_add_u32_e32 v200, 4, v210
	v_ashrrev_i32_e32 v201, 31, v200
	v_lshl_add_u64 v[200:201], v[200:201], 2, s[22:23]
	global_load_dword v145, v[200:201], off
	v_add_u32_e32 v210, v130, v129
	v_add_u32_e32 v200, 8, v210
	v_ashrrev_i32_e32 v201, 31, v200
	v_lshl_add_u64 v[202:203], v[200:201], 2, s[22:23]
	global_load_dword v146, v[202:203], off
	v_add_u32_e32 v210, v130, v129
	v_add_u32_e32 v200, 12, v210
	v_ashrrev_i32_e32 v201, 31, v200
	v_lshl_add_u64 v[202:203], v[200:201], 2, s[22:23]
	global_load_dword v147, v[202:203], off
	v_add_u32_e32 v210, v130, v129
	v_add_u32_e32 v200, 16, v210
	v_ashrrev_i32_e32 v201, 31, v200
	v_lshl_add_u64 v[202:203], v[200:201], 2, s[22:23]
	global_load_dword v148, v[202:203], off
	v_add_u32_e32 v210, v130, v129
	v_add_u32_e32 v200, 20, v210
	v_ashrrev_i32_e32 v201, 31, v200
	v_lshl_add_u64 v[202:203], v[200:201], 2, s[22:23]
	global_load_dword v149, v[202:203], off
	v_add_u32_e32 v210, v130, v129
	v_add_u32_e32 v200, 24, v210
	v_ashrrev_i32_e32 v201, 31, v200
	v_lshl_add_u64 v[202:203], v[200:201], 2, s[22:23]
	global_load_dword v150, v[202:203], off
	v_add_u32_e32 v210, v130, v129
	v_add_u32_e32 v200, 28, v210
	v_ashrrev_i32_e32 v201, 31, v200
	v_lshl_add_u64 v[202:203], v[200:201], 2, s[22:23]
	global_load_dword v151, v[202:203], off
	v_add_u32_e32 v210, v130, v129
	v_lshl_add_u32 v200, v210, 10, v128
	v_ashrrev_i32_e32 v201, 31, v200
	v_lshlrev_b64 v[202:203], 1, v[200:201]
	v_lshl_add_u64 v[206:207], s[14:15], 0, v[202:203]
	global_load_dwordx2 v[152:153], v[206:207], off
	v_add_u32_e32 v210, v130, v129
	v_lshl_add_u32 v200, v210, 10, v128
	v_ashrrev_i32_e32 v201, 31, v200
	v_lshl_add_u64 v[200:201], v[200:201], 2, s[8:9]
	global_load_dwordx4 v[154:157], v[200:201], off
	v_or_b32_e32 v211, 4, v130
	v_add_u32_e32 v210, v211, v129
	v_lshl_add_u32 v200, v210, 10, v128
	v_ashrrev_i32_e32 v201, 31, v200
	v_lshlrev_b64 v[206:207], 1, v[200:201]
	v_lshl_add_u64 v[202:203], s[14:15], 0, v[206:207]
	global_load_dwordx2 v[158:159], v[202:203], off
	v_or_b32_e32 v211, 4, v130
	v_add_u32_e32 v210, v211, v129
	v_lshl_add_u32 v200, v210, 10, v128
	v_ashrrev_i32_e32 v201, 31, v200
	v_lshl_add_u64 v[202:203], v[200:201], 2, s[8:9]
	global_load_dwordx4 v[160:163], v[202:203], off
	v_or_b32_e32 v211, 8, v130
	v_add_u32_e32 v210, v211, v129
	v_lshl_add_u32 v200, v210, 10, v128
	v_ashrrev_i32_e32 v201, 31, v200
	v_lshlrev_b64 v[206:207], 1, v[200:201]
	v_lshl_add_u64 v[202:203], s[14:15], 0, v[206:207]
	global_load_dwordx2 v[164:165], v[202:203], off
	v_or_b32_e32 v211, 8, v130
	v_add_u32_e32 v210, v211, v129
	v_lshl_add_u32 v200, v210, 10, v128
	v_ashrrev_i32_e32 v201, 31, v200
	v_lshl_add_u64 v[202:203], v[200:201], 2, s[8:9]
	global_load_dwordx4 v[166:169], v[202:203], off
	v_or_b32_e32 v211, 12, v130
	v_add_u32_e32 v210, v211, v129
	v_lshl_add_u32 v200, v210, 10, v128
	v_ashrrev_i32_e32 v201, 31, v200
	v_lshlrev_b64 v[206:207], 1, v[200:201]
	v_lshl_add_u64 v[202:203], s[14:15], 0, v[206:207]
	global_load_dwordx2 v[170:171], v[202:203], off
	v_or_b32_e32 v211, 12, v130
	v_add_u32_e32 v210, v211, v129
	v_lshl_add_u32 v200, v210, 10, v128
	v_ashrrev_i32_e32 v201, 31, v200
	v_lshl_add_u64 v[202:203], v[200:201], 2, s[8:9]
	global_load_dwordx4 v[172:175], v[202:203], off
	v_or_b32_e32 v211, 16, v130
	v_add_u32_e32 v210, v211, v129
	v_lshl_add_u32 v200, v210, 10, v128
	v_ashrrev_i32_e32 v201, 31, v200
	v_lshlrev_b64 v[206:207], 1, v[200:201]
	v_lshl_add_u64 v[202:203], s[14:15], 0, v[206:207]
	global_load_dwordx2 v[176:177], v[202:203], off
	v_or_b32_e32 v211, 16, v130
	v_add_u32_e32 v210, v211, v129
	v_lshl_add_u32 v200, v210, 10, v128
	v_ashrrev_i32_e32 v201, 31, v200
	v_lshl_add_u64 v[202:203], v[200:201], 2, s[8:9]
	global_load_dwordx4 v[178:181], v[202:203], off
	v_or_b32_e32 v211, 20, v130
	v_add_u32_e32 v210, v211, v129
	v_lshl_add_u32 v200, v210, 10, v128
	v_ashrrev_i32_e32 v201, 31, v200
	v_lshlrev_b64 v[206:207], 1, v[200:201]
; __device__ __forceinline__ float bfs2f(short h) { return __uint_as_float(((unsigned)(u16)h) << 16); }
; __device__ __forceinline__ float sigm(float x) { return __builtin_amdgcn_rcpf(1.f + __expf(-x)); }
; __device__ __forceinline__ float rs_of(float ss) { return rsqrtf(ss * (1.f / 1024) + EPS); }
;   __device__ __forceinline__ void tile(const float* reg, int row0, int col0, int lane) const {
;     float rsv[8];
; #pragma unroll
;     for (int i = 0; i < 8; ++i) rsv[i] = rs_of(ssq[row0 + i * 4 + (lane >> 4)]);
;     rows4(reg, lane, [&](int it, int rr, int c4, float4 v) {
;       int row = row0 + rr, idx = row * 1024 + col0 + c4;
;       float rs = rsv[it];
;       float4 xo = *(const float4*)(xold + idx);
;       bf16x4 t = *(const bf16x4*)(tmp + idx);
;       v.x = fmaf(sigm(v.x * rs), bfs2f(t[0]), xo.x); v.y = fmaf(sigm(v.y * rs), bfs2f(t[1]), xo.y);
;       v.z = fmaf(sigm(v.z * rs), bfs2f(t[2]), xo.z); v.w = fmaf(sigm(v.w * rs), bfs2f(t[3]), xo.w);
;       *(float4*)(xnew + idx) = v;
;       *(bf16x4*)(xb + idx) = pack4(v.x, v.y, v.z, v.w);
;       float s = row16_sum(v.x * v.x + v.y * v.y + v.z * v.z + v.w * v.w);
;       if ((lane & 15) == 0) atomicAdd(ssqn + row, s);
;     });
	v_lshl_add_u64 v[202:203], s[14:15], 0, v[206:207]
	global_load_dwordx2 v[182:183], v[202:203], off
	v_or_b32_e32 v211, 20, v130
	v_add_u32_e32 v210, v211, v129
	v_lshl_add_u32 v200, v210, 10, v128
	v_ashrrev_i32_e32 v201, 31, v200
	v_lshl_add_u64 v[202:203], v[200:201], 2, s[8:9]
	global_load_dwordx4 v[184:187], v[202:203], off
	v_or_b32_e32 v211, 24, v130
	v_add_u32_e32 v210, v211, v129
	v_lshl_add_u32 v200, v210, 10, v128
	v_ashrrev_i32_e32 v201, 31, v200
	v_lshlrev_b64 v[206:207], 1, v[200:201]
	v_lshl_add_u64 v[202:203], s[14:15], 0, v[206:207]
	global_load_dwordx2 v[188:189], v[202:203], off
	v_or_b32_e32 v211, 24, v130
	v_add_u32_e32 v210, v211, v129
	v_lshl_add_u32 v200, v210, 10, v128
	v_ashrrev_i32_e32 v201, 31, v200
	v_lshl_add_u64 v[202:203], v[200:201], 2, s[8:9]
	global_load_dwordx4 v[190:193], v[202:203], off
	v_or_b32_e32 v211, 28, v130
	v_add_u32_e32 v210, v211, v129
	v_lshl_add_u32 v200, v210, 10, v128
	v_ashrrev_i32_e32 v201, 31, v200
	v_lshlrev_b64 v[206:207], 1, v[200:201]
	v_lshl_add_u64 v[202:203], s[14:15], 0, v[206:207]
	global_load_dwordx2 v[194:195], v[202:203], off
	v_or_b32_e32 v211, 28, v130
	v_add_u32_e32 v210, v211, v129
	v_lshl_add_u32 v200, v210, 10, v128
	v_ashrrev_i32_e32 v201, 31, v200
	v_lshl_add_u64 v[202:203], v[200:201], 2, s[8:9]
	global_load_dwordx4 v[196:199], v[202:203], off
	v_add_u32_e32 v96, v130, v129
	v_add_u32_e32 v100, 8, v96
	v_ashrrev_i32_e32 v101, 31, v100
	v_lshl_add_u64 v[102:103], v[100:101], 2, s[22:23]
	v_add_u32_e32 v100, 12, v96
	v_ashrrev_i32_e32 v101, 31, v100
	v_lshl_add_u64 v[106:107], v[100:101], 2, s[22:23]
	v_add_u32_e32 v100, 16, v96
	v_ashrrev_i32_e32 v101, 31, v100
	v_ashrrev_i32_e32 v97, 31, v96
	v_lshl_add_u64 v[108:109], v[100:101], 2, s[22:23]
	v_add_u32_e32 v100, 20, v96
	v_lshl_add_u64 v[98:99], v[96:97], 2, s[22:23]
	v_ashrrev_i32_e32 v101, 31, v100
	v_lshl_add_u64 v[110:111], v[100:101], 2, s[22:23]
	v_add_u32_e32 v100, 24, v96
	v_add_u32_e32 v98, 4, v96
	v_ashrrev_i32_e32 v101, 31, v100
	v_ashrrev_i32_e32 v99, 31, v98
	v_lshl_add_u64 v[114:115], v[100:101], 2, s[22:23]
	v_add_u32_e32 v100, 28, v96
	v_lshl_add_u64 v[98:99], v[98:99], 2, s[22:23]
	v_ashrrev_i32_e32 v101, 31, v100
	v_lshl_add_u64 v[116:117], v[100:101], 2, s[22:23]
	s_nop 0
	s_nop 0
	s_nop 0
	s_waitcnt vmcnt(16)
	v_mov_b32_e32 v113, v144
	v_mov_b32_e32 v100, v145
	v_mov_b32_e32 v101, v146
	v_mov_b32_e32 v98, v147
	v_mov_b32_e32 v105, v148
	v_mov_b32_e32 v106, v149
	v_mov_b32_e32 v107, v150
	v_mov_b32_e32 v110, v151
	v_fmamk_f32 v99, v113, 0x3a800000, v135
	v_mul_f32_e32 v102, 0x4b800000, v99
	v_cmp_gt_f32_e64 s[6:7], s57, v99
	s_nop 1
	v_cndmask_b32_e64 v99, v99, v102, s[6:7]
	v_rsq_f32_e32 v99, v99
	s_nop 0
	v_mul_f32_e32 v102, 0x45800000, v99
	v_cndmask_b32_e64 v99, v99, v102, s[6:7]
	v_lshl_add_u32 v102, v96, 10, v128
	v_ashrrev_i32_e32 v103, 31, v102
	v_lshlrev_b64 v[108:109], 1, v[102:103]
	v_lshl_add_u64 v[114:115], s[14:15], 0, v[108:109]
	v_lshl_add_u64 v[102:103], v[102:103], 2, s[8:9]
	ds_read_b128 v[118:121], v140
	v_lshl_add_u64 v[108:109], s[10:11], 0, v[108:109]
	s_waitcnt lgkmcnt(0)
	v_mul_f32_e32 v111, v99, v118
	v_mul_f32_e32 v113, v99, v119
	v_mul_f32_e32 v118, v99, v120
	v_mul_f32_e32 v99, v99, v121
	v_mul_f32_e32 v111, 0xbfb8aa3b, v111
	v_mul_f32_e32 v113, 0xbfb8aa3b, v113
	v_mul_f32_e32 v118, 0xbfb8aa3b, v118
	v_mul_f32_e32 v99, 0xbfb8aa3b, v99
	v_exp_f32_e32 v111, v111
	v_exp_f32_e32 v113, v113
	v_exp_f32_e32 v118, v118
	v_exp_f32_e32 v99, v99
	v_add_f32_e32 v111, 1.0, v111
	v_add_f32_e32 v113, 1.0, v113
	v_add_f32_e32 v120, 1.0, v118
	v_add_f32_e32 v99, 1.0, v99
	v_rcp_f32_e32 v118, v111
	v_rcp_f32_e32 v119, v113
	v_rcp_f32_e32 v120, v120
	v_rcp_f32_e32 v121, v99
	s_waitcnt vmcnt(15)
	v_mov_b32_e32 v122, v152
	v_mov_b32_e32 v123, v153
	v_and_b32_e32 v125, 0xffff0000, v122
	v_lshlrev_b32_e32 v124, 16, v122
	v_and_b32_e32 v127, 0xffff0000, v123
	v_lshlrev_b32_e32 v126, 16, v123
	s_waitcnt vmcnt(14)
	v_mov_b32_e32 v114, v154
	v_mov_b32_e32 v115, v155
	v_mov_b32_e32 v116, v156
	v_mov_b32_e32 v117, v157
	v_pk_fma_f32 v[114:115], v[118:119], v[124:125], v[114:115]
	v_pk_fma_f32 v[116:117], v[120:121], v[126:127], v[116:117]
	global_store_dwordx4 v[102:103], v[114:117], off
	v_cvt_pk_bf16_f32 v102, v114, v115
	v_cvt_pk_bf16_f32 v103, v116, v117
	v_pk_mul_f32 v[114:115], v[114:115], v[114:115]
	v_pk_mul_f32 v[116:117], v[116:117], v[116:117]
	v_add_f32_e32 v99, v114, v115
	v_add_f32_e32 v99, v116, v99
	v_add_f32_e32 v99, v117, v99
	global_store_dwordx2 v[108:109], v[102:103], off
	v_mov_b32_e32 v102, 0
	v_add_f32_dpp v99, v99, v99 quad_perm:[1,0,3,2] row_mask:0xf bank_mask:0xf bound_ctrl:1
	s_nop 1
	v_add_f32_dpp v99, v99, v99 quad_perm:[2,3,0,1] row_mask:0xf bank_mask:0xf bound_ctrl:1
	s_nop 1
	v_add_f32_dpp v99, v99, v99 row_half_mirror row_mask:0xf bank_mask:0xf bound_ctrl:1
	s_nop 1
	v_mov_b32_dpp v102, v99 row_mirror row_mask:0xf bank_mask:0xf
	s_and_saveexec_b64 s[0:1], vcc
	s_cbranch_execz .LBB0_3280
	v_add_f32_e32 v99, v99, v102
	v_lshl_add_u64 v[96:97], v[96:97], 2, s[24:25]
	global_atomic_add_f32 v[96:97], v99, off
; __device__ __forceinline__ float bfs2f(short h) { return __uint_as_float(((unsigned)(u16)h) << 16); }
; __device__ __forceinline__ float sigm(float x) { return __builtin_amdgcn_rcpf(1.f + __expf(-x)); }
;   __device__ __forceinline__ void tile(const float* reg, int row0, int col0, int lane) const {
;     ...
;     rows4(reg, lane, [&](int it, int rr, int c4, float4 v) {
;       int row = row0 + rr, idx = row * 1024 + col0 + c4;
;       float rs = rsv[it];
;       float4 xo = *(const float4*)(xold + idx);
;       bf16x4 t = *(const bf16x4*)(tmp + idx);
;       v.x = fmaf(sigm(v.x * rs), bfs2f(t[0]), xo.x); v.y = fmaf(sigm(v.y * rs), bfs2f(t[1]), xo.y);
;       v.z = fmaf(sigm(v.z * rs), bfs2f(t[2]), xo.z); v.w = fmaf(sigm(v.w * rs), bfs2f(t[3]), xo.w);
;       *(float4*)(xnew + idx) = v;
;       *(bf16x4*)(xb + idx) = pack4(v.x, v.y, v.z, v.w);
;       float s = row16_sum(v.x * v.x + v.y * v.y + v.z * v.z + v.w * v.w);
;       if ((lane & 15) == 0) atomicAdd(ssqn + row, s);
;     });
.LBB0_3280:
	s_or_b64 exec, exec, s[0:1]
	v_or_b32_e32 v99, 4, v130
	v_add_u32_e32 v96, v99, v129
	v_lshl_add_u32 v102, v96, 10, v128
	v_ashrrev_i32_e32 v103, 31, v102
	v_lshlrev_b64 v[122:123], 1, v[102:103]
	v_lshl_add_u64 v[108:109], s[14:15], 0, v[122:123]
	v_lshl_add_u64 v[126:127], v[102:103], 2, s[8:9]
	v_fmamk_f32 v97, v100, 0x3a800000, v135
	v_mul_u32_u24_e32 v109, 0x110, v130
	v_mul_f32_e32 v100, 0x4b800000, v97
	v_cmp_gt_f32_e64 s[6:7], s57, v97
	v_add_u32_e32 v103, 0x440, v109
	v_add_u32_e32 v102, v136, v103
	v_cndmask_b32_e64 v97, v97, v100, s[6:7]
	v_rsq_f32_e32 v97, v97
	ds_read_b128 v[118:121], v102
	v_lshl_add_u64 v[122:123], s[10:11], 0, v[122:123]
	v_mul_f32_e32 v100, 0x45800000, v97
	v_cndmask_b32_e64 v97, v97, v100, s[6:7]
	s_waitcnt lgkmcnt(0)
	v_mul_f32_e32 v100, v97, v118
	v_mul_f32_e32 v108, v97, v119
	v_mul_f32_e32 v111, v97, v120
	v_mul_f32_e32 v97, v97, v121
	v_mul_f32_e32 v100, 0xbfb8aa3b, v100
	v_mul_f32_e32 v108, 0xbfb8aa3b, v108
	v_mul_f32_e32 v111, 0xbfb8aa3b, v111
	v_mul_f32_e32 v97, 0xbfb8aa3b, v97
	v_exp_f32_e32 v100, v100
	v_exp_f32_e32 v108, v108
	v_exp_f32_e32 v111, v111
	v_exp_f32_e32 v97, v97
	v_add_f32_e32 v100, 1.0, v100
	v_add_f32_e32 v108, 1.0, v108
	v_add_f32_e32 v111, 1.0, v111
	v_add_f32_e32 v97, 1.0, v97
	v_rcp_f32_e32 v118, v100
	v_rcp_f32_e32 v119, v108
	v_rcp_f32_e32 v120, v111
	v_rcp_f32_e32 v121, v97
	v_mov_b32_e32 v100, 0
	s_waitcnt vmcnt(16)
	v_mov_b32_e32 v124, v158
	v_mov_b32_e32 v125, v159
	v_and_b32_e32 v139, 0xffff0000, v124
	v_lshlrev_b32_e32 v138, 16, v124
	v_and_b32_e32 v141, 0xffff0000, v125
	v_lshlrev_b32_e32 v140, 16, v125
	s_waitcnt vmcnt(15)
	v_mov_b32_e32 v114, v160
	v_mov_b32_e32 v115, v161
	v_mov_b32_e32 v116, v162
	v_mov_b32_e32 v117, v163
	v_pk_fma_f32 v[114:115], v[118:119], v[138:139], v[114:115]
	v_pk_fma_f32 v[116:117], v[120:121], v[140:141], v[116:117]
	global_store_dwordx4 v[126:127], v[114:117], off
	v_cvt_pk_bf16_f32 v118, v114, v115
	v_cvt_pk_bf16_f32 v119, v116, v117
	v_pk_mul_f32 v[114:115], v[114:115], v[114:115]
	v_pk_mul_f32 v[116:117], v[116:117], v[116:117]
	v_add_f32_e32 v97, v114, v115
	v_add_f32_e32 v97, v116, v97
	v_add_f32_e32 v97, v117, v97
	global_store_dwordx2 v[122:123], v[118:119], off
	s_nop 0
	v_add_f32_dpp v97, v97, v97 quad_perm:[1,0,3,2] row_mask:0xf bank_mask:0xf bound_ctrl:1
	s_nop 1
	v_add_f32_dpp v97, v97, v97 quad_perm:[2,3,0,1] row_mask:0xf bank_mask:0xf bound_ctrl:1
	s_nop 1
	v_add_f32_dpp v97, v97, v97 row_half_mirror row_mask:0xf bank_mask:0xf bound_ctrl:1
	s_nop 1
	v_mov_b32_dpp v100, v97 row_mirror row_mask:0xf bank_mask:0xf
	s_and_saveexec_b64 s[0:1], vcc
	s_cbranch_execz .LBB0_3282
	v_add_f32_e32 v100, v97, v100
	v_ashrrev_i32_e32 v97, 31, v96
	v_lshl_add_u64 v[96:97], v[96:97], 2, s[24:25]
	global_atomic_add_f32 v[96:97], v100, off
.LBB0_3282:
	s_or_b64 exec, exec, s[0:1]
	v_or_b32_e32 v100, 8, v130
	v_add_u32_e32 v96, v100, v129
	v_lshl_add_u32 v114, v96, 10, v128
	v_ashrrev_i32_e32 v115, 31, v114
	v_lshlrev_b64 v[122:123], 1, v[114:115]
	v_lshl_add_u64 v[116:117], s[14:15], 0, v[122:123]
	v_lshl_add_u64 v[126:127], v[114:115], 2, s[8:9]
	v_fmamk_f32 v97, v101, 0x3a800000, v135
	v_mul_f32_e32 v101, 0x4b800000, v97
	v_cmp_gt_f32_e64 s[6:7], s57, v97
	v_add_u32_e32 v108, 0x440, v103
	v_add_u32_e32 v103, v136, v108
	v_cndmask_b32_e64 v97, v97, v101, s[6:7]
	v_rsq_f32_e32 v97, v97
	ds_read_b128 v[118:121], v103
	v_lshl_add_u64 v[122:123], s[10:11], 0, v[122:123]
	v_mul_f32_e32 v101, 0x45800000, v97
	v_cndmask_b32_e64 v97, v97, v101, s[6:7]
	s_waitcnt lgkmcnt(0)
	v_mul_f32_e32 v101, v97, v118
	v_mul_f32_e32 v111, v97, v119
	v_mul_f32_e32 v113, v97, v120
	v_mul_f32_e32 v97, v97, v121
	v_mul_f32_e32 v101, 0xbfb8aa3b, v101
	v_mul_f32_e32 v111, 0xbfb8aa3b, v111
	v_mul_f32_e32 v113, 0xbfb8aa3b, v113
	v_mul_f32_e32 v97, 0xbfb8aa3b, v97
	v_exp_f32_e32 v101, v101
	v_exp_f32_e32 v111, v111
	v_exp_f32_e32 v113, v113
	v_exp_f32_e32 v97, v97
	v_add_f32_e32 v101, 1.0, v101
	v_add_f32_e32 v111, 1.0, v111
	v_add_f32_e32 v113, 1.0, v113
	v_add_f32_e32 v97, 1.0, v97
	v_rcp_f32_e32 v118, v101
	v_rcp_f32_e32 v119, v111
	v_rcp_f32_e32 v120, v113
	v_rcp_f32_e32 v121, v97
	v_mov_b32_e32 v101, 0
	s_waitcnt vmcnt(17)
	v_mov_b32_e32 v124, v164
	v_mov_b32_e32 v125, v165
	v_and_b32_e32 v139, 0xffff0000, v124
	v_lshlrev_b32_e32 v138, 16, v124
	v_and_b32_e32 v141, 0xffff0000, v125
	v_lshlrev_b32_e32 v140, 16, v125
	s_waitcnt vmcnt(16)
	v_mov_b32_e32 v114, v166
	v_mov_b32_e32 v115, v167
	v_mov_b32_e32 v116, v168
	v_mov_b32_e32 v117, v169
	v_pk_fma_f32 v[114:115], v[118:119], v[138:139], v[114:115]
	v_pk_fma_f32 v[116:117], v[120:121], v[140:141], v[116:117]
	global_store_dwordx4 v[126:127], v[114:117], off
	v_cvt_pk_bf16_f32 v118, v114, v115
	v_cvt_pk_bf16_f32 v119, v116, v117
	v_pk_mul_f32 v[114:115], v[114:115], v[114:115]
	v_pk_mul_f32 v[116:117], v[116:117], v[116:117]
	v_add_f32_e32 v97, v114, v115
	v_add_f32_e32 v97, v116, v97
	v_add_f32_e32 v97, v117, v97
	global_store_dwordx2 v[122:123], v[118:119], off
	s_nop 0
	v_add_f32_dpp v97, v97, v97 quad_perm:[1,0,3,2] row_mask:0xf bank_mask:0xf bound_ctrl:1
	s_nop 1
	v_add_f32_dpp v97, v97, v97 quad_perm:[2,3,0,1] row_mask:0xf bank_mask:0xf bound_ctrl:1
	s_nop 1
	v_add_f32_dpp v97, v97, v97 row_half_mirror row_mask:0xf bank_mask:0xf bound_ctrl:1
	s_nop 1
	v_mov_b32_dpp v101, v97 row_mirror row_mask:0xf bank_mask:0xf
	s_and_saveexec_b64 s[0:1], vcc
	s_cbranch_execz .LBB0_3284
	v_add_f32_e32 v101, v97, v101
	v_ashrrev_i32_e32 v97, 31, v96
	v_lshl_add_u64 v[96:97], v[96:97], 2, s[24:25]
	global_atomic_add_f32 v[96:97], v101, off
; __device__ __forceinline__ float bfs2f(short h) { return __uint_as_float(((unsigned)(u16)h) << 16); }
; __device__ __forceinline__ float sigm(float x) { return __builtin_amdgcn_rcpf(1.f + __expf(-x)); }
;   __device__ __forceinline__ void tile(const float* reg, int row0, int col0, int lane) const {
;     ...
;     rows4(reg, lane, [&](int it, int rr, int c4, float4 v) {
;       int row = row0 + rr, idx = row * 1024 + col0 + c4;
;       float rs = rsv[it];
;       float4 xo = *(const float4*)(xold + idx);
;       bf16x4 t = *(const bf16x4*)(tmp + idx);
;       v.x = fmaf(sigm(v.x * rs), bfs2f(t[0]), xo.x); v.y = fmaf(sigm(v.y * rs), bfs2f(t[1]), xo.y);
;       v.z = fmaf(sigm(v.z * rs), bfs2f(t[2]), xo.z); v.w = fmaf(sigm(v.w * rs), bfs2f(t[3]), xo.w);
;       *(float4*)(xnew + idx) = v;
;       *(bf16x4*)(xb + idx) = pack4(v.x, v.y, v.z, v.w);
;       float s = row16_sum(v.x * v.x + v.y * v.y + v.z * v.z + v.w * v.w);
;       if ((lane & 15) == 0) atomicAdd(ssqn + row, s);
;     });
.LBB0_3284:
	s_or_b64 exec, exec, s[0:1]
	v_or_b32_e32 v101, 12, v130
	v_add_u32_e32 v96, v101, v129
	v_lshl_add_u32 v114, v96, 10, v128
	v_ashrrev_i32_e32 v115, 31, v114
	v_lshlrev_b64 v[122:123], 1, v[114:115]
	v_lshl_add_u64 v[116:117], s[14:15], 0, v[122:123]
	v_lshl_add_u64 v[126:127], v[114:115], 2, s[8:9]
	v_add_u32_e32 v97, 0x440, v108
	v_fmamk_f32 v108, v98, 0x3a800000, v135
	v_mul_f32_e32 v111, 0x4b800000, v108
	v_cmp_gt_f32_e64 s[6:7], s57, v108
	v_add_u32_e32 v98, v136, v97
	ds_read_b128 v[118:121], v98
	v_cndmask_b32_e64 v97, v108, v111, s[6:7]
	v_rsq_f32_e32 v97, v97
	v_lshl_add_u64 v[122:123], s[10:11], 0, v[122:123]
	v_mul_f32_e32 v108, 0x45800000, v97
	v_cndmask_b32_e64 v97, v97, v108, s[6:7]
	s_waitcnt lgkmcnt(0)
	v_mul_f32_e32 v108, v97, v118
	v_mul_f32_e32 v111, v97, v119
	v_mul_f32_e32 v113, v97, v120
	v_mul_f32_e32 v97, v97, v121
	v_mul_f32_e32 v108, 0xbfb8aa3b, v108
	v_mul_f32_e32 v111, 0xbfb8aa3b, v111
	v_mul_f32_e32 v113, 0xbfb8aa3b, v113
	v_mul_f32_e32 v97, 0xbfb8aa3b, v97
	v_exp_f32_e32 v108, v108
	v_exp_f32_e32 v111, v111
	v_exp_f32_e32 v113, v113
	v_exp_f32_e32 v97, v97
	v_add_f32_e32 v108, 1.0, v108
	v_add_f32_e32 v111, 1.0, v111
	v_add_f32_e32 v113, 1.0, v113
	v_add_f32_e32 v97, 1.0, v97
	v_rcp_f32_e32 v118, v108
	v_rcp_f32_e32 v119, v111
	v_rcp_f32_e32 v120, v113
	v_rcp_f32_e32 v121, v97
	v_mov_b32_e32 v108, 0
	s_waitcnt vmcnt(18)
	v_mov_b32_e32 v124, v170
	v_mov_b32_e32 v125, v171
	v_and_b32_e32 v139, 0xffff0000, v124
	v_lshlrev_b32_e32 v138, 16, v124
	v_and_b32_e32 v141, 0xffff0000, v125
	v_lshlrev_b32_e32 v140, 16, v125
	s_waitcnt vmcnt(17)
	v_mov_b32_e32 v114, v172
	v_mov_b32_e32 v115, v173
	v_mov_b32_e32 v116, v174
	v_mov_b32_e32 v117, v175
	v_pk_fma_f32 v[114:115], v[118:119], v[138:139], v[114:115]
	v_pk_fma_f32 v[116:117], v[120:121], v[140:141], v[116:117]
	global_store_dwordx4 v[126:127], v[114:117], off
	v_cvt_pk_bf16_f32 v118, v114, v115
	v_cvt_pk_bf16_f32 v119, v116, v117
	v_pk_mul_f32 v[114:115], v[114:115], v[114:115]
	v_pk_mul_f32 v[116:117], v[116:117], v[116:117]
	v_add_f32_e32 v97, v114, v115
	v_add_f32_e32 v97, v116, v97
	v_add_f32_e32 v97, v117, v97
	global_store_dwordx2 v[122:123], v[118:119], off
	s_nop 0
	v_add_f32_dpp v97, v97, v97 quad_perm:[1,0,3,2] row_mask:0xf bank_mask:0xf bound_ctrl:1
	s_nop 1
	v_add_f32_dpp v97, v97, v97 quad_perm:[2,3,0,1] row_mask:0xf bank_mask:0xf bound_ctrl:1
	s_nop 1
	v_add_f32_dpp v97, v97, v97 row_half_mirror row_mask:0xf bank_mask:0xf bound_ctrl:1
	s_nop 1
	v_mov_b32_dpp v108, v97 row_mirror row_mask:0xf bank_mask:0xf
	s_and_saveexec_b64 s[0:1], vcc
	s_cbranch_execz .LBB0_3286
	v_add_f32_e32 v108, v97, v108
	v_ashrrev_i32_e32 v97, 31, v96
	v_lshl_add_u64 v[96:97], v[96:97], 2, s[24:25]
	global_atomic_add_f32 v[96:97], v108, off
.LBB0_3286:
	s_or_b64 exec, exec, s[0:1]
	v_fmamk_f32 v96, v105, 0x3a800000, v135
	v_mul_f32_e32 v97, 0x4b800000, v96
	v_cmp_gt_f32_e64 s[6:7], s57, v96
	v_or_b32_e32 v108, 16, v130
	s_nop 0
	v_cndmask_b32_e64 v96, v96, v97, s[6:7]
	v_rsq_f32_e32 v96, v96
	s_nop 0
	v_mul_f32_e32 v97, 0x45800000, v96
	v_cndmask_b32_e64 v97, v96, v97, s[6:7]
	v_add_u32_e32 v96, v108, v129
	v_lshl_add_u32 v114, v96, 10, v128
	v_ashrrev_i32_e32 v115, 31, v114
	v_lshlrev_b64 v[122:123], 1, v[114:115]
	v_lshl_add_u64 v[116:117], s[14:15], 0, v[122:123]
	v_lshl_add_u64 v[126:127], v[114:115], 2, s[8:9]
	ds_read_b128 v[118:121], v98 offset:1088
	v_lshl_add_u64 v[122:123], s[10:11], 0, v[122:123]
	s_waitcnt lgkmcnt(0)
	v_mul_f32_e32 v105, v97, v118
	v_mul_f32_e32 v111, v97, v119
	v_mul_f32_e32 v113, v97, v120
	v_mul_f32_e32 v97, v97, v121
	v_mul_f32_e32 v105, 0xbfb8aa3b, v105
	v_mul_f32_e32 v111, 0xbfb8aa3b, v111
	v_mul_f32_e32 v113, 0xbfb8aa3b, v113
	v_mul_f32_e32 v97, 0xbfb8aa3b, v97
	v_exp_f32_e32 v105, v105
	v_exp_f32_e32 v111, v111
	v_exp_f32_e32 v113, v113
	v_exp_f32_e32 v97, v97
	v_add_f32_e32 v105, 1.0, v105
	v_add_f32_e32 v111, 1.0, v111
	v_add_f32_e32 v113, 1.0, v113
	v_add_f32_e32 v97, 1.0, v97
	v_rcp_f32_e32 v118, v105
	v_rcp_f32_e32 v119, v111
	v_rcp_f32_e32 v120, v113
	v_rcp_f32_e32 v121, v97
	v_mov_b32_e32 v105, 0
	s_waitcnt vmcnt(19)
	v_mov_b32_e32 v124, v176
	v_mov_b32_e32 v125, v177
	v_and_b32_e32 v139, 0xffff0000, v124
	v_lshlrev_b32_e32 v138, 16, v124
	v_and_b32_e32 v141, 0xffff0000, v125
	v_lshlrev_b32_e32 v140, 16, v125
	s_waitcnt vmcnt(18)
	v_mov_b32_e32 v114, v178
	v_mov_b32_e32 v115, v179
	v_mov_b32_e32 v116, v180
	v_mov_b32_e32 v117, v181
	v_pk_fma_f32 v[114:115], v[118:119], v[138:139], v[114:115]
	v_pk_fma_f32 v[116:117], v[120:121], v[140:141], v[116:117]
	global_store_dwordx4 v[126:127], v[114:117], off
	v_cvt_pk_bf16_f32 v118, v114, v115
	v_cvt_pk_bf16_f32 v119, v116, v117
	v_pk_mul_f32 v[114:115], v[114:115], v[114:115]
	v_pk_mul_f32 v[116:117], v[116:117], v[116:117]
	v_add_f32_e32 v97, v114, v115
	v_add_f32_e32 v97, v116, v97
	v_add_f32_e32 v97, v117, v97
	global_store_dwordx2 v[122:123], v[118:119], off
	s_nop 0
	v_add_f32_dpp v97, v97, v97 quad_perm:[1,0,3,2] row_mask:0xf bank_mask:0xf bound_ctrl:1
	s_nop 1
	v_add_f32_dpp v97, v97, v97 quad_perm:[2,3,0,1] row_mask:0xf bank_mask:0xf bound_ctrl:1
	s_nop 1
	v_add_f32_dpp v97, v97, v97 row_half_mirror row_mask:0xf bank_mask:0xf bound_ctrl:1
	s_nop 1
	v_mov_b32_dpp v105, v97 row_mirror row_mask:0xf bank_mask:0xf
	s_and_saveexec_b64 s[0:1], vcc
	s_cbranch_execz .LBB0_3288
	v_add_f32_e32 v105, v97, v105
	v_ashrrev_i32_e32 v97, 31, v96
	v_lshl_add_u64 v[96:97], v[96:97], 2, s[24:25]
	global_atomic_add_f32 v[96:97], v105, off
; __device__ __forceinline__ float bfs2f(short h) { return __uint_as_float(((unsigned)(u16)h) << 16); }
; __device__ __forceinline__ float sigm(float x) { return __builtin_amdgcn_rcpf(1.f + __expf(-x)); }
;   __device__ __forceinline__ void tile(const float* reg, int row0, int col0, int lane) const {
;     ...
;     rows4(reg, lane, [&](int it, int rr, int c4, float4 v) {
;       int row = row0 + rr, idx = row * 1024 + col0 + c4;
;       float rs = rsv[it];
;       float4 xo = *(const float4*)(xold + idx);
;       bf16x4 t = *(const bf16x4*)(tmp + idx);
;       v.x = fmaf(sigm(v.x * rs), bfs2f(t[0]), xo.x); v.y = fmaf(sigm(v.y * rs), bfs2f(t[1]), xo.y);
;       v.z = fmaf(sigm(v.z * rs), bfs2f(t[2]), xo.z); v.w = fmaf(sigm(v.w * rs), bfs2f(t[3]), xo.w);
;       *(float4*)(xnew + idx) = v;
;       *(bf16x4*)(xb + idx) = pack4(v.x, v.y, v.z, v.w);
;       float s = row16_sum(v.x * v.x + v.y * v.y + v.z * v.z + v.w * v.w);
;       if ((lane & 15) == 0) atomicAdd(ssqn + row, s);
;     });
.LBB0_3288:
	s_or_b64 exec, exec, s[0:1]
	v_or_b32_e32 v105, 20, v130
	v_add_u32_e32 v96, v105, v129
	v_lshl_add_u32 v114, v96, 10, v128
	v_ashrrev_i32_e32 v115, 31, v114
	v_lshlrev_b64 v[122:123], 1, v[114:115]
	v_lshl_add_u64 v[116:117], s[14:15], 0, v[122:123]
	v_lshl_add_u64 v[126:127], v[114:115], 2, s[8:9]
	v_fmamk_f32 v97, v106, 0x3a800000, v135
	v_mul_f32_e32 v106, 0x4b800000, v97
	v_cmp_gt_f32_e64 s[6:7], s57, v97
	ds_read_b128 v[118:121], v98 offset:2176
	v_lshl_add_u64 v[122:123], s[10:11], 0, v[122:123]
	v_cndmask_b32_e64 v97, v97, v106, s[6:7]
	v_rsq_f32_e32 v97, v97
	s_waitcnt vmcnt(20)
	v_mov_b32_e32 v124, v182
	v_mov_b32_e32 v125, v183
	v_and_b32_e32 v139, 0xffff0000, v124
	v_mul_f32_e32 v106, 0x45800000, v97
	v_cndmask_b32_e64 v97, v97, v106, s[6:7]
	s_waitcnt lgkmcnt(0)
	v_mul_f32_e32 v106, v97, v118
	v_mul_f32_e32 v111, v97, v119
	v_mul_f32_e32 v113, v97, v120
	v_mul_f32_e32 v97, v97, v121
	v_mul_f32_e32 v106, 0xbfb8aa3b, v106
	v_mul_f32_e32 v111, 0xbfb8aa3b, v111
	v_mul_f32_e32 v113, 0xbfb8aa3b, v113
	v_mul_f32_e32 v97, 0xbfb8aa3b, v97
	v_exp_f32_e32 v106, v106
	v_exp_f32_e32 v111, v111
	v_exp_f32_e32 v113, v113
	v_exp_f32_e32 v97, v97
	v_add_f32_e32 v106, 1.0, v106
	v_add_f32_e32 v111, 1.0, v111
	v_add_f32_e32 v113, 1.0, v113
	v_add_f32_e32 v97, 1.0, v97
	v_rcp_f32_e32 v118, v106
	v_rcp_f32_e32 v119, v111
	v_rcp_f32_e32 v120, v113
	v_rcp_f32_e32 v121, v97
	v_lshlrev_b32_e32 v138, 16, v124
	v_and_b32_e32 v141, 0xffff0000, v125
	v_lshlrev_b32_e32 v140, 16, v125
	s_waitcnt vmcnt(19)
	v_mov_b32_e32 v114, v184
	v_mov_b32_e32 v115, v185
	v_mov_b32_e32 v116, v186
	v_mov_b32_e32 v117, v187
	v_pk_fma_f32 v[114:115], v[118:119], v[138:139], v[114:115]
	v_pk_fma_f32 v[116:117], v[120:121], v[140:141], v[116:117]
	global_store_dwordx4 v[126:127], v[114:117], off
	v_cvt_pk_bf16_f32 v118, v114, v115
	v_cvt_pk_bf16_f32 v119, v116, v117
	v_pk_mul_f32 v[114:115], v[114:115], v[114:115]
	v_pk_mul_f32 v[116:117], v[116:117], v[116:117]
	v_add_f32_e32 v97, v114, v115
	v_add_f32_e32 v97, v116, v97
	v_add_f32_e32 v97, v117, v97
	v_mov_b32_e32 v106, 0
	global_store_dwordx2 v[122:123], v[118:119], off
	v_add_f32_dpp v97, v97, v97 quad_perm:[1,0,3,2] row_mask:0xf bank_mask:0xf bound_ctrl:1
	s_nop 1
	v_add_f32_dpp v97, v97, v97 quad_perm:[2,3,0,1] row_mask:0xf bank_mask:0xf bound_ctrl:1
	s_nop 1
	v_add_f32_dpp v97, v97, v97 row_half_mirror row_mask:0xf bank_mask:0xf bound_ctrl:1
	s_nop 1
	v_mov_b32_dpp v106, v97 row_mirror row_mask:0xf bank_mask:0xf
	s_and_saveexec_b64 s[0:1], vcc
	s_cbranch_execz .LBB0_3290
	v_add_f32_e32 v106, v97, v106
	v_ashrrev_i32_e32 v97, 31, v96
	v_lshl_add_u64 v[96:97], v[96:97], 2, s[24:25]
	global_atomic_add_f32 v[96:97], v106, off
.LBB0_3290:
	s_or_b64 exec, exec, s[0:1]
	v_or_b32_e32 v106, 24, v130
	v_add_u32_e32 v96, v106, v129
	v_lshl_add_u32 v114, v96, 10, v128
	v_ashrrev_i32_e32 v115, 31, v114
	v_lshlrev_b64 v[122:123], 1, v[114:115]
	v_lshl_add_u64 v[116:117], s[14:15], 0, v[122:123]
	v_lshl_add_u64 v[126:127], v[114:115], 2, s[8:9]
	v_fmamk_f32 v97, v107, 0x3a800000, v135
	v_mul_f32_e32 v107, 0x4b800000, v97
	v_cmp_gt_f32_e64 s[6:7], s57, v97
	ds_read_b128 v[118:121], v98 offset:3264
	v_lshl_add_u64 v[122:123], s[10:11], 0, v[122:123]
	v_cndmask_b32_e64 v97, v97, v107, s[6:7]
	v_rsq_f32_e32 v97, v97
	s_waitcnt vmcnt(21)
	v_mov_b32_e32 v124, v188
	v_mov_b32_e32 v125, v189
	v_and_b32_e32 v139, 0xffff0000, v124
	v_mul_f32_e32 v107, 0x45800000, v97
	v_cndmask_b32_e64 v97, v97, v107, s[6:7]
	s_waitcnt lgkmcnt(0)
	v_mul_f32_e32 v107, v97, v118
	v_mul_f32_e32 v111, v97, v119
	v_mul_f32_e32 v113, v97, v120
	v_mul_f32_e32 v97, v97, v121
	v_mul_f32_e32 v107, 0xbfb8aa3b, v107
	v_mul_f32_e32 v111, 0xbfb8aa3b, v111
	v_mul_f32_e32 v113, 0xbfb8aa3b, v113
	v_mul_f32_e32 v97, 0xbfb8aa3b, v97
	v_exp_f32_e32 v107, v107
	v_exp_f32_e32 v111, v111
	v_exp_f32_e32 v113, v113
	v_exp_f32_e32 v97, v97
	v_add_f32_e32 v107, 1.0, v107
	v_add_f32_e32 v111, 1.0, v111
	v_add_f32_e32 v113, 1.0, v113
	v_add_f32_e32 v97, 1.0, v97
	v_rcp_f32_e32 v118, v107
	v_rcp_f32_e32 v119, v111
	v_rcp_f32_e32 v120, v113
	v_rcp_f32_e32 v121, v97
	v_lshlrev_b32_e32 v138, 16, v124
	v_and_b32_e32 v141, 0xffff0000, v125
	v_lshlrev_b32_e32 v140, 16, v125
	s_waitcnt vmcnt(20)
	v_mov_b32_e32 v114, v190
	v_mov_b32_e32 v115, v191
	v_mov_b32_e32 v116, v192
	v_mov_b32_e32 v117, v193
	v_pk_fma_f32 v[114:115], v[118:119], v[138:139], v[114:115]
	v_pk_fma_f32 v[116:117], v[120:121], v[140:141], v[116:117]
	global_store_dwordx4 v[126:127], v[114:117], off
	v_cvt_pk_bf16_f32 v118, v114, v115
	v_cvt_pk_bf16_f32 v119, v116, v117
	v_pk_mul_f32 v[114:115], v[114:115], v[114:115]
	v_pk_mul_f32 v[116:117], v[116:117], v[116:117]
	v_add_f32_e32 v97, v114, v115
	v_add_f32_e32 v97, v116, v97
	v_add_f32_e32 v97, v117, v97
	v_mov_b32_e32 v107, 0
	global_store_dwordx2 v[122:123], v[118:119], off
	v_add_f32_dpp v97, v97, v97 quad_perm:[1,0,3,2] row_mask:0xf bank_mask:0xf bound_ctrl:1
	s_nop 1
	v_add_f32_dpp v97, v97, v97 quad_perm:[2,3,0,1] row_mask:0xf bank_mask:0xf bound_ctrl:1
	s_nop 1
	v_add_f32_dpp v97, v97, v97 row_half_mirror row_mask:0xf bank_mask:0xf bound_ctrl:1
	s_nop 1
	v_mov_b32_dpp v107, v97 row_mirror row_mask:0xf bank_mask:0xf
	s_and_saveexec_b64 s[0:1], vcc
	s_cbranch_execz .LBB0_3292
	v_add_f32_e32 v107, v97, v107
	v_ashrrev_i32_e32 v97, 31, v96
	v_lshl_add_u64 v[96:97], v[96:97], 2, s[24:25]
	global_atomic_add_f32 v[96:97], v107, off
; __device__ __forceinline__ float bfs2f(short h) { return __uint_as_float(((unsigned)(u16)h) << 16); }
; __device__ __forceinline__ float sigm(float x) { return __builtin_amdgcn_rcpf(1.f + __expf(-x)); }
;   __device__ __forceinline__ void tile(const float* reg, int row0, int col0, int lane) const {
;     ...
;     rows4(reg, lane, [&](int it, int rr, int c4, float4 v) {
;       int row = row0 + rr, idx = row * 1024 + col0 + c4;
;       float rs = rsv[it];
;       float4 xo = *(const float4*)(xold + idx);
;       bf16x4 t = *(const bf16x4*)(tmp + idx);
;       v.x = fmaf(sigm(v.x * rs), bfs2f(t[0]), xo.x); v.y = fmaf(sigm(v.y * rs), bfs2f(t[1]), xo.y);
;       v.z = fmaf(sigm(v.z * rs), bfs2f(t[2]), xo.z); v.w = fmaf(sigm(v.w * rs), bfs2f(t[3]), xo.w);
;       *(float4*)(xnew + idx) = v;
;       *(bf16x4*)(xb + idx) = pack4(v.x, v.y, v.z, v.w);
;       float s = row16_sum(v.x * v.x + v.y * v.y + v.z * v.z + v.w * v.w);
;       if ((lane & 15) == 0) atomicAdd(ssqn + row, s);
;     });
; template <int MF, class Epi>
; __device__ __forceinline__ void staged_epilogue(f32x4 (&acc)[MF][4], int row0, int col0, const Epi& epi) {
;     ...
; #pragma unroll
;   for (int mp = 0; mp < MF / 2; ++mp) {
;     __builtin_amdgcn_sched_barrier(0);
; #pragma unroll
;     for (int mm = 0; mm < 2; ++mm)
; #pragma unroll
;       for (int n = 0; n < 4; ++n)
; #pragma unroll
;         for (int j = 0; j < 4; ++j) reg[(mm * 16 + fq * 4 + j) * 68 + n * 16 + fr] = acc[mp * 2 + mm][n][j];
;     __builtin_amdgcn_fence(__ATOMIC_ACQ_REL, "wavefront");
;     epi.tile(reg, row0 + mp * 32, col0, lane);
;     __builtin_amdgcn_fence(__ATOMIC_ACQ_REL, "wavefront");
.LBB0_3292:
	s_or_b64 exec, exec, s[0:1]
	v_or_b32_e32 v107, 28, v130
	v_add_u32_e32 v96, v107, v129
	v_lshl_add_u32 v114, v96, 10, v128
	v_ashrrev_i32_e32 v115, 31, v114
	v_lshlrev_b64 v[122:123], 1, v[114:115]
	v_lshl_add_u64 v[116:117], s[14:15], 0, v[122:123]
	v_lshl_add_u64 v[126:127], v[114:115], 2, s[8:9]
	v_fmamk_f32 v97, v110, 0x3a800000, v135
	v_mul_f32_e32 v110, 0x4b800000, v97
	v_cmp_gt_f32_e64 s[6:7], s57, v97
	ds_read_b128 v[118:121], v98 offset:4352
	s_waitcnt vmcnt(22)
	v_mov_b32_e32 v124, v194
	v_mov_b32_e32 v125, v195
	v_and_b32_e32 v139, 0xffff0000, v125
	v_cndmask_b32_e64 v97, v97, v110, s[6:7]
	v_rsq_f32_e32 v97, v97
	v_lshl_add_u64 v[110:111], s[10:11], 0, v[122:123]
	v_and_b32_e32 v123, 0xffff0000, v124
	v_lshlrev_b32_e32 v122, 16, v124
	v_mul_f32_e32 v113, 0x45800000, v97
	v_cndmask_b32_e64 v97, v97, v113, s[6:7]
	s_waitcnt lgkmcnt(0)
	v_mul_f32_e32 v113, v97, v118
	v_mul_f32_e32 v118, v97, v119
	v_mul_f32_e32 v119, v97, v120
	v_mul_f32_e32 v97, v97, v121
	v_mul_f32_e32 v113, 0xbfb8aa3b, v113
	v_mul_f32_e32 v118, 0xbfb8aa3b, v118
	v_mul_f32_e32 v119, 0xbfb8aa3b, v119
	v_mul_f32_e32 v97, 0xbfb8aa3b, v97
	v_exp_f32_e32 v113, v113
	v_exp_f32_e32 v118, v118
	v_exp_f32_e32 v119, v119
	v_exp_f32_e32 v97, v97
	v_add_f32_e32 v113, 1.0, v113
	v_add_f32_e32 v120, 1.0, v118
	v_add_f32_e32 v121, 1.0, v119
	v_add_f32_e32 v97, 1.0, v97
	v_rcp_f32_e32 v118, v113
	v_rcp_f32_e32 v119, v120
	v_rcp_f32_e32 v120, v121
	v_rcp_f32_e32 v121, v97
	v_lshlrev_b32_e32 v138, 16, v125
	s_waitcnt vmcnt(21)
	v_mov_b32_e32 v114, v196
	v_mov_b32_e32 v115, v197
	v_mov_b32_e32 v116, v198
	v_mov_b32_e32 v117, v199
	v_pk_fma_f32 v[114:115], v[118:119], v[122:123], v[114:115]
	v_pk_fma_f32 v[116:117], v[120:121], v[138:139], v[116:117]
	global_store_dwordx4 v[126:127], v[114:117], off
	v_cvt_pk_bf16_f32 v118, v114, v115
	v_cvt_pk_bf16_f32 v119, v116, v117
	v_pk_mul_f32 v[114:115], v[114:115], v[114:115]
	v_pk_mul_f32 v[116:117], v[116:117], v[116:117]
	v_add_f32_e32 v97, v114, v115
	v_add_f32_e32 v97, v116, v97
	v_add_f32_e32 v97, v117, v97
	global_store_dwordx2 v[110:111], v[118:119], off
	v_mov_b32_e32 v110, 0
	v_add_f32_dpp v97, v97, v97 quad_perm:[1,0,3,2] row_mask:0xf bank_mask:0xf bound_ctrl:1
	s_nop 1
	v_add_f32_dpp v97, v97, v97 quad_perm:[2,3,0,1] row_mask:0xf bank_mask:0xf bound_ctrl:1
	s_nop 1
	v_add_f32_dpp v97, v97, v97 row_half_mirror row_mask:0xf bank_mask:0xf bound_ctrl:1
	s_nop 1
	v_mov_b32_dpp v110, v97 row_mirror row_mask:0xf bank_mask:0xf
	s_and_saveexec_b64 s[0:1], vcc
	s_cbranch_execz .LBB0_3294
	v_add_f32_e32 v110, v97, v110
	v_ashrrev_i32_e32 v97, 31, v96
	v_lshl_add_u64 v[96:97], v[96:97], 2, s[24:25]
	global_atomic_add_f32 v[96:97], v110, off
.LBB0_3294:
	s_or_b64 exec, exec, s[0:1]
	ds_write2_b32 v131, v88, v92 offset1:16
	ds_write2_b32 v131, v89, v93 offset0:68 offset1:84
	ds_write2_b32 v131, v90, v94 offset0:136 offset1:152
	ds_write2_b32 v131, v91, v95 offset0:204 offset1:220
	ds_write2_b32 v131, v80, v84 offset0:32 offset1:48
	ds_write2_b32 v131, v81, v85 offset0:100 offset1:116
	ds_write2_b32 v131, v82, v86 offset0:168 offset1:184
	ds_write2_b32 v131, v83, v87 offset0:236 offset1:252
	ds_write2_b32 v112, v72, v76 offset0:64 offset1:80
	ds_write2_b32 v112, v73, v77 offset0:132 offset1:148
	ds_write2_b32 v112, v74, v78 offset0:200 offset1:216
	ds_write2_b32 v104, v75, v79 offset0:12 offset1:28
	ds_write2_b32 v112, v64, v68 offset0:96 offset1:112
	ds_write2_b32 v112, v65, v69 offset0:164 offset1:180
	ds_write2_b32 v112, v66, v70 offset0:232 offset1:248
	ds_write2_b32 v104, v67, v71 offset0:44 offset1:60
	v_add_u32_e32 v210, 32, v129
	v_add_u32_e32 v200, v130, v210
	v_ashrrev_i32_e32 v201, 31, v200
	v_lshl_add_u64 v[202:203], v[200:201], 2, s[22:23]
	global_load_dword v144, v[202:203], off
	v_add_u32_e32 v211, 32, v129
	v_add_u32_e32 v210, v130, v211
	v_add_u32_e32 v200, 4, v210
	v_ashrrev_i32_e32 v201, 31, v200
	v_lshl_add_u64 v[200:201], v[200:201], 2, s[22:23]
	global_load_dword v145, v[200:201], off
	v_add_u32_e32 v211, 32, v129
	v_add_u32_e32 v210, v130, v211
	v_add_u32_e32 v200, 8, v210
	v_ashrrev_i32_e32 v201, 31, v200
	v_lshl_add_u64 v[200:201], v[200:201], 2, s[22:23]
	global_load_dword v146, v[200:201], off
	v_add_u32_e32 v211, 32, v129
	v_add_u32_e32 v210, v130, v211
	v_add_u32_e32 v200, 12, v210
	v_ashrrev_i32_e32 v201, 31, v200
	v_lshl_add_u64 v[202:203], v[200:201], 2, s[22:23]
	global_load_dword v147, v[202:203], off
	v_add_u32_e32 v211, 32, v129
	v_add_u32_e32 v210, v130, v211
	v_add_u32_e32 v200, 16, v210
	v_ashrrev_i32_e32 v201, 31, v200
	v_lshl_add_u64 v[202:203], v[200:201], 2, s[22:23]
	global_load_dword v148, v[202:203], off
	v_add_u32_e32 v211, 32, v129
	v_add_u32_e32 v210, v130, v211
	v_add_u32_e32 v200, 20, v210
	v_ashrrev_i32_e32 v201, 31, v200
	v_lshl_add_u64 v[202:203], v[200:201], 2, s[22:23]
	global_load_dword v149, v[202:203], off
	v_add_u32_e32 v211, 32, v129
	v_add_u32_e32 v210, v130, v211
	v_add_u32_e32 v200, 24, v210
	v_ashrrev_i32_e32 v201, 31, v200
	v_lshl_add_u64 v[202:203], v[200:201], 2, s[22:23]
	global_load_dword v150, v[202:203], off
	v_add_u32_e32 v211, 32, v129
	v_add_u32_e32 v210, v130, v211
	v_add_u32_e32 v200, 28, v210
	v_ashrrev_i32_e32 v201, 31, v200
	v_lshl_add_u64 v[202:203], v[200:201], 2, s[22:23]
	global_load_dword v151, v[202:203], off
	v_add_u32_e32 v211, 32, v129
	v_add_u32_e32 v210, v130, v211
	v_lshl_add_u32 v200, v210, 10, v128
	v_ashrrev_i32_e32 v201, 31, v200
	v_lshlrev_b64 v[206:207], 1, v[200:201]
	v_lshl_add_u64 v[202:203], s[14:15], 0, v[206:207]
	global_load_dwordx2 v[152:153], v[202:203], off
	v_add_u32_e32 v211, 32, v129
	v_add_u32_e32 v210, v130, v211
; __device__ __forceinline__ float bfs2f(short h) { return __uint_as_float(((unsigned)(u16)h) << 16); }
; __device__ __forceinline__ float sigm(float x) { return __builtin_amdgcn_rcpf(1.f + __expf(-x)); }
; __device__ __forceinline__ float rs_of(float ss) { return rsqrtf(ss * (1.f / 1024) + EPS); }
;   __device__ __forceinline__ void tile(const float* reg, int row0, int col0, int lane) const {
;     float rsv[8];
; #pragma unroll
;     for (int i = 0; i < 8; ++i) rsv[i] = rs_of(ssq[row0 + i * 4 + (lane >> 4)]);
;     rows4(reg, lane, [&](int it, int rr, int c4, float4 v) {
;       int row = row0 + rr, idx = row * 1024 + col0 + c4;
;       float rs = rsv[it];
;       float4 xo = *(const float4*)(xold + idx);
;       bf16x4 t = *(const bf16x4*)(tmp + idx);
;       v.x = fmaf(sigm(v.x * rs), bfs2f(t[0]), xo.x); v.y = fmaf(sigm(v.y * rs), bfs2f(t[1]), xo.y);
;       v.z = fmaf(sigm(v.z * rs), bfs2f(t[2]), xo.z); v.w = fmaf(sigm(v.w * rs), bfs2f(t[3]), xo.w);
;       *(float4*)(xnew + idx) = v;
;       *(bf16x4*)(xb + idx) = pack4(v.x, v.y, v.z, v.w);
;       float s = row16_sum(v.x * v.x + v.y * v.y + v.z * v.z + v.w * v.w);
;       if ((lane & 15) == 0) atomicAdd(ssqn + row, s);
;     });
	v_lshl_add_u32 v200, v210, 10, v128
	v_ashrrev_i32_e32 v201, 31, v200
	v_lshl_add_u64 v[202:203], v[200:201], 2, s[8:9]
	global_load_dwordx4 v[154:157], v[202:203], off
	v_add_u32_e32 v211, 32, v129
	v_add_u32_e32 v210, v99, v211
	v_lshl_add_u32 v200, v210, 10, v128
	v_ashrrev_i32_e32 v201, 31, v200
	v_lshlrev_b64 v[206:207], 1, v[200:201]
	v_lshl_add_u64 v[202:203], s[14:15], 0, v[206:207]
	global_load_dwordx2 v[158:159], v[202:203], off
	v_add_u32_e32 v211, 32, v129
	v_add_u32_e32 v210, v99, v211
	v_lshl_add_u32 v200, v210, 10, v128
	v_ashrrev_i32_e32 v201, 31, v200
	v_lshl_add_u64 v[202:203], v[200:201], 2, s[8:9]
	global_load_dwordx4 v[160:163], v[202:203], off
	v_add_u32_e32 v211, 32, v129
	v_add_u32_e32 v210, v100, v211
	v_lshl_add_u32 v200, v210, 10, v128
	v_ashrrev_i32_e32 v201, 31, v200
	v_lshlrev_b64 v[206:207], 1, v[200:201]
	v_lshl_add_u64 v[202:203], s[14:15], 0, v[206:207]
	global_load_dwordx2 v[164:165], v[202:203], off
	v_add_u32_e32 v211, 32, v129
	v_add_u32_e32 v210, v100, v211
	v_lshl_add_u32 v200, v210, 10, v128
	v_ashrrev_i32_e32 v201, 31, v200
	v_lshl_add_u64 v[202:203], v[200:201], 2, s[8:9]
	global_load_dwordx4 v[166:169], v[202:203], off
	v_add_u32_e32 v211, 32, v129
	v_add_u32_e32 v210, v101, v211
	v_lshl_add_u32 v200, v210, 10, v128
	v_ashrrev_i32_e32 v201, 31, v200
	v_lshlrev_b64 v[206:207], 1, v[200:201]
	v_lshl_add_u64 v[202:203], s[14:15], 0, v[206:207]
	global_load_dwordx2 v[170:171], v[202:203], off
	v_add_u32_e32 v211, 32, v129
	v_add_u32_e32 v210, v101, v211
	v_lshl_add_u32 v200, v210, 10, v128
	v_ashrrev_i32_e32 v201, 31, v200
	v_lshl_add_u64 v[202:203], v[200:201], 2, s[8:9]
	global_load_dwordx4 v[172:175], v[202:203], off
	v_add_u32_e32 v211, 32, v129
	v_add_u32_e32 v210, v108, v211
	v_lshl_add_u32 v200, v210, 10, v128
	v_ashrrev_i32_e32 v201, 31, v200
	v_lshlrev_b64 v[206:207], 1, v[200:201]
	v_lshl_add_u64 v[202:203], s[14:15], 0, v[206:207]
	global_load_dwordx2 v[176:177], v[202:203], off
	v_add_u32_e32 v211, 32, v129
	v_add_u32_e32 v210, v108, v211
	v_lshl_add_u32 v200, v210, 10, v128
	v_ashrrev_i32_e32 v201, 31, v200
	v_lshl_add_u64 v[202:203], v[200:201], 2, s[8:9]
	global_load_dwordx4 v[178:181], v[202:203], off
	v_add_u32_e32 v211, 32, v129
	v_add_u32_e32 v210, v105, v211
	v_lshl_add_u32 v200, v210, 10, v128
	v_ashrrev_i32_e32 v201, 31, v200
	v_lshlrev_b64 v[206:207], 1, v[200:201]
	v_lshl_add_u64 v[202:203], s[14:15], 0, v[206:207]
	global_load_dwordx2 v[182:183], v[202:203], off
	v_add_u32_e32 v211, 32, v129
	v_add_u32_e32 v210, v105, v211
	v_lshl_add_u32 v200, v210, 10, v128
	v_ashrrev_i32_e32 v201, 31, v200
	v_lshl_add_u64 v[202:203], v[200:201], 2, s[8:9]
	global_load_dwordx4 v[184:187], v[202:203], off
	v_add_u32_e32 v211, 32, v129
	v_add_u32_e32 v210, v106, v211
	v_lshl_add_u32 v200, v210, 10, v128
	v_ashrrev_i32_e32 v201, 31, v200
	v_lshlrev_b64 v[206:207], 1, v[200:201]
	v_lshl_add_u64 v[202:203], s[14:15], 0, v[206:207]
	global_load_dwordx2 v[188:189], v[202:203], off
	v_add_u32_e32 v211, 32, v129
	v_add_u32_e32 v210, v106, v211
	v_lshl_add_u32 v200, v210, 10, v128
	v_ashrrev_i32_e32 v201, 31, v200
	v_lshl_add_u64 v[202:203], v[200:201], 2, s[8:9]
	global_load_dwordx4 v[190:193], v[202:203], off
	v_add_u32_e32 v211, 32, v129
	v_add_u32_e32 v210, v107, v211
	v_lshl_add_u32 v200, v210, 10, v128
	v_ashrrev_i32_e32 v201, 31, v200
	v_lshlrev_b64 v[206:207], 1, v[200:201]
	v_lshl_add_u64 v[202:203], s[14:15], 0, v[206:207]
	global_load_dwordx2 v[194:195], v[202:203], off
	v_add_u32_e32 v211, 32, v129
	v_add_u32_e32 v210, v107, v211
	v_lshl_add_u32 v200, v210, 10, v128
	v_ashrrev_i32_e32 v201, 31, v200
	v_lshl_add_u64 v[202:203], v[200:201], 2, s[8:9]
	global_load_dwordx4 v[196:199], v[202:203], off
	v_add_u32_e32 v67, 32, v129
	v_add_u32_e32 v64, v130, v67
	v_add_u32_e32 v72, 12, v64
	v_ashrrev_i32_e32 v73, 31, v72
	v_lshl_add_u64 v[76:77], v[72:73], 2, s[22:23]
	v_add_u32_e32 v72, 16, v64
	v_ashrrev_i32_e32 v73, 31, v72
	v_ashrrev_i32_e32 v65, 31, v64
	v_lshl_add_u64 v[78:79], v[72:73], 2, s[22:23]
	v_add_u32_e32 v72, 20, v64
	v_lshl_add_u64 v[68:69], v[64:65], 2, s[22:23]
	v_ashrrev_i32_e32 v73, 31, v72
	v_lshl_add_u64 v[80:81], v[72:73], 2, s[22:23]
	v_add_u32_e32 v72, 24, v64
	v_add_u32_e32 v68, 4, v64
	v_add_u32_e32 v70, 8, v64
	v_ashrrev_i32_e32 v73, 31, v72
	v_ashrrev_i32_e32 v69, 31, v68
	v_ashrrev_i32_e32 v71, 31, v70
	v_lshl_add_u64 v[82:83], v[72:73], 2, s[22:23]
	v_add_u32_e32 v72, 28, v64
	v_lshl_add_u64 v[68:69], v[68:69], 2, s[22:23]
	v_lshl_add_u64 v[70:71], v[70:71], 2, s[22:23]
	v_ashrrev_i32_e32 v73, 31, v72
	v_lshl_add_u64 v[84:85], v[72:73], 2, s[22:23]
	s_nop 0
	s_waitcnt vmcnt(23)
	v_mov_b32_e32 v66, v144
	v_fmamk_f32 v66, v66, 0x3a800000, v135
	v_mul_f32_e32 v75, 0x4b800000, v66
	v_cmp_gt_f32_e64 s[6:7], s57, v66
	s_nop 1
	v_cndmask_b32_e64 v66, v66, v75, s[6:7]
	v_rsq_f32_e32 v66, v66
	s_nop 0
	v_mul_f32_e32 v75, 0x45800000, v66
	v_cndmask_b32_e64 v75, v66, v75, s[6:7]
	v_lshl_add_u32 v76, v64, 10, v128
	v_ashrrev_i32_e32 v77, 31, v76
	v_lshlrev_b64 v[84:85], 1, v[76:77]
	v_lshl_add_u64 v[78:79], s[14:15], 0, v[84:85]
	v_lshl_add_u64 v[88:89], v[76:77], 2, s[8:9]
	v_add_u32_e32 v66, v136, v109
	ds_read_b128 v[80:83], v66
	v_lshl_add_u64 v[84:85], s[10:11], 0, v[84:85]
	s_waitcnt lgkmcnt(0)
	v_mul_f32_e32 v80, v75, v80
	v_mul_f32_e32 v81, v75, v81
	v_mul_f32_e32 v82, v75, v82
	v_mul_f32_e32 v75, v75, v83
	v_mul_f32_e32 v80, 0xbfb8aa3b, v80
	v_mul_f32_e32 v81, 0xbfb8aa3b, v81
	v_mul_f32_e32 v82, 0xbfb8aa3b, v82
	v_mul_f32_e32 v75, 0xbfb8aa3b, v75
	v_exp_f32_e32 v80, v80
	v_exp_f32_e32 v81, v81
	v_exp_f32_e32 v82, v82
	v_exp_f32_e32 v75, v75
	v_add_f32_e32 v80, 1.0, v80
	v_add_f32_e32 v81, 1.0, v81
	v_add_f32_e32 v82, 1.0, v82
	v_add_f32_e32 v75, 1.0, v75
	v_rcp_f32_e32 v80, v80
	v_rcp_f32_e32 v81, v81
	v_rcp_f32_e32 v82, v82
	v_rcp_f32_e32 v83, v75
	s_waitcnt vmcnt(15)
; __device__ __forceinline__ float bfs2f(short h) { return __uint_as_float(((unsigned)(u16)h) << 16); }
; __device__ __forceinline__ float sigm(float x) { return __builtin_amdgcn_rcpf(1.f + __expf(-x)); }
;   __device__ __forceinline__ void tile(const float* reg, int row0, int col0, int lane) const {
;     ...
;     rows4(reg, lane, [&](int it, int rr, int c4, float4 v) {
;       int row = row0 + rr, idx = row * 1024 + col0 + c4;
;       float rs = rsv[it];
;       float4 xo = *(const float4*)(xold + idx);
;       bf16x4 t = *(const bf16x4*)(tmp + idx);
;       v.x = fmaf(sigm(v.x * rs), bfs2f(t[0]), xo.x); v.y = fmaf(sigm(v.y * rs), bfs2f(t[1]), xo.y);
;       v.z = fmaf(sigm(v.z * rs), bfs2f(t[2]), xo.z); v.w = fmaf(sigm(v.w * rs), bfs2f(t[3]), xo.w);
;       *(float4*)(xnew + idx) = v;
;       *(bf16x4*)(xb + idx) = pack4(v.x, v.y, v.z, v.w);
;       float s = row16_sum(v.x * v.x + v.y * v.y + v.z * v.z + v.w * v.w);
;       if ((lane & 15) == 0) atomicAdd(ssqn + row, s);
;     });
	v_mov_b32_e32 v74, v145
	v_mov_b32_e32 v73, v146
	v_mov_b32_e32 v72, v147
	v_mov_b32_e32 v71, v148
	v_mov_b32_e32 v70, v149
	v_mov_b32_e32 v69, v150
	v_mov_b32_e32 v68, v151
	v_mov_b32_e32 v86, v152
	v_mov_b32_e32 v87, v153
	v_and_b32_e32 v91, 0xffff0000, v86
	v_lshlrev_b32_e32 v90, 16, v86
	v_and_b32_e32 v93, 0xffff0000, v87
	v_lshlrev_b32_e32 v92, 16, v87
	s_waitcnt vmcnt(14)
	v_mov_b32_e32 v76, v154
	v_mov_b32_e32 v77, v155
	v_mov_b32_e32 v78, v156
	v_mov_b32_e32 v79, v157
	v_pk_fma_f32 v[76:77], v[80:81], v[90:91], v[76:77]
	v_pk_fma_f32 v[78:79], v[82:83], v[92:93], v[78:79]
	global_store_dwordx4 v[88:89], v[76:79], off
	v_cvt_pk_bf16_f32 v80, v76, v77
	v_cvt_pk_bf16_f32 v81, v78, v79
	v_pk_mul_f32 v[76:77], v[76:77], v[76:77]
	v_pk_mul_f32 v[78:79], v[78:79], v[78:79]
	v_add_f32_e32 v75, v76, v77
	v_add_f32_e32 v75, v78, v75
	v_add_f32_e32 v75, v79, v75
	v_mov_b32_e32 v76, 0
	global_store_dwordx2 v[84:85], v[80:81], off
	v_add_f32_dpp v75, v75, v75 quad_perm:[1,0,3,2] row_mask:0xf bank_mask:0xf bound_ctrl:1
	s_nop 1
	v_add_f32_dpp v75, v75, v75 quad_perm:[2,3,0,1] row_mask:0xf bank_mask:0xf bound_ctrl:1
	s_nop 1
	v_add_f32_dpp v75, v75, v75 row_half_mirror row_mask:0xf bank_mask:0xf bound_ctrl:1
	s_nop 1
	v_mov_b32_dpp v76, v75 row_mirror row_mask:0xf bank_mask:0xf
	s_and_saveexec_b64 s[0:1], vcc
	s_cbranch_execz .LBB0_3296
	v_add_f32_e32 v75, v75, v76
	v_lshl_add_u64 v[64:65], v[64:65], 2, s[24:25]
	global_atomic_add_f32 v[64:65], v75, off
.LBB0_3296:
	s_or_b64 exec, exec, s[0:1]
	v_add_u32_e32 v64, v99, v67
	v_lshl_add_u32 v76, v64, 10, v128
	v_ashrrev_i32_e32 v77, 31, v76
	v_lshlrev_b64 v[84:85], 1, v[76:77]
	v_lshl_add_u64 v[78:79], s[14:15], 0, v[84:85]
	v_lshl_add_u64 v[88:89], v[76:77], 2, s[8:9]
	v_fmamk_f32 v65, v74, 0x3a800000, v135
	v_mul_f32_e32 v74, 0x4b800000, v65
	v_cmp_gt_f32_e64 s[6:7], s57, v65
	ds_read_b128 v[80:83], v102
	v_lshl_add_u64 v[84:85], s[10:11], 0, v[84:85]
	v_cndmask_b32_e64 v65, v65, v74, s[6:7]
	v_rsq_f32_e32 v65, v65
	s_waitcnt vmcnt(16)
	v_mov_b32_e32 v86, v158
	v_mov_b32_e32 v87, v159
	v_and_b32_e32 v91, 0xffff0000, v87
	v_mul_f32_e32 v74, 0x45800000, v65
	v_cndmask_b32_e64 v65, v65, v74, s[6:7]
	s_waitcnt lgkmcnt(0)
	v_mul_f32_e32 v74, v65, v80
	v_mul_f32_e32 v75, v65, v81
	v_mul_f32_e32 v80, v65, v82
	v_mul_f32_e32 v65, v65, v83
	v_mul_f32_e32 v74, 0xbfb8aa3b, v74
	v_mul_f32_e32 v75, 0xbfb8aa3b, v75
	v_mul_f32_e32 v80, 0xbfb8aa3b, v80
	v_mul_f32_e32 v65, 0xbfb8aa3b, v65
	v_exp_f32_e32 v74, v74
	v_exp_f32_e32 v75, v75
	v_exp_f32_e32 v80, v80
	v_exp_f32_e32 v65, v65
	v_add_f32_e32 v74, 1.0, v74
	v_add_f32_e32 v75, 1.0, v75
	v_add_f32_e32 v80, 1.0, v80
	v_add_f32_e32 v65, 1.0, v65
	v_rcp_f32_e32 v74, v74
	v_rcp_f32_e32 v75, v75
	v_rcp_f32_e32 v80, v80
	v_rcp_f32_e32 v81, v65
	v_and_b32_e32 v83, 0xffff0000, v86
	v_lshlrev_b32_e32 v82, 16, v86
	v_lshlrev_b32_e32 v90, 16, v87
	s_waitcnt vmcnt(15)
	v_mov_b32_e32 v76, v160
	v_mov_b32_e32 v77, v161
	v_mov_b32_e32 v78, v162
	v_mov_b32_e32 v79, v163
	v_pk_fma_f32 v[74:75], v[74:75], v[82:83], v[76:77]
	v_pk_fma_f32 v[76:77], v[80:81], v[90:91], v[78:79]
	global_store_dwordx4 v[88:89], v[74:77], off
	v_cvt_pk_bf16_f32 v78, v74, v75
	v_cvt_pk_bf16_f32 v79, v76, v77
	v_pk_mul_f32 v[74:75], v[74:75], v[74:75]
	v_pk_mul_f32 v[76:77], v[76:77], v[76:77]
	v_add_f32_e32 v65, v74, v75
	v_add_f32_e32 v65, v76, v65
	v_add_f32_e32 v65, v77, v65
	v_mov_b32_e32 v74, 0
	global_store_dwordx2 v[84:85], v[78:79], off
	v_add_f32_dpp v65, v65, v65 quad_perm:[1,0,3,2] row_mask:0xf bank_mask:0xf bound_ctrl:1
	s_nop 1
	v_add_f32_dpp v65, v65, v65 quad_perm:[2,3,0,1] row_mask:0xf bank_mask:0xf bound_ctrl:1
	s_nop 1
	v_add_f32_dpp v65, v65, v65 row_half_mirror row_mask:0xf bank_mask:0xf bound_ctrl:1
	s_nop 1
	v_mov_b32_dpp v74, v65 row_mirror row_mask:0xf bank_mask:0xf
	s_and_saveexec_b64 s[0:1], vcc
	s_cbranch_execz .LBB0_3298
	v_add_f32_e32 v74, v65, v74
	v_ashrrev_i32_e32 v65, 31, v64
	v_lshl_add_u64 v[64:65], v[64:65], 2, s[24:25]
	global_atomic_add_f32 v[64:65], v74, off
.LBB0_3298:
	s_or_b64 exec, exec, s[0:1]
	v_add_u32_e32 v64, v100, v67
	v_lshl_add_u32 v74, v64, 10, v128
	v_ashrrev_i32_e32 v75, 31, v74
	v_lshlrev_b64 v[82:83], 1, v[74:75]
	v_lshl_add_u64 v[76:77], s[14:15], 0, v[82:83]
	v_lshl_add_u64 v[86:87], v[74:75], 2, s[8:9]
	v_fmamk_f32 v65, v73, 0x3a800000, v135
	v_mul_f32_e32 v73, 0x4b800000, v65
	v_cmp_gt_f32_e64 s[6:7], s57, v65
	ds_read_b128 v[78:81], v103
	v_lshl_add_u64 v[82:83], s[10:11], 0, v[82:83]
	v_cndmask_b32_e64 v65, v65, v73, s[6:7]
	v_rsq_f32_e32 v65, v65
	s_waitcnt vmcnt(17)
	v_mov_b32_e32 v84, v164
	v_mov_b32_e32 v85, v165
	v_and_b32_e32 v89, 0xffff0000, v84
	v_mul_f32_e32 v73, 0x45800000, v65
	v_cndmask_b32_e64 v65, v65, v73, s[6:7]
	s_waitcnt lgkmcnt(0)
	v_mul_f32_e32 v73, v65, v78
	v_mul_f32_e32 v78, v65, v79
	v_mul_f32_e32 v79, v65, v80
	v_mul_f32_e32 v65, v65, v81
	v_mul_f32_e32 v73, 0xbfb8aa3b, v73
	v_mul_f32_e32 v78, 0xbfb8aa3b, v78
	v_mul_f32_e32 v79, 0xbfb8aa3b, v79
	v_mul_f32_e32 v65, 0xbfb8aa3b, v65
	v_exp_f32_e32 v73, v73
	v_exp_f32_e32 v78, v78
	v_exp_f32_e32 v79, v79
	v_exp_f32_e32 v65, v65
	v_add_f32_e32 v73, 1.0, v73
	v_add_f32_e32 v80, 1.0, v78
	v_add_f32_e32 v81, 1.0, v79
	v_add_f32_e32 v65, 1.0, v65
	v_rcp_f32_e32 v78, v73
	v_rcp_f32_e32 v79, v80
	v_rcp_f32_e32 v80, v81
	v_rcp_f32_e32 v81, v65
	v_lshlrev_b32_e32 v88, 16, v84
	v_and_b32_e32 v91, 0xffff0000, v85
	v_lshlrev_b32_e32 v90, 16, v85
	s_waitcnt vmcnt(16)
	v_mov_b32_e32 v74, v166
	v_mov_b32_e32 v75, v167
	v_mov_b32_e32 v76, v168
	v_mov_b32_e32 v77, v169
	v_pk_fma_f32 v[74:75], v[78:79], v[88:89], v[74:75]
	v_pk_fma_f32 v[76:77], v[80:81], v[90:91], v[76:77]
	global_store_dwordx4 v[86:87], v[74:77], off
	v_cvt_pk_bf16_f32 v78, v74, v75
	v_cvt_pk_bf16_f32 v79, v76, v77
	v_pk_mul_f32 v[74:75], v[74:75], v[74:75]
	v_pk_mul_f32 v[76:77], v[76:77], v[76:77]
	v_add_f32_e32 v65, v74, v75
	v_add_f32_e32 v65, v76, v65
	v_add_f32_e32 v65, v77, v65
	v_mov_b32_e32 v73, 0
	global_store_dwordx2 v[82:83], v[78:79], off
	v_add_f32_dpp v65, v65, v65 quad_perm:[1,0,3,2] row_mask:0xf bank_mask:0xf bound_ctrl:1
	s_nop 1
	v_add_f32_dpp v65, v65, v65 quad_perm:[2,3,0,1] row_mask:0xf bank_mask:0xf bound_ctrl:1
	s_nop 1
	v_add_f32_dpp v65, v65, v65 row_half_mirror row_mask:0xf bank_mask:0xf bound_ctrl:1
	s_nop 1
	v_mov_b32_dpp v73, v65 row_mirror row_mask:0xf bank_mask:0xf
	s_and_saveexec_b64 s[0:1], vcc
	s_cbranch_execz .LBB0_3300
	v_add_f32_e32 v73, v65, v73
	v_ashrrev_i32_e32 v65, 31, v64
	v_lshl_add_u64 v[64:65], v[64:65], 2, s[24:25]
	global_atomic_add_f32 v[64:65], v73, off
; __device__ __forceinline__ float bfs2f(short h) { return __uint_as_float(((unsigned)(u16)h) << 16); }
; __device__ __forceinline__ float sigm(float x) { return __builtin_amdgcn_rcpf(1.f + __expf(-x)); }
;   __device__ __forceinline__ void tile(const float* reg, int row0, int col0, int lane) const {
;     ...
;     rows4(reg, lane, [&](int it, int rr, int c4, float4 v) {
;       int row = row0 + rr, idx = row * 1024 + col0 + c4;
;       float rs = rsv[it];
;       float4 xo = *(const float4*)(xold + idx);
;       bf16x4 t = *(const bf16x4*)(tmp + idx);
;       v.x = fmaf(sigm(v.x * rs), bfs2f(t[0]), xo.x); v.y = fmaf(sigm(v.y * rs), bfs2f(t[1]), xo.y);
;       v.z = fmaf(sigm(v.z * rs), bfs2f(t[2]), xo.z); v.w = fmaf(sigm(v.w * rs), bfs2f(t[3]), xo.w);
;       *(float4*)(xnew + idx) = v;
;       *(bf16x4*)(xb + idx) = pack4(v.x, v.y, v.z, v.w);
;       float s = row16_sum(v.x * v.x + v.y * v.y + v.z * v.z + v.w * v.w);
;       if ((lane & 15) == 0) atomicAdd(ssqn + row, s);
;     });
.LBB0_3300:
	s_or_b64 exec, exec, s[0:1]
	v_add_u32_e32 v64, v101, v67
	v_lshl_add_u32 v74, v64, 10, v128
	v_ashrrev_i32_e32 v75, 31, v74
	v_lshlrev_b64 v[82:83], 1, v[74:75]
	v_lshl_add_u64 v[76:77], s[14:15], 0, v[82:83]
	v_lshl_add_u64 v[86:87], v[74:75], 2, s[8:9]
	v_fmamk_f32 v65, v72, 0x3a800000, v135
	v_mul_f32_e32 v72, 0x4b800000, v65
	v_cmp_gt_f32_e64 s[6:7], s57, v65
	ds_read_b128 v[78:81], v98
	v_lshl_add_u64 v[82:83], s[10:11], 0, v[82:83]
	v_cndmask_b32_e64 v65, v65, v72, s[6:7]
	v_rsq_f32_e32 v65, v65
	s_waitcnt vmcnt(18)
	v_mov_b32_e32 v84, v170
	v_mov_b32_e32 v85, v171
	v_and_b32_e32 v89, 0xffff0000, v85
	v_mul_f32_e32 v72, 0x45800000, v65
	v_cndmask_b32_e64 v65, v65, v72, s[6:7]
	s_waitcnt lgkmcnt(0)
	v_mul_f32_e32 v72, v65, v78
	v_mul_f32_e32 v73, v65, v79
	v_mul_f32_e32 v78, v65, v80
	v_mul_f32_e32 v65, v65, v81
	v_mul_f32_e32 v72, 0xbfb8aa3b, v72
	v_mul_f32_e32 v73, 0xbfb8aa3b, v73
	v_mul_f32_e32 v78, 0xbfb8aa3b, v78
	v_mul_f32_e32 v65, 0xbfb8aa3b, v65
	v_exp_f32_e32 v72, v72
	v_exp_f32_e32 v73, v73
	v_exp_f32_e32 v78, v78
	v_exp_f32_e32 v65, v65
	v_add_f32_e32 v72, 1.0, v72
	v_add_f32_e32 v73, 1.0, v73
	v_add_f32_e32 v78, 1.0, v78
	v_add_f32_e32 v65, 1.0, v65
	v_rcp_f32_e32 v72, v72
	v_rcp_f32_e32 v73, v73
	v_rcp_f32_e32 v78, v78
	v_rcp_f32_e32 v79, v65
	v_and_b32_e32 v81, 0xffff0000, v84
	v_lshlrev_b32_e32 v80, 16, v84
	v_lshlrev_b32_e32 v88, 16, v85
	s_waitcnt vmcnt(17)
	v_mov_b32_e32 v74, v172
	v_mov_b32_e32 v75, v173
	v_mov_b32_e32 v76, v174
	v_mov_b32_e32 v77, v175
	v_pk_fma_f32 v[72:73], v[72:73], v[80:81], v[74:75]
	v_pk_fma_f32 v[74:75], v[78:79], v[88:89], v[76:77]
	global_store_dwordx4 v[86:87], v[72:75], off
	v_cvt_pk_bf16_f32 v76, v72, v73
	v_cvt_pk_bf16_f32 v77, v74, v75
	v_pk_mul_f32 v[72:73], v[72:73], v[72:73]
	v_pk_mul_f32 v[74:75], v[74:75], v[74:75]
	v_add_f32_e32 v65, v72, v73
	v_add_f32_e32 v65, v74, v65
	v_add_f32_e32 v65, v75, v65
	v_mov_b32_e32 v72, 0
	global_store_dwordx2 v[82:83], v[76:77], off
	v_add_f32_dpp v65, v65, v65 quad_perm:[1,0,3,2] row_mask:0xf bank_mask:0xf bound_ctrl:1
	s_nop 1
	v_add_f32_dpp v65, v65, v65 quad_perm:[2,3,0,1] row_mask:0xf bank_mask:0xf bound_ctrl:1
	s_nop 1
	v_add_f32_dpp v65, v65, v65 row_half_mirror row_mask:0xf bank_mask:0xf bound_ctrl:1
	s_nop 1
	v_mov_b32_dpp v72, v65 row_mirror row_mask:0xf bank_mask:0xf
	s_and_saveexec_b64 s[0:1], vcc
	s_cbranch_execz .LBB0_3302
	v_add_f32_e32 v72, v65, v72
	v_ashrrev_i32_e32 v65, 31, v64
	v_lshl_add_u64 v[64:65], v[64:65], 2, s[24:25]
	global_atomic_add_f32 v[64:65], v72, off
.LBB0_3302:
	s_or_b64 exec, exec, s[0:1]
	v_fmamk_f32 v64, v71, 0x3a800000, v135
	v_mul_f32_e32 v65, 0x4b800000, v64
	v_cmp_gt_f32_e64 s[6:7], s57, v64
	s_nop 1
	v_cndmask_b32_e64 v64, v64, v65, s[6:7]
	v_rsq_f32_e32 v64, v64
	s_nop 0
	v_mul_f32_e32 v65, 0x45800000, v64
	v_cndmask_b32_e64 v65, v64, v65, s[6:7]
	v_add_u32_e32 v64, v108, v67
	v_lshl_add_u32 v72, v64, 10, v128
	v_ashrrev_i32_e32 v73, 31, v72
	v_lshlrev_b64 v[80:81], 1, v[72:73]
	v_lshl_add_u64 v[74:75], s[14:15], 0, v[80:81]
	v_lshl_add_u64 v[84:85], v[72:73], 2, s[8:9]
	ds_read_b128 v[76:79], v98 offset:1088
	v_lshl_add_u64 v[80:81], s[10:11], 0, v[80:81]
	s_waitcnt lgkmcnt(0)
	v_mul_f32_e32 v71, v65, v76
	v_mul_f32_e32 v76, v65, v77
	v_mul_f32_e32 v77, v65, v78
	v_mul_f32_e32 v65, v65, v79
	v_mul_f32_e32 v71, 0xbfb8aa3b, v71
	v_mul_f32_e32 v76, 0xbfb8aa3b, v76
	v_mul_f32_e32 v77, 0xbfb8aa3b, v77
	v_mul_f32_e32 v65, 0xbfb8aa3b, v65
	v_exp_f32_e32 v71, v71
	v_exp_f32_e32 v76, v76
	v_exp_f32_e32 v77, v77
	v_exp_f32_e32 v65, v65
	v_add_f32_e32 v71, 1.0, v71
	v_add_f32_e32 v78, 1.0, v76
	v_add_f32_e32 v79, 1.0, v77
	v_add_f32_e32 v65, 1.0, v65
	v_rcp_f32_e32 v76, v71
	v_rcp_f32_e32 v77, v78
	v_rcp_f32_e32 v78, v79
	v_rcp_f32_e32 v79, v65
	v_mov_b32_e32 v71, 0
	s_waitcnt vmcnt(19)
	v_mov_b32_e32 v82, v176
	v_mov_b32_e32 v83, v177
	v_and_b32_e32 v87, 0xffff0000, v82
	v_lshlrev_b32_e32 v86, 16, v82
	v_and_b32_e32 v89, 0xffff0000, v83
	v_lshlrev_b32_e32 v88, 16, v83
	s_waitcnt vmcnt(18)
	v_mov_b32_e32 v72, v178
	v_mov_b32_e32 v73, v179
	v_mov_b32_e32 v74, v180
	v_mov_b32_e32 v75, v181
	v_pk_fma_f32 v[72:73], v[76:77], v[86:87], v[72:73]
	v_pk_fma_f32 v[74:75], v[78:79], v[88:89], v[74:75]
	global_store_dwordx4 v[84:85], v[72:75], off
	v_cvt_pk_bf16_f32 v76, v72, v73
	v_cvt_pk_bf16_f32 v77, v74, v75
	v_pk_mul_f32 v[72:73], v[72:73], v[72:73]
	v_pk_mul_f32 v[74:75], v[74:75], v[74:75]
	v_add_f32_e32 v65, v72, v73
	v_add_f32_e32 v65, v74, v65
	v_add_f32_e32 v65, v75, v65
	global_store_dwordx2 v[80:81], v[76:77], off
	s_nop 0
	v_add_f32_dpp v65, v65, v65 quad_perm:[1,0,3,2] row_mask:0xf bank_mask:0xf bound_ctrl:1
	s_nop 1
	v_add_f32_dpp v65, v65, v65 quad_perm:[2,3,0,1] row_mask:0xf bank_mask:0xf bound_ctrl:1
	s_nop 1
	v_add_f32_dpp v65, v65, v65 row_half_mirror row_mask:0xf bank_mask:0xf bound_ctrl:1
	s_nop 1
	v_mov_b32_dpp v71, v65 row_mirror row_mask:0xf bank_mask:0xf
	s_and_saveexec_b64 s[0:1], vcc
	s_cbranch_execz .LBB0_3304
	v_add_f32_e32 v71, v65, v71
	v_ashrrev_i32_e32 v65, 31, v64
	v_lshl_add_u64 v[64:65], v[64:65], 2, s[24:25]
	global_atomic_add_f32 v[64:65], v71, off
; __device__ __forceinline__ float bfs2f(short h) { return __uint_as_float(((unsigned)(u16)h) << 16); }
; __device__ __forceinline__ float sigm(float x) { return __builtin_amdgcn_rcpf(1.f + __expf(-x)); }
;   __device__ __forceinline__ void tile(const float* reg, int row0, int col0, int lane) const {
;     ...
;     rows4(reg, lane, [&](int it, int rr, int c4, float4 v) {
;       int row = row0 + rr, idx = row * 1024 + col0 + c4;
;       float rs = rsv[it];
;       float4 xo = *(const float4*)(xold + idx);
;       bf16x4 t = *(const bf16x4*)(tmp + idx);
;       v.x = fmaf(sigm(v.x * rs), bfs2f(t[0]), xo.x); v.y = fmaf(sigm(v.y * rs), bfs2f(t[1]), xo.y);
;       v.z = fmaf(sigm(v.z * rs), bfs2f(t[2]), xo.z); v.w = fmaf(sigm(v.w * rs), bfs2f(t[3]), xo.w);
;       *(float4*)(xnew + idx) = v;
;       *(bf16x4*)(xb + idx) = pack4(v.x, v.y, v.z, v.w);
;       float s = row16_sum(v.x * v.x + v.y * v.y + v.z * v.z + v.w * v.w);
;       if ((lane & 15) == 0) atomicAdd(ssqn + row, s);
;     });
.LBB0_3304:
	s_or_b64 exec, exec, s[0:1]
	v_add_u32_e32 v64, v105, v67
	v_lshl_add_u32 v72, v64, 10, v128
	v_ashrrev_i32_e32 v73, 31, v72
	v_lshlrev_b64 v[80:81], 1, v[72:73]
	v_lshl_add_u64 v[74:75], s[14:15], 0, v[80:81]
	v_lshl_add_u64 v[84:85], v[72:73], 2, s[8:9]
	v_fmamk_f32 v65, v70, 0x3a800000, v135
	v_mul_f32_e32 v70, 0x4b800000, v65
	v_cmp_gt_f32_e64 s[6:7], s57, v65
	ds_read_b128 v[76:79], v98 offset:2176
	v_lshl_add_u64 v[80:81], s[10:11], 0, v[80:81]
	v_cndmask_b32_e64 v65, v65, v70, s[6:7]
	v_rsq_f32_e32 v65, v65
	s_waitcnt vmcnt(20)
	v_mov_b32_e32 v82, v182
	v_mov_b32_e32 v83, v183
	v_and_b32_e32 v87, 0xffff0000, v83
	v_mul_f32_e32 v70, 0x45800000, v65
	v_cndmask_b32_e64 v65, v65, v70, s[6:7]
	s_waitcnt lgkmcnt(0)
	v_mul_f32_e32 v70, v65, v76
	v_mul_f32_e32 v71, v65, v77
	v_mul_f32_e32 v76, v65, v78
	v_mul_f32_e32 v65, v65, v79
	v_mul_f32_e32 v70, 0xbfb8aa3b, v70
	v_mul_f32_e32 v71, 0xbfb8aa3b, v71
	v_mul_f32_e32 v76, 0xbfb8aa3b, v76
	v_mul_f32_e32 v65, 0xbfb8aa3b, v65
	v_exp_f32_e32 v70, v70
	v_exp_f32_e32 v71, v71
	v_exp_f32_e32 v76, v76
	v_exp_f32_e32 v65, v65
	v_add_f32_e32 v70, 1.0, v70
	v_add_f32_e32 v71, 1.0, v71
	v_add_f32_e32 v76, 1.0, v76
	v_add_f32_e32 v65, 1.0, v65
	v_rcp_f32_e32 v70, v70
	v_rcp_f32_e32 v71, v71
	v_rcp_f32_e32 v76, v76
	v_rcp_f32_e32 v77, v65
	v_and_b32_e32 v79, 0xffff0000, v82
	v_lshlrev_b32_e32 v78, 16, v82
	v_lshlrev_b32_e32 v86, 16, v83
	s_waitcnt vmcnt(19)
	v_mov_b32_e32 v72, v184
	v_mov_b32_e32 v73, v185
	v_mov_b32_e32 v74, v186
	v_mov_b32_e32 v75, v187
	v_pk_fma_f32 v[70:71], v[70:71], v[78:79], v[72:73]
	v_pk_fma_f32 v[72:73], v[76:77], v[86:87], v[74:75]
	global_store_dwordx4 v[84:85], v[70:73], off
	v_cvt_pk_bf16_f32 v74, v70, v71
	v_cvt_pk_bf16_f32 v75, v72, v73
	v_pk_mul_f32 v[70:71], v[70:71], v[70:71]
	v_pk_mul_f32 v[72:73], v[72:73], v[72:73]
	v_add_f32_e32 v65, v70, v71
	v_add_f32_e32 v65, v72, v65
	v_add_f32_e32 v65, v73, v65
	v_mov_b32_e32 v70, 0
	global_store_dwordx2 v[80:81], v[74:75], off
	v_add_f32_dpp v65, v65, v65 quad_perm:[1,0,3,2] row_mask:0xf bank_mask:0xf bound_ctrl:1
	s_nop 1
	v_add_f32_dpp v65, v65, v65 quad_perm:[2,3,0,1] row_mask:0xf bank_mask:0xf bound_ctrl:1
	s_nop 1
	v_add_f32_dpp v65, v65, v65 row_half_mirror row_mask:0xf bank_mask:0xf bound_ctrl:1
	s_nop 1
	v_mov_b32_dpp v70, v65 row_mirror row_mask:0xf bank_mask:0xf
	s_and_saveexec_b64 s[0:1], vcc
	s_cbranch_execz .LBB0_3306
	v_add_f32_e32 v70, v65, v70
	v_ashrrev_i32_e32 v65, 31, v64
	v_lshl_add_u64 v[64:65], v[64:65], 2, s[24:25]
	global_atomic_add_f32 v[64:65], v70, off
.LBB0_3306:
	s_or_b64 exec, exec, s[0:1]
	v_add_u32_e32 v64, v106, v67
	v_lshl_add_u32 v70, v64, 10, v128
	v_ashrrev_i32_e32 v71, 31, v70
	v_lshlrev_b64 v[78:79], 1, v[70:71]
	v_lshl_add_u64 v[72:73], s[14:15], 0, v[78:79]
	v_lshl_add_u64 v[82:83], v[70:71], 2, s[8:9]
	v_fmamk_f32 v65, v69, 0x3a800000, v135
	v_mul_f32_e32 v69, 0x4b800000, v65
	v_cmp_gt_f32_e64 s[6:7], s57, v65
	ds_read_b128 v[74:77], v98 offset:3264
	v_lshl_add_u64 v[78:79], s[10:11], 0, v[78:79]
	v_cndmask_b32_e64 v65, v65, v69, s[6:7]
	v_rsq_f32_e32 v65, v65
	s_waitcnt vmcnt(21)
	v_mov_b32_e32 v80, v188
	v_mov_b32_e32 v81, v189
	v_and_b32_e32 v85, 0xffff0000, v80
	v_mul_f32_e32 v69, 0x45800000, v65
	v_cndmask_b32_e64 v65, v65, v69, s[6:7]
	s_waitcnt lgkmcnt(0)
	v_mul_f32_e32 v69, v65, v74
	v_mul_f32_e32 v74, v65, v75
	v_mul_f32_e32 v75, v65, v76
	v_mul_f32_e32 v65, v65, v77
	v_mul_f32_e32 v69, 0xbfb8aa3b, v69
	v_mul_f32_e32 v74, 0xbfb8aa3b, v74
	v_mul_f32_e32 v75, 0xbfb8aa3b, v75
	v_mul_f32_e32 v65, 0xbfb8aa3b, v65
	v_exp_f32_e32 v69, v69
	v_exp_f32_e32 v74, v74
	v_exp_f32_e32 v75, v75
	v_exp_f32_e32 v65, v65
	v_add_f32_e32 v69, 1.0, v69
	v_add_f32_e32 v76, 1.0, v74
	v_add_f32_e32 v77, 1.0, v75
	v_add_f32_e32 v65, 1.0, v65
	v_rcp_f32_e32 v74, v69
	v_rcp_f32_e32 v75, v76
	v_rcp_f32_e32 v76, v77
	v_rcp_f32_e32 v77, v65
	v_lshlrev_b32_e32 v84, 16, v80
	v_and_b32_e32 v87, 0xffff0000, v81
	v_lshlrev_b32_e32 v86, 16, v81
	s_waitcnt vmcnt(20)
	v_mov_b32_e32 v70, v190
	v_mov_b32_e32 v71, v191
	v_mov_b32_e32 v72, v192
	v_mov_b32_e32 v73, v193
	v_pk_fma_f32 v[70:71], v[74:75], v[84:85], v[70:71]
	v_pk_fma_f32 v[72:73], v[76:77], v[86:87], v[72:73]
	global_store_dwordx4 v[82:83], v[70:73], off
	v_cvt_pk_bf16_f32 v74, v70, v71
	v_cvt_pk_bf16_f32 v75, v72, v73
	v_pk_mul_f32 v[70:71], v[70:71], v[70:71]
	v_pk_mul_f32 v[72:73], v[72:73], v[72:73]
	v_add_f32_e32 v65, v70, v71
	v_add_f32_e32 v65, v72, v65
	v_add_f32_e32 v65, v73, v65
	v_mov_b32_e32 v69, 0
	global_store_dwordx2 v[78:79], v[74:75], off
	v_add_f32_dpp v65, v65, v65 quad_perm:[1,0,3,2] row_mask:0xf bank_mask:0xf bound_ctrl:1
	s_nop 1
	v_add_f32_dpp v65, v65, v65 quad_perm:[2,3,0,1] row_mask:0xf bank_mask:0xf bound_ctrl:1
	s_nop 1
	v_add_f32_dpp v65, v65, v65 row_half_mirror row_mask:0xf bank_mask:0xf bound_ctrl:1
	s_nop 1
	v_mov_b32_dpp v69, v65 row_mirror row_mask:0xf bank_mask:0xf
	s_and_saveexec_b64 s[0:1], vcc
	s_cbranch_execz .LBB0_3308
	v_add_f32_e32 v69, v65, v69
	v_ashrrev_i32_e32 v65, 31, v64
	v_lshl_add_u64 v[64:65], v[64:65], 2, s[24:25]
	global_atomic_add_f32 v[64:65], v69, off
; __device__ __forceinline__ float bfs2f(short h) { return __uint_as_float(((unsigned)(u16)h) << 16); }
; __device__ __forceinline__ float sigm(float x) { return __builtin_amdgcn_rcpf(1.f + __expf(-x)); }
;   __device__ __forceinline__ void tile(const float* reg, int row0, int col0, int lane) const {
;     ...
;     rows4(reg, lane, [&](int it, int rr, int c4, float4 v) {
;       int row = row0 + rr, idx = row * 1024 + col0 + c4;
;       float rs = rsv[it];
;       float4 xo = *(const float4*)(xold + idx);
;       bf16x4 t = *(const bf16x4*)(tmp + idx);
;       v.x = fmaf(sigm(v.x * rs), bfs2f(t[0]), xo.x); v.y = fmaf(sigm(v.y * rs), bfs2f(t[1]), xo.y);
;       v.z = fmaf(sigm(v.z * rs), bfs2f(t[2]), xo.z); v.w = fmaf(sigm(v.w * rs), bfs2f(t[3]), xo.w);
;       *(float4*)(xnew + idx) = v;
;       *(bf16x4*)(xb + idx) = pack4(v.x, v.y, v.z, v.w);
;       float s = row16_sum(v.x * v.x + v.y * v.y + v.z * v.z + v.w * v.w);
;       if ((lane & 15) == 0) atomicAdd(ssqn + row, s);
;     });
; template <int MF, class Epi>
; __device__ __forceinline__ void staged_epilogue(f32x4 (&acc)[MF][4], int row0, int col0, const Epi& epi) {
;     ...
; #pragma unroll
;   for (int mp = 0; mp < MF / 2; ++mp) {
;     __builtin_amdgcn_sched_barrier(0);
; #pragma unroll
;     for (int mm = 0; mm < 2; ++mm)
; #pragma unroll
;       for (int n = 0; n < 4; ++n)
; #pragma unroll
;         for (int j = 0; j < 4; ++j) reg[(mm * 16 + fq * 4 + j) * 68 + n * 16 + fr] = acc[mp * 2 + mm][n][j];
;     __builtin_amdgcn_fence(__ATOMIC_ACQ_REL, "wavefront");
;     epi.tile(reg, row0 + mp * 32, col0, lane);
;     __builtin_amdgcn_fence(__ATOMIC_ACQ_REL, "wavefront");
.LBB0_3308:
	s_or_b64 exec, exec, s[0:1]
	v_add_u32_e32 v64, v107, v67
	v_lshl_add_u32 v70, v64, 10, v128
	v_ashrrev_i32_e32 v71, 31, v70
	v_lshlrev_b64 v[78:79], 1, v[70:71]
	v_lshl_add_u64 v[72:73], s[14:15], 0, v[78:79]
	v_lshl_add_u64 v[82:83], v[70:71], 2, s[8:9]
	v_fmamk_f32 v65, v68, 0x3a800000, v135
	v_mul_f32_e32 v67, 0x4b800000, v65
	v_cmp_gt_f32_e64 s[6:7], s57, v65
	ds_read_b128 v[74:77], v98 offset:4352
	v_lshl_add_u64 v[78:79], s[10:11], 0, v[78:79]
	v_cndmask_b32_e64 v65, v65, v67, s[6:7]
	v_rsq_f32_e32 v65, v65
	s_waitcnt vmcnt(22)
	v_mov_b32_e32 v80, v194
	v_mov_b32_e32 v81, v195
	v_and_b32_e32 v85, 0xffff0000, v81
	v_mul_f32_e32 v67, 0x45800000, v65
	v_cndmask_b32_e64 v65, v65, v67, s[6:7]
	s_waitcnt lgkmcnt(0)
	v_mul_f32_e32 v67, v65, v74
	v_mul_f32_e32 v68, v65, v75
	v_mul_f32_e32 v69, v65, v76
	v_mul_f32_e32 v65, v65, v77
	v_mul_f32_e32 v67, 0xbfb8aa3b, v67
	v_mul_f32_e32 v68, 0xbfb8aa3b, v68
	v_mul_f32_e32 v69, 0xbfb8aa3b, v69
	v_mul_f32_e32 v65, 0xbfb8aa3b, v65
	v_exp_f32_e32 v67, v67
	v_exp_f32_e32 v68, v68
	v_exp_f32_e32 v69, v69
	v_exp_f32_e32 v65, v65
	v_add_f32_e32 v67, 1.0, v67
	v_add_f32_e32 v74, 1.0, v68
	v_add_f32_e32 v75, 1.0, v69
	v_add_f32_e32 v65, 1.0, v65
	v_rcp_f32_e32 v68, v67
	v_rcp_f32_e32 v69, v74
	v_rcp_f32_e32 v74, v75
	v_rcp_f32_e32 v75, v65
	v_and_b32_e32 v77, 0xffff0000, v80
	v_lshlrev_b32_e32 v76, 16, v80
	v_lshlrev_b32_e32 v84, 16, v81
	s_waitcnt vmcnt(21)
	v_mov_b32_e32 v70, v196
	v_mov_b32_e32 v71, v197
	v_mov_b32_e32 v72, v198
	v_mov_b32_e32 v73, v199
	v_pk_fma_f32 v[68:69], v[68:69], v[76:77], v[70:71]
	v_pk_fma_f32 v[70:71], v[74:75], v[84:85], v[72:73]
	global_store_dwordx4 v[82:83], v[68:71], off
	v_cvt_pk_bf16_f32 v72, v68, v69
	v_cvt_pk_bf16_f32 v73, v70, v71
	v_pk_mul_f32 v[68:69], v[68:69], v[68:69]
	v_pk_mul_f32 v[70:71], v[70:71], v[70:71]
	v_add_f32_e32 v65, v68, v69
	v_add_f32_e32 v65, v70, v65
	v_add_f32_e32 v65, v71, v65
	v_mov_b32_e32 v67, 0
	global_store_dwordx2 v[78:79], v[72:73], off
	v_add_f32_dpp v65, v65, v65 quad_perm:[1,0,3,2] row_mask:0xf bank_mask:0xf bound_ctrl:1
	s_nop 1
	v_add_f32_dpp v65, v65, v65 quad_perm:[2,3,0,1] row_mask:0xf bank_mask:0xf bound_ctrl:1
	s_nop 1
	v_add_f32_dpp v65, v65, v65 row_half_mirror row_mask:0xf bank_mask:0xf bound_ctrl:1
	s_nop 1
	v_mov_b32_dpp v67, v65 row_mirror row_mask:0xf bank_mask:0xf
	s_and_saveexec_b64 s[0:1], vcc
	s_cbranch_execz .LBB0_3310
	v_add_f32_e32 v67, v65, v67
	v_ashrrev_i32_e32 v65, 31, v64
	v_lshl_add_u64 v[64:65], v[64:65], 2, s[24:25]
	global_atomic_add_f32 v[64:65], v67, off
.LBB0_3310:
	s_or_b64 exec, exec, s[0:1]
	ds_write2_b32 v131, v56, v60 offset1:16
	ds_write2_b32 v131, v57, v61 offset0:68 offset1:84
	ds_write2_b32 v131, v58, v62 offset0:136 offset1:152
	ds_write2_b32 v131, v59, v63 offset0:204 offset1:220
	ds_write2_b32 v131, v48, v52 offset0:32 offset1:48
	ds_write2_b32 v131, v49, v53 offset0:100 offset1:116
	ds_write2_b32 v131, v50, v54 offset0:168 offset1:184
	ds_write2_b32 v131, v51, v55 offset0:236 offset1:252
	ds_write2_b32 v112, v40, v44 offset0:64 offset1:80
	ds_write2_b32 v112, v41, v45 offset0:132 offset1:148
	ds_write2_b32 v112, v42, v46 offset0:200 offset1:216
	ds_write2_b32 v104, v43, v47 offset0:12 offset1:28
	ds_write2_b32 v112, v32, v36 offset0:96 offset1:112
	ds_write2_b32 v112, v33, v37 offset0:164 offset1:180
	ds_write2_b32 v112, v34, v38 offset0:232 offset1:248
	ds_write2_b32 v104, v35, v39 offset0:44 offset1:60
	v_add_u32_e32 v210, 64, v129
	v_add_u32_e32 v200, v130, v210
	v_ashrrev_i32_e32 v201, 31, v200
	v_lshl_add_u64 v[202:203], v[200:201], 2, s[22:23]
	global_load_dword v144, v[202:203], off
	v_add_u32_e32 v211, 64, v129
	v_add_u32_e32 v210, v130, v211
	v_add_u32_e32 v200, 4, v210
	v_ashrrev_i32_e32 v201, 31, v200
	v_lshl_add_u64 v[200:201], v[200:201], 2, s[22:23]
	global_load_dword v145, v[200:201], off
	v_add_u32_e32 v211, 64, v129
	v_add_u32_e32 v210, v130, v211
	v_add_u32_e32 v200, 8, v210
	v_ashrrev_i32_e32 v201, 31, v200
	v_lshl_add_u64 v[200:201], v[200:201], 2, s[22:23]
	global_load_dword v146, v[200:201], off
	v_add_u32_e32 v211, 64, v129
	v_add_u32_e32 v210, v130, v211
	v_add_u32_e32 v200, 12, v210
	v_ashrrev_i32_e32 v201, 31, v200
	v_lshl_add_u64 v[202:203], v[200:201], 2, s[22:23]
	global_load_dword v147, v[202:203], off
	v_add_u32_e32 v211, 64, v129
	v_add_u32_e32 v210, v130, v211
	v_add_u32_e32 v200, 16, v210
	v_ashrrev_i32_e32 v201, 31, v200
	v_lshl_add_u64 v[202:203], v[200:201], 2, s[22:23]
	global_load_dword v148, v[202:203], off
	v_add_u32_e32 v211, 64, v129
	v_add_u32_e32 v210, v130, v211
	v_add_u32_e32 v200, 20, v210
	v_ashrrev_i32_e32 v201, 31, v200
	v_lshl_add_u64 v[202:203], v[200:201], 2, s[22:23]
	global_load_dword v149, v[202:203], off
	v_add_u32_e32 v211, 64, v129
	v_add_u32_e32 v210, v130, v211
	v_add_u32_e32 v200, 24, v210
	v_ashrrev_i32_e32 v201, 31, v200
	v_lshl_add_u64 v[202:203], v[200:201], 2, s[22:23]
	global_load_dword v150, v[202:203], off
	v_add_u32_e32 v211, 64, v129
	v_add_u32_e32 v210, v130, v211
	v_add_u32_e32 v200, 28, v210
	v_ashrrev_i32_e32 v201, 31, v200
	v_lshl_add_u64 v[202:203], v[200:201], 2, s[22:23]
	global_load_dword v151, v[202:203], off
	v_add_u32_e32 v211, 64, v129
	v_add_u32_e32 v210, v130, v211
	v_lshl_add_u32 v200, v210, 10, v128
	v_ashrrev_i32_e32 v201, 31, v200
	v_lshlrev_b64 v[206:207], 1, v[200:201]
	v_lshl_add_u64 v[202:203], s[14:15], 0, v[206:207]
	global_load_dwordx2 v[152:153], v[202:203], off
	v_add_u32_e32 v211, 64, v129
	v_add_u32_e32 v210, v130, v211
	v_lshl_add_u32 v200, v210, 10, v128
	v_ashrrev_i32_e32 v201, 31, v200
	v_lshl_add_u64 v[202:203], v[200:201], 2, s[8:9]
	global_load_dwordx4 v[154:157], v[202:203], off
; __device__ __forceinline__ float bfs2f(short h) { return __uint_as_float(((unsigned)(u16)h) << 16); }
; __device__ __forceinline__ float sigm(float x) { return __builtin_amdgcn_rcpf(1.f + __expf(-x)); }
; __device__ __forceinline__ float rs_of(float ss) { return rsqrtf(ss * (1.f / 1024) + EPS); }
;   __device__ __forceinline__ void tile(const float* reg, int row0, int col0, int lane) const {
;     float rsv[8];
; #pragma unroll
;     for (int i = 0; i < 8; ++i) rsv[i] = rs_of(ssq[row0 + i * 4 + (lane >> 4)]);
;     rows4(reg, lane, [&](int it, int rr, int c4, float4 v) {
;       int row = row0 + rr, idx = row * 1024 + col0 + c4;
;       float rs = rsv[it];
;       float4 xo = *(const float4*)(xold + idx);
;       bf16x4 t = *(const bf16x4*)(tmp + idx);
;       v.x = fmaf(sigm(v.x * rs), bfs2f(t[0]), xo.x); v.y = fmaf(sigm(v.y * rs), bfs2f(t[1]), xo.y);
;       v.z = fmaf(sigm(v.z * rs), bfs2f(t[2]), xo.z); v.w = fmaf(sigm(v.w * rs), bfs2f(t[3]), xo.w);
;       *(float4*)(xnew + idx) = v;
;       *(bf16x4*)(xb + idx) = pack4(v.x, v.y, v.z, v.w);
;       float s = row16_sum(v.x * v.x + v.y * v.y + v.z * v.z + v.w * v.w);
;       if ((lane & 15) == 0) atomicAdd(ssqn + row, s);
;     });
	v_add_u32_e32 v211, 64, v129
	v_add_u32_e32 v210, v99, v211
	v_lshl_add_u32 v200, v210, 10, v128
	v_ashrrev_i32_e32 v201, 31, v200
	v_lshlrev_b64 v[206:207], 1, v[200:201]
	v_lshl_add_u64 v[202:203], s[14:15], 0, v[206:207]
	global_load_dwordx2 v[158:159], v[202:203], off
	v_add_u32_e32 v211, 64, v129
	v_add_u32_e32 v210, v99, v211
	v_lshl_add_u32 v200, v210, 10, v128
	v_ashrrev_i32_e32 v201, 31, v200
	v_lshl_add_u64 v[202:203], v[200:201], 2, s[8:9]
	global_load_dwordx4 v[160:163], v[202:203], off
	v_add_u32_e32 v211, 64, v129
	v_add_u32_e32 v210, v100, v211
	v_lshl_add_u32 v200, v210, 10, v128
	v_ashrrev_i32_e32 v201, 31, v200
	v_lshlrev_b64 v[206:207], 1, v[200:201]
	v_lshl_add_u64 v[202:203], s[14:15], 0, v[206:207]
	global_load_dwordx2 v[164:165], v[202:203], off
	v_add_u32_e32 v211, 64, v129
	v_add_u32_e32 v210, v100, v211
	v_lshl_add_u32 v200, v210, 10, v128
	v_ashrrev_i32_e32 v201, 31, v200
	v_lshl_add_u64 v[202:203], v[200:201], 2, s[8:9]
	global_load_dwordx4 v[166:169], v[202:203], off
	v_add_u32_e32 v211, 64, v129
	v_add_u32_e32 v210, v101, v211
	v_lshl_add_u32 v200, v210, 10, v128
	v_ashrrev_i32_e32 v201, 31, v200
	v_lshlrev_b64 v[206:207], 1, v[200:201]
	v_lshl_add_u64 v[202:203], s[14:15], 0, v[206:207]
	global_load_dwordx2 v[170:171], v[202:203], off
	v_add_u32_e32 v211, 64, v129
	v_add_u32_e32 v210, v101, v211
	v_lshl_add_u32 v200, v210, 10, v128
	v_ashrrev_i32_e32 v201, 31, v200
	v_lshl_add_u64 v[202:203], v[200:201], 2, s[8:9]
	global_load_dwordx4 v[172:175], v[202:203], off
	v_add_u32_e32 v211, 64, v129
	v_add_u32_e32 v210, v108, v211
	v_lshl_add_u32 v200, v210, 10, v128
	v_ashrrev_i32_e32 v201, 31, v200
	v_lshlrev_b64 v[206:207], 1, v[200:201]
	v_lshl_add_u64 v[202:203], s[14:15], 0, v[206:207]
	global_load_dwordx2 v[176:177], v[202:203], off
	v_add_u32_e32 v211, 64, v129
	v_add_u32_e32 v210, v108, v211
	v_lshl_add_u32 v200, v210, 10, v128
	v_ashrrev_i32_e32 v201, 31, v200
	v_lshl_add_u64 v[202:203], v[200:201], 2, s[8:9]
	global_load_dwordx4 v[178:181], v[202:203], off
	v_add_u32_e32 v211, 64, v129
	v_add_u32_e32 v210, v105, v211
	v_lshl_add_u32 v200, v210, 10, v128
	v_ashrrev_i32_e32 v201, 31, v200
	v_lshlrev_b64 v[206:207], 1, v[200:201]
	v_lshl_add_u64 v[202:203], s[14:15], 0, v[206:207]
	global_load_dwordx2 v[182:183], v[202:203], off
	v_add_u32_e32 v211, 64, v129
	v_add_u32_e32 v210, v105, v211
	v_lshl_add_u32 v200, v210, 10, v128
	v_ashrrev_i32_e32 v201, 31, v200
	v_lshl_add_u64 v[202:203], v[200:201], 2, s[8:9]
	global_load_dwordx4 v[184:187], v[202:203], off
	v_add_u32_e32 v211, 64, v129
	v_add_u32_e32 v210, v106, v211
	v_lshl_add_u32 v200, v210, 10, v128
	v_ashrrev_i32_e32 v201, 31, v200
	v_lshlrev_b64 v[206:207], 1, v[200:201]
	v_lshl_add_u64 v[202:203], s[14:15], 0, v[206:207]
	global_load_dwordx2 v[188:189], v[202:203], off
	v_add_u32_e32 v211, 64, v129
	v_add_u32_e32 v210, v106, v211
	v_lshl_add_u32 v200, v210, 10, v128
	v_ashrrev_i32_e32 v201, 31, v200
	v_lshl_add_u64 v[202:203], v[200:201], 2, s[8:9]
	global_load_dwordx4 v[190:193], v[202:203], off
	v_add_u32_e32 v211, 64, v129
	v_add_u32_e32 v210, v107, v211
	v_lshl_add_u32 v200, v210, 10, v128
	v_ashrrev_i32_e32 v201, 31, v200
	v_lshlrev_b64 v[206:207], 1, v[200:201]
	v_lshl_add_u64 v[202:203], s[14:15], 0, v[206:207]
	global_load_dwordx2 v[194:195], v[202:203], off
	v_add_u32_e32 v211, 64, v129
	v_add_u32_e32 v210, v107, v211
	v_lshl_add_u32 v200, v210, 10, v128
	v_ashrrev_i32_e32 v201, 31, v200
	v_lshl_add_u64 v[202:203], v[200:201], 2, s[8:9]
	global_load_dwordx4 v[196:199], v[202:203], off
	v_add_u32_e32 v34, 64, v129
	v_add_u32_e32 v32, v130, v34
	v_add_u32_e32 v40, 12, v32
	v_ashrrev_i32_e32 v41, 31, v40
	v_lshl_add_u64 v[42:43], v[40:41], 2, s[22:23]
	v_add_u32_e32 v40, 16, v32
	v_ashrrev_i32_e32 v41, 31, v40
	v_lshl_add_u64 v[44:45], v[40:41], 2, s[22:23]
	v_add_u32_e32 v40, 20, v32
	v_ashrrev_i32_e32 v33, 31, v32
	v_ashrrev_i32_e32 v41, 31, v40
	v_lshl_add_u64 v[36:37], v[32:33], 2, s[22:23]
	v_lshl_add_u64 v[46:47], v[40:41], 2, s[22:23]
	v_add_u32_e32 v40, 24, v32
	v_add_u32_e32 v36, 4, v32
	v_add_u32_e32 v38, 8, v32
	v_ashrrev_i32_e32 v41, 31, v40
	v_ashrrev_i32_e32 v37, 31, v36
	v_ashrrev_i32_e32 v39, 31, v38
	v_lshl_add_u64 v[48:49], v[40:41], 2, s[22:23]
	v_add_u32_e32 v40, 28, v32
	v_lshl_add_u64 v[36:37], v[36:37], 2, s[22:23]
	v_lshl_add_u64 v[38:39], v[38:39], 2, s[22:23]
	v_ashrrev_i32_e32 v41, 31, v40
	v_lshl_add_u64 v[50:51], v[40:41], 2, s[22:23]
	s_nop 0
	s_waitcnt vmcnt(23)
	v_mov_b32_e32 v52, v144
	v_fmamk_f32 v42, v52, 0x3a800000, v135
	v_mul_f32_e32 v43, 0x4b800000, v42
	v_cmp_gt_f32_e64 s[6:7], s57, v42
	s_nop 1
	v_cndmask_b32_e64 v42, v42, v43, s[6:7]
	v_rsq_f32_e32 v42, v42
	s_nop 0
	v_mul_f32_e32 v43, 0x45800000, v42
	v_cndmask_b32_e64 v56, v42, v43, s[6:7]
	v_lshl_add_u32 v42, v32, 10, v128
	v_ashrrev_i32_e32 v43, 31, v42
	v_lshlrev_b64 v[50:51], 1, v[42:43]
	v_lshl_add_u64 v[44:45], s[14:15], 0, v[50:51]
	v_lshl_add_u64 v[54:55], v[42:43], 2, s[8:9]
	ds_read_b128 v[46:49], v66
	v_lshl_add_u64 v[50:51], s[10:11], 0, v[50:51]
	s_waitcnt lgkmcnt(0)
	v_mul_f32_e32 v46, v56, v46
	v_mul_f32_e32 v47, v56, v47
	v_mul_f32_e32 v48, v56, v48
	v_mul_f32_e32 v49, v56, v49
	v_mul_f32_e32 v46, 0xbfb8aa3b, v46
	v_mul_f32_e32 v47, 0xbfb8aa3b, v47
	v_mul_f32_e32 v48, 0xbfb8aa3b, v48
	v_mul_f32_e32 v49, 0xbfb8aa3b, v49
	v_exp_f32_e32 v46, v46
	v_exp_f32_e32 v47, v47
	v_exp_f32_e32 v48, v48
	v_exp_f32_e32 v49, v49
	v_add_f32_e32 v46, 1.0, v46
	v_add_f32_e32 v47, 1.0, v47
	v_add_f32_e32 v48, 1.0, v48
	v_add_f32_e32 v49, 1.0, v49
	v_rcp_f32_e32 v46, v46
	v_rcp_f32_e32 v47, v47
	v_rcp_f32_e32 v48, v48
	v_rcp_f32_e32 v49, v49
	s_waitcnt vmcnt(15)
	v_mov_b32_e32 v41, v145
	v_mov_b32_e32 v40, v146
	v_mov_b32_e32 v39, v147
	v_mov_b32_e32 v38, v148
	v_mov_b32_e32 v37, v149
	v_mov_b32_e32 v36, v150
	v_mov_b32_e32 v35, v151
	v_mov_b32_e32 v52, v152
	v_mov_b32_e32 v53, v153
	v_and_b32_e32 v57, 0xffff0000, v52
	v_lshlrev_b32_e32 v56, 16, v52
	v_and_b32_e32 v59, 0xffff0000, v53
	v_lshlrev_b32_e32 v58, 16, v53
	s_waitcnt vmcnt(14)
	v_mov_b32_e32 v42, v154
	v_mov_b32_e32 v43, v155
	v_mov_b32_e32 v44, v156
	v_mov_b32_e32 v45, v157
	v_pk_fma_f32 v[42:43], v[46:47], v[56:57], v[42:43]
	v_pk_fma_f32 v[44:45], v[48:49], v[58:59], v[44:45]
	global_store_dwordx4 v[54:55], v[42:45], off
	v_cvt_pk_bf16_f32 v46, v42, v43
	v_cvt_pk_bf16_f32 v47, v44, v45
	v_pk_mul_f32 v[42:43], v[42:43], v[42:43]
	v_pk_mul_f32 v[44:45], v[44:45], v[44:45]
	v_add_f32_e32 v42, v42, v43
	v_add_f32_e32 v42, v44, v42
	v_add_f32_e32 v42, v45, v42
	v_mov_b32_e32 v43, 0
	global_store_dwordx2 v[50:51], v[46:47], off
	v_add_f32_dpp v42, v42, v42 quad_perm:[1,0,3,2] row_mask:0xf bank_mask:0xf bound_ctrl:1
	s_nop 1
	v_add_f32_dpp v42, v42, v42 quad_perm:[2,3,0,1] row_mask:0xf bank_mask:0xf bound_ctrl:1
	s_nop 1
	v_add_f32_dpp v42, v42, v42 row_half_mirror row_mask:0xf bank_mask:0xf bound_ctrl:1
	s_nop 1
	v_mov_b32_dpp v43, v42 row_mirror row_mask:0xf bank_mask:0xf
	s_and_saveexec_b64 s[0:1], vcc
	s_cbranch_execz .LBB0_3312
; __device__ __forceinline__ float bfs2f(short h) { return __uint_as_float(((unsigned)(u16)h) << 16); }
; __device__ __forceinline__ float sigm(float x) { return __builtin_amdgcn_rcpf(1.f + __expf(-x)); }
;   __device__ __forceinline__ void tile(const float* reg, int row0, int col0, int lane) const {
;     ...
;     rows4(reg, lane, [&](int it, int rr, int c4, float4 v) {
;       int row = row0 + rr, idx = row * 1024 + col0 + c4;
;       float rs = rsv[it];
;       float4 xo = *(const float4*)(xold + idx);
;       bf16x4 t = *(const bf16x4*)(tmp + idx);
;       v.x = fmaf(sigm(v.x * rs), bfs2f(t[0]), xo.x); v.y = fmaf(sigm(v.y * rs), bfs2f(t[1]), xo.y);
;       v.z = fmaf(sigm(v.z * rs), bfs2f(t[2]), xo.z); v.w = fmaf(sigm(v.w * rs), bfs2f(t[3]), xo.w);
;       *(float4*)(xnew + idx) = v;
;       *(bf16x4*)(xb + idx) = pack4(v.x, v.y, v.z, v.w);
;       float s = row16_sum(v.x * v.x + v.y * v.y + v.z * v.z + v.w * v.w);
;       if ((lane & 15) == 0) atomicAdd(ssqn + row, s);
;     });
	v_add_f32_e32 v42, v42, v43
	v_lshl_add_u64 v[32:33], v[32:33], 2, s[24:25]
	global_atomic_add_f32 v[32:33], v42, off
.LBB0_3312:
	s_or_b64 exec, exec, s[0:1]
	v_add_u32_e32 v32, v99, v34
	v_lshl_add_u32 v42, v32, 10, v128
	v_ashrrev_i32_e32 v43, 31, v42
	v_lshlrev_b64 v[50:51], 1, v[42:43]
	v_lshl_add_u64 v[44:45], s[14:15], 0, v[50:51]
	v_lshl_add_u64 v[54:55], v[42:43], 2, s[8:9]
	v_fmamk_f32 v33, v41, 0x3a800000, v135
	v_mul_f32_e32 v41, 0x4b800000, v33
	v_cmp_gt_f32_e64 s[6:7], s57, v33
	ds_read_b128 v[46:49], v102
	v_lshl_add_u64 v[50:51], s[10:11], 0, v[50:51]
	v_cndmask_b32_e64 v33, v33, v41, s[6:7]
	v_rsq_f32_e32 v33, v33
	s_waitcnt vmcnt(16)
	v_mov_b32_e32 v52, v158
	v_mov_b32_e32 v53, v159
	v_and_b32_e32 v57, 0xffff0000, v52
	v_mul_f32_e32 v41, 0x45800000, v33
	v_cndmask_b32_e64 v33, v33, v41, s[6:7]
	s_waitcnt lgkmcnt(0)
	v_mul_f32_e32 v41, v33, v46
	v_mul_f32_e32 v46, v33, v47
	v_mul_f32_e32 v47, v33, v48
	v_mul_f32_e32 v33, v33, v49
	v_mul_f32_e32 v41, 0xbfb8aa3b, v41
	v_mul_f32_e32 v46, 0xbfb8aa3b, v46
	v_mul_f32_e32 v47, 0xbfb8aa3b, v47
	v_mul_f32_e32 v33, 0xbfb8aa3b, v33
	v_exp_f32_e32 v41, v41
	v_exp_f32_e32 v46, v46
	v_exp_f32_e32 v47, v47
	v_exp_f32_e32 v33, v33
	v_add_f32_e32 v41, 1.0, v41
	v_add_f32_e32 v48, 1.0, v46
	v_add_f32_e32 v49, 1.0, v47
	v_add_f32_e32 v33, 1.0, v33
	v_rcp_f32_e32 v46, v41
	v_rcp_f32_e32 v47, v48
	v_rcp_f32_e32 v48, v49
	v_rcp_f32_e32 v49, v33
	v_lshlrev_b32_e32 v56, 16, v52
	v_and_b32_e32 v59, 0xffff0000, v53
	v_lshlrev_b32_e32 v58, 16, v53
	s_waitcnt vmcnt(15)
	v_mov_b32_e32 v42, v160
	v_mov_b32_e32 v43, v161
	v_mov_b32_e32 v44, v162
	v_mov_b32_e32 v45, v163
	v_pk_fma_f32 v[42:43], v[46:47], v[56:57], v[42:43]
	v_pk_fma_f32 v[44:45], v[48:49], v[58:59], v[44:45]
	global_store_dwordx4 v[54:55], v[42:45], off
	v_cvt_pk_bf16_f32 v46, v42, v43
	v_cvt_pk_bf16_f32 v47, v44, v45
	v_pk_mul_f32 v[42:43], v[42:43], v[42:43]
	v_pk_mul_f32 v[44:45], v[44:45], v[44:45]
	v_add_f32_e32 v33, v42, v43
	v_add_f32_e32 v33, v44, v33
	v_add_f32_e32 v33, v45, v33
	v_mov_b32_e32 v41, 0
	global_store_dwordx2 v[50:51], v[46:47], off
	v_add_f32_dpp v33, v33, v33 quad_perm:[1,0,3,2] row_mask:0xf bank_mask:0xf bound_ctrl:1
	s_nop 1
	v_add_f32_dpp v33, v33, v33 quad_perm:[2,3,0,1] row_mask:0xf bank_mask:0xf bound_ctrl:1
	s_nop 1
	v_add_f32_dpp v33, v33, v33 row_half_mirror row_mask:0xf bank_mask:0xf bound_ctrl:1
	s_nop 1
	v_mov_b32_dpp v41, v33 row_mirror row_mask:0xf bank_mask:0xf
	s_and_saveexec_b64 s[0:1], vcc
	s_cbranch_execz .LBB0_3314
	v_add_f32_e32 v41, v33, v41
	v_ashrrev_i32_e32 v33, 31, v32
	v_lshl_add_u64 v[32:33], v[32:33], 2, s[24:25]
	global_atomic_add_f32 v[32:33], v41, off
.LBB0_3314:
	s_or_b64 exec, exec, s[0:1]
	v_add_u32_e32 v32, v100, v34
	v_lshl_add_u32 v42, v32, 10, v128
	v_ashrrev_i32_e32 v43, 31, v42
	v_lshlrev_b64 v[50:51], 1, v[42:43]
	v_lshl_add_u64 v[44:45], s[14:15], 0, v[50:51]
	v_lshl_add_u64 v[54:55], v[42:43], 2, s[8:9]
	v_fmamk_f32 v33, v40, 0x3a800000, v135
	v_mul_f32_e32 v40, 0x4b800000, v33
	v_cmp_gt_f32_e64 s[6:7], s57, v33
	ds_read_b128 v[46:49], v103
	v_lshl_add_u64 v[50:51], s[10:11], 0, v[50:51]
	v_cndmask_b32_e64 v33, v33, v40, s[6:7]
	v_rsq_f32_e32 v33, v33
	s_waitcnt vmcnt(17)
	v_mov_b32_e32 v52, v164
	v_mov_b32_e32 v53, v165
	v_and_b32_e32 v57, 0xffff0000, v53
	v_mul_f32_e32 v40, 0x45800000, v33
	v_cndmask_b32_e64 v33, v33, v40, s[6:7]
	s_waitcnt lgkmcnt(0)
	v_mul_f32_e32 v40, v33, v46
	v_mul_f32_e32 v41, v33, v47
	v_mul_f32_e32 v46, v33, v48
	v_mul_f32_e32 v33, v33, v49
	v_mul_f32_e32 v40, 0xbfb8aa3b, v40
	v_mul_f32_e32 v41, 0xbfb8aa3b, v41
	v_mul_f32_e32 v46, 0xbfb8aa3b, v46
	v_mul_f32_e32 v33, 0xbfb8aa3b, v33
	v_exp_f32_e32 v40, v40
	v_exp_f32_e32 v41, v41
	v_exp_f32_e32 v46, v46
	v_exp_f32_e32 v33, v33
	v_add_f32_e32 v40, 1.0, v40
	v_add_f32_e32 v41, 1.0, v41
	v_add_f32_e32 v46, 1.0, v46
	v_add_f32_e32 v33, 1.0, v33
	v_rcp_f32_e32 v40, v40
	v_rcp_f32_e32 v41, v41
	v_rcp_f32_e32 v46, v46
	v_rcp_f32_e32 v47, v33
	v_and_b32_e32 v49, 0xffff0000, v52
	v_lshlrev_b32_e32 v48, 16, v52
	v_lshlrev_b32_e32 v56, 16, v53
	s_waitcnt vmcnt(16)
	v_mov_b32_e32 v42, v166
	v_mov_b32_e32 v43, v167
	v_mov_b32_e32 v44, v168
	v_mov_b32_e32 v45, v169
	v_pk_fma_f32 v[40:41], v[40:41], v[48:49], v[42:43]
	v_pk_fma_f32 v[42:43], v[46:47], v[56:57], v[44:45]
	global_store_dwordx4 v[54:55], v[40:43], off
	v_cvt_pk_bf16_f32 v44, v40, v41
	v_cvt_pk_bf16_f32 v45, v42, v43
	v_pk_mul_f32 v[40:41], v[40:41], v[40:41]
	v_pk_mul_f32 v[42:43], v[42:43], v[42:43]
	v_add_f32_e32 v33, v40, v41
	v_add_f32_e32 v33, v42, v33
	v_add_f32_e32 v33, v43, v33
	v_mov_b32_e32 v40, 0
	global_store_dwordx2 v[50:51], v[44:45], off
	v_add_f32_dpp v33, v33, v33 quad_perm:[1,0,3,2] row_mask:0xf bank_mask:0xf bound_ctrl:1
	s_nop 1
	v_add_f32_dpp v33, v33, v33 quad_perm:[2,3,0,1] row_mask:0xf bank_mask:0xf bound_ctrl:1
	s_nop 1
	v_add_f32_dpp v33, v33, v33 row_half_mirror row_mask:0xf bank_mask:0xf bound_ctrl:1
	s_nop 1
	v_mov_b32_dpp v40, v33 row_mirror row_mask:0xf bank_mask:0xf
	s_and_saveexec_b64 s[0:1], vcc
	s_cbranch_execz .LBB0_3316
	v_add_f32_e32 v40, v33, v40
	v_ashrrev_i32_e32 v33, 31, v32
	v_lshl_add_u64 v[32:33], v[32:33], 2, s[24:25]
	global_atomic_add_f32 v[32:33], v40, off
; __device__ __forceinline__ float bfs2f(short h) { return __uint_as_float(((unsigned)(u16)h) << 16); }
; __device__ __forceinline__ float sigm(float x) { return __builtin_amdgcn_rcpf(1.f + __expf(-x)); }
; __device__ __forceinline__ float rs_of(float ss) { return rsqrtf(ss * (1.f / 1024) + EPS); }
;   __device__ __forceinline__ void tile(const float* reg, int row0, int col0, int lane) const {
;     float rsv[8];
; #pragma unroll
;     for (int i = 0; i < 8; ++i) rsv[i] = rs_of(ssq[row0 + i * 4 + (lane >> 4)]);
;     rows4(reg, lane, [&](int it, int rr, int c4, float4 v) {
;       int row = row0 + rr, idx = row * 1024 + col0 + c4;
;       float rs = rsv[it];
;       float4 xo = *(const float4*)(xold + idx);
;       bf16x4 t = *(const bf16x4*)(tmp + idx);
;       v.x = fmaf(sigm(v.x * rs), bfs2f(t[0]), xo.x); v.y = fmaf(sigm(v.y * rs), bfs2f(t[1]), xo.y);
;       v.z = fmaf(sigm(v.z * rs), bfs2f(t[2]), xo.z); v.w = fmaf(sigm(v.w * rs), bfs2f(t[3]), xo.w);
;       *(float4*)(xnew + idx) = v;
;       *(bf16x4*)(xb + idx) = pack4(v.x, v.y, v.z, v.w);
;       float s = row16_sum(v.x * v.x + v.y * v.y + v.z * v.z + v.w * v.w);
;       if ((lane & 15) == 0) atomicAdd(ssqn + row, s);
;     });
.LBB0_3316:
	s_or_b64 exec, exec, s[0:1]
	v_add_u32_e32 v32, v101, v34
	v_lshl_add_u32 v40, v32, 10, v128
	v_ashrrev_i32_e32 v41, 31, v40
	v_lshlrev_b64 v[48:49], 1, v[40:41]
	v_lshl_add_u64 v[42:43], s[14:15], 0, v[48:49]
	v_lshl_add_u64 v[52:53], v[40:41], 2, s[8:9]
	v_fmamk_f32 v33, v39, 0x3a800000, v135
	v_mul_f32_e32 v39, 0x4b800000, v33
	v_cmp_gt_f32_e64 s[6:7], s57, v33
	ds_read_b128 v[44:47], v98
	v_lshl_add_u64 v[48:49], s[10:11], 0, v[48:49]
	v_cndmask_b32_e64 v33, v33, v39, s[6:7]
	v_rsq_f32_e32 v33, v33
	s_waitcnt vmcnt(18)
	v_mov_b32_e32 v50, v170
	v_mov_b32_e32 v51, v171
	v_and_b32_e32 v55, 0xffff0000, v50
	v_mul_f32_e32 v39, 0x45800000, v33
	v_cndmask_b32_e64 v33, v33, v39, s[6:7]
	s_waitcnt lgkmcnt(0)
	v_mul_f32_e32 v39, v33, v44
	v_mul_f32_e32 v44, v33, v45
	v_mul_f32_e32 v45, v33, v46
	v_mul_f32_e32 v33, v33, v47
	v_mul_f32_e32 v39, 0xbfb8aa3b, v39
	v_mul_f32_e32 v44, 0xbfb8aa3b, v44
	v_mul_f32_e32 v45, 0xbfb8aa3b, v45
	v_mul_f32_e32 v33, 0xbfb8aa3b, v33
	v_exp_f32_e32 v39, v39
	v_exp_f32_e32 v44, v44
	v_exp_f32_e32 v45, v45
	v_exp_f32_e32 v33, v33
	v_add_f32_e32 v39, 1.0, v39
	v_add_f32_e32 v46, 1.0, v44
	v_add_f32_e32 v47, 1.0, v45
	v_add_f32_e32 v33, 1.0, v33
	v_rcp_f32_e32 v44, v39
	v_rcp_f32_e32 v45, v46
	v_rcp_f32_e32 v46, v47
	v_rcp_f32_e32 v47, v33
	v_lshlrev_b32_e32 v54, 16, v50
	v_and_b32_e32 v57, 0xffff0000, v51
	v_lshlrev_b32_e32 v56, 16, v51
	s_waitcnt vmcnt(17)
	v_mov_b32_e32 v40, v172
	v_mov_b32_e32 v41, v173
	v_mov_b32_e32 v42, v174
	v_mov_b32_e32 v43, v175
	v_pk_fma_f32 v[40:41], v[44:45], v[54:55], v[40:41]
	v_pk_fma_f32 v[42:43], v[46:47], v[56:57], v[42:43]
	global_store_dwordx4 v[52:53], v[40:43], off
	v_cvt_pk_bf16_f32 v44, v40, v41
	v_cvt_pk_bf16_f32 v45, v42, v43
	v_pk_mul_f32 v[40:41], v[40:41], v[40:41]
	v_pk_mul_f32 v[42:43], v[42:43], v[42:43]
	v_add_f32_e32 v33, v40, v41
	v_add_f32_e32 v33, v42, v33
	v_add_f32_e32 v33, v43, v33
	v_mov_b32_e32 v39, 0
	global_store_dwordx2 v[48:49], v[44:45], off
	v_add_f32_dpp v33, v33, v33 quad_perm:[1,0,3,2] row_mask:0xf bank_mask:0xf bound_ctrl:1
	s_nop 1
	v_add_f32_dpp v33, v33, v33 quad_perm:[2,3,0,1] row_mask:0xf bank_mask:0xf bound_ctrl:1
	s_nop 1
	v_add_f32_dpp v33, v33, v33 row_half_mirror row_mask:0xf bank_mask:0xf bound_ctrl:1
	s_nop 1
	v_mov_b32_dpp v39, v33 row_mirror row_mask:0xf bank_mask:0xf
	s_and_saveexec_b64 s[0:1], vcc
	s_cbranch_execz .LBB0_3318
	v_add_f32_e32 v39, v33, v39
	v_ashrrev_i32_e32 v33, 31, v32
	v_lshl_add_u64 v[32:33], v[32:33], 2, s[24:25]
	global_atomic_add_f32 v[32:33], v39, off
.LBB0_3318:
	s_or_b64 exec, exec, s[0:1]
	v_fmamk_f32 v32, v38, 0x3a800000, v135
	v_mul_f32_e32 v33, 0x4b800000, v32
	v_cmp_gt_f32_e64 s[6:7], s57, v32
	s_nop 1
	v_cndmask_b32_e64 v32, v32, v33, s[6:7]
	v_rsq_f32_e32 v32, v32
	s_nop 0
	v_mul_f32_e32 v33, 0x45800000, v32
	v_cndmask_b32_e64 v33, v32, v33, s[6:7]
	v_add_u32_e32 v32, v108, v34
	v_lshl_add_u32 v38, v32, 10, v128
	v_ashrrev_i32_e32 v39, 31, v38
	v_lshlrev_b64 v[46:47], 1, v[38:39]
	v_lshl_add_u64 v[40:41], s[14:15], 0, v[46:47]
	v_lshl_add_u64 v[50:51], v[38:39], 2, s[8:9]
	ds_read_b128 v[42:45], v98 offset:1088
	v_lshl_add_u64 v[46:47], s[10:11], 0, v[46:47]
	s_waitcnt lgkmcnt(0)
	v_mul_f32_e32 v42, v33, v42
	v_mul_f32_e32 v43, v33, v43
	v_mul_f32_e32 v44, v33, v44
	v_mul_f32_e32 v33, v33, v45
	v_mul_f32_e32 v42, 0xbfb8aa3b, v42
	v_mul_f32_e32 v43, 0xbfb8aa3b, v43
	v_mul_f32_e32 v44, 0xbfb8aa3b, v44
	v_mul_f32_e32 v33, 0xbfb8aa3b, v33
	v_exp_f32_e32 v42, v42
	v_exp_f32_e32 v43, v43
	v_exp_f32_e32 v44, v44
	v_exp_f32_e32 v33, v33
	v_add_f32_e32 v42, 1.0, v42
	v_add_f32_e32 v43, 1.0, v43
	v_add_f32_e32 v44, 1.0, v44
	v_add_f32_e32 v33, 1.0, v33
	v_rcp_f32_e32 v42, v42
	v_rcp_f32_e32 v43, v43
	v_rcp_f32_e32 v44, v44
	v_rcp_f32_e32 v45, v33
	s_waitcnt vmcnt(19)
	v_mov_b32_e32 v48, v176
	v_mov_b32_e32 v49, v177
	v_and_b32_e32 v53, 0xffff0000, v48
	v_lshlrev_b32_e32 v52, 16, v48
	v_and_b32_e32 v55, 0xffff0000, v49
	v_lshlrev_b32_e32 v54, 16, v49
	s_waitcnt vmcnt(18)
	v_mov_b32_e32 v38, v178
	v_mov_b32_e32 v39, v179
	v_mov_b32_e32 v40, v180
	v_mov_b32_e32 v41, v181
	v_pk_fma_f32 v[38:39], v[42:43], v[52:53], v[38:39]
	v_pk_fma_f32 v[40:41], v[44:45], v[54:55], v[40:41]
	global_store_dwordx4 v[50:51], v[38:41], off
	v_cvt_pk_bf16_f32 v42, v38, v39
	v_cvt_pk_bf16_f32 v43, v40, v41
	v_pk_mul_f32 v[38:39], v[38:39], v[38:39]
	v_pk_mul_f32 v[40:41], v[40:41], v[40:41]
	v_add_f32_e32 v33, v38, v39
	v_add_f32_e32 v33, v40, v33
	v_add_f32_e32 v33, v41, v33
	v_mov_b32_e32 v38, 0
	global_store_dwordx2 v[46:47], v[42:43], off
	v_add_f32_dpp v33, v33, v33 quad_perm:[1,0,3,2] row_mask:0xf bank_mask:0xf bound_ctrl:1
	s_nop 1
	v_add_f32_dpp v33, v33, v33 quad_perm:[2,3,0,1] row_mask:0xf bank_mask:0xf bound_ctrl:1
	s_nop 1
	v_add_f32_dpp v33, v33, v33 row_half_mirror row_mask:0xf bank_mask:0xf bound_ctrl:1
	s_nop 1
	v_mov_b32_dpp v38, v33 row_mirror row_mask:0xf bank_mask:0xf
	s_and_saveexec_b64 s[0:1], vcc
	s_cbranch_execz .LBB0_3320
	v_add_f32_e32 v38, v33, v38
	v_ashrrev_i32_e32 v33, 31, v32
	v_lshl_add_u64 v[32:33], v[32:33], 2, s[24:25]
	global_atomic_add_f32 v[32:33], v38, off
; __device__ __forceinline__ float bfs2f(short h) { return __uint_as_float(((unsigned)(u16)h) << 16); }
; __device__ __forceinline__ float sigm(float x) { return __builtin_amdgcn_rcpf(1.f + __expf(-x)); }
; __device__ __forceinline__ float rs_of(float ss) { return rsqrtf(ss * (1.f / 1024) + EPS); }
;   __device__ __forceinline__ void tile(const float* reg, int row0, int col0, int lane) const {
;     float rsv[8];
; #pragma unroll
;     for (int i = 0; i < 8; ++i) rsv[i] = rs_of(ssq[row0 + i * 4 + (lane >> 4)]);
;     rows4(reg, lane, [&](int it, int rr, int c4, float4 v) {
;       int row = row0 + rr, idx = row * 1024 + col0 + c4;
;       float rs = rsv[it];
;       float4 xo = *(const float4*)(xold + idx);
;       bf16x4 t = *(const bf16x4*)(tmp + idx);
;       v.x = fmaf(sigm(v.x * rs), bfs2f(t[0]), xo.x); v.y = fmaf(sigm(v.y * rs), bfs2f(t[1]), xo.y);
;       v.z = fmaf(sigm(v.z * rs), bfs2f(t[2]), xo.z); v.w = fmaf(sigm(v.w * rs), bfs2f(t[3]), xo.w);
;       *(float4*)(xnew + idx) = v;
;       *(bf16x4*)(xb + idx) = pack4(v.x, v.y, v.z, v.w);
;       float s = row16_sum(v.x * v.x + v.y * v.y + v.z * v.z + v.w * v.w);
;       if ((lane & 15) == 0) atomicAdd(ssqn + row, s);
;     });
.LBB0_3320:
	s_or_b64 exec, exec, s[0:1]
	v_add_u32_e32 v32, v105, v34
	v_lshl_add_u32 v38, v32, 10, v128
	v_ashrrev_i32_e32 v39, 31, v38
	v_lshlrev_b64 v[46:47], 1, v[38:39]
	v_lshl_add_u64 v[40:41], s[14:15], 0, v[46:47]
	v_lshl_add_u64 v[50:51], v[38:39], 2, s[8:9]
	v_fmamk_f32 v33, v37, 0x3a800000, v135
	v_mul_f32_e32 v37, 0x4b800000, v33
	v_cmp_gt_f32_e64 s[6:7], s57, v33
	ds_read_b128 v[42:45], v98 offset:2176
	v_lshl_add_u64 v[46:47], s[10:11], 0, v[46:47]
	v_cndmask_b32_e64 v33, v33, v37, s[6:7]
	v_rsq_f32_e32 v33, v33
	s_waitcnt vmcnt(20)
	v_mov_b32_e32 v48, v182
	v_mov_b32_e32 v49, v183
	v_and_b32_e32 v53, 0xffff0000, v48
	v_mul_f32_e32 v37, 0x45800000, v33
	v_cndmask_b32_e64 v33, v33, v37, s[6:7]
	s_waitcnt lgkmcnt(0)
	v_mul_f32_e32 v37, v33, v42
	v_mul_f32_e32 v42, v33, v43
	v_mul_f32_e32 v43, v33, v44
	v_mul_f32_e32 v33, v33, v45
	v_mul_f32_e32 v37, 0xbfb8aa3b, v37
	v_mul_f32_e32 v42, 0xbfb8aa3b, v42
	v_mul_f32_e32 v43, 0xbfb8aa3b, v43
	v_mul_f32_e32 v33, 0xbfb8aa3b, v33
	v_exp_f32_e32 v37, v37
	v_exp_f32_e32 v42, v42
	v_exp_f32_e32 v43, v43
	v_exp_f32_e32 v33, v33
	v_add_f32_e32 v37, 1.0, v37
	v_add_f32_e32 v44, 1.0, v42
	v_add_f32_e32 v45, 1.0, v43
	v_add_f32_e32 v33, 1.0, v33
	v_rcp_f32_e32 v42, v37
	v_rcp_f32_e32 v43, v44
	v_rcp_f32_e32 v44, v45
	v_rcp_f32_e32 v45, v33
	v_lshlrev_b32_e32 v52, 16, v48
	v_and_b32_e32 v55, 0xffff0000, v49
	v_lshlrev_b32_e32 v54, 16, v49
	s_waitcnt vmcnt(19)
	v_mov_b32_e32 v38, v184
	v_mov_b32_e32 v39, v185
	v_mov_b32_e32 v40, v186
	v_mov_b32_e32 v41, v187
	v_pk_fma_f32 v[38:39], v[42:43], v[52:53], v[38:39]
	v_pk_fma_f32 v[40:41], v[44:45], v[54:55], v[40:41]
	global_store_dwordx4 v[50:51], v[38:41], off
	v_cvt_pk_bf16_f32 v42, v38, v39
	v_cvt_pk_bf16_f32 v43, v40, v41
	v_pk_mul_f32 v[38:39], v[38:39], v[38:39]
	v_pk_mul_f32 v[40:41], v[40:41], v[40:41]
	v_add_f32_e32 v33, v38, v39
	v_add_f32_e32 v33, v40, v33
	v_add_f32_e32 v33, v41, v33
	v_mov_b32_e32 v37, 0
	global_store_dwordx2 v[46:47], v[42:43], off
	v_add_f32_dpp v33, v33, v33 quad_perm:[1,0,3,2] row_mask:0xf bank_mask:0xf bound_ctrl:1
	s_nop 1
	v_add_f32_dpp v33, v33, v33 quad_perm:[2,3,0,1] row_mask:0xf bank_mask:0xf bound_ctrl:1
	s_nop 1
	v_add_f32_dpp v33, v33, v33 row_half_mirror row_mask:0xf bank_mask:0xf bound_ctrl:1
	s_nop 1
	v_mov_b32_dpp v37, v33 row_mirror row_mask:0xf bank_mask:0xf
	s_and_saveexec_b64 s[0:1], vcc
	s_cbranch_execz .LBB0_3322
	v_add_f32_e32 v37, v33, v37
	v_ashrrev_i32_e32 v33, 31, v32
	v_lshl_add_u64 v[32:33], v[32:33], 2, s[24:25]
	global_atomic_add_f32 v[32:33], v37, off
; __device__ __forceinline__ float bfs2f(short h) { return __uint_as_float(((unsigned)(u16)h) << 16); }
; __device__ __forceinline__ float sigm(float x) { return __builtin_amdgcn_rcpf(1.f + __expf(-x)); }
; __device__ __forceinline__ float rs_of(float ss) { return rsqrtf(ss * (1.f / 1024) + EPS); }
;   __device__ __forceinline__ void tile(const float* reg, int row0, int col0, int lane) const {
;     float rsv[8];
; #pragma unroll
;     for (int i = 0; i < 8; ++i) rsv[i] = rs_of(ssq[row0 + i * 4 + (lane >> 4)]);
;     rows4(reg, lane, [&](int it, int rr, int c4, float4 v) {
;       int row = row0 + rr, idx = row * 1024 + col0 + c4;
;       float rs = rsv[it];
;       float4 xo = *(const float4*)(xold + idx);
;       bf16x4 t = *(const bf16x4*)(tmp + idx);
;       v.x = fmaf(sigm(v.x * rs), bfs2f(t[0]), xo.x); v.y = fmaf(sigm(v.y * rs), bfs2f(t[1]), xo.y);
;       v.z = fmaf(sigm(v.z * rs), bfs2f(t[2]), xo.z); v.w = fmaf(sigm(v.w * rs), bfs2f(t[3]), xo.w);
;       *(float4*)(xnew + idx) = v;
;       *(bf16x4*)(xb + idx) = pack4(v.x, v.y, v.z, v.w);
;       float s = row16_sum(v.x * v.x + v.y * v.y + v.z * v.z + v.w * v.w);
;       if ((lane & 15) == 0) atomicAdd(ssqn + row, s);
;     });
.LBB0_3322:
	s_or_b64 exec, exec, s[0:1]
	v_add_u32_e32 v32, v106, v34
	v_lshl_add_u32 v38, v32, 10, v128
	v_ashrrev_i32_e32 v39, 31, v38
	v_lshlrev_b64 v[46:47], 1, v[38:39]
	v_lshl_add_u64 v[40:41], s[14:15], 0, v[46:47]
	v_lshl_add_u64 v[50:51], v[38:39], 2, s[8:9]
	v_fmamk_f32 v33, v36, 0x3a800000, v135
	v_mul_f32_e32 v36, 0x4b800000, v33
	v_cmp_gt_f32_e64 s[6:7], s57, v33
	ds_read_b128 v[42:45], v98 offset:3264
	v_lshl_add_u64 v[46:47], s[10:11], 0, v[46:47]
	v_cndmask_b32_e64 v33, v33, v36, s[6:7]
	v_rsq_f32_e32 v33, v33
	s_waitcnt vmcnt(21)
	v_mov_b32_e32 v48, v188
	v_mov_b32_e32 v49, v189
	v_and_b32_e32 v53, 0xffff0000, v49
	v_mul_f32_e32 v36, 0x45800000, v33
	v_cndmask_b32_e64 v33, v33, v36, s[6:7]
	s_waitcnt lgkmcnt(0)
	v_mul_f32_e32 v36, v33, v42
	v_mul_f32_e32 v37, v33, v43
	v_mul_f32_e32 v42, v33, v44
	v_mul_f32_e32 v33, v33, v45
	v_mul_f32_e32 v36, 0xbfb8aa3b, v36
	v_mul_f32_e32 v37, 0xbfb8aa3b, v37
	v_mul_f32_e32 v42, 0xbfb8aa3b, v42
	v_mul_f32_e32 v33, 0xbfb8aa3b, v33
	v_exp_f32_e32 v36, v36
	v_exp_f32_e32 v37, v37
	v_exp_f32_e32 v42, v42
	v_exp_f32_e32 v33, v33
	v_add_f32_e32 v36, 1.0, v36
	v_add_f32_e32 v37, 1.0, v37
	v_add_f32_e32 v42, 1.0, v42
	v_add_f32_e32 v33, 1.0, v33
	v_rcp_f32_e32 v36, v36
	v_rcp_f32_e32 v37, v37
	v_rcp_f32_e32 v42, v42
	v_rcp_f32_e32 v43, v33
	v_and_b32_e32 v45, 0xffff0000, v48
	v_lshlrev_b32_e32 v44, 16, v48
	v_lshlrev_b32_e32 v52, 16, v49
	s_waitcnt vmcnt(20)
	v_mov_b32_e32 v38, v190
	v_mov_b32_e32 v39, v191
	v_mov_b32_e32 v40, v192
	v_mov_b32_e32 v41, v193
	v_pk_fma_f32 v[36:37], v[36:37], v[44:45], v[38:39]
	v_pk_fma_f32 v[38:39], v[42:43], v[52:53], v[40:41]
	global_store_dwordx4 v[50:51], v[36:39], off
	v_cvt_pk_bf16_f32 v40, v36, v37
	v_cvt_pk_bf16_f32 v41, v38, v39
	v_pk_mul_f32 v[36:37], v[36:37], v[36:37]
	v_pk_mul_f32 v[38:39], v[38:39], v[38:39]
	v_add_f32_e32 v33, v36, v37
	v_add_f32_e32 v33, v38, v33
	v_add_f32_e32 v33, v39, v33
	v_mov_b32_e32 v36, 0
	global_store_dwordx2 v[46:47], v[40:41], off
	v_add_f32_dpp v33, v33, v33 quad_perm:[1,0,3,2] row_mask:0xf bank_mask:0xf bound_ctrl:1
	s_nop 1
	v_add_f32_dpp v33, v33, v33 quad_perm:[2,3,0,1] row_mask:0xf bank_mask:0xf bound_ctrl:1
	s_nop 1
	v_add_f32_dpp v33, v33, v33 row_half_mirror row_mask:0xf bank_mask:0xf bound_ctrl:1
	s_nop 1
	v_mov_b32_dpp v36, v33 row_mirror row_mask:0xf bank_mask:0xf
	s_and_saveexec_b64 s[0:1], vcc
	s_cbranch_execz .LBB0_3324
	v_add_f32_e32 v36, v33, v36
	v_ashrrev_i32_e32 v33, 31, v32
	v_lshl_add_u64 v[32:33], v[32:33], 2, s[24:25]
	global_atomic_add_f32 v[32:33], v36, off
.LBB0_3324:
	s_or_b64 exec, exec, s[0:1]
	v_add_u32_e32 v32, v107, v34
	v_lshl_add_u32 v36, v32, 10, v128
	v_ashrrev_i32_e32 v37, 31, v36
	v_lshlrev_b64 v[44:45], 1, v[36:37]
	v_lshl_add_u64 v[38:39], s[14:15], 0, v[44:45]
	v_lshl_add_u64 v[48:49], v[36:37], 2, s[8:9]
	v_fmamk_f32 v33, v35, 0x3a800000, v135
	v_mul_f32_e32 v34, 0x4b800000, v33
	v_cmp_gt_f32_e64 s[6:7], s57, v33
	ds_read_b128 v[40:43], v98 offset:4352
	v_lshl_add_u64 v[44:45], s[10:11], 0, v[44:45]
	v_cndmask_b32_e64 v33, v33, v34, s[6:7]
	v_rsq_f32_e32 v33, v33
	s_waitcnt vmcnt(22)
	v_mov_b32_e32 v46, v194
	v_mov_b32_e32 v47, v195
	v_and_b32_e32 v51, 0xffff0000, v47
	v_mul_f32_e32 v34, 0x45800000, v33
	v_cndmask_b32_e64 v33, v33, v34, s[6:7]
	s_waitcnt lgkmcnt(0)
	v_mul_f32_e32 v34, v33, v40
	v_mul_f32_e32 v35, v33, v41
	v_mul_f32_e32 v40, v33, v42
	v_mul_f32_e32 v33, v33, v43
	v_mul_f32_e32 v34, 0xbfb8aa3b, v34
	v_mul_f32_e32 v35, 0xbfb8aa3b, v35
	v_mul_f32_e32 v40, 0xbfb8aa3b, v40
	v_mul_f32_e32 v33, 0xbfb8aa3b, v33
	v_exp_f32_e32 v34, v34
	v_exp_f32_e32 v35, v35
	v_exp_f32_e32 v40, v40
	v_exp_f32_e32 v33, v33
	v_add_f32_e32 v34, 1.0, v34
	v_add_f32_e32 v35, 1.0, v35
	v_add_f32_e32 v40, 1.0, v40
	v_add_f32_e32 v33, 1.0, v33
	v_rcp_f32_e32 v34, v34
	v_rcp_f32_e32 v35, v35
	v_rcp_f32_e32 v40, v40
	v_rcp_f32_e32 v41, v33
	v_and_b32_e32 v43, 0xffff0000, v46
	v_lshlrev_b32_e32 v42, 16, v46
	v_lshlrev_b32_e32 v50, 16, v47
	s_waitcnt vmcnt(21)
	v_mov_b32_e32 v36, v196
	v_mov_b32_e32 v37, v197
	v_mov_b32_e32 v38, v198
	v_mov_b32_e32 v39, v199
	v_pk_fma_f32 v[34:35], v[34:35], v[42:43], v[36:37]
	v_pk_fma_f32 v[36:37], v[40:41], v[50:51], v[38:39]
	global_store_dwordx4 v[48:49], v[34:37], off
	v_cvt_pk_bf16_f32 v38, v34, v35
	v_cvt_pk_bf16_f32 v39, v36, v37
	v_pk_mul_f32 v[34:35], v[34:35], v[34:35]
	v_pk_mul_f32 v[36:37], v[36:37], v[36:37]
	v_add_f32_e32 v33, v34, v35
	v_add_f32_e32 v33, v36, v33
	v_add_f32_e32 v33, v37, v33
	v_mov_b32_e32 v34, 0
	global_store_dwordx2 v[44:45], v[38:39], off
	v_add_f32_dpp v33, v33, v33 quad_perm:[1,0,3,2] row_mask:0xf bank_mask:0xf bound_ctrl:1
	s_nop 1
	v_add_f32_dpp v33, v33, v33 quad_perm:[2,3,0,1] row_mask:0xf bank_mask:0xf bound_ctrl:1
	s_nop 1
	v_add_f32_dpp v33, v33, v33 row_half_mirror row_mask:0xf bank_mask:0xf bound_ctrl:1
	s_nop 1
	v_mov_b32_dpp v34, v33 row_mirror row_mask:0xf bank_mask:0xf
	s_and_saveexec_b64 s[0:1], vcc
	s_cbranch_execz .LBB0_3326
	v_add_f32_e32 v34, v33, v34
	v_ashrrev_i32_e32 v33, 31, v32
	v_lshl_add_u64 v[32:33], v[32:33], 2, s[24:25]
	global_atomic_add_f32 v[32:33], v34, off
